# mixer_pass3_prefetch_v8
# speedup vs baseline: 1.0103x; 1.0103x over previous
; __device__ __forceinline__ void w_lru_m3(unsigned char* ws, const bf16_t* proj, bf16_t* y, int b, int ck_, int h, int lane) {
;     const int q = lane & 7, col = 64 * h + 8 * q;
;     const float* hinp = (const float*)(ws + WS_LRUIN) + (size_t)(b * NCH + ck_) * 512 + col;
;     const f32x4 h0 = *(const f32x4*)hinp, h1 = *(const f32x4*)(hinp + 4);
;     const float hin[8] = {h0[0], h0[1], h0[2], h0[3], h1[0], h1[1], h1[2], h1[3]};
; #pragma unroll
;     for (int i0 = 0; i0 < 8; i0 += 4) {
;         u32x4 rh[4], rp[4], rg[4];
; #pragma unroll
;         for (int i = 0; i < 4; ++i) { const size_t row = (size_t)b * SEQ + 64 * ck_ + (lane >> 3) + 8 * (i0 + i);
;             rh[i] = *(const u32x4*)(y + row * DM + col); rp[i] = *(const u32x4*)((const bf16_t*)(ws + WS_P) + row * 512 + col); rg[i] = *(const u32x4*)(proj + row * NIN + C_LG + col); }
.LBB0_184:
	s_lshr_b32 s21, s20, 8
	s_lshr_b32 s24, s20, 9
	s_add_i32 s21, s21, s20
	s_and_b32 s24, s24, 12
	s_add_i32 s21, s21, s24
	s_and_b32 s21, s21, 15
	s_cmp_gt_u32 s21, 7
	s_cbranch_scc1 .LBB0_183
	s_ashr_i32 s24, s20, 31
	s_ashr_i32 s34, s20, 4
	s_lshr_b32 s24, s24, 25
	s_add_i32 s24, s34, s24
	s_ashr_i32 s40, s24, 7
	s_and_b32 s24, s24, 0x3ffff80
	v_mov_b32_e32 v12, v132
	s_ashr_i32 s35, s34, 31
	s_sub_i32 s24, s34, s24
	s_lshl_b32 s21, s21, 6
	v_lshlrev_b32_e32 v0, 3, v12
	s_lshl_b64 s[34:35], s[34:35], 11
	v_and_or_b32 v13, v0, 56, s21
	s_add_u32 s34, s7, s34
	s_addc_u32 s35, s28, s35
	v_lshlrev_b32_e32 v2, 2, v13
	s_ashr_i32 s41, s40, 31
	s_lshl_b32 s21, s24, 6
	v_lshl_add_u64 v[0:1], s[34:35], 0, v[2:3]
	s_lshl_b64 s[34:35], s[40:41], 13
	s_ashr_i32 s24, s21, 31
	global_load_dwordx4 v[8:11], v[0:1], off
	global_load_dwordx4 v[4:7], v[0:1], off offset:16
	s_add_u32 s34, s34, s21
	v_ashrrev_i32_e32 v0, 3, v12
	s_addc_u32 s35, s35, s24
	v_ashrrev_i32_e32 v1, 31, v0
	v_lshl_add_u64 v[60:61], s[34:35], 0, v[0:1]
	v_lshlrev_b32_e32 v2, 1, v13
	v_lshl_add_u64 v[62:63], s[10:11], 0, v[2:3]
	v_lshlrev_b64 v[12:13], 11, v[60:61]
	v_lshl_add_u64 v[0:1], s[82:83], 0, v[2:3]
	v_lshl_add_u64 v[72:73], v[62:63], 0, v[12:13]
	v_lshlrev_b64 v[12:13], 10, v[60:61]
	v_lshl_add_u64 v[12:13], v[0:1], 0, v[12:13]
	global_load_dwordx4 v[52:55], v[72:73], off
	global_load_dwordx4 v[56:59], v[12:13], off
	v_mov_b64_e32 v[12:13], s[8:9]
	v_mad_u64_u32 v[12:13], s[34:35], v60, s72, v[12:13]
	v_mad_i32_i24 v13, v61, s72, v13
	v_lshl_add_u64 v[64:65], v[12:13], 0, v[2:3]
	global_load_dwordx4 v[48:51], v[64:65], off offset:1024
	v_lshl_add_u64 v[12:13], v[60:61], 0, 8
	v_lshlrev_b64 v[14:15], 11, v[12:13]
	v_lshlrev_b64 v[12:13], 10, v[12:13]
	v_lshl_add_u64 v[12:13], v[0:1], 0, v[12:13]
	global_load_dwordx4 v[44:47], v[12:13], off
	v_add_co_u32_e32 v12, vcc, s97, v64
	v_lshl_add_u64 v[70:71], v[62:63], 0, v[14:15]
	s_nop 0
	v_addc_co_u32_e32 v13, vcc, 0, v65, vcc
	global_load_dwordx4 v[40:43], v[70:71], off
	global_load_dwordx4 v[36:39], v[12:13], off offset:1024
	v_lshl_add_u64 v[12:13], v[60:61], 0, 16
	v_lshlrev_b64 v[14:15], 11, v[12:13]
	v_lshlrev_b64 v[12:13], 10, v[12:13]
	v_lshl_add_u64 v[68:69], v[62:63], 0, v[14:15]
	v_lshl_add_u64 v[12:13], v[0:1], 0, v[12:13]
	global_load_dwordx4 v[28:31], v[68:69], off
	global_load_dwordx4 v[32:35], v[12:13], off
	v_add_co_u32_e32 v12, vcc, s13, v64
	v_lshl_add_u64 v[16:17], v[60:61], 0, 24
	s_nop 0
	v_addc_co_u32_e32 v13, vcc, 0, v65, vcc
	v_add_co_u32_e32 v20, vcc, s47, v64
	global_load_dwordx4 v[24:27], v[12:13], off offset:1024
	s_nop 0
	v_addc_co_u32_e32 v21, vcc, 0, v65, vcc
	global_load_dwordx4 v[20:23], v[20:21], off offset:1024
	v_lshlrev_b64 v[12:13], 11, v[16:17]
	v_lshlrev_b64 v[16:17], 10, v[16:17]
	v_lshl_add_u64 v[66:67], v[62:63], 0, v[12:13]
	v_lshl_add_u64 v[16:17], v[0:1], 0, v[16:17]
	global_load_dwordx4 v[12:15], v[66:67], off
	s_mov_b32 s21, 0x54000
	global_load_dwordx4 v[16:19], v[16:17], off
	v_lshl_add_u64 v[186:187], v[60:61], 0, 32
	v_lshlrev_b64 v[188:189], 11, v[186:187]
	v_lshl_add_u64 v[188:189], v[62:63], 0, v[188:189]
	global_load_dwordx4 v[222:225], v[188:189], off
	v_lshlrev_b64 v[188:189], 10, v[186:187]
	v_lshl_add_u64 v[188:189], v[0:1], 0, v[188:189]
	global_load_dwordx4 v[238:241], v[188:189], off
	v_mov_b32_e32 v190, s33
	v_mov_b32_e32 v191, 0
	v_lshl_add_u64 v[188:189], v[64:65], 0, v[190:191]
	global_load_dwordx4 v[134:137], v[188:189], off offset:1024
	v_lshl_add_u64 v[186:187], v[60:61], 0, 40
	v_lshlrev_b64 v[188:189], 11, v[186:187]
	v_lshl_add_u64 v[188:189], v[62:63], 0, v[188:189]
	global_load_dwordx4 v[226:229], v[188:189], off
	v_lshlrev_b64 v[188:189], 10, v[186:187]
	v_lshl_add_u64 v[188:189], v[0:1], 0, v[188:189]
	global_load_dwordx4 v[242:245], v[188:189], off
	v_mov_b32_e32 v190, s52
	v_mov_b32_e32 v191, 0
	v_lshl_add_u64 v[188:189], v[64:65], 0, v[190:191]
	global_load_dwordx4 v[138:141], v[188:189], off offset:1024
	v_lshl_add_u64 v[186:187], v[60:61], 0, 48
	v_lshlrev_b64 v[188:189], 11, v[186:187]
	v_lshl_add_u64 v[188:189], v[62:63], 0, v[188:189]
	global_load_dwordx4 v[230:233], v[188:189], off
	v_lshlrev_b64 v[188:189], 10, v[186:187]
	v_lshl_add_u64 v[188:189], v[0:1], 0, v[188:189]
	global_load_dwordx4 v[246:249], v[188:189], off
	v_mov_b32_e32 v190, s69
	v_mov_b32_e32 v191, 0
	v_lshl_add_u64 v[188:189], v[64:65], 0, v[190:191]
	global_load_dwordx4 v[146:149], v[188:189], off offset:1024
	v_lshl_add_u64 v[186:187], v[60:61], 0, 56
	v_lshlrev_b64 v[188:189], 11, v[186:187]
	v_lshl_add_u64 v[188:189], v[62:63], 0, v[188:189]
	global_load_dwordx4 v[234:237], v[188:189], off
	v_lshlrev_b64 v[188:189], 10, v[186:187]
	v_lshl_add_u64 v[188:189], v[0:1], 0, v[188:189]
	global_load_dwordx4 v[250:253], v[188:189], off
	v_mov_b32_e32 v190, s21
	v_mov_b32_e32 v191, 0
	v_lshl_add_u64 v[188:189], v[64:65], 0, v[190:191]
	global_load_dwordx4 v[150:153], v[188:189], off offset:1024
	s_waitcnt vmcnt(12) lgkmcnt(0)
; __device__ __forceinline__ u32x4 pack8(const float (&v)[8]) { u32x4 w; w.x = pk2(v[0], v[1]); w.y = pk2(v[2], v[3]); w.z = pk2(v[4], v[5]); w.w = pk2(v[6], v[7]); return w; }
; __device__ __forceinline__ float gelu_tanh(float x) { const float z = 0.7978845608028654f * (x + 0.044715f * x * x * x); const float t = 1.0f - 2.0f * __builtin_amdgcn_rcpf(__expf(2.0f * z) + 1.0f); return 0.5f * x * (1.0f + t); }
; __device__ __forceinline__ void w_lru_m3(unsigned char* ws, const bf16_t* proj, bf16_t* y, int b, int ck_, int h, int lane) {
;     ...
; #pragma unroll
;         for (int i = 0; i < 4; ++i) { const size_t row = (size_t)b * SEQ + 64 * ck_ + (lane >> 3) + 8 * (i0 + i);
;             float hl[8], pv[8], g[8], o[8]; unpack8(rh[i], hl); unpack8(rp[i], pv); unpack8(rg[i], g);
; #pragma unroll
;             for (int j = 0; j < 8; ++j) o[j] = (hl[j] + pv[j] * hin[j]) * gelu_tanh(g[j]);
;             *(u32x4*)(y + row * DM + col) = pack8(o); }
	v_lshlrev_b32_e32 v74, 16, v52
	v_and_b32_e32 v75, 0xffff0000, v52
	v_lshlrev_b32_e32 v76, 16, v56
	v_and_b32_e32 v77, 0xffff0000, v56
	v_pk_fma_f32 v[74:75], v[8:9], v[76:77], v[74:75]
	v_lshlrev_b32_e32 v52, 16, v53
	v_and_b32_e32 v53, 0xffff0000, v53
	v_lshlrev_b32_e32 v78, 16, v48
	v_mul_f32_e32 v2, 0x3d372713, v78
	v_and_b32_e32 v79, 0xffff0000, v48
	v_mul_f32_e32 v2, v2, v78
	v_mov_b32_e32 v48, v78
	v_fmac_f32_e32 v48, v2, v48
	v_mul_f32_e32 v2, 0x3f4c422a, v48
	v_add_f32_e32 v2, v2, v2
	v_mul_f32_e32 v2, 0x3fb8aa3b, v2
	v_exp_f32_e32 v2, v2
	v_mov_b32_e32 v48, v79
	v_lshlrev_b32_e32 v56, 16, v57
	v_and_b32_e32 v57, 0xffff0000, v57
	v_add_f32_e32 v2, 1.0, v2
	v_rcp_f32_e32 v80, v2
	v_mul_f32_e32 v2, 0x3d372713, v79
	v_mul_f32_e32 v2, v2, v79
	v_fmac_f32_e32 v48, v2, v48
	v_mul_f32_e32 v2, 0x3f4c422a, v48
	v_add_f32_e32 v2, v2, v2
	v_mul_f32_e32 v2, 0x3fb8aa3b, v2
	v_exp_f32_e32 v2, v2
	v_pk_mul_f32 v[78:79], v[78:79], 0.5 op_sel_hi:[1,0]
	v_lshlrev_b32_e32 v48, 16, v49
	v_and_b32_e32 v49, 0xffff0000, v49
	v_add_f32_e32 v2, 1.0, v2
	v_rcp_f32_e32 v81, v2
	v_mul_f32_e32 v2, 0x3d372713, v48
	v_mul_f32_e32 v2, v2, v48
	v_pk_fma_f32 v[52:53], v[10:11], v[56:57], v[52:53]
	v_pk_fma_f32 v[76:77], v[80:81], 2.0, 1.0 op_sel_hi:[1,0,0] neg_lo:[1,0,0] neg_hi:[1,0,0]
	v_mov_b32_e32 v56, v49
	v_pk_add_f32 v[76:77], v[76:77], 1.0 op_sel_hi:[1,0]
	s_nop 0
	v_pk_mul_f32 v[76:77], v[78:79], v[76:77]
	s_nop 0
	v_pk_mul_f32 v[74:75], v[74:75], v[76:77]
	v_mov_b32_e32 v76, v48
	v_fmac_f32_e32 v76, v2, v76
	v_mul_f32_e32 v2, 0x3f4c422a, v76
	v_add_f32_e32 v2, v2, v2
	v_mul_f32_e32 v2, 0x3fb8aa3b, v2
	v_exp_f32_e32 v2, v2
	s_nop 0
	v_add_f32_e32 v2, 1.0, v2
	v_rcp_f32_e32 v76, v2
	v_mul_f32_e32 v2, 0x3d372713, v49
	v_mul_f32_e32 v2, v2, v49
	v_fmac_f32_e32 v56, v2, v56
	v_mul_f32_e32 v2, 0x3f4c422a, v56
	v_add_f32_e32 v2, v2, v2
	v_mul_f32_e32 v2, 0x3fb8aa3b, v2
	v_exp_f32_e32 v2, v2
	v_pk_mul_f32 v[48:49], v[48:49], 0.5 op_sel_hi:[1,0]
	v_add_f32_e32 v2, 1.0, v2
	v_rcp_f32_e32 v77, v2
	s_nop 0
	v_pk_fma_f32 v[56:57], v[76:77], 2.0, 1.0 op_sel_hi:[1,0,0] neg_lo:[1,0,0] neg_hi:[1,0,0]
	v_lshlrev_b32_e32 v76, 16, v50
	v_mul_f32_e32 v2, 0x3d372713, v76
	v_and_b32_e32 v77, 0xffff0000, v50
	v_mul_f32_e32 v2, v2, v76
	v_mov_b32_e32 v50, v76
	v_fmac_f32_e32 v50, v2, v50
	v_mul_f32_e32 v2, 0x3f4c422a, v50
	v_add_f32_e32 v2, v2, v2
	v_mul_f32_e32 v2, 0x3fb8aa3b, v2
	v_exp_f32_e32 v2, v2
	v_mov_b32_e32 v50, v77
	v_pk_add_f32 v[56:57], v[56:57], 1.0 op_sel_hi:[1,0]
	v_add_f32_e32 v2, 1.0, v2
	v_rcp_f32_e32 v78, v2
	v_mul_f32_e32 v2, 0x3d372713, v77
	v_mul_f32_e32 v2, v2, v77
	v_fmac_f32_e32 v50, v2, v50
	v_mul_f32_e32 v2, 0x3f4c422a, v50
	v_add_f32_e32 v2, v2, v2
	v_mul_f32_e32 v2, 0x3fb8aa3b, v2
	v_exp_f32_e32 v2, v2
	v_lshlrev_b32_e32 v50, 16, v51
	v_pk_mul_f32 v[48:49], v[48:49], v[56:57]
	v_lshlrev_b32_e32 v56, 16, v58
	v_add_f32_e32 v2, 1.0, v2
	v_rcp_f32_e32 v79, v2
	v_mul_f32_e32 v2, 0x3d372713, v50
	v_and_b32_e32 v57, 0xffff0000, v58
	v_mul_f32_e32 v2, v2, v50
	v_mov_b32_e32 v58, v50
	v_fmac_f32_e32 v58, v2, v58
	v_mul_f32_e32 v2, 0x3f4c422a, v58
	v_add_f32_e32 v2, v2, v2
	v_mul_f32_e32 v2, 0x3fb8aa3b, v2
	v_exp_f32_e32 v2, v2
	v_pk_mul_f32 v[52:53], v[52:53], v[48:49]
	v_lshlrev_b32_e32 v48, 16, v54
	v_and_b32_e32 v49, 0xffff0000, v54
	v_pk_fma_f32 v[48:49], v[4:5], v[56:57], v[48:49]
	v_pk_fma_f32 v[56:57], v[78:79], 2.0, 1.0 op_sel_hi:[1,0,0] neg_lo:[1,0,0] neg_hi:[1,0,0]
	v_pk_mul_f32 v[76:77], v[76:77], 0.5 op_sel_hi:[1,0]
	v_pk_add_f32 v[56:57], v[56:57], 1.0 op_sel_hi:[1,0]
	v_and_b32_e32 v51, 0xffff0000, v51
	v_pk_mul_f32 v[56:57], v[76:77], v[56:57]
	v_add_f32_e32 v2, 1.0, v2
	v_pk_mul_f32 v[56:57], v[48:49], v[56:57]
	v_lshlrev_b32_e32 v48, 16, v55
	v_and_b32_e32 v49, 0xffff0000, v55
	v_lshlrev_b32_e32 v54, 16, v59
	v_and_b32_e32 v55, 0xffff0000, v59
	v_rcp_f32_e32 v58, v2
	v_mul_f32_e32 v2, 0x3d372713, v51
	v_pk_fma_f32 v[48:49], v[6:7], v[54:55], v[48:49]
	v_mul_f32_e32 v2, v2, v51
	v_mov_b32_e32 v54, v51
	v_fmac_f32_e32 v54, v2, v54
	v_mul_f32_e32 v2, 0x3f4c422a, v54
	v_add_f32_e32 v2, v2, v2
	v_mul_f32_e32 v2, 0x3fb8aa3b, v2
	v_exp_f32_e32 v2, v2
	v_pk_mul_f32 v[50:51], v[50:51], 0.5 op_sel_hi:[1,0]
	v_add_f32_e32 v2, 1.0, v2
	v_rcp_f32_e32 v59, v2
	s_nop 0
	v_pk_fma_f32 v[54:55], v[58:59], 2.0, 1.0 op_sel_hi:[1,0,0] neg_lo:[1,0,0] neg_hi:[1,0,0]
	s_nop 0
	v_pk_add_f32 v[54:55], v[54:55], 1.0 op_sel_hi:[1,0]
	s_nop 0
	v_pk_mul_f32 v[50:51], v[50:51], v[54:55]
	s_nop 0
	v_pk_mul_f32 v[54:55], v[48:49], v[50:51]
	v_cvt_pk_bf16_f32 v49, v52, v53
	v_lshlrev_b32_e32 v52, 16, v36
	v_mul_f32_e32 v2, 0x3d372713, v52
	v_and_b32_e32 v53, 0xffff0000, v36
	v_mul_f32_e32 v2, v2, v52
	v_mov_b32_e32 v36, v52
	v_fmac_f32_e32 v36, v2, v36
	v_mul_f32_e32 v2, 0x3f4c422a, v36
	v_add_f32_e32 v2, v2, v2
	v_mul_f32_e32 v2, 0x3fb8aa3b, v2
	v_exp_f32_e32 v2, v2
	v_cvt_pk_bf16_f32 v51, v54, v55
	v_mov_b32_e32 v36, v53
	v_cvt_pk_bf16_f32 v48, v74, v75
	v_add_f32_e32 v2, 1.0, v2
	v_rcp_f32_e32 v54, v2
	v_mul_f32_e32 v2, 0x3d372713, v53
	v_mul_f32_e32 v2, v2, v53
	v_fmac_f32_e32 v36, v2, v36
	v_mul_f32_e32 v2, 0x3f4c422a, v36
	v_add_f32_e32 v2, v2, v2
	v_mul_f32_e32 v2, 0x3fb8aa3b, v2
	v_exp_f32_e32 v2, v2
	v_cvt_pk_bf16_f32 v50, v56, v57
	global_store_dwordx4 v[72:73], v[48:51], off
	v_pk_mul_f32 v[52:53], v[52:53], 0.5 op_sel_hi:[1,0]
	v_add_f32_e32 v2, 1.0, v2
	v_rcp_f32_e32 v55, v2
	v_lshlrev_b32_e32 v48, 16, v40
	v_and_b32_e32 v49, 0xffff0000, v40
	v_lshlrev_b32_e32 v50, 16, v44
	v_and_b32_e32 v51, 0xffff0000, v44
	v_pk_fma_f32 v[48:49], v[8:9], v[50:51], v[48:49]
	v_pk_fma_f32 v[50:51], v[54:55], 2.0, 1.0 op_sel_hi:[1,0,0] neg_lo:[1,0,0] neg_hi:[1,0,0]
; __device__ __forceinline__ u32x4 pack8(const float (&v)[8]) { u32x4 w; w.x = pk2(v[0], v[1]); w.y = pk2(v[2], v[3]); w.z = pk2(v[4], v[5]); w.w = pk2(v[6], v[7]); return w; }
; __device__ __forceinline__ float gelu_tanh(float x) { const float z = 0.7978845608028654f * (x + 0.044715f * x * x * x); const float t = 1.0f - 2.0f * __builtin_amdgcn_rcpf(__expf(2.0f * z) + 1.0f); return 0.5f * x * (1.0f + t); }
; __device__ __forceinline__ void w_lru_m3(unsigned char* ws, const bf16_t* proj, bf16_t* y, int b, int ck_, int h, int lane) {
;     ...
; #pragma unroll
;         for (int i = 0; i < 4; ++i) { const size_t row = (size_t)b * SEQ + 64 * ck_ + (lane >> 3) + 8 * (i0 + i);
;             float hl[8], pv[8], g[8], o[8]; unpack8(rh[i], hl); unpack8(rp[i], pv); unpack8(rg[i], g);
; #pragma unroll
;             for (int j = 0; j < 8; ++j) o[j] = (hl[j] + pv[j] * hin[j]) * gelu_tanh(g[j]);
;             *(u32x4*)(y + row * DM + col) = pack8(o); }
	v_lshlrev_b32_e32 v36, 16, v37
	v_pk_add_f32 v[50:51], v[50:51], 1.0 op_sel_hi:[1,0]
	v_mul_f32_e32 v2, 0x3d372713, v36
	v_pk_mul_f32 v[50:51], v[52:53], v[50:51]
	v_mul_f32_e32 v2, v2, v36
	v_pk_mul_f32 v[48:49], v[48:49], v[50:51]
	v_mov_b32_e32 v50, v36
	v_fmac_f32_e32 v50, v2, v50
	v_mul_f32_e32 v2, 0x3f4c422a, v50
	v_add_f32_e32 v2, v2, v2
	v_mul_f32_e32 v2, 0x3fb8aa3b, v2
	v_exp_f32_e32 v2, v2
	v_and_b32_e32 v37, 0xffff0000, v37
	v_lshlrev_b32_e32 v40, 16, v41
	v_and_b32_e32 v41, 0xffff0000, v41
	v_add_f32_e32 v2, 1.0, v2
	v_lshlrev_b32_e32 v44, 16, v45
	v_and_b32_e32 v45, 0xffff0000, v45
	v_rcp_f32_e32 v50, v2
	v_mul_f32_e32 v2, 0x3d372713, v37
	v_pk_fma_f32 v[40:41], v[10:11], v[44:45], v[40:41]
	v_mul_f32_e32 v2, v2, v37
	v_mov_b32_e32 v44, v37
	v_fmac_f32_e32 v44, v2, v44
	v_mul_f32_e32 v2, 0x3f4c422a, v44
	v_add_f32_e32 v2, v2, v2
	v_mul_f32_e32 v2, 0x3fb8aa3b, v2
	v_exp_f32_e32 v2, v2
	v_pk_mul_f32 v[36:37], v[36:37], 0.5 op_sel_hi:[1,0]
	v_add_f32_e32 v2, 1.0, v2
	v_rcp_f32_e32 v51, v2
	s_nop 0
	v_pk_fma_f32 v[44:45], v[50:51], 2.0, 1.0 op_sel_hi:[1,0,0] neg_lo:[1,0,0] neg_hi:[1,0,0]
	v_lshlrev_b32_e32 v50, 16, v38
	v_mul_f32_e32 v2, 0x3d372713, v50
	v_and_b32_e32 v51, 0xffff0000, v38
	v_mul_f32_e32 v2, v2, v50
	v_mov_b32_e32 v38, v50
	v_fmac_f32_e32 v38, v2, v38
	v_mul_f32_e32 v2, 0x3f4c422a, v38
	v_add_f32_e32 v2, v2, v2
	v_mul_f32_e32 v2, 0x3fb8aa3b, v2
	v_exp_f32_e32 v2, v2
	v_mov_b32_e32 v38, v51
	v_pk_add_f32 v[44:45], v[44:45], 1.0 op_sel_hi:[1,0]
	v_add_f32_e32 v2, 1.0, v2
	v_rcp_f32_e32 v52, v2
	v_mul_f32_e32 v2, 0x3d372713, v51
	v_mul_f32_e32 v2, v2, v51
	v_fmac_f32_e32 v38, v2, v38
	v_mul_f32_e32 v2, 0x3f4c422a, v38
	v_add_f32_e32 v2, v2, v2
	v_mul_f32_e32 v2, 0x3fb8aa3b, v2
	v_exp_f32_e32 v2, v2
	v_lshlrev_b32_e32 v38, 16, v39
	v_pk_mul_f32 v[36:37], v[36:37], v[44:45]
	v_lshlrev_b32_e32 v44, 16, v46
	v_add_f32_e32 v2, 1.0, v2
	v_rcp_f32_e32 v53, v2
	v_mul_f32_e32 v2, 0x3d372713, v38
	v_and_b32_e32 v45, 0xffff0000, v46
	v_mul_f32_e32 v2, v2, v38
	v_mov_b32_e32 v46, v38
	v_fmac_f32_e32 v46, v2, v46
	v_mul_f32_e32 v2, 0x3f4c422a, v46
	v_add_f32_e32 v2, v2, v2
	v_mul_f32_e32 v2, 0x3fb8aa3b, v2
	v_exp_f32_e32 v2, v2
	v_pk_mul_f32 v[40:41], v[40:41], v[36:37]
	v_lshlrev_b32_e32 v36, 16, v42
	v_and_b32_e32 v37, 0xffff0000, v42
	v_pk_fma_f32 v[36:37], v[4:5], v[44:45], v[36:37]
	v_pk_fma_f32 v[44:45], v[52:53], 2.0, 1.0 op_sel_hi:[1,0,0] neg_lo:[1,0,0] neg_hi:[1,0,0]
	v_pk_mul_f32 v[50:51], v[50:51], 0.5 op_sel_hi:[1,0]
	v_pk_add_f32 v[44:45], v[44:45], 1.0 op_sel_hi:[1,0]
	v_and_b32_e32 v39, 0xffff0000, v39
	v_pk_mul_f32 v[44:45], v[50:51], v[44:45]
	v_add_f32_e32 v2, 1.0, v2
	v_pk_mul_f32 v[44:45], v[36:37], v[44:45]
	v_lshlrev_b32_e32 v36, 16, v43
	v_and_b32_e32 v37, 0xffff0000, v43
	v_lshlrev_b32_e32 v42, 16, v47
	v_and_b32_e32 v43, 0xffff0000, v47
	v_rcp_f32_e32 v46, v2
	v_mul_f32_e32 v2, 0x3d372713, v39
	v_pk_fma_f32 v[36:37], v[6:7], v[42:43], v[36:37]
	v_mul_f32_e32 v2, v2, v39
	v_mov_b32_e32 v42, v39
	v_fmac_f32_e32 v42, v2, v42
	v_mul_f32_e32 v2, 0x3f4c422a, v42
	v_add_f32_e32 v2, v2, v2
	v_mul_f32_e32 v2, 0x3fb8aa3b, v2
	v_exp_f32_e32 v2, v2
	v_pk_mul_f32 v[38:39], v[38:39], 0.5 op_sel_hi:[1,0]
	v_add_f32_e32 v2, 1.0, v2
	v_rcp_f32_e32 v47, v2
	s_nop 0
	v_pk_fma_f32 v[42:43], v[46:47], 2.0, 1.0 op_sel_hi:[1,0,0] neg_lo:[1,0,0] neg_hi:[1,0,0]
	s_nop 0
	v_pk_add_f32 v[42:43], v[42:43], 1.0 op_sel_hi:[1,0]
	s_nop 0
	v_pk_mul_f32 v[38:39], v[38:39], v[42:43]
	s_nop 0
	v_pk_mul_f32 v[42:43], v[36:37], v[38:39]
	v_cvt_pk_bf16_f32 v37, v40, v41
	v_lshlrev_b32_e32 v40, 16, v24
	v_mul_f32_e32 v2, 0x3d372713, v40
	v_and_b32_e32 v41, 0xffff0000, v24
	v_mul_f32_e32 v2, v2, v40
	v_mov_b32_e32 v24, v40
	v_fmac_f32_e32 v24, v2, v24
	v_mul_f32_e32 v2, 0x3f4c422a, v24
	v_add_f32_e32 v2, v2, v2
	v_mul_f32_e32 v2, 0x3fb8aa3b, v2
	v_exp_f32_e32 v2, v2
	v_cvt_pk_bf16_f32 v39, v42, v43
	v_mov_b32_e32 v24, v41
	v_cvt_pk_bf16_f32 v36, v48, v49
	v_add_f32_e32 v2, 1.0, v2
	v_rcp_f32_e32 v42, v2
	v_mul_f32_e32 v2, 0x3d372713, v41
	v_mul_f32_e32 v2, v2, v41
	v_fmac_f32_e32 v24, v2, v24
	v_mul_f32_e32 v2, 0x3f4c422a, v24
	v_add_f32_e32 v2, v2, v2
	v_mul_f32_e32 v2, 0x3fb8aa3b, v2
	v_exp_f32_e32 v2, v2
	v_cvt_pk_bf16_f32 v38, v44, v45
	global_store_dwordx4 v[70:71], v[36:39], off
	v_pk_mul_f32 v[40:41], v[40:41], 0.5 op_sel_hi:[1,0]
	v_add_f32_e32 v2, 1.0, v2
	v_rcp_f32_e32 v43, v2
	v_lshlrev_b32_e32 v36, 16, v28
	v_and_b32_e32 v37, 0xffff0000, v28
	v_lshlrev_b32_e32 v38, 16, v32
	v_and_b32_e32 v39, 0xffff0000, v32
	v_pk_fma_f32 v[36:37], v[8:9], v[38:39], v[36:37]
	v_pk_fma_f32 v[38:39], v[42:43], 2.0, 1.0 op_sel_hi:[1,0,0] neg_lo:[1,0,0] neg_hi:[1,0,0]
	v_lshlrev_b32_e32 v24, 16, v25
	v_pk_add_f32 v[38:39], v[38:39], 1.0 op_sel_hi:[1,0]
	v_mul_f32_e32 v2, 0x3d372713, v24
	v_pk_mul_f32 v[38:39], v[40:41], v[38:39]
	v_mul_f32_e32 v2, v2, v24
	v_pk_mul_f32 v[36:37], v[36:37], v[38:39]
	v_mov_b32_e32 v38, v24
	v_fmac_f32_e32 v38, v2, v38
	v_mul_f32_e32 v2, 0x3f4c422a, v38
	v_add_f32_e32 v2, v2, v2
	v_mul_f32_e32 v2, 0x3fb8aa3b, v2
	v_exp_f32_e32 v2, v2
	v_and_b32_e32 v25, 0xffff0000, v25
	v_lshlrev_b32_e32 v28, 16, v29
	v_and_b32_e32 v29, 0xffff0000, v29
	v_add_f32_e32 v2, 1.0, v2
	v_lshlrev_b32_e32 v32, 16, v33
	v_and_b32_e32 v33, 0xffff0000, v33
	v_rcp_f32_e32 v38, v2
	v_mul_f32_e32 v2, 0x3d372713, v25
	v_pk_fma_f32 v[28:29], v[10:11], v[32:33], v[28:29]
	v_mul_f32_e32 v2, v2, v25
	v_mov_b32_e32 v32, v25
	v_fmac_f32_e32 v32, v2, v32
	v_mul_f32_e32 v2, 0x3f4c422a, v32
	v_add_f32_e32 v2, v2, v2
	v_mul_f32_e32 v2, 0x3fb8aa3b, v2
	v_exp_f32_e32 v2, v2
	v_pk_mul_f32 v[24:25], v[24:25], 0.5 op_sel_hi:[1,0]
	v_add_f32_e32 v2, 1.0, v2
; __device__ __forceinline__ u32x4 pack8(const float (&v)[8]) { u32x4 w; w.x = pk2(v[0], v[1]); w.y = pk2(v[2], v[3]); w.z = pk2(v[4], v[5]); w.w = pk2(v[6], v[7]); return w; }
; __device__ __forceinline__ float gelu_tanh(float x) { const float z = 0.7978845608028654f * (x + 0.044715f * x * x * x); const float t = 1.0f - 2.0f * __builtin_amdgcn_rcpf(__expf(2.0f * z) + 1.0f); return 0.5f * x * (1.0f + t); }
; __device__ __forceinline__ void w_lru_m3(unsigned char* ws, const bf16_t* proj, bf16_t* y, int b, int ck_, int h, int lane) {
;     ...
; #pragma unroll
;         for (int i = 0; i < 4; ++i) { const size_t row = (size_t)b * SEQ + 64 * ck_ + (lane >> 3) + 8 * (i0 + i);
;             float hl[8], pv[8], g[8], o[8]; unpack8(rh[i], hl); unpack8(rp[i], pv); unpack8(rg[i], g);
; #pragma unroll
;             for (int j = 0; j < 8; ++j) o[j] = (hl[j] + pv[j] * hin[j]) * gelu_tanh(g[j]);
;             *(u32x4*)(y + row * DM + col) = pack8(o); }
	v_rcp_f32_e32 v39, v2
	s_nop 0
	v_pk_fma_f32 v[32:33], v[38:39], 2.0, 1.0 op_sel_hi:[1,0,0] neg_lo:[1,0,0] neg_hi:[1,0,0]
	v_lshlrev_b32_e32 v38, 16, v26
	v_mul_f32_e32 v2, 0x3d372713, v38
	v_and_b32_e32 v39, 0xffff0000, v26
	v_mul_f32_e32 v2, v2, v38
	v_mov_b32_e32 v26, v38
	v_fmac_f32_e32 v26, v2, v26
	v_mul_f32_e32 v2, 0x3f4c422a, v26
	v_add_f32_e32 v2, v2, v2
	v_mul_f32_e32 v2, 0x3fb8aa3b, v2
	v_exp_f32_e32 v2, v2
	v_mov_b32_e32 v26, v39
	v_pk_add_f32 v[32:33], v[32:33], 1.0 op_sel_hi:[1,0]
	v_add_f32_e32 v2, 1.0, v2
	v_rcp_f32_e32 v40, v2
	v_mul_f32_e32 v2, 0x3d372713, v39
	v_mul_f32_e32 v2, v2, v39
	v_fmac_f32_e32 v26, v2, v26
	v_mul_f32_e32 v2, 0x3f4c422a, v26
	v_add_f32_e32 v2, v2, v2
	v_mul_f32_e32 v2, 0x3fb8aa3b, v2
	v_exp_f32_e32 v2, v2
	v_lshlrev_b32_e32 v26, 16, v27
	v_pk_mul_f32 v[24:25], v[24:25], v[32:33]
	v_lshlrev_b32_e32 v32, 16, v34
	v_add_f32_e32 v2, 1.0, v2
	v_rcp_f32_e32 v41, v2
	v_mul_f32_e32 v2, 0x3d372713, v26
	v_and_b32_e32 v33, 0xffff0000, v34
	v_mul_f32_e32 v2, v2, v26
	v_mov_b32_e32 v34, v26
	v_fmac_f32_e32 v34, v2, v34
	v_mul_f32_e32 v2, 0x3f4c422a, v34
	v_add_f32_e32 v2, v2, v2
	v_mul_f32_e32 v2, 0x3fb8aa3b, v2
	v_exp_f32_e32 v2, v2
	v_pk_mul_f32 v[28:29], v[28:29], v[24:25]
	v_lshlrev_b32_e32 v24, 16, v30
	v_and_b32_e32 v25, 0xffff0000, v30
	v_pk_fma_f32 v[24:25], v[4:5], v[32:33], v[24:25]
	v_pk_fma_f32 v[32:33], v[40:41], 2.0, 1.0 op_sel_hi:[1,0,0] neg_lo:[1,0,0] neg_hi:[1,0,0]
	v_pk_mul_f32 v[38:39], v[38:39], 0.5 op_sel_hi:[1,0]
	v_pk_add_f32 v[32:33], v[32:33], 1.0 op_sel_hi:[1,0]
	v_and_b32_e32 v27, 0xffff0000, v27
	v_pk_mul_f32 v[32:33], v[38:39], v[32:33]
	v_add_f32_e32 v2, 1.0, v2
	v_pk_mul_f32 v[32:33], v[24:25], v[32:33]
	v_lshlrev_b32_e32 v24, 16, v31
	v_and_b32_e32 v25, 0xffff0000, v31
	v_lshlrev_b32_e32 v30, 16, v35
	v_and_b32_e32 v31, 0xffff0000, v35
	v_rcp_f32_e32 v34, v2
	v_mul_f32_e32 v2, 0x3d372713, v27
	v_pk_fma_f32 v[24:25], v[6:7], v[30:31], v[24:25]
	v_mul_f32_e32 v2, v2, v27
	v_mov_b32_e32 v30, v27
	v_fmac_f32_e32 v30, v2, v30
	v_mul_f32_e32 v2, 0x3f4c422a, v30
	v_add_f32_e32 v2, v2, v2
	v_mul_f32_e32 v2, 0x3fb8aa3b, v2
	v_exp_f32_e32 v2, v2
	v_pk_mul_f32 v[26:27], v[26:27], 0.5 op_sel_hi:[1,0]
	v_add_f32_e32 v2, 1.0, v2
	v_rcp_f32_e32 v35, v2
	s_nop 0
	v_pk_fma_f32 v[30:31], v[34:35], 2.0, 1.0 op_sel_hi:[1,0,0] neg_lo:[1,0,0] neg_hi:[1,0,0]
	s_nop 0
	v_pk_add_f32 v[30:31], v[30:31], 1.0 op_sel_hi:[1,0]
	s_nop 0
	v_pk_mul_f32 v[26:27], v[26:27], v[30:31]
	s_nop 0
	v_pk_mul_f32 v[30:31], v[24:25], v[26:27]
	v_cvt_pk_bf16_f32 v25, v28, v29
	v_lshlrev_b32_e32 v28, 16, v20
	v_cvt_pk_bf16_f32 v24, v36, v37
	v_cvt_pk_bf16_f32 v26, v32, v33
	v_cvt_pk_bf16_f32 v27, v30, v31
	v_mul_f32_e32 v2, 0x3d372713, v28
	global_store_dwordx4 v[68:69], v[24:27], off
	v_mul_f32_e32 v2, v2, v28
	v_and_b32_e32 v29, 0xffff0000, v20
	v_lshlrev_b32_e32 v24, 16, v12
	v_and_b32_e32 v25, 0xffff0000, v12
	v_mov_b32_e32 v12, v28
	v_fmac_f32_e32 v12, v2, v12
	v_mul_f32_e32 v2, 0x3f4c422a, v12
	v_add_f32_e32 v2, v2, v2
	v_mul_f32_e32 v2, 0x3fb8aa3b, v2
	v_exp_f32_e32 v2, v2
	v_mov_b32_e32 v12, v29
	v_lshlrev_b32_e32 v26, 16, v16
	v_and_b32_e32 v27, 0xffff0000, v16
	v_add_f32_e32 v2, 1.0, v2
	v_rcp_f32_e32 v30, v2
	v_mul_f32_e32 v2, 0x3d372713, v29
	v_mul_f32_e32 v2, v2, v29
	v_fmac_f32_e32 v12, v2, v12
	v_mul_f32_e32 v2, 0x3f4c422a, v12
	v_add_f32_e32 v2, v2, v2
	v_mul_f32_e32 v2, 0x3fb8aa3b, v2
	v_exp_f32_e32 v2, v2
	v_pk_fma_f32 v[24:25], v[8:9], v[26:27], v[24:25]
	v_pk_mul_f32 v[28:29], v[28:29], 0.5 op_sel_hi:[1,0]
	v_lshlrev_b32_e32 v20, 16, v21
	v_add_f32_e32 v2, 1.0, v2
	v_rcp_f32_e32 v31, v2
	v_mul_f32_e32 v2, 0x3d372713, v20
	v_mul_f32_e32 v2, v2, v20
	v_and_b32_e32 v21, 0xffff0000, v21
	v_pk_fma_f32 v[26:27], v[30:31], 2.0, 1.0 op_sel_hi:[1,0,0] neg_lo:[1,0,0] neg_hi:[1,0,0]
	v_lshlrev_b32_e32 v12, 16, v13
	v_pk_add_f32 v[26:27], v[26:27], 1.0 op_sel_hi:[1,0]
	v_and_b32_e32 v13, 0xffff0000, v13
	v_pk_mul_f32 v[26:27], v[28:29], v[26:27]
	v_lshlrev_b32_e32 v16, 16, v17
	v_pk_mul_f32 v[24:25], v[24:25], v[26:27]
	v_mov_b32_e32 v26, v20
	v_fmac_f32_e32 v26, v2, v26
	v_mul_f32_e32 v2, 0x3f4c422a, v26
	v_add_f32_e32 v2, v2, v2
	v_mul_f32_e32 v2, 0x3fb8aa3b, v2
	v_exp_f32_e32 v2, v2
	v_and_b32_e32 v17, 0xffff0000, v17
	v_pk_fma_f32 v[12:13], v[10:11], v[16:17], v[12:13]
	v_mov_b32_e32 v16, v21
	v_add_f32_e32 v2, 1.0, v2
	v_rcp_f32_e32 v26, v2
	v_mul_f32_e32 v2, 0x3d372713, v21
	v_mul_f32_e32 v2, v2, v21
	v_fmac_f32_e32 v16, v2, v16
	v_mul_f32_e32 v2, 0x3f4c422a, v16
	v_add_f32_e32 v2, v2, v2
	v_mul_f32_e32 v2, 0x3fb8aa3b, v2
	v_exp_f32_e32 v2, v2
	v_pk_mul_f32 v[20:21], v[20:21], 0.5 op_sel_hi:[1,0]
	v_add_f32_e32 v2, 1.0, v2
	v_rcp_f32_e32 v27, v2
	s_nop 0
	v_pk_fma_f32 v[16:17], v[26:27], 2.0, 1.0 op_sel_hi:[1,0,0] neg_lo:[1,0,0] neg_hi:[1,0,0]
	s_nop 0
	v_pk_add_f32 v[16:17], v[16:17], 1.0 op_sel_hi:[1,0]
	v_lshlrev_b32_e32 v26, 16, v22
	v_pk_mul_f32 v[16:17], v[20:21], v[16:17]
	v_mul_f32_e32 v2, 0x3d372713, v26
	v_pk_mul_f32 v[16:17], v[12:13], v[16:17]
	v_lshlrev_b32_e32 v12, 16, v14
	v_and_b32_e32 v13, 0xffff0000, v14
	v_mul_f32_e32 v2, v2, v26
	v_mov_b32_e32 v14, v26
	v_fmac_f32_e32 v14, v2, v14
	v_mul_f32_e32 v2, 0x3f4c422a, v14
	v_add_f32_e32 v2, v2, v2
	v_mul_f32_e32 v2, 0x3fb8aa3b, v2
	v_exp_f32_e32 v2, v2
	v_and_b32_e32 v27, 0xffff0000, v22
	v_mov_b32_e32 v14, v27
	v_lshlrev_b32_e32 v20, 16, v18
	v_add_f32_e32 v2, 1.0, v2
	v_rcp_f32_e32 v28, v2
	v_mul_f32_e32 v2, 0x3d372713, v27
	v_mul_f32_e32 v2, v2, v27
	v_fmac_f32_e32 v14, v2, v14
	v_mul_f32_e32 v2, 0x3f4c422a, v14
	v_add_f32_e32 v2, v2, v2
	v_mul_f32_e32 v2, 0x3fb8aa3b, v2
	v_exp_f32_e32 v2, v2
	v_and_b32_e32 v21, 0xffff0000, v18
; __device__ __forceinline__ u32x4 pack8(const float (&v)[8]) { u32x4 w; w.x = pk2(v[0], v[1]); w.y = pk2(v[2], v[3]); w.z = pk2(v[4], v[5]); w.w = pk2(v[6], v[7]); return w; }
; __device__ __forceinline__ float gelu_tanh(float x) { const float z = 0.7978845608028654f * (x + 0.044715f * x * x * x); const float t = 1.0f - 2.0f * __builtin_amdgcn_rcpf(__expf(2.0f * z) + 1.0f); return 0.5f * x * (1.0f + t); }
; __device__ __forceinline__ void w_lru_m3(unsigned char* ws, const bf16_t* proj, bf16_t* y, int b, int ck_, int h, int lane) {
;     ...
;     for (int i0 = 0; i0 < 8; i0 += 4) {
;         u32x4 rh[4], rp[4], rg[4];
; #pragma unroll
;         for (int i = 0; i < 4; ++i) { const size_t row = (size_t)b * SEQ + 64 * ck_ + (lane >> 3) + 8 * (i0 + i);
;             rh[i] = *(const u32x4*)(y + row * DM + col); rp[i] = *(const u32x4*)((const bf16_t*)(ws + WS_P) + row * 512 + col); rg[i] = *(const u32x4*)(proj + row * NIN + C_LG + col); }
; #pragma unroll
;         for (int i = 0; i < 4; ++i) { const size_t row = (size_t)b * SEQ + 64 * ck_ + (lane >> 3) + 8 * (i0 + i);
;             float hl[8], pv[8], g[8], o[8]; unpack8(rh[i], hl); unpack8(rp[i], pv); unpack8(rg[i], g);
; #pragma unroll
;             for (int j = 0; j < 8; ++j) o[j] = (hl[j] + pv[j] * hin[j]) * gelu_tanh(g[j]);
;             *(u32x4*)(y + row * DM + col) = pack8(o); }
	v_lshlrev_b32_e32 v18, 16, v23
	v_mov_b32_e32 v22, v18
	v_add_f32_e32 v2, 1.0, v2
	v_rcp_f32_e32 v29, v2
	v_mul_f32_e32 v2, 0x3d372713, v18
	v_mul_f32_e32 v2, v2, v18
	v_fmac_f32_e32 v22, v2, v22
	v_mul_f32_e32 v2, 0x3f4c422a, v22
	v_add_f32_e32 v2, v2, v2
	v_mul_f32_e32 v2, 0x3fb8aa3b, v2
	v_exp_f32_e32 v2, v2
	v_pk_fma_f32 v[12:13], v[4:5], v[20:21], v[12:13]
	v_pk_fma_f32 v[20:21], v[28:29], 2.0, 1.0 op_sel_hi:[1,0,0] neg_lo:[1,0,0] neg_hi:[1,0,0]
	v_pk_mul_f32 v[26:27], v[26:27], 0.5 op_sel_hi:[1,0]
	v_pk_add_f32 v[20:21], v[20:21], 1.0 op_sel_hi:[1,0]
	v_lshlrev_b32_e32 v14, 16, v19
	v_pk_mul_f32 v[20:21], v[26:27], v[20:21]
	v_add_f32_e32 v2, 1.0, v2
	v_pk_mul_f32 v[20:21], v[12:13], v[20:21]
	v_lshlrev_b32_e32 v12, 16, v15
	v_and_b32_e32 v13, 0xffff0000, v15
	v_and_b32_e32 v15, 0xffff0000, v19
	v_and_b32_e32 v19, 0xffff0000, v23
	v_rcp_f32_e32 v22, v2
	v_mul_f32_e32 v2, 0x3d372713, v19
	v_pk_fma_f32 v[12:13], v[6:7], v[14:15], v[12:13]
	v_mul_f32_e32 v2, v2, v19
	v_mov_b32_e32 v14, v19
	v_fmac_f32_e32 v14, v2, v14
	v_mul_f32_e32 v2, 0x3f4c422a, v14
	v_add_f32_e32 v2, v2, v2
	v_mul_f32_e32 v2, 0x3fb8aa3b, v2
	v_exp_f32_e32 v2, v2
	v_pk_mul_f32 v[18:19], v[18:19], 0.5 op_sel_hi:[1,0]
	v_add_f32_e32 v2, 1.0, v2
	v_rcp_f32_e32 v23, v2
	s_nop 0
	v_pk_fma_f32 v[14:15], v[22:23], 2.0, 1.0 op_sel_hi:[1,0,0] neg_lo:[1,0,0] neg_hi:[1,0,0]
	s_nop 0
	v_pk_add_f32 v[14:15], v[14:15], 1.0 op_sel_hi:[1,0]
	s_nop 0
	v_pk_mul_f32 v[14:15], v[18:19], v[14:15]
	s_nop 0
	v_pk_mul_f32 v[18:19], v[12:13], v[14:15]
	v_cvt_pk_bf16_f32 v12, v24, v25
	v_cvt_pk_bf16_f32 v13, v16, v17
	v_cvt_pk_bf16_f32 v14, v20, v21
	v_cvt_pk_bf16_f32 v15, v18, v19
	global_store_dwordx4 v[66:67], v[12:15], off
	s_nop 1
	v_lshl_add_u64 v[12:13], v[60:61], 0, 32
	v_lshlrev_b64 v[14:15], 11, v[12:13]
	v_lshlrev_b64 v[12:13], 10, v[12:13]
	v_lshl_add_u64 v[70:71], v[62:63], 0, v[14:15]
	v_lshl_add_u64 v[12:13], v[0:1], 0, v[12:13]
	s_waitcnt vmcnt(4)
	v_mov_b64_e32 v[48:49], v[222:223]
	v_mov_b64_e32 v[50:51], v[224:225]
	v_mov_b64_e32 v[56:57], v[238:239]
	v_mov_b64_e32 v[58:59], v[240:241]
	v_add_co_u32_e32 v12, vcc, s33, v64
	s_nop 1
	v_addc_co_u32_e32 v13, vcc, 0, v65, vcc
	v_mov_b64_e32 v[52:53], v[134:135]
	v_mov_b64_e32 v[54:55], v[136:137]
	v_lshl_add_u64 v[12:13], v[60:61], 0, 40
	v_lshlrev_b64 v[14:15], 11, v[12:13]
	v_lshlrev_b64 v[12:13], 10, v[12:13]
	v_lshl_add_u64 v[68:69], v[62:63], 0, v[14:15]
	v_lshl_add_u64 v[12:13], v[0:1], 0, v[12:13]
	v_mov_b64_e32 v[40:41], v[226:227]
	v_mov_b64_e32 v[42:43], v[228:229]
	v_mov_b64_e32 v[44:45], v[242:243]
	v_mov_b64_e32 v[46:47], v[244:245]
	v_add_co_u32_e32 v12, vcc, s52, v64
	s_nop 1
	v_addc_co_u32_e32 v13, vcc, 0, v65, vcc
	v_mov_b64_e32 v[36:37], v[138:139]
	v_mov_b64_e32 v[38:39], v[140:141]
	v_lshl_add_u64 v[12:13], v[60:61], 0, 48
	v_lshlrev_b64 v[14:15], 11, v[12:13]
	v_lshlrev_b64 v[12:13], 10, v[12:13]
	v_lshl_add_u64 v[66:67], v[62:63], 0, v[14:15]
	v_lshl_add_u64 v[12:13], v[0:1], 0, v[12:13]
	v_mov_b64_e32 v[28:29], v[230:231]
	v_mov_b64_e32 v[30:31], v[232:233]
	v_mov_b64_e32 v[32:33], v[246:247]
	v_mov_b64_e32 v[34:35], v[248:249]
	v_add_co_u32_e32 v12, vcc, s69, v64
	s_nop 1
	v_addc_co_u32_e32 v13, vcc, 0, v65, vcc
	v_mov_b64_e32 v[24:25], v[146:147]
	v_mov_b64_e32 v[26:27], v[148:149]
	v_lshl_add_u64 v[12:13], v[60:61], 0, 56
	v_lshlrev_b64 v[14:15], 11, v[12:13]
	v_lshlrev_b64 v[12:13], 10, v[12:13]
	v_lshl_add_u64 v[60:61], v[62:63], 0, v[14:15]
	v_lshl_add_u64 v[0:1], v[0:1], 0, v[12:13]
	v_mov_b64_e32 v[16:17], v[234:235]
	v_mov_b64_e32 v[18:19], v[236:237]
	v_mov_b64_e32 v[20:21], v[250:251]
	v_mov_b64_e32 v[22:23], v[252:253]
	v_add_co_u32_e32 v0, vcc, s21, v64
	s_waitcnt lgkmcnt(0)
	v_lshlrev_b32_e32 v62, 16, v56
	v_addc_co_u32_e32 v1, vcc, 0, v65, vcc
	v_mov_b64_e32 v[12:13], v[150:151]
	v_mov_b64_e32 v[14:15], v[152:153]
	v_lshlrev_b32_e32 v0, 16, v48
	v_and_b32_e32 v1, 0xffff0000, v48
	v_lshlrev_b32_e32 v64, 16, v52
	v_mul_f32_e32 v2, 0x3d372713, v64
	v_mul_f32_e32 v2, v2, v64
	v_mov_b32_e32 v48, v64
	v_fmac_f32_e32 v48, v2, v48
	v_mul_f32_e32 v2, 0x3f4c422a, v48
	v_add_f32_e32 v2, v2, v2
	v_mul_f32_e32 v2, 0x3fb8aa3b, v2
	v_exp_f32_e32 v2, v2
	v_and_b32_e32 v65, 0xffff0000, v52
	v_mov_b32_e32 v48, v65
	v_and_b32_e32 v63, 0xffff0000, v56
	v_add_f32_e32 v2, 1.0, v2
	v_rcp_f32_e32 v72, v2
	v_mul_f32_e32 v2, 0x3d372713, v65
	v_mul_f32_e32 v2, v2, v65
	v_fmac_f32_e32 v48, v2, v48
	v_mul_f32_e32 v2, 0x3f4c422a, v48
	v_add_f32_e32 v2, v2, v2
	v_mul_f32_e32 v2, 0x3fb8aa3b, v2
	v_exp_f32_e32 v2, v2
	v_pk_fma_f32 v[0:1], v[8:9], v[62:63], v[0:1]
	v_pk_mul_f32 v[64:65], v[64:65], 0.5 op_sel_hi:[1,0]
	v_lshlrev_b32_e32 v52, 16, v53
	v_add_f32_e32 v2, 1.0, v2
	v_rcp_f32_e32 v73, v2
	v_mul_f32_e32 v2, 0x3d372713, v52
	v_mul_f32_e32 v2, v2, v52
	v_and_b32_e32 v53, 0xffff0000, v53
	v_pk_fma_f32 v[62:63], v[72:73], 2.0, 1.0 op_sel_hi:[1,0,0] neg_lo:[1,0,0] neg_hi:[1,0,0]
	v_lshlrev_b32_e32 v48, 16, v49
	v_pk_add_f32 v[62:63], v[62:63], 1.0 op_sel_hi:[1,0]
	v_and_b32_e32 v49, 0xffff0000, v49
	v_pk_mul_f32 v[62:63], v[64:65], v[62:63]
	v_lshlrev_b32_e32 v56, 16, v57
	v_pk_mul_f32 v[0:1], v[0:1], v[62:63]
	v_mov_b32_e32 v62, v52
	v_fmac_f32_e32 v62, v2, v62
	v_mul_f32_e32 v2, 0x3f4c422a, v62
	v_add_f32_e32 v2, v2, v2
	v_mul_f32_e32 v2, 0x3fb8aa3b, v2
	v_exp_f32_e32 v2, v2
	v_and_b32_e32 v57, 0xffff0000, v57
	v_pk_fma_f32 v[48:49], v[10:11], v[56:57], v[48:49]
	v_mov_b32_e32 v56, v53
	v_add_f32_e32 v2, 1.0, v2
	v_rcp_f32_e32 v62, v2
	v_mul_f32_e32 v2, 0x3d372713, v53
	v_mul_f32_e32 v2, v2, v53
	v_fmac_f32_e32 v56, v2, v56
	v_mul_f32_e32 v2, 0x3f4c422a, v56
	v_add_f32_e32 v2, v2, v2
	v_mul_f32_e32 v2, 0x3fb8aa3b, v2
; __device__ __forceinline__ u32x4 pack8(const float (&v)[8]) { u32x4 w; w.x = pk2(v[0], v[1]); w.y = pk2(v[2], v[3]); w.z = pk2(v[4], v[5]); w.w = pk2(v[6], v[7]); return w; }
; __device__ __forceinline__ float gelu_tanh(float x) { const float z = 0.7978845608028654f * (x + 0.044715f * x * x * x); const float t = 1.0f - 2.0f * __builtin_amdgcn_rcpf(__expf(2.0f * z) + 1.0f); return 0.5f * x * (1.0f + t); }
; __device__ __forceinline__ void w_lru_m3(unsigned char* ws, const bf16_t* proj, bf16_t* y, int b, int ck_, int h, int lane) {
;     ...
;         for (int i = 0; i < 4; ++i) { const size_t row = (size_t)b * SEQ + 64 * ck_ + (lane >> 3) + 8 * (i0 + i);
;             float hl[8], pv[8], g[8], o[8]; unpack8(rh[i], hl); unpack8(rp[i], pv); unpack8(rg[i], g);
; #pragma unroll
;             for (int j = 0; j < 8; ++j) o[j] = (hl[j] + pv[j] * hin[j]) * gelu_tanh(g[j]);
;             *(u32x4*)(y + row * DM + col) = pack8(o); }
	v_exp_f32_e32 v2, v2
	v_pk_mul_f32 v[52:53], v[52:53], 0.5 op_sel_hi:[1,0]
	v_add_f32_e32 v2, 1.0, v2
	v_rcp_f32_e32 v63, v2
	s_nop 0
	v_pk_fma_f32 v[56:57], v[62:63], 2.0, 1.0 op_sel_hi:[1,0,0] neg_lo:[1,0,0] neg_hi:[1,0,0]
	s_nop 0
	v_pk_add_f32 v[56:57], v[56:57], 1.0 op_sel_hi:[1,0]
	v_lshlrev_b32_e32 v62, 16, v54
	v_pk_mul_f32 v[52:53], v[52:53], v[56:57]
	v_mul_f32_e32 v2, 0x3d372713, v62
	v_pk_mul_f32 v[52:53], v[48:49], v[52:53]
	v_lshlrev_b32_e32 v48, 16, v50
	v_and_b32_e32 v49, 0xffff0000, v50
	v_mul_f32_e32 v2, v2, v62
	v_mov_b32_e32 v50, v62
	v_fmac_f32_e32 v50, v2, v50
	v_mul_f32_e32 v2, 0x3f4c422a, v50
	v_add_f32_e32 v2, v2, v2
	v_mul_f32_e32 v2, 0x3fb8aa3b, v2
	v_exp_f32_e32 v2, v2
	v_and_b32_e32 v63, 0xffff0000, v54
	v_mov_b32_e32 v50, v63
	v_lshlrev_b32_e32 v54, 16, v55
	v_add_f32_e32 v2, 1.0, v2
	v_rcp_f32_e32 v64, v2
	v_mul_f32_e32 v2, 0x3d372713, v63
	v_mul_f32_e32 v2, v2, v63
	v_fmac_f32_e32 v50, v2, v50
	v_mul_f32_e32 v2, 0x3f4c422a, v50
	v_add_f32_e32 v2, v2, v2
	v_mul_f32_e32 v2, 0x3fb8aa3b, v2
	v_exp_f32_e32 v2, v2
	v_lshlrev_b32_e32 v56, 16, v58
	v_and_b32_e32 v57, 0xffff0000, v58
	v_mov_b32_e32 v58, v54
	v_add_f32_e32 v2, 1.0, v2
	v_rcp_f32_e32 v65, v2
	v_mul_f32_e32 v2, 0x3d372713, v54
	v_mul_f32_e32 v2, v2, v54
	v_fmac_f32_e32 v58, v2, v58
	v_mul_f32_e32 v2, 0x3f4c422a, v58
	v_add_f32_e32 v2, v2, v2
	v_mul_f32_e32 v2, 0x3fb8aa3b, v2
	v_exp_f32_e32 v2, v2
	v_pk_fma_f32 v[48:49], v[4:5], v[56:57], v[48:49]
	v_pk_fma_f32 v[56:57], v[64:65], 2.0, 1.0 op_sel_hi:[1,0,0] neg_lo:[1,0,0] neg_hi:[1,0,0]
	v_pk_mul_f32 v[62:63], v[62:63], 0.5 op_sel_hi:[1,0]
	v_pk_add_f32 v[56:57], v[56:57], 1.0 op_sel_hi:[1,0]
	v_and_b32_e32 v55, 0xffff0000, v55
	v_pk_mul_f32 v[56:57], v[62:63], v[56:57]
	v_add_f32_e32 v2, 1.0, v2
	v_pk_mul_f32 v[56:57], v[48:49], v[56:57]
	v_lshlrev_b32_e32 v48, 16, v51
	v_and_b32_e32 v49, 0xffff0000, v51
	v_lshlrev_b32_e32 v50, 16, v59
	v_and_b32_e32 v51, 0xffff0000, v59
	v_rcp_f32_e32 v58, v2
	v_mul_f32_e32 v2, 0x3d372713, v55
	v_pk_fma_f32 v[48:49], v[6:7], v[50:51], v[48:49]
	v_mul_f32_e32 v2, v2, v55
	v_mov_b32_e32 v50, v55
	v_fmac_f32_e32 v50, v2, v50
	v_mul_f32_e32 v2, 0x3f4c422a, v50
	v_add_f32_e32 v2, v2, v2
	v_mul_f32_e32 v2, 0x3fb8aa3b, v2
	v_exp_f32_e32 v2, v2
	v_pk_mul_f32 v[54:55], v[54:55], 0.5 op_sel_hi:[1,0]
	v_add_f32_e32 v2, 1.0, v2
	v_rcp_f32_e32 v59, v2
	s_nop 0
	v_pk_fma_f32 v[50:51], v[58:59], 2.0, 1.0 op_sel_hi:[1,0,0] neg_lo:[1,0,0] neg_hi:[1,0,0]
	s_nop 0
	v_pk_add_f32 v[50:51], v[50:51], 1.0 op_sel_hi:[1,0]
	s_nop 0
	v_pk_mul_f32 v[50:51], v[54:55], v[50:51]
	s_nop 0
	v_pk_mul_f32 v[54:55], v[48:49], v[50:51]
	v_cvt_pk_bf16_f32 v48, v0, v1
	v_cvt_pk_bf16_f32 v49, v52, v53
	v_cvt_pk_bf16_f32 v50, v56, v57
	v_cvt_pk_bf16_f32 v51, v54, v55
	global_store_dwordx4 v[70:71], v[48:51], off
	v_lshlrev_b32_e32 v0, 16, v40
	v_and_b32_e32 v1, 0xffff0000, v40
	v_lshlrev_b32_e32 v50, 16, v36
	v_mul_f32_e32 v2, 0x3d372713, v50
	v_and_b32_e32 v51, 0xffff0000, v36
	v_mul_f32_e32 v2, v2, v50
	v_mov_b32_e32 v36, v50
	v_fmac_f32_e32 v36, v2, v36
	v_mul_f32_e32 v2, 0x3f4c422a, v36
	v_add_f32_e32 v2, v2, v2
	v_mul_f32_e32 v2, 0x3fb8aa3b, v2
	v_exp_f32_e32 v2, v2
	v_mov_b32_e32 v36, v51
	v_lshlrev_b32_e32 v48, 16, v44
	v_and_b32_e32 v49, 0xffff0000, v44
	v_add_f32_e32 v2, 1.0, v2
	v_rcp_f32_e32 v52, v2
	v_mul_f32_e32 v2, 0x3d372713, v51
	v_mul_f32_e32 v2, v2, v51
	v_fmac_f32_e32 v36, v2, v36
	v_mul_f32_e32 v2, 0x3f4c422a, v36
	v_add_f32_e32 v2, v2, v2
	v_mul_f32_e32 v2, 0x3fb8aa3b, v2
	v_exp_f32_e32 v2, v2
	v_pk_fma_f32 v[0:1], v[8:9], v[48:49], v[0:1]
	v_pk_mul_f32 v[50:51], v[50:51], 0.5 op_sel_hi:[1,0]
	v_lshlrev_b32_e32 v36, 16, v37
	v_add_f32_e32 v2, 1.0, v2
	v_rcp_f32_e32 v53, v2
	v_mul_f32_e32 v2, 0x3d372713, v36
	v_mul_f32_e32 v2, v2, v36
	v_and_b32_e32 v37, 0xffff0000, v37
	v_pk_fma_f32 v[48:49], v[52:53], 2.0, 1.0 op_sel_hi:[1,0,0] neg_lo:[1,0,0] neg_hi:[1,0,0]
	v_lshlrev_b32_e32 v40, 16, v41
	v_pk_add_f32 v[48:49], v[48:49], 1.0 op_sel_hi:[1,0]
	v_and_b32_e32 v41, 0xffff0000, v41
	v_pk_mul_f32 v[48:49], v[50:51], v[48:49]
	v_lshlrev_b32_e32 v44, 16, v45
	v_pk_mul_f32 v[0:1], v[0:1], v[48:49]
	v_mov_b32_e32 v48, v36
	v_fmac_f32_e32 v48, v2, v48
	v_mul_f32_e32 v2, 0x3f4c422a, v48
	v_add_f32_e32 v2, v2, v2
	v_mul_f32_e32 v2, 0x3fb8aa3b, v2
	v_exp_f32_e32 v2, v2
	v_and_b32_e32 v45, 0xffff0000, v45
	v_pk_fma_f32 v[40:41], v[10:11], v[44:45], v[40:41]
	v_mov_b32_e32 v44, v37
	v_add_f32_e32 v2, 1.0, v2
	v_rcp_f32_e32 v48, v2
	v_mul_f32_e32 v2, 0x3d372713, v37
	v_mul_f32_e32 v2, v2, v37
	v_fmac_f32_e32 v44, v2, v44
	v_mul_f32_e32 v2, 0x3f4c422a, v44
	v_add_f32_e32 v2, v2, v2
	v_mul_f32_e32 v2, 0x3fb8aa3b, v2
	v_exp_f32_e32 v2, v2
	v_pk_mul_f32 v[36:37], v[36:37], 0.5 op_sel_hi:[1,0]
	v_add_f32_e32 v2, 1.0, v2
	v_rcp_f32_e32 v49, v2
	s_nop 0
	v_pk_fma_f32 v[44:45], v[48:49], 2.0, 1.0 op_sel_hi:[1,0,0] neg_lo:[1,0,0] neg_hi:[1,0,0]
	v_lshlrev_b32_e32 v48, 16, v38
	v_mul_f32_e32 v2, 0x3d372713, v48
	v_and_b32_e32 v49, 0xffff0000, v38
	v_mul_f32_e32 v2, v2, v48
	v_mov_b32_e32 v38, v48
	v_fmac_f32_e32 v38, v2, v38
	v_mul_f32_e32 v2, 0x3f4c422a, v38
	v_add_f32_e32 v2, v2, v2
	v_mul_f32_e32 v2, 0x3fb8aa3b, v2
	v_exp_f32_e32 v2, v2
	v_mov_b32_e32 v38, v49
	v_pk_add_f32 v[44:45], v[44:45], 1.0 op_sel_hi:[1,0]
	v_add_f32_e32 v2, 1.0, v2
	v_rcp_f32_e32 v50, v2
	v_mul_f32_e32 v2, 0x3d372713, v49
	v_mul_f32_e32 v2, v2, v49
	v_fmac_f32_e32 v38, v2, v38
	v_mul_f32_e32 v2, 0x3f4c422a, v38
	v_add_f32_e32 v2, v2, v2
	v_mul_f32_e32 v2, 0x3fb8aa3b, v2
	v_exp_f32_e32 v2, v2
	v_lshlrev_b32_e32 v38, 16, v39
	v_pk_mul_f32 v[36:37], v[36:37], v[44:45]
	v_lshlrev_b32_e32 v44, 16, v46
	v_add_f32_e32 v2, 1.0, v2
; __device__ __forceinline__ u32x4 pack8(const float (&v)[8]) { u32x4 w; w.x = pk2(v[0], v[1]); w.y = pk2(v[2], v[3]); w.z = pk2(v[4], v[5]); w.w = pk2(v[6], v[7]); return w; }
; __device__ __forceinline__ float gelu_tanh(float x) { const float z = 0.7978845608028654f * (x + 0.044715f * x * x * x); const float t = 1.0f - 2.0f * __builtin_amdgcn_rcpf(__expf(2.0f * z) + 1.0f); return 0.5f * x * (1.0f + t); }
; __device__ __forceinline__ void w_lru_m3(unsigned char* ws, const bf16_t* proj, bf16_t* y, int b, int ck_, int h, int lane) {
;     ...
;         for (int i = 0; i < 4; ++i) { const size_t row = (size_t)b * SEQ + 64 * ck_ + (lane >> 3) + 8 * (i0 + i);
;             rh[i] = *(const u32x4*)(y + row * DM + col); rp[i] = *(const u32x4*)((const bf16_t*)(ws + WS_P) + row * 512 + col); rg[i] = *(const u32x4*)(proj + row * NIN + C_LG + col); }
; #pragma unroll
;         for (int i = 0; i < 4; ++i) { const size_t row = (size_t)b * SEQ + 64 * ck_ + (lane >> 3) + 8 * (i0 + i);
;             float hl[8], pv[8], g[8], o[8]; unpack8(rh[i], hl); unpack8(rp[i], pv); unpack8(rg[i], g);
; #pragma unroll
;             for (int j = 0; j < 8; ++j) o[j] = (hl[j] + pv[j] * hin[j]) * gelu_tanh(g[j]);
;             *(u32x4*)(y + row * DM + col) = pack8(o); }
	v_rcp_f32_e32 v51, v2
	v_mul_f32_e32 v2, 0x3d372713, v38
	v_and_b32_e32 v45, 0xffff0000, v46
	v_mul_f32_e32 v2, v2, v38
	v_mov_b32_e32 v46, v38
	v_fmac_f32_e32 v46, v2, v46
	v_mul_f32_e32 v2, 0x3f4c422a, v46
	v_add_f32_e32 v2, v2, v2
	v_mul_f32_e32 v2, 0x3fb8aa3b, v2
	v_exp_f32_e32 v2, v2
	v_pk_mul_f32 v[40:41], v[40:41], v[36:37]
	v_lshlrev_b32_e32 v36, 16, v42
	v_and_b32_e32 v37, 0xffff0000, v42
	v_pk_fma_f32 v[36:37], v[4:5], v[44:45], v[36:37]
	v_pk_fma_f32 v[44:45], v[50:51], 2.0, 1.0 op_sel_hi:[1,0,0] neg_lo:[1,0,0] neg_hi:[1,0,0]
	v_pk_mul_f32 v[48:49], v[48:49], 0.5 op_sel_hi:[1,0]
	v_pk_add_f32 v[44:45], v[44:45], 1.0 op_sel_hi:[1,0]
	v_and_b32_e32 v39, 0xffff0000, v39
	v_pk_mul_f32 v[44:45], v[48:49], v[44:45]
	v_add_f32_e32 v2, 1.0, v2
	v_pk_mul_f32 v[44:45], v[36:37], v[44:45]
	v_lshlrev_b32_e32 v36, 16, v43
	v_and_b32_e32 v37, 0xffff0000, v43
	v_lshlrev_b32_e32 v42, 16, v47
	v_and_b32_e32 v43, 0xffff0000, v47
	v_rcp_f32_e32 v46, v2
	v_mul_f32_e32 v2, 0x3d372713, v39
	v_pk_fma_f32 v[36:37], v[6:7], v[42:43], v[36:37]
	v_mul_f32_e32 v2, v2, v39
	v_mov_b32_e32 v42, v39
	v_fmac_f32_e32 v42, v2, v42
	v_mul_f32_e32 v2, 0x3f4c422a, v42
	v_add_f32_e32 v2, v2, v2
	v_mul_f32_e32 v2, 0x3fb8aa3b, v2
	v_exp_f32_e32 v2, v2
	v_pk_mul_f32 v[38:39], v[38:39], 0.5 op_sel_hi:[1,0]
	v_add_f32_e32 v2, 1.0, v2
	v_rcp_f32_e32 v47, v2
	s_nop 0
	v_pk_fma_f32 v[42:43], v[46:47], 2.0, 1.0 op_sel_hi:[1,0,0] neg_lo:[1,0,0] neg_hi:[1,0,0]
	s_nop 0
	v_pk_add_f32 v[42:43], v[42:43], 1.0 op_sel_hi:[1,0]
	s_nop 0
	v_pk_mul_f32 v[38:39], v[38:39], v[42:43]
	s_nop 0
	v_pk_mul_f32 v[42:43], v[36:37], v[38:39]
	v_cvt_pk_bf16_f32 v36, v0, v1
	v_cvt_pk_bf16_f32 v37, v40, v41
	v_cvt_pk_bf16_f32 v38, v44, v45
	v_cvt_pk_bf16_f32 v39, v42, v43
	global_store_dwordx4 v[68:69], v[36:39], off
	v_lshlrev_b32_e32 v0, 16, v28
	v_and_b32_e32 v1, 0xffff0000, v28
	v_lshlrev_b32_e32 v38, 16, v24
	v_mul_f32_e32 v2, 0x3d372713, v38
	v_and_b32_e32 v39, 0xffff0000, v24
	v_mul_f32_e32 v2, v2, v38
	v_mov_b32_e32 v24, v38
	v_fmac_f32_e32 v24, v2, v24
	v_mul_f32_e32 v2, 0x3f4c422a, v24
	v_add_f32_e32 v2, v2, v2
	v_mul_f32_e32 v2, 0x3fb8aa3b, v2
	v_exp_f32_e32 v2, v2
	v_mov_b32_e32 v24, v39
	v_lshlrev_b32_e32 v36, 16, v32
	v_and_b32_e32 v37, 0xffff0000, v32
	v_add_f32_e32 v2, 1.0, v2
	v_rcp_f32_e32 v40, v2
	v_mul_f32_e32 v2, 0x3d372713, v39
	v_mul_f32_e32 v2, v2, v39
	v_fmac_f32_e32 v24, v2, v24
	v_mul_f32_e32 v2, 0x3f4c422a, v24
	v_add_f32_e32 v2, v2, v2
	v_mul_f32_e32 v2, 0x3fb8aa3b, v2
	v_exp_f32_e32 v2, v2
	v_pk_fma_f32 v[0:1], v[8:9], v[36:37], v[0:1]
	v_pk_mul_f32 v[38:39], v[38:39], 0.5 op_sel_hi:[1,0]
	v_lshlrev_b32_e32 v24, 16, v25
	v_add_f32_e32 v2, 1.0, v2
	v_rcp_f32_e32 v41, v2
	v_mul_f32_e32 v2, 0x3d372713, v24
	v_mul_f32_e32 v2, v2, v24
	v_and_b32_e32 v25, 0xffff0000, v25
	v_pk_fma_f32 v[36:37], v[40:41], 2.0, 1.0 op_sel_hi:[1,0,0] neg_lo:[1,0,0] neg_hi:[1,0,0]
	v_lshlrev_b32_e32 v28, 16, v29
	v_pk_add_f32 v[36:37], v[36:37], 1.0 op_sel_hi:[1,0]
	v_and_b32_e32 v29, 0xffff0000, v29
	v_pk_mul_f32 v[36:37], v[38:39], v[36:37]
	v_lshlrev_b32_e32 v32, 16, v33
	v_pk_mul_f32 v[0:1], v[0:1], v[36:37]
	v_mov_b32_e32 v36, v24
	v_fmac_f32_e32 v36, v2, v36
	v_mul_f32_e32 v2, 0x3f4c422a, v36
	v_add_f32_e32 v2, v2, v2
	v_mul_f32_e32 v2, 0x3fb8aa3b, v2
	v_exp_f32_e32 v2, v2
	v_and_b32_e32 v33, 0xffff0000, v33
	v_pk_fma_f32 v[28:29], v[10:11], v[32:33], v[28:29]
	v_mov_b32_e32 v32, v25
	v_add_f32_e32 v2, 1.0, v2
	v_rcp_f32_e32 v36, v2
	v_mul_f32_e32 v2, 0x3d372713, v25
	v_mul_f32_e32 v2, v2, v25
	v_fmac_f32_e32 v32, v2, v32
	v_mul_f32_e32 v2, 0x3f4c422a, v32
	v_add_f32_e32 v2, v2, v2
	v_mul_f32_e32 v2, 0x3fb8aa3b, v2
	v_exp_f32_e32 v2, v2
	v_pk_mul_f32 v[24:25], v[24:25], 0.5 op_sel_hi:[1,0]
	v_add_f32_e32 v2, 1.0, v2
	v_rcp_f32_e32 v37, v2
	s_nop 0
	v_pk_fma_f32 v[32:33], v[36:37], 2.0, 1.0 op_sel_hi:[1,0,0] neg_lo:[1,0,0] neg_hi:[1,0,0]
	v_lshlrev_b32_e32 v36, 16, v26
	v_mul_f32_e32 v2, 0x3d372713, v36
	v_and_b32_e32 v37, 0xffff0000, v26
	v_mul_f32_e32 v2, v2, v36
	v_mov_b32_e32 v26, v36
	v_fmac_f32_e32 v26, v2, v26
	v_mul_f32_e32 v2, 0x3f4c422a, v26
	v_add_f32_e32 v2, v2, v2
	v_mul_f32_e32 v2, 0x3fb8aa3b, v2
	v_exp_f32_e32 v2, v2
	v_mov_b32_e32 v26, v37
	v_pk_add_f32 v[32:33], v[32:33], 1.0 op_sel_hi:[1,0]
	v_add_f32_e32 v2, 1.0, v2
	v_rcp_f32_e32 v38, v2
	v_mul_f32_e32 v2, 0x3d372713, v37
	v_mul_f32_e32 v2, v2, v37
	v_fmac_f32_e32 v26, v2, v26
	v_mul_f32_e32 v2, 0x3f4c422a, v26
	v_add_f32_e32 v2, v2, v2
	v_mul_f32_e32 v2, 0x3fb8aa3b, v2
	v_exp_f32_e32 v2, v2
	v_lshlrev_b32_e32 v26, 16, v27
	v_pk_mul_f32 v[24:25], v[24:25], v[32:33]
	v_lshlrev_b32_e32 v32, 16, v34
	v_add_f32_e32 v2, 1.0, v2
	v_rcp_f32_e32 v39, v2
	v_mul_f32_e32 v2, 0x3d372713, v26
	v_and_b32_e32 v33, 0xffff0000, v34
	v_mul_f32_e32 v2, v2, v26
	v_mov_b32_e32 v34, v26
	v_fmac_f32_e32 v34, v2, v34
	v_mul_f32_e32 v2, 0x3f4c422a, v34
	v_add_f32_e32 v2, v2, v2
	v_mul_f32_e32 v2, 0x3fb8aa3b, v2
	v_exp_f32_e32 v2, v2
	v_pk_mul_f32 v[28:29], v[28:29], v[24:25]
	v_lshlrev_b32_e32 v24, 16, v30
	v_and_b32_e32 v25, 0xffff0000, v30
	v_pk_fma_f32 v[24:25], v[4:5], v[32:33], v[24:25]
	v_pk_fma_f32 v[32:33], v[38:39], 2.0, 1.0 op_sel_hi:[1,0,0] neg_lo:[1,0,0] neg_hi:[1,0,0]
	v_pk_mul_f32 v[36:37], v[36:37], 0.5 op_sel_hi:[1,0]
	v_pk_add_f32 v[32:33], v[32:33], 1.0 op_sel_hi:[1,0]
	v_and_b32_e32 v27, 0xffff0000, v27
	v_pk_mul_f32 v[32:33], v[36:37], v[32:33]
	v_add_f32_e32 v2, 1.0, v2
	v_pk_mul_f32 v[32:33], v[24:25], v[32:33]
	v_lshlrev_b32_e32 v24, 16, v31
	v_and_b32_e32 v25, 0xffff0000, v31
	v_lshlrev_b32_e32 v30, 16, v35
	v_and_b32_e32 v31, 0xffff0000, v35
	v_rcp_f32_e32 v34, v2
	v_mul_f32_e32 v2, 0x3d372713, v27
	v_pk_fma_f32 v[24:25], v[6:7], v[30:31], v[24:25]
	v_mul_f32_e32 v2, v2, v27
	v_mov_b32_e32 v30, v27
	v_fmac_f32_e32 v30, v2, v30
	v_mul_f32_e32 v2, 0x3f4c422a, v30
	v_add_f32_e32 v2, v2, v2
	v_mul_f32_e32 v2, 0x3fb8aa3b, v2
	v_exp_f32_e32 v2, v2
	v_pk_mul_f32 v[26:27], v[26:27], 0.5 op_sel_hi:[1,0]
	v_add_f32_e32 v2, 1.0, v2
	v_rcp_f32_e32 v35, v2
	s_nop 0
	v_pk_fma_f32 v[30:31], v[34:35], 2.0, 1.0 op_sel_hi:[1,0,0] neg_lo:[1,0,0] neg_hi:[1,0,0]
	s_nop 0
	v_pk_add_f32 v[30:31], v[30:31], 1.0 op_sel_hi:[1,0]
	s_nop 0
	v_pk_mul_f32 v[26:27], v[26:27], v[30:31]
	s_nop 0
	v_pk_mul_f32 v[30:31], v[24:25], v[26:27]
	v_cvt_pk_bf16_f32 v24, v0, v1
	v_cvt_pk_bf16_f32 v25, v28, v29
	v_cvt_pk_bf16_f32 v26, v32, v33
	v_cvt_pk_bf16_f32 v27, v30, v31
	global_store_dwordx4 v[66:67], v[24:27], off
	v_lshlrev_b32_e32 v0, 16, v16
	v_and_b32_e32 v1, 0xffff0000, v16
	s_waitcnt lgkmcnt(0)
; __device__ __forceinline__ u32x4 pack8(const float (&v)[8]) { u32x4 w; w.x = pk2(v[0], v[1]); w.y = pk2(v[2], v[3]); w.z = pk2(v[4], v[5]); w.w = pk2(v[6], v[7]); return w; }
; __device__ __forceinline__ float gelu_tanh(float x) { const float z = 0.7978845608028654f * (x + 0.044715f * x * x * x); const float t = 1.0f - 2.0f * __builtin_amdgcn_rcpf(__expf(2.0f * z) + 1.0f); return 0.5f * x * (1.0f + t); }
; __device__ __forceinline__ void w_lru_m3(unsigned char* ws, const bf16_t* proj, bf16_t* y, int b, int ck_, int h, int lane) {
;     ...
;         for (int i = 0; i < 4; ++i) { const size_t row = (size_t)b * SEQ + 64 * ck_ + (lane >> 3) + 8 * (i0 + i);
;             rh[i] = *(const u32x4*)(y + row * DM + col); rp[i] = *(const u32x4*)((const bf16_t*)(ws + WS_P) + row * 512 + col); rg[i] = *(const u32x4*)(proj + row * NIN + C_LG + col); }
; #pragma unroll
;         for (int i = 0; i < 4; ++i) { const size_t row = (size_t)b * SEQ + 64 * ck_ + (lane >> 3) + 8 * (i0 + i);
;             float hl[8], pv[8], g[8], o[8]; unpack8(rh[i], hl); unpack8(rp[i], pv); unpack8(rg[i], g);
; #pragma unroll
;             for (int j = 0; j < 8; ++j) o[j] = (hl[j] + pv[j] * hin[j]) * gelu_tanh(g[j]);
;             *(u32x4*)(y + row * DM + col) = pack8(o); }
	v_lshlrev_b32_e32 v26, 16, v12
	v_mul_f32_e32 v2, 0x3d372713, v26
	v_and_b32_e32 v27, 0xffff0000, v12
	v_mul_f32_e32 v2, v2, v26
	v_mov_b32_e32 v12, v26
	v_fmac_f32_e32 v12, v2, v12
	v_mul_f32_e32 v2, 0x3f4c422a, v12
	v_add_f32_e32 v2, v2, v2
	v_mul_f32_e32 v2, 0x3fb8aa3b, v2
	v_exp_f32_e32 v2, v2
	v_lshlrev_b32_e32 v24, 16, v20
	v_and_b32_e32 v25, 0xffff0000, v20
	v_pk_fma_f32 v[0:1], v[8:9], v[24:25], v[0:1]
	v_add_f32_e32 v2, 1.0, v2
	v_rcp_f32_e32 v28, v2
	v_mul_f32_e32 v2, 0x3d372713, v27
	v_mul_f32_e32 v2, v2, v27
	v_mov_b32_e32 v8, v27
	v_fmac_f32_e32 v8, v2, v8
	v_mul_f32_e32 v2, 0x3f4c422a, v8
	v_add_f32_e32 v2, v2, v2
	v_mul_f32_e32 v2, 0x3fb8aa3b, v2
	v_exp_f32_e32 v2, v2
	v_lshlrev_b32_e32 v12, 16, v13
	v_mov_b32_e32 v20, v12
	v_pk_mul_f32 v[24:25], v[26:27], 0.5 op_sel_hi:[1,0]
	v_add_f32_e32 v2, 1.0, v2
	v_rcp_f32_e32 v29, v2
	v_mul_f32_e32 v2, 0x3d372713, v12
	v_mul_f32_e32 v2, v2, v12
	v_fmac_f32_e32 v20, v2, v20
	v_mul_f32_e32 v2, 0x3f4c422a, v20
	v_add_f32_e32 v2, v2, v2
	v_mul_f32_e32 v2, 0x3fb8aa3b, v2
	v_exp_f32_e32 v2, v2
	v_pk_fma_f32 v[8:9], v[28:29], 2.0, 1.0 op_sel_hi:[1,0,0] neg_lo:[1,0,0] neg_hi:[1,0,0]
	v_and_b32_e32 v13, 0xffff0000, v13
	v_pk_add_f32 v[8:9], v[8:9], 1.0 op_sel_hi:[1,0]
	v_add_f32_e32 v2, 1.0, v2
	v_pk_mul_f32 v[8:9], v[24:25], v[8:9]
	v_lshlrev_b32_e32 v16, 16, v21
	v_pk_mul_f32 v[0:1], v[0:1], v[8:9]
	v_lshlrev_b32_e32 v8, 16, v17
	v_and_b32_e32 v9, 0xffff0000, v17
	v_and_b32_e32 v17, 0xffff0000, v21
	v_rcp_f32_e32 v20, v2
	v_mul_f32_e32 v2, 0x3d372713, v13
	v_pk_fma_f32 v[8:9], v[10:11], v[16:17], v[8:9]
	v_mul_f32_e32 v2, v2, v13
	v_mov_b32_e32 v10, v13
	v_fmac_f32_e32 v10, v2, v10
	v_mul_f32_e32 v2, 0x3f4c422a, v10
	v_add_f32_e32 v2, v2, v2
	v_mul_f32_e32 v2, 0x3fb8aa3b, v2
	v_exp_f32_e32 v2, v2
	v_lshlrev_b32_e32 v16, 16, v14
	v_and_b32_e32 v17, 0xffff0000, v14
	v_mov_b32_e32 v14, v16
	v_add_f32_e32 v2, 1.0, v2
	v_rcp_f32_e32 v21, v2
	v_mul_f32_e32 v2, 0x3d372713, v16
	v_mul_f32_e32 v2, v2, v16
	v_fmac_f32_e32 v14, v2, v14
	v_mul_f32_e32 v2, 0x3f4c422a, v14
	v_add_f32_e32 v2, v2, v2
	v_mul_f32_e32 v2, 0x3fb8aa3b, v2
	v_exp_f32_e32 v2, v2
	v_pk_fma_f32 v[10:11], v[20:21], 2.0, 1.0 op_sel_hi:[1,0,0] neg_lo:[1,0,0] neg_hi:[1,0,0]
	v_pk_mul_f32 v[12:13], v[12:13], 0.5 op_sel_hi:[1,0]
	v_pk_add_f32 v[10:11], v[10:11], 1.0 op_sel_hi:[1,0]
	v_add_f32_e32 v2, 1.0, v2
	v_pk_mul_f32 v[10:11], v[12:13], v[10:11]
	v_lshlrev_b32_e32 v12, 16, v22
	v_pk_mul_f32 v[8:9], v[8:9], v[10:11]
	v_lshlrev_b32_e32 v10, 16, v18
	v_and_b32_e32 v11, 0xffff0000, v18
	v_and_b32_e32 v13, 0xffff0000, v22
	v_rcp_f32_e32 v20, v2
	v_mul_f32_e32 v2, 0x3d372713, v17
	v_pk_fma_f32 v[4:5], v[4:5], v[12:13], v[10:11]
	v_mul_f32_e32 v2, v2, v17
	v_mov_b32_e32 v10, v17
	v_fmac_f32_e32 v10, v2, v10
	v_mul_f32_e32 v2, 0x3f4c422a, v10
	v_add_f32_e32 v2, v2, v2
	v_mul_f32_e32 v2, 0x3fb8aa3b, v2
	v_exp_f32_e32 v2, v2
	v_lshlrev_b32_e32 v14, 16, v15
	v_pk_mul_f32 v[12:13], v[16:17], 0.5 op_sel_hi:[1,0]
	v_mov_b32_e32 v16, v14
	v_add_f32_e32 v2, 1.0, v2
	v_rcp_f32_e32 v21, v2
	v_mul_f32_e32 v2, 0x3d372713, v14
	v_mul_f32_e32 v2, v2, v14
	v_fmac_f32_e32 v16, v2, v16
	v_mul_f32_e32 v2, 0x3f4c422a, v16
	v_add_f32_e32 v2, v2, v2
	v_mul_f32_e32 v2, 0x3fb8aa3b, v2
	v_exp_f32_e32 v2, v2
	v_pk_fma_f32 v[10:11], v[20:21], 2.0, 1.0 op_sel_hi:[1,0,0] neg_lo:[1,0,0] neg_hi:[1,0,0]
	v_and_b32_e32 v15, 0xffff0000, v15
	v_pk_add_f32 v[10:11], v[10:11], 1.0 op_sel_hi:[1,0]
	v_add_f32_e32 v2, 1.0, v2
	v_pk_mul_f32 v[10:11], v[12:13], v[10:11]
	v_lshlrev_b32_e32 v12, 16, v23
	v_pk_mul_f32 v[10:11], v[4:5], v[10:11]
	v_lshlrev_b32_e32 v4, 16, v19
	v_and_b32_e32 v5, 0xffff0000, v19
	v_and_b32_e32 v13, 0xffff0000, v23
	v_rcp_f32_e32 v16, v2
	v_mul_f32_e32 v2, 0x3d372713, v15
	v_pk_fma_f32 v[4:5], v[6:7], v[12:13], v[4:5]
	v_mul_f32_e32 v2, v2, v15
	v_mov_b32_e32 v6, v15
	v_fmac_f32_e32 v6, v2, v6
	v_mul_f32_e32 v2, 0x3f4c422a, v6
	v_add_f32_e32 v2, v2, v2
	v_mul_f32_e32 v2, 0x3fb8aa3b, v2
	v_exp_f32_e32 v2, v2
	v_pk_mul_f32 v[12:13], v[14:15], 0.5 op_sel_hi:[1,0]
	v_add_f32_e32 v2, 1.0, v2
	v_rcp_f32_e32 v17, v2
	s_nop 0
	v_pk_fma_f32 v[6:7], v[16:17], 2.0, 1.0 op_sel_hi:[1,0,0] neg_lo:[1,0,0] neg_hi:[1,0,0]
	s_nop 0
	v_pk_add_f32 v[6:7], v[6:7], 1.0 op_sel_hi:[1,0]
	s_nop 0
	v_pk_mul_f32 v[6:7], v[12:13], v[6:7]
	s_nop 0
	v_pk_mul_f32 v[12:13], v[4:5], v[6:7]
	v_cvt_pk_bf16_f32 v4, v0, v1
	v_cvt_pk_bf16_f32 v5, v8, v9
	v_cvt_pk_bf16_f32 v6, v10, v11
	v_cvt_pk_bf16_f32 v7, v12, v13
	global_store_dwordx4 v[60:61], v[4:7], off
	s_branch .LBB0_183

; #define LAS __attribute__((address_space(3)))
; __device__ __forceinline__ float ret_lg(int h) { return log1pf(-exp2f(-5.0f - (float)h)); }
; __device__ __forceinline__ void w_ret_m3(const Args& a, int l, unsigned char* ws, const bf16_t* proj, bf16_t* y, LAS unsigned char* wl, int b, int ck_, int h, int lane) {
;     LAS bf16_t* vT = (LAS bf16_t*)wl;
;     const int row0 = b * SEQ + 64 * ck_, lo = lane & 15, fq = lane >> 4; const float lg = ret_lg(h);
;     const float* cosT = (const float*)(ws + WS_ROPE); const float* sinT = cosT + SEQ * 32;
;     w_store_vT(vT, proj + (size_t)row0 * NIN + C_RV + 64 * h, lane);
.LBB0_187:
	s_lshr_b32 s20, s46, 8
	s_lshr_b32 s21, s46, 9
	s_add_i32 s20, s20, s46
	s_and_b32 s21, s21, 12
	s_add_i32 s20, s20, s21
	s_and_b32 s21, s20, 12
	s_cmp_lg_u32 s21, 8
	s_cbranch_scc1 .LBB0_186
	s_and_b32 s27, s20, 11
	s_ashr_i32 s20, s46, 31
	s_ashr_i32 s21, s46, 4
	s_lshr_b32 s20, s20, 25
	s_add_i32 s27, s27, -8
	s_add_i32 s24, s21, s20
	v_cvt_f32_u32_e32 v0, s27
	s_ashr_i32 s20, s24, 7
	s_and_b32 s24, s24, 0xffffff80
	s_sub_i32 s21, s21, s24
	s_lshl_b32 s24, s20, 13
	s_lshl_b32 s38, s21, 6
	s_add_i32 s34, s38, s24
	v_sub_f32_e32 v0, 0xc0a00000, v0
	s_mov_b32 s24, 0xc2fc0000
	v_cmp_gt_f32_e32 vcc, s24, v0
	s_and_b64 s[40:41], vcc, exec
	s_cselect_b32 s24, 0xffffffc0, 0
	v_cndmask_b32_e32 v1, 0, v204, vcc
	v_add_f32_e32 v0, v0, v1
	v_exp_f32_e32 v0, v0
	s_ashr_i32 s35, s34, 31
	s_mul_i32 s39, s34, 0x1800
	s_add_u32 s39, s8, s39
	v_ldexp_f32 v102, v0, s24
	v_sub_f32_e32 v2, 1.0, v102
	v_add_f32_e32 v0, -1.0, v2
	v_sub_f32_e32 v1, v0, v2
	v_add_f32_e32 v1, 1.0, v1
	v_sub_f32_e64 v0, -v102, v0
	v_add_f32_e32 v4, v0, v1
	v_frexp_mant_f32_e32 v0, v2
	v_cmp_gt_f32_e32 vcc, s77, v0
	v_cvt_f64_f32_e32 v[0:1], v2
	v_frexp_exp_i32_f64_e32 v0, v[0:1]
	v_subbrev_co_u32_e32 v10, vcc, 0, v0, vcc
	v_sub_u32_e32 v0, 0, v10
	v_ldexp_f32 v1, v2, v0
	v_add_f32_e32 v2, -1.0, v1
	v_add_f32_e32 v5, 1.0, v1
	v_ldexp_f32 v0, v4, v0
	v_add_f32_e32 v4, 1.0, v2
	v_add_f32_e32 v6, -1.0, v5
	v_sub_f32_e32 v4, v1, v4
	v_sub_f32_e32 v1, v1, v6
	v_add_f32_e32 v4, v0, v4
	v_add_f32_e32 v0, v0, v1
	v_add_f32_e32 v11, v5, v0
	v_rcp_f32_e32 v13, v11
	v_sub_f32_e32 v1, v11, v5
	v_sub_f32_e32 v12, v0, v1
	v_add_f32_e32 v1, v2, v4
	v_sub_f32_e32 v0, v1, v2
	v_mul_f32_e32 v14, v1, v13
	v_sub_f32_e32 v2, v4, v0
	v_mul_f32_e32 v4, v11, v14
	v_fma_f32 v6, v14, v11, -v4
	v_fmac_f32_e32 v6, v14, v12
	v_add_f32_e32 v0, v4, v6
	v_sub_f32_e32 v5, v1, v0
	v_pk_add_f32 v[8:9], v[0:1], v[4:5] neg_lo:[0,1] neg_hi:[0,1]
	v_mov_b32_e32 v7, v0
	v_pk_add_f32 v[0:1], v[8:9], v[6:7] neg_lo:[0,1] neg_hi:[0,1]
	s_mul_hi_i32 s24, s34, 0x1800
	v_add_f32_e32 v1, v2, v1
	v_add_f32_e32 v0, v0, v1
	v_add_f32_e32 v1, v5, v0
	v_mul_f32_e32 v2, v13, v1
	v_mul_f32_e32 v4, v11, v2
	v_fma_f32 v6, v2, v11, -v4
	v_fmac_f32_e32 v6, v2, v12
	v_sub_f32_e32 v5, v5, v1
	v_add_f32_e32 v11, v0, v5
	v_add_f32_e32 v0, v4, v6
	v_sub_f32_e32 v5, v1, v0
	v_pk_add_f32 v[8:9], v[0:1], v[4:5] neg_lo:[0,1] neg_hi:[0,1]
	v_mov_b32_e32 v7, v0
	v_pk_add_f32 v[0:1], v[8:9], v[6:7] neg_lo:[0,1] neg_hi:[0,1]
	v_mov_b32_e32 v101, v132
	v_add_f32_e32 v1, v11, v1
	v_add_f32_e32 v0, v0, v1
	v_add_f32_e32 v1, v14, v2
	v_add_f32_e32 v0, v5, v0
	v_sub_f32_e32 v4, v1, v14
	v_mul_f32_e32 v0, v13, v0
	v_sub_f32_e32 v2, v2, v4
	v_add_f32_e32 v2, v2, v0
	v_add_f32_e32 v4, v1, v2
	v_mul_f32_e32 v6, v4, v4
	v_fmamk_f32 v0, v6, 0x3e9b6dac, v201
	v_fmaak_f32 v169, v6, v0, 0x3f2aaada
	v_cvt_f32_i32_e32 v0, v10
	v_sub_f32_e32 v1, v4, v1
	v_sub_f32_e32 v1, v2, v1
	v_ldexp_f32 v2, v1, 1
	v_mul_f32_e32 v1, v4, v6
	v_pk_mul_f32 v[6:7], v[0:1], v[168:169]
	v_ldexp_f32 v5, v4, 1
	v_fma_f32 v4, v0, s94, -v6
	v_fmac_f32_e32 v4, 0xb102e308, v0
	v_pk_add_f32 v[8:9], v[6:7], v[4:5]
	v_mov_b32_e32 v10, v6
	v_sub_f32_e32 v0, v9, v5
	v_sub_f32_e32 v0, v7, v0
	v_add_f32_e32 v11, v2, v0
	v_pk_add_f32 v[6:7], v[8:9], v[6:7] neg_lo:[0,1] neg_hi:[0,1]
	v_pk_add_f32 v[12:13], v[8:9], v[10:11]
	v_mov_b32_e32 v5, v8
	v_mov_b32_e32 v7, v13
	v_pk_add_f32 v[0:1], v[4:5], v[6:7] neg_lo:[0,1] neg_hi:[0,1]
	v_pk_add_f32 v[4:5], v[4:5], v[6:7]
	v_mov_b32_e32 v16, v9
	v_pk_add_f32 v[6:7], v[4:5], v[8:9] op_sel:[1,0] op_sel_hi:[0,1] neg_lo:[0,1] neg_hi:[0,1]
	v_pk_add_f32 v[14:15], v[12:13], v[6:7] op_sel_hi:[1,0] neg_lo:[0,1] neg_hi:[0,1]
	v_mov_b32_e32 v12, v13
	v_mov_b32_e32 v13, v5
	v_mov_b32_e32 v17, v6
	v_pk_add_f32 v[6:7], v[12:13], v[16:17] neg_lo:[0,1] neg_hi:[0,1]
	v_mov_b32_e32 v10, v11
	v_mov_b32_e32 v11, v8
	v_pk_add_f32 v[6:7], v[10:11], v[6:7] neg_lo:[0,1] neg_hi:[0,1]
	v_mov_b32_e32 v14, v0
	v_pk_add_f32 v[14:15], v[14:15], v[6:7]
	s_addc_u32 s43, s9, s24
	s_lshl_b32 s24, s27, 6
	s_lshl_b32 s40, s27, 7
	v_pk_add_f32 v[8:9], v[14:15], v[14:15] op_sel:[0,1] op_sel_hi:[1,0]
	s_add_u32 s42, s39, s40
	v_lshlrev_b32_e32 v2, 4, v101
	v_pk_add_f32 v[12:13], v[4:5], v[8:9] op_sel:[1,0] op_sel_hi:[0,1]
	s_addc_u32 s43, s43, 0
	v_and_b32_e32 v2, 0x70, v2
	v_mov_b32_e32 v1, v5
	v_mov_b32_e32 v15, v12
	v_mov_b32_e32 v7, v8
	v_ashrrev_i32_e32 v10, 3, v101
	v_lshl_add_u64 v[8:9], s[42:43], 0, v[2:3]
	v_pk_add_f32 v[18:19], v[14:15], v[0:1] neg_lo:[0,1] neg_hi:[0,1]
	v_mad_i64_i32 v[4:5], s[44:45], v10, s72, v[8:9]
	v_pk_add_f32 v[16:17], v[6:7], v[18:19] neg_lo:[0,1] neg_hi:[0,1]
	global_load_dwordx4 v[222:225], v[4:5], off offset:3072
	v_add_u32_e32 v4, 8, v10
	v_mad_i64_i32 v[4:5], s[44:45], v4, s72, v[8:9]
	global_load_dwordx4 v[226:229], v[4:5], off offset:3072
	v_add_u32_e32 v4, 16, v10
	v_mad_i64_i32 v[4:5], s[44:45], v4, s72, v[8:9]
	global_load_dwordx4 v[230:233], v[4:5], off offset:3072
	v_add_u32_e32 v4, 24, v10
	v_mad_i64_i32 v[4:5], s[44:45], v4, s72, v[8:9]
	global_load_dwordx4 v[234:237], v[4:5], off offset:3072
	v_add_u32_e32 v4, 32, v10
	v_mad_i64_i32 v[4:5], s[44:45], v4, s72, v[8:9]
	global_load_dwordx4 v[238:241], v[4:5], off offset:3072
	v_add_u32_e32 v4, 40, v10
	v_mad_i64_i32 v[4:5], s[44:45], v4, s72, v[8:9]
	global_load_dwordx4 v[242:245], v[4:5], off offset:3072
	v_add_u32_e32 v4, 48, v10
	v_mad_i64_i32 v[4:5], s[44:45], v4, s72, v[8:9]
	global_load_dwordx4 v[246:249], v[4:5], off offset:3072
	v_add_u32_e32 v4, 56, v10
	v_mad_i64_i32 v[4:5], s[44:45], v4, s72, v[8:9]
	global_load_dwordx4 v[250:253], v[4:5], off offset:3072
	v_mul_lo_u32 v11, v10, s23
	v_add3_u32 v2, s2, v2, v11
	v_and_b32_e32 v133, 15, v101
	v_ashrrev_i32_e32 v100, 4, v101
	s_mov_b32 s41, s25
	v_or_b32_e32 v144, 16, v133
	v_or_b32_e32 v136, 32, v133
	v_or_b32_e32 v134, 48, v133
	s_lshl_b32 s20, s20, 9
	s_lshl_b32 s21, s21, 2
	s_add_i32 s21, s21, s20
	s_or_b32 s20, s27, s21
	s_ashr_i32 s21, s20, 31
	s_lshl_b64 s[20:21], s[20:21], 13
	s_waitcnt lgkmcnt(0)
; __device__ __forceinline__ void ld8bf(const bf16_t* p, float (&o)[8]) { unpack8(*(const u32x4*)p, o); }
; __device__ __forceinline__ bf16x8 pack_frag(const float (&v)[8]) { return __builtin_bit_cast(bf16x8, pack8(v)); }
; __device__ __forceinline__ void w_ret_m3(const Args& a, int l, unsigned char* ws, const bf16_t* proj, bf16_t* y, LAS unsigned char* wl, int b, int ck_, int h, int lane) {
;     ...
;     w_store_vT(vT, proj + (size_t)row0 * NIN + C_RV + 64 * h, lane);
;     bf16x8 Qf[4][2], Kf[4][2], Sf[4][2];
; #pragma unroll
;     for (int tb = 0; tb < 4; ++tb) { const int n = 16 * tb + lo; float x1[8], x2[8], o1[8], o2[8], cs[8], sn[8];
;         const float* cp_ = cosT + (64 * ck_ + n) * 32 + 8 * fq; const float* sp_ = sinT + (64 * ck_ + n) * 32 + 8 * fq;
; #pragma unroll
;         for (int j = 0; j < 8; ++j) { cs[j] = cp_[j]; sn[j] = sp_[j]; }
;         const bf16_t* qs = proj + (size_t)(row0 + n) * NIN + C_RQ + 64 * h + 8 * fq;
;         ld8bf(qs, x1); ld8bf(qs + 32, x2);
; #pragma unroll
;         for (int j = 0; j < 8; ++j) { o1[j] = x1[j] * cs[j] - x2[j] * sn[j]; o2[j] = x2[j] * cs[j] + x1[j] * sn[j]; }
;         Qf[tb][0] = pack_frag(o1); Qf[tb][1] = pack_frag(o2);
;         const bf16_t* ks = proj + (size_t)(row0 + n) * NIN + C_RK + 64 * h + 8 * fq;
;         ld8bf(ks, x1); ld8bf(ks + 32, x2);
; #pragma unroll
;         for (int j = 0; j < 8; ++j) { o1[j] = (x1[j] * cs[j] - x2[j] * sn[j]) * 0.125f; o2[j] = (x2[j] * cs[j] + x1[j] * sn[j]) * 0.125f; }
;         Kf[tb][0] = pack_frag(o1); Kf[tb][1] = pack_frag(o2);
;     }
	s_add_u32 s20, s48, s20
	s_addc_u32 s21, s49, s21
	v_cmp_gt_f32_e32 vcc, s95, v102
	v_lshlrev_b32_e32 v124, 2, v100
	v_add_u32_e32 v140, 16, v124
	v_lshlrev_b32_e32 v1, 3, v101
	v_not_b32_e32 v143, v124
	v_and_b32_e32 v1, 24, v1
	v_or_b32_e32 v141, 3, v124
	v_or_b32_e32 v142, 2, v124
	v_add_u32_e32 v104, s2, v1
	v_sub_u32_e32 v1, v133, v141
	v_cvt_f32_i32_e32 v1, v1
	v_ashrrev_i32_e32 v125, 31, v124
	v_mov_b32_e32 v186, v2
	v_lshlrev_b32_e32 v10, 3, v100
	v_ashrrev_i32_e32 v11, 31, v10
	v_or_b32_e32 v2, s38, v133
	v_lshlrev_b32_e32 v8, 5, v2
	v_lshlrev_b64 v[6:7], 2, v[10:11]
	v_ashrrev_i32_e32 v9, 31, v8
	v_lshl_add_u64 v[4:5], s[60:61], 0, v[6:7]
	v_lshl_add_u64 v[6:7], s[62:63], 0, v[6:7]
	v_lshlrev_b64 v[8:9], 2, v[8:9]
	v_lshl_add_u64 v[46:47], v[4:5], 0, v[8:9]
	v_lshl_add_u64 v[48:49], v[6:7], 0, v[8:9]
	v_or_b32_e32 v2, s34, v133
	v_mov_b64_e32 v[8:9], s[8:9]
	v_mad_i64_i32 v[20:21], s[44:45], v2, s72, v[8:9]
	v_lshl_add_u64 v[22:23], v[20:21], 0, s[40:41]
	v_lshlrev_b64 v[20:21], 1, v[10:11]
	v_lshl_add_u64 v[10:11], v[22:23], 0, v[20:21]
	global_load_dwordx4 v[22:25], v[10:11], off offset:2048
	global_load_dwordx4 v[26:29], v[10:11], off offset:2112
	global_load_dwordx4 v[30:33], v[10:11], off offset:2560
	global_load_dwordx4 v[34:37], v[10:11], off offset:2624
	global_load_dwordx4 v[38:41], v[46:47], off
	global_load_dwordx4 v[42:45], v[48:49], off
	global_load_dwordx4 v[174:177], v[46:47], off offset:16
	global_load_dwordx4 v[178:181], v[48:49], off offset:16
	s_waitcnt vmcnt(8)
	ds_write_b128 v186, v[222:225]
	ds_write_b128 v186, v[226:229] offset:1152
	ds_write_b128 v186, v[230:233] offset:2304
	ds_write_b128 v186, v[234:237] offset:3456
	ds_write_b128 v186, v[238:241] offset:4608
	ds_write_b128 v186, v[242:245] offset:5760
	ds_write_b128 v186, v[246:249] offset:6912
	ds_write_b128 v186, v[250:253] offset:8064
	v_lshlrev_b64 v[182:183], 1, v[124:125]
	v_lshl_add_u64 v[182:183], s[42:43], 0, v[182:183]
	v_mad_u64_u32 v[184:185], s[44:45], v133, s72, v[182:183]
	global_load_dwordx2 v[222:223], v[184:185], off offset:3584
	global_load_dwordx2 v[224:225], v[184:185], off offset:3616
	global_load_dwordx2 v[226:227], v[184:185], off offset:3648
	global_load_dwordx2 v[228:229], v[184:185], off offset:3680
	v_mad_u64_u32 v[184:185], s[44:45], v144, s72, v[182:183]
	global_load_dwordx2 v[230:231], v[184:185], off offset:3584
	global_load_dwordx2 v[232:233], v[184:185], off offset:3616
	global_load_dwordx2 v[234:235], v[184:185], off offset:3648
	global_load_dwordx2 v[236:237], v[184:185], off offset:3680
	v_mad_u64_u32 v[184:185], s[44:45], v136, s72, v[182:183]
	global_load_dwordx2 v[238:239], v[184:185], off offset:3584
	global_load_dwordx2 v[240:241], v[184:185], off offset:3616
	global_load_dwordx2 v[242:243], v[184:185], off offset:3648
	global_load_dwordx2 v[244:245], v[184:185], off offset:3680
	v_mad_u64_u32 v[184:185], s[44:45], v134, s72, v[182:183]
	global_load_dwordx2 v[246:247], v[184:185], off offset:3584
	global_load_dwordx2 v[248:249], v[184:185], off offset:3616
	global_load_dwordx2 v[250:251], v[184:185], off offset:3648
	global_load_dwordx2 v[252:253], v[184:185], off offset:3680
	v_mov_b32_e32 v184, 0x18000
	v_mov_b32_e32 v185, 0
	v_lshl_add_u64 v[182:183], v[10:11], 0, v[184:185]
	global_load_dwordx4 v[108:111], v[182:183], off offset:2048
	global_load_dwordx4 v[112:115], v[182:183], off offset:2112
	global_load_dwordx4 v[116:119], v[182:183], off offset:2560
	global_load_dwordx4 v[120:123], v[182:183], off offset:2624
	v_lshl_add_u64 v[182:183], v[182:183], 0, v[184:185]
	global_load_dwordx4 v[126:129], v[182:183], off offset:2048
	global_load_dwordx4 v[146:149], v[182:183], off offset:2112
	global_load_dwordx4 v[150:153], v[182:183], off offset:2560
	global_load_dwordx4 v[154:157], v[182:183], off offset:2624
	v_lshl_add_u64 v[182:183], v[182:183], 0, v[184:185]
	global_load_dwordx4 v[158:161], v[182:183], off offset:2048
	global_load_dwordx4 v[188:191], v[182:183], off offset:2112
	global_load_dwordx4 v[192:195], v[182:183], off offset:2560
	global_load_dwordx4 v[196:199], v[182:183], off offset:2624
	v_or_b32_e32 v2, s38, v144
	s_waitcnt vmcnt(28) lgkmcnt(0)
	v_lshlrev_b32_e32 v10, 16, v22
	v_lshlrev_b32_e32 v50, 16, v26
	v_and_b32_e32 v51, 0xffff0000, v26
	v_and_b32_e32 v11, 0xffff0000, v22
	v_pk_mul_f32 v[52:53], v[38:39], v[50:51]
	v_pk_mul_f32 v[50:51], v[42:43], v[50:51]
	v_pk_fma_f32 v[52:53], v[42:43], v[10:11], v[52:53]
	v_pk_fma_f32 v[10:11], v[38:39], v[10:11], v[50:51] neg_lo:[0,0,1] neg_hi:[0,0,1]
	v_lshlrev_b32_e32 v50, 16, v34
	v_and_b32_e32 v51, 0xffff0000, v34
	v_cvt_pk_bf16_f32 v96, v10, v11
	v_cvt_pk_bf16_f32 v92, v52, v53
	v_lshlrev_b32_e32 v10, 16, v30
	v_and_b32_e32 v11, 0xffff0000, v30
	v_pk_mul_f32 v[52:53], v[38:39], v[50:51]
	v_lshlrev_b32_e32 v26, 16, v27
	v_pk_fma_f32 v[52:53], v[42:43], v[10:11], v[52:53]
	v_pk_mul_f32 v[42:43], v[42:43], v[50:51]
	v_and_b32_e32 v27, 0xffff0000, v27
	v_pk_fma_f32 v[10:11], v[38:39], v[10:11], v[42:43] neg_lo:[0,0,1] neg_hi:[0,0,1]
	v_lshlrev_b32_e32 v22, 16, v23
	v_and_b32_e32 v23, 0xffff0000, v23
	v_pk_mul_f32 v[38:39], v[40:41], v[26:27]
	v_pk_mul_f32 v[26:27], v[44:45], v[26:27]
	v_pk_fma_f32 v[38:39], v[44:45], v[22:23], v[38:39]
	v_pk_fma_f32 v[22:23], v[40:41], v[22:23], v[26:27] neg_lo:[0,0,1] neg_hi:[0,0,1]
	v_lshlrev_b32_e32 v26, 16, v35
	v_and_b32_e32 v27, 0xffff0000, v35
	v_cvt_pk_bf16_f32 v97, v22, v23
	v_lshlrev_b32_e32 v22, 16, v31
	v_and_b32_e32 v23, 0xffff0000, v31
	v_pk_mul_f32 v[30:31], v[40:41], v[26:27]
	v_pk_mul_f32 v[26:27], v[44:45], v[26:27]
	v_cvt_pk_bf16_f32 v93, v38, v39
	v_pk_fma_f32 v[30:31], v[44:45], v[22:23], v[30:31]
	v_pk_fma_f32 v[22:23], v[40:41], v[22:23], v[26:27] neg_lo:[0,0,1] neg_hi:[0,0,1]
	v_mov_b64_e32 v[38:39], v[174:175]
	v_mov_b64_e32 v[40:41], v[176:177]
	v_mov_b64_e32 v[42:43], v[178:179]
	v_mov_b64_e32 v[44:45], v[180:181]
	v_lshlrev_b32_e32 v34, 16, v28
	v_and_b32_e32 v35, 0xffff0000, v28
	v_lshlrev_b32_e32 v26, 16, v24
	v_and_b32_e32 v27, 0xffff0000, v24
	v_lshlrev_b32_e32 v28, 16, v29
	v_and_b32_e32 v29, 0xffff0000, v29
	v_pk_mul_f32 v[10:11], v[10:11], s[16:17] op_sel_hi:[1,0]
	v_lshlrev_b32_e32 v24, 16, v25
	v_and_b32_e32 v25, 0xffff0000, v25
	v_pk_mul_f32 v[22:23], v[22:23], s[16:17] op_sel_hi:[1,0]
	v_cvt_pk_bf16_f32 v64, v10, v11
	v_lshlrev_b32_e32 v10, 5, v2
	v_or_b32_e32 v2, s34, v144
	v_cvt_pk_bf16_f32 v65, v22, v23
	v_mad_i64_i32 v[22:23], s[44:45], v2, s72, v[8:9]
	v_ashrrev_i32_e32 v11, 31, v10
	v_lshl_add_u64 v[22:23], v[22:23], 0, s[40:41]
	v_pk_mul_f32 v[30:31], v[30:31], s[16:17] op_sel_hi:[1,0]
	v_lshlrev_b64 v[10:11], 2, v[10:11]
	v_cvt_pk_bf16_f32 v73, v30, v31
	v_or_b32_e32 v2, s38, v136
	v_pk_mul_f32 v[52:53], v[52:53], s[16:17] op_sel_hi:[1,0]
	s_waitcnt vmcnt(0) lgkmcnt(0)
; __device__ __forceinline__ void ld8bf(const bf16_t* p, float (&o)[8]) { unpack8(*(const u32x4*)p, o); }
; __device__ __forceinline__ bf16x8 pack_frag(const float (&v)[8]) { return __builtin_bit_cast(bf16x8, pack8(v)); }
; __device__ __forceinline__ void w_ret_m3(const Args& a, int l, unsigned char* ws, const bf16_t* proj, bf16_t* y, LAS unsigned char* wl, int b, int ck_, int h, int lane) {
;     ...
;     for (int tb = 0; tb < 4; ++tb) { const int n = 16 * tb + lo; float x1[8], x2[8], o1[8], o2[8], cs[8], sn[8];
;         const float* cp_ = cosT + (64 * ck_ + n) * 32 + 8 * fq; const float* sp_ = sinT + (64 * ck_ + n) * 32 + 8 * fq;
; #pragma unroll
;         for (int j = 0; j < 8; ++j) { cs[j] = cp_[j]; sn[j] = sp_[j]; }
;         const bf16_t* qs = proj + (size_t)(row0 + n) * NIN + C_RQ + 64 * h + 8 * fq;
;         ld8bf(qs, x1); ld8bf(qs + 32, x2);
; #pragma unroll
;         for (int j = 0; j < 8; ++j) { o1[j] = x1[j] * cs[j] - x2[j] * sn[j]; o2[j] = x2[j] * cs[j] + x1[j] * sn[j]; }
;         Qf[tb][0] = pack_frag(o1); Qf[tb][1] = pack_frag(o2);
;         const bf16_t* ks = proj + (size_t)(row0 + n) * NIN + C_RK + 64 * h + 8 * fq;
;         ld8bf(ks, x1); ld8bf(ks + 32, x2);
; #pragma unroll
;         for (int j = 0; j < 8; ++j) { o1[j] = (x1[j] * cs[j] - x2[j] * sn[j]) * 0.125f; o2[j] = (x2[j] * cs[j] + x1[j] * sn[j]) * 0.125f; }
;         Kf[tb][0] = pack_frag(o1); Kf[tb][1] = pack_frag(o2);
	v_pk_mul_f32 v[46:47], v[38:39], v[34:35]
	v_pk_mul_f32 v[34:35], v[42:43], v[34:35]
	v_pk_fma_f32 v[46:47], v[42:43], v[26:27], v[46:47]
	v_pk_fma_f32 v[26:27], v[38:39], v[26:27], v[34:35] neg_lo:[0,0,1] neg_hi:[0,0,1]
	v_lshlrev_b32_e32 v34, 16, v36
	v_and_b32_e32 v35, 0xffff0000, v36
	v_cvt_pk_bf16_f32 v98, v26, v27
	v_cvt_pk_bf16_f32 v94, v46, v47
	v_lshlrev_b32_e32 v26, 16, v32
	v_and_b32_e32 v27, 0xffff0000, v32
	v_pk_mul_f32 v[46:47], v[38:39], v[34:35]
	v_pk_mul_f32 v[34:35], v[42:43], v[34:35]
	v_pk_fma_f32 v[46:47], v[42:43], v[26:27], v[46:47]
	v_pk_fma_f32 v[26:27], v[38:39], v[26:27], v[34:35] neg_lo:[0,0,1] neg_hi:[0,0,1]
	v_pk_mul_f32 v[34:35], v[40:41], v[28:29]
	v_pk_mul_f32 v[28:29], v[44:45], v[28:29]
	v_pk_fma_f32 v[34:35], v[44:45], v[24:25], v[34:35]
	v_pk_fma_f32 v[24:25], v[40:41], v[24:25], v[28:29] neg_lo:[0,0,1] neg_hi:[0,0,1]
	v_lshlrev_b32_e32 v28, 16, v37
	v_and_b32_e32 v29, 0xffff0000, v37
	v_cvt_pk_bf16_f32 v99, v24, v25
	v_lshlrev_b32_e32 v24, 16, v33
	v_and_b32_e32 v25, 0xffff0000, v33
	v_pk_mul_f32 v[32:33], v[40:41], v[28:29]
	v_pk_mul_f32 v[28:29], v[44:45], v[28:29]
	v_pk_fma_f32 v[32:33], v[44:45], v[24:25], v[32:33]
	v_pk_fma_f32 v[24:25], v[40:41], v[24:25], v[28:29] neg_lo:[0,0,1] neg_hi:[0,0,1]
	v_pk_mul_f32 v[46:47], v[46:47], s[16:17] op_sel_hi:[1,0]
	v_pk_mul_f32 v[26:27], v[26:27], s[16:17] op_sel_hi:[1,0]
	v_cvt_pk_bf16_f32 v95, v34, v35
	v_pk_mul_f32 v[32:33], v[32:33], s[16:17] op_sel_hi:[1,0]
	v_pk_mul_f32 v[24:25], v[24:25], s[16:17] op_sel_hi:[1,0]
	v_lshl_add_u64 v[34:35], v[22:23], 0, v[20:21]
	v_cvt_pk_bf16_f32 v66, v26, v27
	v_cvt_pk_bf16_f32 v67, v24, v25
	v_cvt_pk_bf16_f32 v74, v46, v47
	v_cvt_pk_bf16_f32 v75, v32, v33
	v_lshl_add_u64 v[46:47], v[4:5], 0, v[10:11]
	v_lshl_add_u64 v[10:11], v[6:7], 0, v[10:11]
	v_mov_b64_e32 v[22:23], v[108:109]
	v_mov_b64_e32 v[24:25], v[110:111]
	v_mov_b64_e32 v[26:27], v[112:113]
	v_mov_b64_e32 v[28:29], v[114:115]
	v_mov_b64_e32 v[30:31], v[116:117]
	v_mov_b64_e32 v[32:33], v[118:119]
	s_nop 0
	v_mov_b64_e32 v[34:35], v[120:121]
	v_mov_b64_e32 v[36:37], v[122:123]
	s_nop 0
	global_load_dwordx2 v[42:43], v[46:47], off
	global_load_dwordx4 v[38:41], v[10:11], off
	global_load_dwordx4 v[174:177], v[46:47], off offset:8
	global_load_dwordx4 v[178:181], v[10:11], off offset:16
	global_load_dwordx2 v[182:183], v[46:47], off offset:24
	v_cvt_pk_bf16_f32 v72, v52, v53
	s_waitcnt vmcnt(0) lgkmcnt(0)
	v_lshlrev_b32_e32 v44, 16, v22
	v_lshlrev_b32_e32 v48, 16, v26
	v_and_b32_e32 v49, 0xffff0000, v26
	v_and_b32_e32 v45, 0xffff0000, v22
	v_pk_mul_f32 v[50:51], v[42:43], v[48:49]
	v_pk_mul_f32 v[48:49], v[38:39], v[48:49]
	v_pk_fma_f32 v[50:51], v[38:39], v[44:45], v[50:51]
	v_pk_fma_f32 v[44:45], v[42:43], v[44:45], v[48:49] neg_lo:[0,0,1] neg_hi:[0,0,1]
	v_lshlrev_b32_e32 v48, 16, v34
	v_and_b32_e32 v49, 0xffff0000, v34
	v_cvt_pk_bf16_f32 v88, v44, v45
	v_cvt_pk_bf16_f32 v84, v50, v51
	v_lshlrev_b32_e32 v44, 16, v30
	v_and_b32_e32 v45, 0xffff0000, v30
	v_pk_mul_f32 v[50:51], v[42:43], v[48:49]
	v_lshlrev_b32_e32 v26, 16, v27
	v_pk_fma_f32 v[50:51], v[38:39], v[44:45], v[50:51]
	v_pk_mul_f32 v[38:39], v[38:39], v[48:49]
	v_and_b32_e32 v27, 0xffff0000, v27
	v_pk_fma_f32 v[38:39], v[42:43], v[44:45], v[38:39] neg_lo:[0,0,1] neg_hi:[0,0,1]
	v_mov_b64_e32 v[42:43], v[174:175]
	v_mov_b64_e32 v[44:45], v[176:177]
	v_pk_mul_f32 v[48:49], v[38:39], s[16:17] op_sel_hi:[1,0]
	v_lshlrev_b32_e32 v22, 16, v23
	v_and_b32_e32 v23, 0xffff0000, v23
	v_pk_mul_f32 v[50:51], v[50:51], s[16:17] op_sel_hi:[1,0]
	v_cvt_pk_bf16_f32 v60, v48, v49
	v_cvt_pk_bf16_f32 v68, v50, v51
	s_waitcnt vmcnt(0) lgkmcnt(0)
	v_pk_mul_f32 v[38:39], v[42:43], v[26:27]
	v_pk_mul_f32 v[26:27], v[40:41], v[26:27]
	v_pk_fma_f32 v[38:39], v[40:41], v[22:23], v[38:39]
	v_pk_fma_f32 v[22:23], v[42:43], v[22:23], v[26:27] neg_lo:[0,0,1] neg_hi:[0,0,1]
	v_lshlrev_b32_e32 v26, 16, v35
	v_and_b32_e32 v27, 0xffff0000, v35
	v_cvt_pk_bf16_f32 v89, v22, v23
	v_lshlrev_b32_e32 v22, 16, v31
	v_and_b32_e32 v23, 0xffff0000, v31
	v_pk_mul_f32 v[30:31], v[42:43], v[26:27]
	v_cvt_pk_bf16_f32 v85, v38, v39
	v_pk_fma_f32 v[30:31], v[40:41], v[22:23], v[30:31]
	v_pk_mul_f32 v[26:27], v[40:41], v[26:27]
	v_mov_b64_e32 v[38:39], v[178:179]
	v_mov_b64_e32 v[40:41], v[180:181]
	v_pk_fma_f32 v[22:23], v[42:43], v[22:23], v[26:27] neg_lo:[0,0,1] neg_hi:[0,0,1]
	v_lshlrev_b32_e32 v26, 16, v28
	v_and_b32_e32 v27, 0xffff0000, v28
	v_lshlrev_b32_e32 v10, 16, v24
	v_and_b32_e32 v11, 0xffff0000, v24
	v_pk_mul_f32 v[34:35], v[44:45], v[26:27]
	v_lshlrev_b32_e32 v28, 16, v29
	v_and_b32_e32 v29, 0xffff0000, v29
	v_lshlrev_b32_e32 v24, 16, v25
	v_and_b32_e32 v25, 0xffff0000, v25
	v_pk_mul_f32 v[22:23], v[22:23], s[16:17] op_sel_hi:[1,0]
	v_pk_mul_f32 v[30:31], v[30:31], s[16:17] op_sel_hi:[1,0]
	v_cvt_pk_bf16_f32 v61, v22, v23
	v_cvt_pk_bf16_f32 v69, v30, v31
	s_waitcnt vmcnt(0) lgkmcnt(0)
	v_pk_mul_f32 v[26:27], v[38:39], v[26:27]
	v_pk_fma_f32 v[34:35], v[38:39], v[10:11], v[34:35]
	v_pk_fma_f32 v[10:11], v[44:45], v[10:11], v[26:27] neg_lo:[0,0,1] neg_hi:[0,0,1]
	v_lshlrev_b32_e32 v26, 16, v36
	v_and_b32_e32 v27, 0xffff0000, v36
	v_cvt_pk_bf16_f32 v90, v10, v11
	v_cvt_pk_bf16_f32 v86, v34, v35
	v_lshlrev_b32_e32 v10, 16, v32
	v_and_b32_e32 v11, 0xffff0000, v32
	v_pk_mul_f32 v[34:35], v[44:45], v[26:27]
	v_pk_mul_f32 v[26:27], v[38:39], v[26:27]
	v_pk_fma_f32 v[34:35], v[38:39], v[10:11], v[34:35]
	v_pk_fma_f32 v[10:11], v[44:45], v[10:11], v[26:27] neg_lo:[0,0,1] neg_hi:[0,0,1]
	v_mov_b64_e32 v[26:27], v[182:183]
	v_pk_mul_f32 v[10:11], v[10:11], s[16:17] op_sel_hi:[1,0]
	v_pk_mul_f32 v[34:35], v[34:35], s[16:17] op_sel_hi:[1,0]
	v_cvt_pk_bf16_f32 v62, v10, v11
	v_lshlrev_b32_e32 v10, 5, v2
	v_or_b32_e32 v2, s34, v136
	v_mad_i64_i32 v[22:23], s[44:45], v2, s72, v[8:9]
	v_ashrrev_i32_e32 v11, 31, v10
	v_lshl_add_u64 v[22:23], v[22:23], 0, s[40:41]
	v_cvt_pk_bf16_f32 v70, v34, v35
	v_lshlrev_b64 v[10:11], 2, v[10:11]
	v_lshl_add_u64 v[34:35], v[22:23], 0, v[20:21]
	v_lshl_add_u64 v[46:47], v[4:5], 0, v[10:11]
	v_lshl_add_u64 v[10:11], v[6:7], 0, v[10:11]
	v_or_b32_e32 v2, s38, v134
	s_waitcnt vmcnt(0) lgkmcnt(0)
; __device__ __forceinline__ void ld8bf(const bf16_t* p, float (&o)[8]) { unpack8(*(const u32x4*)p, o); }
; __device__ __forceinline__ bf16x8 pack_frag(const float (&v)[8]) { return __builtin_bit_cast(bf16x8, pack8(v)); }
; __device__ __forceinline__ void w_ret_m3(const Args& a, int l, unsigned char* ws, const bf16_t* proj, bf16_t* y, LAS unsigned char* wl, int b, int ck_, int h, int lane) {
;     ...
;     for (int tb = 0; tb < 4; ++tb) { const int n = 16 * tb + lo; float x1[8], x2[8], o1[8], o2[8], cs[8], sn[8];
;         const float* cp_ = cosT + (64 * ck_ + n) * 32 + 8 * fq; const float* sp_ = sinT + (64 * ck_ + n) * 32 + 8 * fq;
; #pragma unroll
;         for (int j = 0; j < 8; ++j) { cs[j] = cp_[j]; sn[j] = sp_[j]; }
;         const bf16_t* qs = proj + (size_t)(row0 + n) * NIN + C_RQ + 64 * h + 8 * fq;
;         ld8bf(qs, x1); ld8bf(qs + 32, x2);
; #pragma unroll
;         for (int j = 0; j < 8; ++j) { o1[j] = x1[j] * cs[j] - x2[j] * sn[j]; o2[j] = x2[j] * cs[j] + x1[j] * sn[j]; }
;         Qf[tb][0] = pack_frag(o1); Qf[tb][1] = pack_frag(o2);
;         const bf16_t* ks = proj + (size_t)(row0 + n) * NIN + C_RK + 64 * h + 8 * fq;
;         ld8bf(ks, x1); ld8bf(ks + 32, x2);
; #pragma unroll
;         for (int j = 0; j < 8; ++j) { o1[j] = (x1[j] * cs[j] - x2[j] * sn[j]) * 0.125f; o2[j] = (x2[j] * cs[j] + x1[j] * sn[j]) * 0.125f; }
;         Kf[tb][0] = pack_frag(o1); Kf[tb][1] = pack_frag(o2);
	v_pk_mul_f32 v[38:39], v[26:27], v[28:29]
	v_pk_mul_f32 v[28:29], v[40:41], v[28:29]
	v_pk_fma_f32 v[38:39], v[40:41], v[24:25], v[38:39]
	v_pk_fma_f32 v[24:25], v[26:27], v[24:25], v[28:29] neg_lo:[0,0,1] neg_hi:[0,0,1]
	v_lshlrev_b32_e32 v28, 16, v37
	v_and_b32_e32 v29, 0xffff0000, v37
	v_cvt_pk_bf16_f32 v91, v24, v25
	v_lshlrev_b32_e32 v24, 16, v33
	v_and_b32_e32 v25, 0xffff0000, v33
	v_pk_mul_f32 v[32:33], v[26:27], v[28:29]
	v_pk_mul_f32 v[28:29], v[40:41], v[28:29]
	v_pk_fma_f32 v[32:33], v[40:41], v[24:25], v[32:33]
	v_pk_fma_f32 v[24:25], v[26:27], v[24:25], v[28:29] neg_lo:[0,0,1] neg_hi:[0,0,1]
	v_pk_mul_f32 v[32:33], v[32:33], s[16:17] op_sel_hi:[1,0]
	v_pk_mul_f32 v[24:25], v[24:25], s[16:17] op_sel_hi:[1,0]
	v_cvt_pk_bf16_f32 v87, v38, v39
	v_cvt_pk_bf16_f32 v63, v24, v25
	v_cvt_pk_bf16_f32 v71, v32, v33
	v_mov_b64_e32 v[22:23], v[126:127]
	v_mov_b64_e32 v[24:25], v[128:129]
	v_mov_b64_e32 v[26:27], v[146:147]
	v_mov_b64_e32 v[28:29], v[148:149]
	v_mov_b64_e32 v[30:31], v[150:151]
	v_mov_b64_e32 v[32:33], v[152:153]
	s_nop 0
	v_mov_b64_e32 v[34:35], v[154:155]
	v_mov_b64_e32 v[36:37], v[156:157]
	s_nop 0
	global_load_dwordx4 v[38:41], v[46:47], off
	global_load_dwordx4 v[42:45], v[10:11], off
	global_load_dwordx4 v[174:177], v[46:47], off offset:16
	global_load_dwordx4 v[178:181], v[10:11], off offset:16
	s_waitcnt vmcnt(0) lgkmcnt(0)
	v_lshlrev_b32_e32 v48, 16, v22
	v_lshlrev_b32_e32 v50, 16, v26
	v_and_b32_e32 v51, 0xffff0000, v26
	v_and_b32_e32 v49, 0xffff0000, v22
	v_pk_mul_f32 v[52:53], v[38:39], v[50:51]
	v_pk_mul_f32 v[50:51], v[42:43], v[50:51]
	v_pk_fma_f32 v[52:53], v[42:43], v[48:49], v[52:53]
	v_pk_fma_f32 v[48:49], v[38:39], v[48:49], v[50:51] neg_lo:[0,0,1] neg_hi:[0,0,1]
	v_lshlrev_b32_e32 v50, 16, v34
	v_and_b32_e32 v51, 0xffff0000, v34
	v_cvt_pk_bf16_f32 v80, v48, v49
	v_cvt_pk_bf16_f32 v76, v52, v53
	v_lshlrev_b32_e32 v48, 16, v30
	v_and_b32_e32 v49, 0xffff0000, v30
	v_pk_mul_f32 v[52:53], v[38:39], v[50:51]
	v_lshlrev_b32_e32 v26, 16, v27
	v_pk_fma_f32 v[52:53], v[42:43], v[48:49], v[52:53]
	v_pk_mul_f32 v[42:43], v[42:43], v[50:51]
	v_and_b32_e32 v27, 0xffff0000, v27
	v_pk_fma_f32 v[38:39], v[38:39], v[48:49], v[42:43] neg_lo:[0,0,1] neg_hi:[0,0,1]
	v_lshlrev_b32_e32 v22, 16, v23
	v_pk_mul_f32 v[48:49], v[38:39], s[16:17] op_sel_hi:[1,0]
	v_and_b32_e32 v23, 0xffff0000, v23
	v_pk_mul_f32 v[38:39], v[40:41], v[26:27]
	v_pk_mul_f32 v[26:27], v[44:45], v[26:27]
	v_pk_fma_f32 v[38:39], v[44:45], v[22:23], v[38:39]
	v_pk_fma_f32 v[22:23], v[40:41], v[22:23], v[26:27] neg_lo:[0,0,1] neg_hi:[0,0,1]
	v_lshlrev_b32_e32 v26, 16, v35
	v_and_b32_e32 v27, 0xffff0000, v35
	v_cvt_pk_bf16_f32 v81, v22, v23
	v_lshlrev_b32_e32 v22, 16, v31
	v_and_b32_e32 v23, 0xffff0000, v31
	v_pk_mul_f32 v[30:31], v[40:41], v[26:27]
	v_pk_mul_f32 v[26:27], v[44:45], v[26:27]
	v_cvt_pk_bf16_f32 v77, v38, v39
	v_pk_fma_f32 v[30:31], v[44:45], v[22:23], v[30:31]
	v_pk_fma_f32 v[22:23], v[40:41], v[22:23], v[26:27] neg_lo:[0,0,1] neg_hi:[0,0,1]
	v_mov_b64_e32 v[38:39], v[174:175]
	v_mov_b64_e32 v[40:41], v[176:177]
	v_mov_b64_e32 v[42:43], v[178:179]
	v_mov_b64_e32 v[44:45], v[180:181]
	v_lshlrev_b32_e32 v26, 16, v28
	v_and_b32_e32 v27, 0xffff0000, v28
	v_lshlrev_b32_e32 v10, 16, v24
	v_and_b32_e32 v11, 0xffff0000, v24
	v_lshlrev_b32_e32 v24, 16, v25
	v_and_b32_e32 v25, 0xffff0000, v25
	v_pk_mul_f32 v[30:31], v[30:31], s[16:17] op_sel_hi:[1,0]
	v_pk_mul_f32 v[22:23], v[22:23], s[16:17] op_sel_hi:[1,0]
	v_pk_mul_f32 v[52:53], v[52:53], s[16:17] op_sel_hi:[1,0]
	s_waitcnt vmcnt(0) lgkmcnt(0)
	v_pk_mul_f32 v[34:35], v[38:39], v[26:27]
	v_pk_mul_f32 v[26:27], v[42:43], v[26:27]
	v_pk_fma_f32 v[34:35], v[42:43], v[10:11], v[34:35]
	v_pk_fma_f32 v[10:11], v[38:39], v[10:11], v[26:27] neg_lo:[0,0,1] neg_hi:[0,0,1]
	v_lshlrev_b32_e32 v26, 16, v36
	v_and_b32_e32 v27, 0xffff0000, v36
	v_cvt_pk_bf16_f32 v82, v10, v11
	v_cvt_pk_bf16_f32 v78, v34, v35
	v_lshlrev_b32_e32 v10, 16, v32
	v_and_b32_e32 v11, 0xffff0000, v32
	v_pk_mul_f32 v[34:35], v[38:39], v[26:27]
	v_pk_mul_f32 v[26:27], v[42:43], v[26:27]
	v_pk_fma_f32 v[34:35], v[42:43], v[10:11], v[34:35]
	v_pk_fma_f32 v[10:11], v[38:39], v[10:11], v[26:27] neg_lo:[0,0,1] neg_hi:[0,0,1]
	v_lshlrev_b32_e32 v26, 16, v29
	v_pk_mul_f32 v[10:11], v[10:11], s[16:17] op_sel_hi:[1,0]
	v_and_b32_e32 v27, 0xffff0000, v29
	v_cvt_pk_bf16_f32 v46, v10, v11
	v_lshlrev_b32_e32 v10, 5, v2
	v_pk_mul_f32 v[28:29], v[40:41], v[26:27]
	v_pk_mul_f32 v[26:27], v[44:45], v[26:27]
	v_ashrrev_i32_e32 v11, 31, v10
	v_pk_fma_f32 v[28:29], v[44:45], v[24:25], v[28:29]
	v_pk_fma_f32 v[24:25], v[40:41], v[24:25], v[26:27] neg_lo:[0,0,1] neg_hi:[0,0,1]
	v_lshlrev_b32_e32 v26, 16, v37
	v_and_b32_e32 v27, 0xffff0000, v37
	v_lshlrev_b64 v[10:11], 2, v[10:11]
	v_or_b32_e32 v2, s34, v134
	v_cvt_pk_bf16_f32 v83, v24, v25
	v_cvt_pk_bf16_f32 v79, v28, v29
	v_lshlrev_b32_e32 v24, 16, v33
	v_and_b32_e32 v25, 0xffff0000, v33
	v_pk_mul_f32 v[28:29], v[40:41], v[26:27]
	v_pk_mul_f32 v[26:27], v[44:45], v[26:27]
	v_lshl_add_u64 v[38:39], v[4:5], 0, v[10:11]
	v_mad_i64_i32 v[4:5], s[38:39], v2, s72, v[8:9]
	v_pk_fma_f32 v[28:29], v[44:45], v[24:25], v[28:29]
	v_pk_fma_f32 v[24:25], v[40:41], v[24:25], v[26:27] neg_lo:[0,0,1] neg_hi:[0,0,1]
	v_lshl_add_u64 v[4:5], v[4:5], 0, s[40:41]
	v_pk_mul_f32 v[34:35], v[34:35], s[16:17] op_sel_hi:[1,0]
	v_pk_mul_f32 v[28:29], v[28:29], s[16:17] op_sel_hi:[1,0]
	v_pk_mul_f32 v[24:25], v[24:25], s[16:17] op_sel_hi:[1,0]
	v_lshl_add_u64 v[26:27], v[4:5], 0, v[20:21]
	v_cvt_pk_bf16_f32 v44, v48, v49
	v_cvt_pk_bf16_f32 v45, v22, v23
	v_cvt_pk_bf16_f32 v47, v24, v25
	v_cvt_pk_bf16_f32 v49, v30, v31
	v_cvt_pk_bf16_f32 v50, v34, v35
	v_cvt_pk_bf16_f32 v51, v28, v29
	v_lshl_add_u64 v[40:41], v[6:7], 0, v[10:11]
	v_mov_b64_e32 v[4:5], v[158:159]
	v_mov_b64_e32 v[6:7], v[160:161]
	v_mov_b64_e32 v[8:9], v[188:189]
	v_mov_b64_e32 v[10:11], v[190:191]
	v_mov_b64_e32 v[22:23], v[192:193]
	v_mov_b64_e32 v[24:25], v[194:195]
	s_nop 0
	v_mov_b64_e32 v[26:27], v[196:197]
	v_mov_b64_e32 v[28:29], v[198:199]
	s_nop 0
	global_load_dwordx4 v[30:33], v[38:39], off
	global_load_dwordx4 v[34:37], v[40:41], off
	global_load_dwordx4 v[174:177], v[38:39], off offset:16
	global_load_dwordx4 v[178:181], v[40:41], off offset:16
	v_cvt_pk_bf16_f32 v48, v52, v53
	v_sub_f32_e32 v2, v14, v18
	v_sub_f32_e32 v0, v0, v2
	v_add_f32_e32 v0, v16, v0
	v_add_f32_e32 v0, v0, v17
	v_add_f32_e32 v0, v12, v0
	v_cmp_nlt_f32_e64 s[38:39], 1.0, v102
	v_lshl_add_u64 v[12:13], s[20:21], 0, v[20:21]
	v_lshlrev_b32_e32 v2, 7, v133
	v_cndmask_b32_e64 v0, v205, v0, s[38:39]
	v_cmp_neq_f32_e64 s[38:39], 1.0, v102
	s_mov_b32 s20, 10
	s_waitcnt vmcnt(0) lgkmcnt(0)
; template <int KIND>
; __device__ __forceinline__ void w_m3_core(const bf16x8 (&Qf)[4][2], const bf16x8 (&Kf)[4][2], const bf16x8 (&Sf)[4][2], const LAS bf16_t* vT, float lg,
;                                           const bf16_t* gsrc, const float* nw, bf16_t* ydst, int lo, int fq) {
;     ...
;                     s = __builtin_amdgcn_mfma_f32_16x16x32_bf16(Kf[mb][0], Qf[nb][0], s, 0, 0, 0); s = __builtin_amdgcn_mfma_f32_16x16x32_bf16(Kf[mb][1], Qf[nb][1], s, 0, 0, 0);
; #pragma unroll
;                     for (int r = 0; r < 4; ++r) { const int m = 16 * mb + 4 * fq + r, n = 16 * nb + lo; float v = s[r];
;                         if (KIND == 0) v *= __expf((float)(n - m) * lg);
;                         if (mb == nb) v = (m <= n) ? v : 0.f;
;                         pv[4 * hh + r] = v; }
; __device__ __forceinline__ void w_ret_m3(const Args& a, int l, unsigned char* ws, const bf16_t* proj, bf16_t* y, LAS unsigned char* wl, int b, int ck_, int h, int lane) {
;     ...
;     const bf16_t* Sb = (const bf16_t*)((const unsigned char*)a.out + OUT_SBR) + (size_t)((b * NCH + ck_) * 4 + h) * 4096;
; #pragma unroll
;     for (int eb = 0; eb < 4; ++eb)
; #pragma unroll
;         for (int kk = 0; kk < 2; ++kk) Sf[eb][kk] = *(const bf16x8*)(Sb + (16 * eb + lo) * 64 + 32 * kk + 8 * fq);
	v_lshlrev_b32_e32 v42, 16, v4
	v_lshlrev_b32_e32 v52, 16, v8
	v_and_b32_e32 v53, 0xffff0000, v8
	v_and_b32_e32 v43, 0xffff0000, v4
	v_pk_mul_f32 v[54:55], v[30:31], v[52:53]
	v_pk_mul_f32 v[52:53], v[34:35], v[52:53]
	v_pk_fma_f32 v[54:55], v[34:35], v[42:43], v[54:55]
	v_pk_fma_f32 v[42:43], v[30:31], v[42:43], v[52:53] neg_lo:[0,0,1] neg_hi:[0,0,1]
	v_lshlrev_b32_e32 v52, 16, v26
	v_and_b32_e32 v53, 0xffff0000, v26
	v_cvt_pk_bf16_f32 v8, v42, v43
	v_cvt_pk_bf16_f32 v4, v54, v55
	v_lshlrev_b32_e32 v42, 16, v22
	v_and_b32_e32 v43, 0xffff0000, v22
	v_pk_mul_f32 v[54:55], v[30:31], v[52:53]
	v_lshlrev_b32_e32 v26, 16, v27
	v_pk_fma_f32 v[54:55], v[34:35], v[42:43], v[54:55]
	v_pk_mul_f32 v[34:35], v[34:35], v[52:53]
	v_and_b32_e32 v27, 0xffff0000, v27
	v_pk_fma_f32 v[30:31], v[30:31], v[42:43], v[34:35] neg_lo:[0,0,1] neg_hi:[0,0,1]
	v_lshlrev_b32_e32 v34, 16, v9
	v_and_b32_e32 v35, 0xffff0000, v9
	v_pk_mul_f32 v[42:43], v[30:31], s[16:17] op_sel_hi:[1,0]
	v_lshlrev_b32_e32 v30, 16, v5
	v_and_b32_e32 v31, 0xffff0000, v5
	v_pk_mul_f32 v[52:53], v[32:33], v[34:35]
	v_pk_mul_f32 v[34:35], v[36:37], v[34:35]
	v_pk_fma_f32 v[52:53], v[36:37], v[30:31], v[52:53]
	v_pk_fma_f32 v[30:31], v[32:33], v[30:31], v[34:35] neg_lo:[0,0,1] neg_hi:[0,0,1]
	v_lshlrev_b32_e32 v22, 16, v23
	v_cvt_pk_bf16_f32 v9, v30, v31
	v_and_b32_e32 v23, 0xffff0000, v23
	v_pk_mul_f32 v[30:31], v[32:33], v[26:27]
	v_pk_mul_f32 v[26:27], v[36:37], v[26:27]
	v_pk_fma_f32 v[30:31], v[36:37], v[22:23], v[30:31]
	v_pk_fma_f32 v[22:23], v[32:33], v[22:23], v[26:27] neg_lo:[0,0,1] neg_hi:[0,0,1]
	v_pk_mul_f32 v[58:59], v[30:31], s[16:17] op_sel_hi:[1,0]
	v_mov_b64_e32 v[30:31], v[174:175]
	v_mov_b64_e32 v[32:33], v[176:177]
	v_mov_b64_e32 v[34:35], v[178:179]
	v_mov_b64_e32 v[36:37], v[180:181]
	v_lshlrev_b32_e32 v38, 16, v10
	v_and_b32_e32 v39, 0xffff0000, v10
	v_lshlrev_b32_e32 v26, 16, v6
	v_and_b32_e32 v27, 0xffff0000, v6
	v_cndmask_b32_e64 v0, v206, v0, s[38:39]
	v_pk_mul_f32 v[56:57], v[54:55], s[16:17] op_sel_hi:[1,0]
	v_pk_mul_f32 v[22:23], v[22:23], s[16:17] op_sel_hi:[1,0]
	v_cvt_pk_bf16_f32 v5, v52, v53
	v_cvt_pk_bf16_f32 v52, v42, v43
	v_cvt_pk_bf16_f32 v53, v22, v23
	v_cvt_pk_bf16_f32 v56, v56, v57
	v_cvt_pk_bf16_f32 v57, v58, v59
	v_cndmask_b32_e64 v135, v0, -v102, vcc
	v_bfe_u32 v0, v101, 2, 2
	v_or_b32_e32 v105, v124, v0
	v_or_b32_e32 v106, v140, v0
	v_lshlrev_b32_e32 v0, 6, v100
	v_mfma_f32_16x16x32_bf16 v[100:103], v[64:67], v[96:99], 0
	v_cmp_lt_i32_e32 vcc, v133, v124
	v_mul_f32_e32 v1, v135, v1
	v_mul_f32_e32 v1, 0x3fb8aa3b, v1
	v_mfma_f32_16x16x32_bf16 v[100:103], v[72:75], v[92:95], v[100:103]
	v_exp_f32_e32 v1, v1
	s_waitcnt vmcnt(0) lgkmcnt(0)
	v_pk_mul_f32 v[40:41], v[30:31], v[38:39]
	v_pk_mul_f32 v[38:39], v[34:35], v[38:39]
	v_pk_fma_f32 v[40:41], v[34:35], v[26:27], v[40:41]
	v_pk_fma_f32 v[26:27], v[30:31], v[26:27], v[38:39] neg_lo:[0,0,1] neg_hi:[0,0,1]
	v_lshlrev_b32_e32 v38, 16, v28
	v_and_b32_e32 v39, 0xffff0000, v28
	v_cvt_pk_bf16_f32 v10, v26, v27
	v_cvt_pk_bf16_f32 v6, v40, v41
	v_lshlrev_b32_e32 v26, 16, v24
	v_and_b32_e32 v27, 0xffff0000, v24
	v_pk_mul_f32 v[40:41], v[30:31], v[38:39]
	v_lshlrev_b32_e32 v28, 16, v29
	v_pk_fma_f32 v[40:41], v[34:35], v[26:27], v[40:41]
	v_pk_mul_f32 v[34:35], v[34:35], v[38:39]
	v_and_b32_e32 v29, 0xffff0000, v29
	v_pk_fma_f32 v[26:27], v[30:31], v[26:27], v[34:35] neg_lo:[0,0,1] neg_hi:[0,0,1]
	v_lshlrev_b32_e32 v34, 16, v11
	v_and_b32_e32 v35, 0xffff0000, v11
	v_lshlrev_b32_e32 v30, 16, v7
	v_and_b32_e32 v31, 0xffff0000, v7
	v_pk_mul_f32 v[38:39], v[32:33], v[34:35]
	v_pk_mul_f32 v[34:35], v[36:37], v[34:35]
	v_pk_fma_f32 v[38:39], v[36:37], v[30:31], v[38:39]
	v_pk_fma_f32 v[30:31], v[32:33], v[30:31], v[34:35] neg_lo:[0,0,1] neg_hi:[0,0,1]
	v_lshlrev_b32_e32 v24, 16, v25
	v_cvt_pk_bf16_f32 v11, v30, v31
	v_and_b32_e32 v25, 0xffff0000, v25
	v_pk_mul_f32 v[30:31], v[32:33], v[28:29]
	v_pk_mul_f32 v[28:29], v[36:37], v[28:29]
	v_pk_fma_f32 v[30:31], v[36:37], v[24:25], v[30:31]
	v_pk_fma_f32 v[24:25], v[32:33], v[24:25], v[28:29] neg_lo:[0,0,1] neg_hi:[0,0,1]
	v_lshl_add_u64 v[28:29], v[12:13], 0, v[2:3]
	v_add_co_u32_e64 v32, s[38:39], s73, v28
	v_pk_mul_f32 v[40:41], v[40:41], s[16:17] op_sel_hi:[1,0]
	v_pk_mul_f32 v[26:27], v[26:27], s[16:17] op_sel_hi:[1,0]
	v_pk_mul_f32 v[30:31], v[30:31], s[16:17] op_sel_hi:[1,0]
	v_pk_mul_f32 v[24:25], v[24:25], s[16:17] op_sel_hi:[1,0]
	v_addc_co_u32_e64 v33, s[38:39], 0, v29, s[38:39]
	v_cvt_pk_bf16_f32 v7, v38, v39
	v_cvt_pk_bf16_f32 v54, v26, v27
	v_cvt_pk_bf16_f32 v55, v24, v25
	v_cvt_pk_bf16_f32 v58, v40, v41
	v_cvt_pk_bf16_f32 v59, v30, v31
	global_load_dwordx4 v[20:23], v[28:29], off
	global_load_dwordx4 v[12:15], v[28:29], off offset:64
	global_load_dwordx4 v[24:27], v[28:29], off offset:2048
	global_load_dwordx4 v[16:19], v[28:29], off offset:2112
	global_load_dwordx4 v[36:39], v[32:33], off
	s_nop 0
	global_load_dwordx4 v[28:31], v[32:33], off offset:64
	global_load_dwordx4 v[40:43], v[32:33], off offset:2048
	s_nop 0
	global_load_dwordx4 v[32:35], v[32:33], off offset:2112
	v_lshlrev_b32_e32 v2, 2, v133
	v_bitop3_b32 v138, v0, 64, v2 bitop3:0x36
	v_bitop3_b32 v137, v0, s96, v2 bitop3:0x36
	v_sub_u32_e32 v0, v133, v124
	v_cvt_f32_i32_e32 v0, v0
	s_waitcnt lgkmcnt(0)
	s_ashr_i32 s21, s20, 31
	v_mul_f32_e32 v0, v135, v0
	v_mul_f32_e32 v0, 0x3fb8aa3b, v0
	v_exp_f32_e32 v139, v0
	s_lshl_b64 s[20:21], s[20:21], 3
	s_add_u32 s20, s0, s20
	s_addc_u32 s21, s1, s21
	v_mul_f32_e32 v0, v139, v100
	v_cndmask_b32_e64 v2, v0, 0, vcc
	v_add_u32_e32 v0, v133, v143
	v_cvt_f32_i32_e32 v0, v0
	s_load_dwordx2 s[20:21], s[20:21], 0x0
	s_lshl_b64 s[38:39], s[36:37], 2
	s_waitcnt vmcnt(7)
; __device__ __forceinline__ float bperm_f(int src_lane, float v) { return __builtin_bit_cast(float, __builtin_amdgcn_ds_bpermute(src_lane << 2, __builtin_bit_cast(int, v))); }
; __device__ __forceinline__ bf16x8 pack_frag(const float (&v)[8]) { return __builtin_bit_cast(bf16x8, pack8(v)); }
; template <int KIND>
; __device__ __forceinline__ void w_m3_core(const bf16x8 (&Qf)[4][2], const bf16x8 (&Kf)[4][2], const bf16x8 (&Sf)[4][2], const LAS bf16_t* vT, float lg,
;                                           const bf16_t* gsrc, const float* nw, bf16_t* ydst, int lo, int fq) {
;     ...
;                 if (mb <= nb) { f32x4 s = {0.f, 0.f, 0.f, 0.f};
;                     s = __builtin_amdgcn_mfma_f32_16x16x32_bf16(Kf[mb][0], Qf[nb][0], s, 0, 0, 0); s = __builtin_amdgcn_mfma_f32_16x16x32_bf16(Kf[mb][1], Qf[nb][1], s, 0, 0, 0);
; #pragma unroll
;                     for (int r = 0; r < 4; ++r) { const int m = 16 * mb + 4 * fq + r, n = 16 * nb + lo; float v = s[r];
;                         if (KIND == 0) v *= __expf((float)(n - m) * lg);
;                         if (mb == nb) v = (m <= n) ? v : 0.f;
;                         pv[4 * hh + r] = v; }
;                 } else {
; #pragma unroll
;                     for (int r = 0; r < 4; ++r) pv[4 * hh + r] = 0.f; }
;             }
;             const bf16x8 Pf = pack_frag(pv);
; #pragma unroll
;             for (int eb = 0; eb < 4; ++eb)
;                 O[eb] = __builtin_amdgcn_mfma_f32_16x16x32_bf16(tr_frag(vT, 32 * kk2 + 4 * fq, 32 * kk2 + 16 + 4 * fq, 16 * eb, lo), Pf, O[eb], 0, 0, 0);
;         }
; #pragma unroll
;         for (int kk = 0; kk < 2; ++kk)
; #pragma unroll
;             for (int eb = 0; eb < 4; ++eb) O2[eb] = __builtin_amdgcn_mfma_f32_16x16x32_bf16(Sf[eb][kk], Qf[nb][kk], O2[eb], 0, 0, 0);
;         const float osc = KIND == 0 ? __expf((float)(16 * nb + lo + 1) * lg) : 1.0f;
; #pragma unroll
;         for (int eb = 0; eb < 4; ++eb) O[eb] = O[eb] + O2[eb] * osc;
;         float ss = 0.f;
; #pragma unroll
;         for (int eb = 0; eb < 4; ++eb) ss += (O[eb][0] * O[eb][0] + O[eb][1] * O[eb][1]) + (O[eb][2] * O[eb][2] + O[eb][3] * O[eb][3]);
;         { const int ln = (fq << 4) | lo; ss += bperm_f(ln ^ 16, ss); ss += bperm_f(ln ^ 32, ss); }
;         const float rs = rsqrtf(ss * (1.0f / 64.0f) + EPS);
	v_mfma_f32_16x16x32_bf16 v[116:119], v[20:23], v[96:99], 0
	v_mul_f32_e32 v0, v135, v0
	v_mul_f32_e32 v0, 0x3fb8aa3b, v0
	v_exp_f32_e32 v0, v0
	s_waitcnt lgkmcnt(0)
	s_add_u32 s27, s20, s38
	s_addc_u32 s38, s21, s39
	s_lshl_b64 s[20:21], s[24:25], 2
	s_add_u32 s44, s27, s20
	s_addc_u32 s45, s38, s21
	v_lshl_add_u64 v[182:183], v[124:125], 2, s[44:45]
	global_load_dwordx4 v[184:187], v[182:183], off
	global_load_dwordx4 v[188:191], v[182:183], off offset:64
	global_load_dwordx4 v[192:195], v[182:183], off offset:128
	global_load_dwordx4 v[196:199], v[182:183], off offset:192
	v_mul_f32_e32 v0, v0, v101
	v_cmp_gt_i32_e64 s[38:39], v133, v124
	s_lshl_b64 s[20:21], s[34:35], 11
	s_add_u32 s20, s10, s20
	v_cndmask_b32_e64 v107, 0, v0, s[38:39]
	v_sub_u32_e32 v0, v133, v142
	v_cvt_f32_i32_e32 v0, v0
	s_addc_u32 s21, s11, s21
	s_add_u32 s40, s20, s40
	s_addc_u32 s41, s21, 0
	v_mul_f32_e32 v0, v135, v0
	v_mul_f32_e32 v0, 0x3fb8aa3b, v0
	v_exp_f32_e32 v0, v0
	v_mad_u64_u32 v[126:127], s[20:21], v106, s23, v[104:105]
	v_mad_u64_u32 v[128:129], s[20:21], v105, s23, v[104:105]
	v_pk_mul_f32 v[100:101], v[0:1], v[102:103]
	v_cmp_ge_i32_e64 s[38:39], v133, v142
	v_cvt_pk_bf16_f32 v1, v100, v101
	ds_read_b64_tr_b16 v[102:103], v126
	ds_read_b64_tr_b16 v[110:111], v126 offset:32
	ds_read_b64_tr_b16 v[100:101], v128
	ds_read_b64_tr_b16 v[108:109], v128 offset:32
	v_cvt_pk_bf16_f32 v0, v2, v107
	v_cndmask_b32_e64 v2, 0, v1, s[38:39]
	v_lshrrev_b32_e32 v1, 16, v1
	v_cmp_ge_i32_e64 s[38:39], v133, v141
	s_waitcnt vmcnt(9)
	v_mfma_f32_16x16x32_bf16 v[146:149], v[24:27], v[96:99], 0
	v_cndmask_b32_e64 v1, 0, v1, s[38:39]
	v_perm_b32 v1, v1, v2, s53
	v_mov_b32_e32 v2, v3
	s_waitcnt vmcnt(7)
	v_mfma_f32_16x16x32_bf16 v[150:153], v[36:39], v[96:99], 0
	s_waitcnt lgkmcnt(1)
	v_mfma_f32_16x16x32_bf16 v[104:107], v[100:103], v[0:3], 0
	s_waitcnt lgkmcnt(0)
	v_mfma_f32_16x16x32_bf16 v[100:103], v[108:111], v[0:3], 0
	ds_read_b64_tr_b16 v[108:109], v128 offset:64
	ds_read_b64_tr_b16 v[110:111], v126 offset:64
	ds_read_b64_tr_b16 v[112:113], v128 offset:96
	ds_read_b64_tr_b16 v[114:115], v126 offset:96
	s_waitcnt lgkmcnt(2)
	v_mfma_f32_16x16x32_bf16 v[108:111], v[108:111], v[0:3], 0
	s_waitcnt lgkmcnt(0)
	v_mfma_f32_16x16x32_bf16 v[112:115], v[112:115], v[0:3], 0
	v_add_u32_e32 v0, 1, v133
	v_cvt_f32_ubyte0_e32 v0, v0
	v_mul_f32_e32 v0, v135, v0
	s_waitcnt vmcnt(5)
	v_mfma_f32_16x16x32_bf16 v[154:157], v[40:43], v[96:99], 0
	v_mul_f32_e32 v0, 0x3fb8aa3b, v0
	v_exp_f32_e32 v2, v0
	v_mfma_f32_16x16x32_bf16 v[120:123], v[12:15], v[92:95], v[116:119]
	v_mfma_f32_16x16x32_bf16 v[116:119], v[16:19], v[92:95], v[146:149]
	v_mfma_f32_16x16x32_bf16 v[96:99], v[28:31], v[92:95], v[150:153]
	s_nop 5
	v_fma_f32 v122, v2, v122, v106
	v_fma_f32 v123, v2, v123, v107
	v_pk_fma_f32 v[120:121], v[2:3], v[120:121], v[104:105] op_sel_hi:[0,1,1]
	v_pk_fma_f32 v[118:119], v[2:3], v[118:119], v[102:103] op_sel_hi:[0,1,1]
	s_waitcnt vmcnt(4)
	v_mfma_f32_16x16x32_bf16 v[92:95], v[32:35], v[92:95], v[154:157]
	v_fma_f32 v116, v2, v116, v100
	v_fma_f32 v117, v2, v117, v101
	v_pk_fma_f32 v[108:109], v[2:3], v[96:97], v[108:109] op_sel_hi:[0,1,1]
	v_pk_fma_f32 v[106:107], v[2:3], v[98:99], v[110:111] op_sel_hi:[0,1,1]
	v_lshl_add_u64 v[100:101], v[124:125], 2, s[44:45]
	s_nop 2
	v_pk_fma_f32 v[0:1], v[2:3], v[94:95], v[114:115] op_sel_hi:[0,1,1]
	v_pk_fma_f32 v[104:105], v[2:3], v[92:93], v[112:113] op_sel_hi:[0,1,1]
	v_pk_mul_f32 v[92:93], v[122:123], v[122:123]
	v_pk_mul_f32 v[94:95], v[120:121], v[120:121]
	v_mul_f32_e32 v2, v104, v104
	v_pk_mov_b32 v[96:97], v[94:95], v[92:93] op_sel:[1,0]
	v_mov_b32_e32 v95, v93
	v_pk_add_f32 v[92:93], v[96:97], v[94:95]
	v_pk_mul_f32 v[94:95], v[118:119], v[118:119]
	v_pk_mul_f32 v[96:97], v[116:117], v[116:117]
	v_pk_add_f32 v[92:93], v[92:93], v[92:93] op_sel:[0,1] op_sel_hi:[1,0]
	v_pk_mov_b32 v[98:99], v[96:97], v[94:95] op_sel:[1,0]
	v_mov_b32_e32 v97, v95
	v_pk_add_f32 v[94:95], v[98:99], v[96:97]
	v_mul_f32_e32 v96, v105, v105
	v_pk_add_f32 v[94:95], v[94:95], v[94:95] op_sel:[0,1] op_sel_hi:[1,0]
	v_mov_b32_e32 v93, v2
	v_mov_b32_e32 v95, v96
	v_mul_f32_e32 v2, v109, v109
	v_mul_f32_e32 v97, v0, v0
	v_pk_add_f32 v[92:93], v[92:93], v[94:95]
	v_pk_fma_f32 v[94:95], v[108:109], v[108:109], v[2:3] op_sel_hi:[1,1,0]
	v_mul_f32_e32 v2, v107, v107
	v_mul_f32_e32 v98, v1, v1
	v_mov_b32_e32 v95, v97
	v_pk_fma_f32 v[96:97], v[106:107], v[106:107], v[2:3] op_sel_hi:[1,1,0]
	s_nop 0
	v_mov_b32_e32 v97, v98
	v_pk_add_f32 v[94:95], v[94:95], v[96:97]
	v_mov_b64_e32 v[98:99], s[42:43]
	v_pk_add_f32 v[92:93], v[92:93], v[94:95]
	v_lshlrev_b64 v[96:97], 1, v[124:125]
	v_add_f32_e32 v2, v92, v93
	ds_bpermute_b32 v92, v138, v2
	s_waitcnt lgkmcnt(0)
	v_add_f32_e32 v2, v2, v92
	ds_bpermute_b32 v92, v137, v2
	s_waitcnt lgkmcnt(0)
	v_add_f32_e32 v2, v2, v92
	v_fmamk_f32 v2, v2, 0x3c800000, v200
	v_cmp_gt_f32_e64 s[38:39], s29, v2
	v_mul_f32_e32 v92, 0x4b800000, v2
	s_nop 0
	v_cndmask_b32_e64 v2, v2, v92, s[38:39]
	v_rsq_f32_e32 v2, v2
	s_nop 0
	v_mul_f32_e32 v92, 0x45800000, v2
	v_cndmask_b32_e64 v102, v2, v92, s[38:39]
	v_mad_u64_u32 v[92:93], s[20:21], v133, s72, v[98:99]
	v_lshl_add_u64 v[110:111], v[92:93], 0, v[96:97]
	s_waitcnt vmcnt(0)
	v_mov_b64_e32 v[114:115], v[222:223]
	v_mov_b64_e32 v[92:93], v[184:185]
	v_mov_b64_e32 v[94:95], v[186:187]
	v_lshlrev_b32_e32 v2, 11, v133
	v_lshl_add_u64 v[112:113], s[40:41], 0, v[2:3]
	v_pk_mul_f32 v[120:121], v[120:121], v[102:103] op_sel_hi:[1,0]
	v_pk_mul_f32 v[122:123], v[122:123], v[102:103] op_sel_hi:[1,0]
	v_lshl_add_u64 v[112:113], v[112:113], 0, v[96:97]
	v_pk_mul_f32 v[116:117], v[116:117], v[102:103] op_sel_hi:[1,0]
	v_pk_mul_f32 v[118:119], v[118:119], v[102:103] op_sel_hi:[1,0]
	v_pk_mul_f32 v[108:109], v[108:109], v[102:103] op_sel_hi:[1,0]
	s_waitcnt lgkmcnt(0)
; __device__ __forceinline__ unsigned pk2(float lo, float hi) { const f32x2_t v = {lo, hi}; const bf16x2_t b = __builtin_convertvector(v, bf16x2_t); return __builtin_bit_cast(unsigned, b); }
; __device__ __forceinline__ float sigmoidf_(float x) { return __builtin_amdgcn_rcpf(1.0f + __expf(-x)); }
; template <int KIND>
; __device__ __forceinline__ void w_m3_core(const bf16x8 (&Qf)[4][2], const bf16x8 (&Kf)[4][2], const bf16x8 (&Sf)[4][2], const LAS bf16_t* vT, float lg,
;                                           const bf16_t* gsrc, const float* nw, bf16_t* ydst, int lo, int fq) {
;     ...
;         const size_t n = 16 * nb + lo;
; #pragma unroll
;         for (int eb = 0; eb < 4; ++eb) { const int e0 = 16 * eb + 4 * fq;
;             const unsigned long long gw_ = *(const unsigned long long*)(gsrc + n * NIN + e0); const f32x4 w4 = *(const f32x4*)(nw + e0);
;             const float g0 = __uint_as_float((unsigned)gw_ << 16), g1 = __uint_as_float((unsigned)gw_ & 0xffff0000u), g2 = __uint_as_float((unsigned)(gw_ >> 32) << 16), g3 = __uint_as_float((unsigned)(gw_ >> 32) & 0xffff0000u);
;             const float o0 = O[eb][0] * rs * w4[0] * (g0 * sigmoidf_(g0)), o1 = O[eb][1] * rs * w4[1] * (g1 * sigmoidf_(g1));
;             const float o2 = O[eb][2] * rs * w4[2] * (g2 * sigmoidf_(g2)), o3 = O[eb][3] * rs * w4[3] * (g3 * sigmoidf_(g3));
;             *(unsigned long long*)(ydst + n * DM + e0) = (unsigned long long)pk2(o0, o1) | ((unsigned long long)pk2(o2, o3) << 32); }
	v_lshlrev_b32_e32 v130, 16, v114
	v_mul_f32_e32 v2, 0xbfb8aa3b, v130
	v_exp_f32_e32 v2, v2
	v_and_b32_e32 v131, 0xffff0000, v114
	v_lshlrev_b32_e32 v114, 16, v115
	v_and_b32_e32 v115, 0xffff0000, v115
	v_add_f32_e32 v2, 1.0, v2
	v_rcp_f32_e32 v146, v2
	v_mul_f32_e32 v2, 0xbfb8aa3b, v131
	v_exp_f32_e32 v2, v2
	v_pk_mul_f32 v[92:93], v[92:93], v[120:121]
	v_pk_mul_f32 v[94:95], v[94:95], v[122:123]
	v_add_f32_e32 v2, 1.0, v2
	v_rcp_f32_e32 v147, v2
	v_mul_f32_e32 v2, 0xbfb8aa3b, v114
	v_exp_f32_e32 v2, v2
	v_pk_mul_f32 v[120:121], v[146:147], v[130:131]
	s_nop 0
	v_pk_mul_f32 v[92:93], v[120:121], v[92:93]
	v_add_f32_e32 v2, 1.0, v2
	v_rcp_f32_e32 v120, v2
	v_mul_f32_e32 v2, 0xbfb8aa3b, v115
	v_exp_f32_e32 v2, v2
	v_cvt_pk_bf16_f32 v92, v92, v93
	v_add_f32_e32 v2, 1.0, v2
	v_rcp_f32_e32 v121, v2
	s_nop 0
	v_pk_mul_f32 v[114:115], v[120:121], v[114:115]
	s_nop 0
	v_pk_mul_f32 v[94:95], v[114:115], v[94:95]
	s_nop 0
	v_cvt_pk_bf16_f32 v93, v94, v95
	global_store_dwordx2 v[112:113], v[92:93], off offset:1024
	v_mov_b64_e32 v[114:115], v[224:225]
	s_nop 0
	v_mov_b64_e32 v[92:93], v[188:189]
	v_mov_b64_e32 v[94:95], v[190:191]
	s_waitcnt lgkmcnt(0)
	v_lshlrev_b32_e32 v120, 16, v114
	v_mul_f32_e32 v2, 0xbfb8aa3b, v120
	v_exp_f32_e32 v2, v2
	v_and_b32_e32 v121, 0xffff0000, v114
	v_lshlrev_b32_e32 v114, 16, v115
	v_and_b32_e32 v115, 0xffff0000, v115
	v_add_f32_e32 v2, 1.0, v2
	v_rcp_f32_e32 v122, v2
	v_mul_f32_e32 v2, 0xbfb8aa3b, v121
	v_exp_f32_e32 v2, v2
	v_pk_mul_f32 v[92:93], v[92:93], v[116:117]
	v_pk_mul_f32 v[94:95], v[94:95], v[118:119]
	v_add_f32_e32 v2, 1.0, v2
	v_rcp_f32_e32 v123, v2
	v_mul_f32_e32 v2, 0xbfb8aa3b, v114
	v_exp_f32_e32 v2, v2
	v_pk_mul_f32 v[116:117], v[122:123], v[120:121]
	s_nop 0
	v_pk_mul_f32 v[92:93], v[116:117], v[92:93]
	v_add_f32_e32 v2, 1.0, v2
	v_rcp_f32_e32 v116, v2
	v_mul_f32_e32 v2, 0xbfb8aa3b, v115
	v_exp_f32_e32 v2, v2
	v_cvt_pk_bf16_f32 v92, v92, v93
	v_add_f32_e32 v2, 1.0, v2
	v_rcp_f32_e32 v117, v2
	s_nop 0
	v_pk_mul_f32 v[114:115], v[116:117], v[114:115]
	s_nop 0
	v_pk_mul_f32 v[94:95], v[114:115], v[94:95]
	v_mul_f32_e32 v116, v106, v102
	v_cvt_pk_bf16_f32 v93, v94, v95
	global_store_dwordx2 v[112:113], v[92:93], off offset:1056
	v_mov_b64_e32 v[114:115], v[226:227]
	s_nop 0
	v_mov_b64_e32 v[92:93], v[192:193]
	v_mov_b64_e32 v[94:95], v[194:195]
	s_waitcnt lgkmcnt(0)
	v_lshlrev_b32_e32 v118, 16, v114
	v_mul_f32_e32 v2, 0xbfb8aa3b, v118
	v_exp_f32_e32 v2, v2
	v_and_b32_e32 v119, 0xffff0000, v114
	v_lshlrev_b32_e32 v117, 16, v115
	v_and_b32_e32 v115, 0xffff0000, v115
	v_add_f32_e32 v2, 1.0, v2
	v_rcp_f32_e32 v120, v2
	v_mul_f32_e32 v2, 0xbfb8aa3b, v119
	v_exp_f32_e32 v2, v2
	v_pk_mul_f32 v[92:93], v[92:93], v[108:109]
	v_mul_f32_e32 v114, v107, v102
	v_mov_b32_e32 v106, v95
	v_add_f32_e32 v2, 1.0, v2
	v_rcp_f32_e32 v121, v2
	v_mul_f32_e32 v2, 0xbfb8aa3b, v117
	v_exp_f32_e32 v2, v2
	v_pk_mul_f32 v[108:109], v[120:121], v[118:119]
	s_nop 0
	v_pk_mul_f32 v[92:93], v[108:109], v[92:93]
	v_add_f32_e32 v2, 1.0, v2
	v_rcp_f32_e32 v109, v2
	v_mul_f32_e32 v2, 0xbfb8aa3b, v115
	v_exp_f32_e32 v2, v2
	v_mov_b32_e32 v108, v94
	v_pk_mul_f32 v[108:109], v[108:109], v[116:117]
	v_cvt_pk_bf16_f32 v92, v92, v93
	v_add_f32_e32 v2, 1.0, v2
	v_rcp_f32_e32 v107, v2
	s_nop 0
	v_pk_mul_f32 v[94:95], v[106:107], v[114:115]
	v_mov_b32_e32 v106, v108
	v_mov_b32_e32 v107, v94
	v_mov_b32_e32 v94, v109
	v_pk_mul_f32 v[94:95], v[106:107], v[94:95]
	v_mul_f32_e32 v106, v0, v102
	v_cvt_pk_bf16_f32 v93, v94, v95
	global_store_dwordx2 v[112:113], v[92:93], off offset:1088
	v_mov_b64_e32 v[114:115], v[228:229]
	s_nop 0
	v_mov_b64_e32 v[92:93], v[196:197]
	v_mov_b64_e32 v[94:95], v[198:199]
	v_mul_f32_e32 v108, v105, v102
	v_mul_f32_e32 v110, v104, v102
	v_mul_f32_e32 v102, v1, v102
	s_waitcnt lgkmcnt(0)
	v_lshlrev_b32_e32 v111, 16, v114
	v_mul_f32_e32 v2, 0xbfb8aa3b, v111
	v_exp_f32_e32 v2, v2
	v_and_b32_e32 v109, 0xffff0000, v114
	v_lshlrev_b32_e32 v107, 16, v115
	v_and_b32_e32 v103, 0xffff0000, v115
	v_add_f32_e32 v2, 1.0, v2
	v_rcp_f32_e32 v115, v2
	v_mul_f32_e32 v2, 0xbfb8aa3b, v109
	v_exp_f32_e32 v2, v2
	v_mul_f32_e32 v0, 0xbfb8aa3b, v107
	v_exp_f32_e32 v0, v0
	v_mov_b32_e32 v104, v93
	v_add_f32_e32 v2, 1.0, v2
	v_rcp_f32_e32 v105, v2
	v_add_f32_e32 v0, 1.0, v0
	v_mov_b32_e32 v114, v92
	v_pk_mul_f32 v[110:111], v[114:115], v[110:111]
	v_pk_mul_f32 v[92:93], v[104:105], v[108:109]
	v_rcp_f32_e32 v105, v0
	v_mul_f32_e32 v0, 0xbfb8aa3b, v103
	v_exp_f32_e32 v0, v0
	v_mov_b32_e32 v104, v94
	v_pk_mul_f32 v[104:105], v[104:105], v[106:107]
	v_mov_b32_e32 v94, v110
	v_add_f32_e32 v0, 1.0, v0
	v_rcp_f32_e32 v1, v0
	v_mov_b32_e32 v0, v95
	v_mov_b32_e32 v95, v92
	v_mov_b32_e32 v92, v111
	v_pk_mul_f32 v[0:1], v[0:1], v[102:103]
	v_pk_mul_f32 v[92:93], v[94:95], v[92:93]
	v_mov_b32_e32 v94, v104
	v_mov_b32_e32 v95, v0
	v_mov_b32_e32 v0, v105
	v_pk_mul_f32 v[0:1], v[94:95], v[0:1]
	v_cvt_pk_bf16_f32 v92, v92, v93
	v_cvt_pk_bf16_f32 v93, v0, v1
	global_store_dwordx2 v[112:113], v[92:93], off offset:1120
	v_sub_u32_e32 v0, v144, v124
	v_add_u32_e32 v1, v144, v143
	v_cvt_f32_i32_e32 v0, v0
	v_cvt_f32_i32_e32 v1, v1
	v_mfma_f32_16x16x32_bf16 v[92:95], v[64:67], v[88:91], 0
	v_sub_u32_e32 v2, v144, v142
	v_mul_f32_e32 v0, v135, v0
	v_mul_f32_e32 v1, v135, v1
	v_cvt_f32_i32_e32 v2, v2
	v_mul_f32_e32 v0, 0x3fb8aa3b, v0
	v_mul_f32_e32 v1, 0x3fb8aa3b, v1
	v_mfma_f32_16x16x32_bf16 v[92:95], v[72:75], v[84:87], v[92:95]
	v_exp_f32_e32 v0, v0
	v_exp_f32_e32 v1, v1
	v_mul_f32_e32 v2, v135, v2
	v_mul_f32_e32 v2, 0x3fb8aa3b, v2
	v_add_u32_e32 v115, 17, v124
	s_nop 2
	v_pk_mul_f32 v[0:1], v[0:1], v[92:93]
	v_exp_f32_e32 v92, v2
	v_sub_u32_e32 v2, v144, v141
; __device__ __forceinline__ float bperm_f(int src_lane, float v) { return __builtin_bit_cast(float, __builtin_amdgcn_ds_bpermute(src_lane << 2, __builtin_bit_cast(int, v))); }
; template <int KIND>
; __device__ __forceinline__ void w_m3_core(const bf16x8 (&Qf)[4][2], const bf16x8 (&Kf)[4][2], const bf16x8 (&Sf)[4][2], const LAS bf16_t* vT, float lg,
;                                           const bf16_t* gsrc, const float* nw, bf16_t* ydst, int lo, int fq) {
;     ...
;         for (int kk2 = 0; kk2 < 2; ++kk2) {
;             if (2 * kk2 > nb) continue;
;             float pv[8];
; #pragma unroll
;             for (int hh = 0; hh < 2; ++hh) { const int mb = 2 * kk2 + hh;
;                 if (mb <= nb) { f32x4 s = {0.f, 0.f, 0.f, 0.f};
;                     s = __builtin_amdgcn_mfma_f32_16x16x32_bf16(Kf[mb][0], Qf[nb][0], s, 0, 0, 0); s = __builtin_amdgcn_mfma_f32_16x16x32_bf16(Kf[mb][1], Qf[nb][1], s, 0, 0, 0);
; #pragma unroll
;                     for (int r = 0; r < 4; ++r) { const int m = 16 * mb + 4 * fq + r, n = 16 * nb + lo; float v = s[r];
;                         if (KIND == 0) v *= __expf((float)(n - m) * lg);
;                         if (mb == nb) v = (m <= n) ? v : 0.f;
;                         pv[4 * hh + r] = v; }
;                 } else {
; #pragma unroll
;                     for (int r = 0; r < 4; ++r) pv[4 * hh + r] = 0.f; }
;             }
;             const bf16x8 Pf = pack_frag(pv);
; #pragma unroll
;             for (int eb = 0; eb < 4; ++eb)
;                 O[eb] = __builtin_amdgcn_mfma_f32_16x16x32_bf16(tr_frag(vT, 32 * kk2 + 4 * fq, 32 * kk2 + 16 + 4 * fq, 16 * eb, lo), Pf, O[eb], 0, 0, 0);
;         }
; #pragma unroll
;         for (int kk = 0; kk < 2; ++kk)
; #pragma unroll
;             for (int eb = 0; eb < 4; ++eb) O2[eb] = __builtin_amdgcn_mfma_f32_16x16x32_bf16(Sf[eb][kk], Qf[nb][kk], O2[eb], 0, 0, 0);
;         const float osc = KIND == 0 ? __expf((float)(16 * nb + lo + 1) * lg) : 1.0f;
; #pragma unroll
;         for (int eb = 0; eb < 4; ++eb) O[eb] = O[eb] + O2[eb] * osc;
;         float ss = 0.f;
; #pragma unroll
;         for (int eb = 0; eb < 4; ++eb) ss += (O[eb][0] * O[eb][0] + O[eb][1] * O[eb][1]) + (O[eb][2] * O[eb][2] + O[eb][3] * O[eb][3]);
;         { const int ln = (fq << 4) | lo; ss += bperm_f(ln ^ 16, ss); ss += bperm_f(ln ^ 32, ss); }
;         const float rs = rsqrtf(ss * (1.0f / 64.0f) + EPS);
	v_cvt_f32_i32_e32 v2, v2
	v_cmp_ge_i32_e64 s[38:39], v144, v115
	v_add_u32_e32 v114, 19, v124
	v_add_u32_e32 v116, 18, v124
	v_mul_f32_e32 v2, v135, v2
	v_mul_f32_e32 v2, 0x3fb8aa3b, v2
	v_exp_f32_e32 v93, v2
	v_mfma_f32_16x16x32_bf16 v[110:113], v[36:39], v[88:91], 0
	v_mul_f32_e64 v102, v92, v94
	v_mul_f32_e64 v103, v93, v95
	v_mfma_f32_16x16x32_bf16 v[92:95], v[60:63], v[88:91], 0
	v_mfma_f32_16x16x32_bf16 v[92:95], v[68:71], v[84:87], v[92:95]
	v_mfma_f32_16x16x32_bf16 v[158:161], v[28:31], v[84:87], v[110:113]
	s_nop 6
	v_mul_f32_e32 v2, v139, v92
	v_sub_u32_e32 v92, v144, v115
	v_cvt_f32_i32_e32 v92, v92
	v_cndmask_b32_e64 v2, v2, 0, vcc
	v_mul_f32_e32 v92, v135, v92
	v_mul_f32_e32 v92, 0x3fb8aa3b, v92
	v_exp_f32_e32 v92, v92
	s_nop 0
	v_mul_f32_e32 v92, v92, v93
	v_cndmask_b32_e64 v106, 0, v92, s[38:39]
	v_sub_u32_e32 v92, v144, v116
	v_sub_u32_e32 v93, v144, v114
	v_cvt_f32_i32_e32 v92, v92
	v_cvt_f32_i32_e32 v93, v93
	v_cmp_ge_i32_e64 s[38:39], v144, v116
	v_mul_f32_e32 v92, v135, v92
	v_mul_f32_e32 v93, v135, v93
	v_mul_f32_e32 v92, 0x3fb8aa3b, v92
	v_mul_f32_e32 v93, 0x3fb8aa3b, v93
	v_exp_f32_e32 v92, v92
	v_exp_f32_e32 v93, v93
	s_nop 0
	v_pk_mul_f32 v[104:105], v[92:93], v[94:95]
	v_cvt_pk_bf16_f32 v92, v0, v1
	v_cvt_pk_bf16_f32 v93, v102, v103
	v_cvt_pk_bf16_f32 v94, v2, v106
	v_cvt_pk_bf16_f32 v0, v104, v105
	ds_read_b64_tr_b16 v[104:105], v126
	ds_read_b64_tr_b16 v[108:109], v126 offset:32
	ds_read_b64_tr_b16 v[102:103], v128
	ds_read_b64_tr_b16 v[106:107], v128 offset:32
	v_cndmask_b32_e64 v1, 0, v0, s[38:39]
	v_lshrrev_b32_e32 v0, 16, v0
	v_cmp_ge_i32_e64 s[38:39], v144, v114
	s_nop 1
	v_cndmask_b32_e64 v0, 0, v0, s[38:39]
	v_perm_b32 v95, v0, v1, s53
	v_add_u32_e32 v0, 17, v133
	v_cvt_f32_ubyte0_e32 v0, v0
	s_waitcnt lgkmcnt(0)
	v_mfma_f32_16x16x32_bf16 v[118:121], v[106:109], v[92:95], 0
	ds_read_b64_tr_b16 v[106:107], v128 offset:64
	ds_read_b64_tr_b16 v[108:109], v126 offset:64
	v_mul_f32_e32 v0, v135, v0
	v_mul_f32_e32 v0, 0x3fb8aa3b, v0
	s_waitcnt lgkmcnt(0)
	v_mfma_f32_16x16x32_bf16 v[146:149], v[106:109], v[92:95], 0
	ds_read_b64_tr_b16 v[106:107], v128 offset:96
	ds_read_b64_tr_b16 v[108:109], v126 offset:96
	v_exp_f32_e32 v2, v0
	v_mfma_f32_16x16x32_bf16 v[102:105], v[102:105], v[92:95], 0
	s_waitcnt lgkmcnt(0)
	v_mfma_f32_16x16x32_bf16 v[150:153], v[106:109], v[92:95], 0
	v_mfma_f32_16x16x32_bf16 v[92:95], v[20:23], v[88:91], 0
	v_mfma_f32_16x16x32_bf16 v[106:109], v[24:27], v[88:91], 0
	v_mfma_f32_16x16x32_bf16 v[88:91], v[40:43], v[88:91], 0
	v_mfma_f32_16x16x32_bf16 v[92:95], v[12:15], v[84:87], v[92:95]
	v_mfma_f32_16x16x32_bf16 v[154:157], v[16:19], v[84:87], v[106:109]
	v_mfma_f32_16x16x32_bf16 v[84:87], v[32:35], v[84:87], v[88:91]
	s_nop 5
	v_fma_f32 v108, v2, v94, v104
	v_fma_f32 v109, v2, v95, v105
	v_pk_fma_f32 v[110:111], v[2:3], v[92:93], v[102:103] op_sel_hi:[0,1,1]
	v_pk_fma_f32 v[102:103], v[2:3], v[156:157], v[120:121] op_sel_hi:[0,1,1]
	v_pk_fma_f32 v[106:107], v[2:3], v[154:155], v[118:119] op_sel_hi:[0,1,1]
	v_pk_fma_f32 v[92:93], v[2:3], v[160:161], v[148:149] op_sel_hi:[0,1,1]
	v_pk_fma_f32 v[0:1], v[2:3], v[86:87], v[152:153] op_sel_hi:[0,1,1]
	v_pk_fma_f32 v[90:91], v[2:3], v[84:85], v[150:151] op_sel_hi:[0,1,1]
	v_pk_mul_f32 v[84:85], v[108:109], v[108:109]
	v_pk_mul_f32 v[86:87], v[110:111], v[110:111]
	v_pk_fma_f32 v[94:95], v[2:3], v[158:159], v[146:147] op_sel_hi:[0,1,1]
	v_pk_mov_b32 v[88:89], v[86:87], v[84:85] op_sel:[1,0]
	v_mov_b32_e32 v87, v85
	v_pk_add_f32 v[84:85], v[88:89], v[86:87]
	v_pk_mul_f32 v[86:87], v[102:103], v[102:103]
	v_pk_mul_f32 v[88:89], v[106:107], v[106:107]
	v_mul_f32_e32 v2, v90, v90
	v_pk_mov_b32 v[104:105], v[88:89], v[86:87] op_sel:[1,0]
	v_mov_b32_e32 v89, v87
	v_pk_add_f32 v[86:87], v[104:105], v[88:89]
	v_mul_f32_e32 v88, v91, v91
	v_pk_add_f32 v[84:85], v[84:85], v[84:85] op_sel:[0,1] op_sel_hi:[1,0]
	v_pk_add_f32 v[86:87], v[86:87], v[86:87] op_sel:[0,1] op_sel_hi:[1,0]
	v_mov_b32_e32 v85, v2
	v_mov_b32_e32 v87, v88
	v_mul_f32_e32 v2, v95, v95
	v_mul_f32_e32 v89, v0, v0
	v_pk_add_f32 v[84:85], v[84:85], v[86:87]
	v_pk_fma_f32 v[86:87], v[94:95], v[94:95], v[2:3] op_sel_hi:[1,1,0]
	v_mul_f32_e32 v2, v93, v93
	v_mul_f32_e32 v104, v1, v1
	v_mov_b32_e32 v87, v89
	v_pk_fma_f32 v[88:89], v[92:93], v[92:93], v[2:3] op_sel_hi:[1,1,0]
	s_nop 0
	v_mov_b32_e32 v89, v104
	v_pk_add_f32 v[86:87], v[86:87], v[88:89]
	s_nop 0
	v_pk_add_f32 v[84:85], v[84:85], v[86:87]
	s_nop 0
	v_add_f32_e32 v2, v84, v85
	ds_bpermute_b32 v84, v138, v2
	s_waitcnt lgkmcnt(0)
	v_add_f32_e32 v2, v2, v84
	ds_bpermute_b32 v84, v137, v2
	s_waitcnt lgkmcnt(0)
	v_add_f32_e32 v2, v2, v84
	v_fmamk_f32 v2, v2, 0x3c800000, v200
	v_cmp_gt_f32_e64 s[38:39], s29, v2
	v_mul_f32_e32 v84, 0x4b800000, v2
	s_nop 0
	v_cndmask_b32_e64 v2, v2, v84, s[38:39]
	v_rsq_f32_e32 v2, v2
	s_nop 0
	v_mul_f32_e32 v84, 0x45800000, v2
	v_cndmask_b32_e64 v88, v2, v84, s[38:39]
	v_mad_u64_u32 v[84:85], s[20:21], v144, s72, v[98:99]
	v_lshl_add_u64 v[104:105], v[84:85], 0, v[96:97]
	v_mov_b64_e32 v[118:119], v[230:231]
	v_mov_b64_e32 v[84:85], v[184:185]
	v_mov_b64_e32 v[86:87], v[186:187]
	v_lshlrev_b32_e32 v2, 11, v144
	v_lshl_add_u64 v[112:113], s[40:41], 0, v[2:3]
	v_pk_mul_f32 v[110:111], v[110:111], v[88:89] op_sel_hi:[1,0]
	v_pk_mul_f32 v[108:109], v[108:109], v[88:89] op_sel_hi:[1,0]
	v_pk_mul_f32 v[106:107], v[106:107], v[88:89] op_sel_hi:[1,0]
	v_pk_mul_f32 v[102:103], v[102:103], v[88:89] op_sel_hi:[1,0]
	v_pk_mul_f32 v[94:95], v[94:95], v[88:89] op_sel_hi:[1,0]
	s_waitcnt lgkmcnt(0)
; __device__ __forceinline__ unsigned pk2(float lo, float hi) { const f32x2_t v = {lo, hi}; const bf16x2_t b = __builtin_convertvector(v, bf16x2_t); return __builtin_bit_cast(unsigned, b); }
; __device__ __forceinline__ float sigmoidf_(float x) { return __builtin_amdgcn_rcpf(1.0f + __expf(-x)); }
; template <int KIND>
; __device__ __forceinline__ void w_m3_core(const bf16x8 (&Qf)[4][2], const bf16x8 (&Kf)[4][2], const bf16x8 (&Sf)[4][2], const LAS bf16_t* vT, float lg,
;                                           const bf16_t* gsrc, const float* nw, bf16_t* ydst, int lo, int fq) {
;     ...
;                     s = __builtin_amdgcn_mfma_f32_16x16x32_bf16(Kf[mb][0], Qf[nb][0], s, 0, 0, 0); s = __builtin_amdgcn_mfma_f32_16x16x32_bf16(Kf[mb][1], Qf[nb][1], s, 0, 0, 0);
; #pragma unroll
;                     for (int r = 0; r < 4; ++r) { const int m = 16 * mb + 4 * fq + r, n = 16 * nb + lo; float v = s[r];
;                         if (KIND == 0) v *= __expf((float)(n - m) * lg);
;                         if (mb == nb) v = (m <= n) ? v : 0.f;
;                         pv[4 * hh + r] = v; }
;     ...
;         const size_t n = 16 * nb + lo;
; #pragma unroll
;         for (int eb = 0; eb < 4; ++eb) { const int e0 = 16 * eb + 4 * fq;
;             const unsigned long long gw_ = *(const unsigned long long*)(gsrc + n * NIN + e0); const f32x4 w4 = *(const f32x4*)(nw + e0);
;             const float g0 = __uint_as_float((unsigned)gw_ << 16), g1 = __uint_as_float((unsigned)gw_ & 0xffff0000u), g2 = __uint_as_float((unsigned)(gw_ >> 32) << 16), g3 = __uint_as_float((unsigned)(gw_ >> 32) & 0xffff0000u);
;             const float o0 = O[eb][0] * rs * w4[0] * (g0 * sigmoidf_(g0)), o1 = O[eb][1] * rs * w4[1] * (g1 * sigmoidf_(g1));
;             const float o2 = O[eb][2] * rs * w4[2] * (g2 * sigmoidf_(g2)), o3 = O[eb][3] * rs * w4[3] * (g3 * sigmoidf_(g3));
;             *(unsigned long long*)(ydst + n * DM + e0) = (unsigned long long)pk2(o0, o1) | ((unsigned long long)pk2(o2, o3) << 32); }
	v_lshlrev_b32_e32 v120, 16, v118
	v_mul_f32_e32 v2, 0xbfb8aa3b, v120
	v_exp_f32_e32 v2, v2
	v_and_b32_e32 v121, 0xffff0000, v118
	v_lshlrev_b32_e32 v118, 16, v119
	v_and_b32_e32 v119, 0xffff0000, v119
	v_add_f32_e32 v2, 1.0, v2
	v_rcp_f32_e32 v122, v2
	v_mul_f32_e32 v2, 0xbfb8aa3b, v121
	v_exp_f32_e32 v2, v2
	v_pk_mul_f32 v[84:85], v[84:85], v[110:111]
	v_pk_mul_f32 v[86:87], v[86:87], v[108:109]
	v_add_f32_e32 v2, 1.0, v2
	v_rcp_f32_e32 v123, v2
	v_mul_f32_e32 v2, 0xbfb8aa3b, v118
	v_exp_f32_e32 v2, v2
	v_pk_mul_f32 v[110:111], v[122:123], v[120:121]
	s_nop 0
	v_pk_mul_f32 v[84:85], v[110:111], v[84:85]
	v_add_f32_e32 v2, 1.0, v2
	v_rcp_f32_e32 v110, v2
	v_mul_f32_e32 v2, 0xbfb8aa3b, v119
	v_exp_f32_e32 v2, v2
	s_nop 0
	v_add_f32_e32 v2, 1.0, v2
	v_rcp_f32_e32 v111, v2
	s_nop 0
	v_pk_mul_f32 v[108:109], v[110:111], v[118:119]
	s_nop 0
	v_pk_mul_f32 v[86:87], v[108:109], v[86:87]
	v_cvt_pk_bf16_f32 v108, v84, v85
	v_cvt_pk_bf16_f32 v109, v86, v87
	v_lshl_add_u64 v[84:85], v[112:113], 0, v[96:97]
	global_store_dwordx2 v[84:85], v[108:109], off offset:1024
	v_mov_b64_e32 v[86:87], v[232:233]
	s_nop 0
	v_mov_b64_e32 v[108:109], v[188:189]
	v_mov_b64_e32 v[110:111], v[190:191]
	s_waitcnt lgkmcnt(0)
	v_lshlrev_b32_e32 v112, 16, v86
	v_mul_f32_e32 v2, 0xbfb8aa3b, v112
	v_exp_f32_e32 v2, v2
	v_and_b32_e32 v113, 0xffff0000, v86
	v_lshlrev_b32_e32 v86, 16, v87
	v_and_b32_e32 v87, 0xffff0000, v87
	v_add_f32_e32 v2, 1.0, v2
	v_rcp_f32_e32 v118, v2
	v_mul_f32_e32 v2, 0xbfb8aa3b, v113
	v_exp_f32_e32 v2, v2
	v_pk_mul_f32 v[106:107], v[108:109], v[106:107]
	v_pk_mul_f32 v[102:103], v[110:111], v[102:103]
	v_mul_f32_e32 v110, v92, v88
	v_add_f32_e32 v2, 1.0, v2
	v_rcp_f32_e32 v119, v2
	v_mul_f32_e32 v2, 0xbfb8aa3b, v86
	v_exp_f32_e32 v2, v2
	v_pk_mul_f32 v[108:109], v[118:119], v[112:113]
	s_nop 0
	v_pk_mul_f32 v[106:107], v[108:109], v[106:107]
	v_add_f32_e32 v2, 1.0, v2
	v_rcp_f32_e32 v108, v2
	v_mul_f32_e32 v2, 0xbfb8aa3b, v87
	v_exp_f32_e32 v2, v2
	s_nop 0
	v_add_f32_e32 v2, 1.0, v2
	v_rcp_f32_e32 v109, v2
	s_nop 0
	v_pk_mul_f32 v[86:87], v[108:109], v[86:87]
	s_nop 0
	v_pk_mul_f32 v[86:87], v[86:87], v[102:103]
	v_cvt_pk_bf16_f32 v102, v106, v107
	v_cvt_pk_bf16_f32 v103, v86, v87
	global_store_dwordx2 v[84:85], v[102:103], off offset:1056
	v_mov_b64_e32 v[86:87], v[234:235]
	v_mov_b64_e32 v[106:107], v[192:193]
	v_mov_b64_e32 v[108:109], v[194:195]
	s_waitcnt lgkmcnt(0)
	v_lshlrev_b32_e32 v102, 16, v86
	v_mul_f32_e32 v2, 0xbfb8aa3b, v102
	v_exp_f32_e32 v2, v2
	v_and_b32_e32 v103, 0xffff0000, v86
	v_lshlrev_b32_e32 v111, 16, v87
	v_and_b32_e32 v87, 0xffff0000, v87
	v_add_f32_e32 v2, 1.0, v2
	v_rcp_f32_e32 v112, v2
	v_mul_f32_e32 v2, 0xbfb8aa3b, v103
	v_exp_f32_e32 v2, v2
	v_pk_mul_f32 v[94:95], v[106:107], v[94:95]
	v_mul_f32_e32 v86, v93, v88
	v_mov_b32_e32 v92, v109
	v_add_f32_e32 v2, 1.0, v2
	v_rcp_f32_e32 v113, v2
	v_mul_f32_e32 v2, 0xbfb8aa3b, v111
	v_exp_f32_e32 v2, v2
	v_mul_f32_e32 v106, v0, v88
	v_pk_mul_f32 v[102:103], v[112:113], v[102:103]
	v_add_f32_e32 v2, 1.0, v2
	v_pk_mul_f32 v[94:95], v[102:103], v[94:95]
	v_rcp_f32_e32 v103, v2
	v_mul_f32_e32 v2, 0xbfb8aa3b, v87
	v_exp_f32_e32 v2, v2
	v_mov_b32_e32 v102, v108
	v_pk_mul_f32 v[102:103], v[102:103], v[110:111]
	v_add_f32_e32 v2, 1.0, v2
	v_rcp_f32_e32 v93, v2
	s_nop 0
	v_pk_mul_f32 v[86:87], v[92:93], v[86:87]
	v_cvt_pk_bf16_f32 v92, v94, v95
	v_mov_b32_e32 v94, v102
	v_mov_b32_e32 v95, v86
	v_mov_b32_e32 v86, v103
	v_pk_mul_f32 v[86:87], v[94:95], v[86:87]
	v_mul_f32_e32 v102, v90, v88
	v_cvt_pk_bf16_f32 v93, v86, v87
	global_store_dwordx2 v[84:85], v[92:93], off offset:1088
	v_mov_b64_e32 v[86:87], v[236:237]
	s_nop 0
	v_mov_b64_e32 v[92:93], v[196:197]
	v_mov_b64_e32 v[94:95], v[198:199]
	v_mul_f32_e32 v104, v91, v88
	s_waitcnt lgkmcnt(0)
	v_lshlrev_b32_e32 v103, 16, v86
	v_lshlrev_b32_e32 v107, 16, v87
	v_mul_f32_e32 v2, 0xbfb8aa3b, v103
	v_mul_f32_e32 v0, 0xbfb8aa3b, v107
	v_exp_f32_e32 v2, v2
	v_exp_f32_e32 v0, v0
	v_and_b32_e32 v105, 0xffff0000, v86
	v_and_b32_e32 v87, 0xffff0000, v87
	v_add_f32_e32 v2, 1.0, v2
	v_add_f32_e32 v0, 1.0, v0
	v_rcp_f32_e32 v109, v2
	v_mul_f32_e32 v2, 0xbfb8aa3b, v105
	v_mov_b32_e32 v90, v93
	v_rcp_f32_e32 v93, v0
	v_mul_f32_e32 v0, 0xbfb8aa3b, v87
	v_exp_f32_e32 v2, v2
	v_exp_f32_e32 v0, v0
	v_mul_f32_e32 v86, v1, v88
	v_mov_b32_e32 v108, v92
	v_add_f32_e32 v2, 1.0, v2
	v_add_f32_e32 v0, 1.0, v0
	v_rcp_f32_e32 v91, v2
	v_rcp_f32_e32 v1, v0
	v_mov_b32_e32 v92, v94
	v_mov_b32_e32 v0, v95
	v_pk_mul_f32 v[102:103], v[108:109], v[102:103]
	v_pk_mul_f32 v[90:91], v[90:91], v[104:105]
	v_pk_mul_f32 v[92:93], v[92:93], v[106:107]
	v_pk_mul_f32 v[0:1], v[0:1], v[86:87]
	v_mov_b32_e32 v86, v102
	v_mov_b32_e32 v87, v90
	v_mov_b32_e32 v90, v103
	v_mov_b32_e32 v88, v92
	v_mov_b32_e32 v89, v0
	v_mov_b32_e32 v0, v93
	v_pk_mul_f32 v[86:87], v[86:87], v[90:91]
	v_pk_mul_f32 v[0:1], v[88:89], v[0:1]
	v_cvt_pk_bf16_f32 v86, v86, v87
	v_cvt_pk_bf16_f32 v87, v0, v1
	global_store_dwordx2 v[84:85], v[86:87], off offset:1120
	v_sub_u32_e32 v0, v136, v124
	v_add_u32_e32 v1, v136, v143
	v_cvt_f32_i32_e32 v0, v0
	v_cvt_f32_i32_e32 v1, v1
	v_mfma_f32_16x16x32_bf16 v[84:87], v[64:67], v[80:83], 0
	v_sub_u32_e32 v2, v136, v142
	v_mul_f32_e32 v0, v135, v0
	v_mul_f32_e32 v1, v135, v1
	v_cvt_f32_i32_e32 v2, v2
	v_mul_f32_e32 v0, 0x3fb8aa3b, v0
	v_mul_f32_e32 v1, 0x3fb8aa3b, v1
	v_mfma_f32_16x16x32_bf16 v[84:87], v[72:75], v[76:79], v[84:87]
	v_exp_f32_e32 v0, v0
	v_exp_f32_e32 v1, v1
	v_mul_f32_e32 v2, v135, v2
	v_mul_f32_e32 v2, 0x3fb8aa3b, v2
	s_nop 3
	v_pk_mul_f32 v[0:1], v[0:1], v[84:85]
	v_exp_f32_e32 v84, v2
	v_sub_u32_e32 v2, v136, v141
	v_cvt_f32_i32_e32 v2, v2
	v_mul_f32_e32 v2, v135, v2
	v_mul_f32_e32 v2, 0x3fb8aa3b, v2
	v_exp_f32_e32 v85, v2
	v_sub_u32_e32 v2, v136, v114
	v_cvt_f32_i32_e32 v2, v2
	v_pk_mul_f32 v[88:89], v[84:85], v[86:87]
	v_mfma_f32_16x16x32_bf16 v[84:87], v[60:63], v[80:83], 0
	v_mul_f32_e32 v2, v135, v2
	v_mul_f32_e32 v2, 0x3fb8aa3b, v2
	v_exp_f32_e32 v91, v2
	v_sub_u32_e32 v2, v136, v140
	v_cvt_f32_i32_e32 v2, v2
	v_mfma_f32_16x16x32_bf16 v[84:87], v[68:71], v[76:79], v[84:87]
	v_mul_f32_e32 v2, v135, v2
	v_mul_f32_e32 v2, 0x3fb8aa3b, v2
	v_exp_f32_e32 v92, v2
	v_sub_u32_e32 v2, v136, v115
	v_cvt_f32_i32_e32 v2, v2
	v_mul_f32_e32 v2, v135, v2
	v_mul_f32_e32 v2, 0x3fb8aa3b, v2
	v_exp_f32_e32 v93, v2
	v_sub_u32_e32 v2, v136, v116
	v_cvt_f32_i32_e32 v2, v2
	v_pk_mul_f32 v[92:93], v[92:93], v[84:85]
	v_cvt_pk_bf16_f32 v85, v88, v89
	v_mul_f32_e32 v2, v135, v2
	v_mul_f32_e32 v2, 0x3fb8aa3b, v2
	v_exp_f32_e32 v90, v2
	v_cvt_pk_bf16_f32 v84, v0, v1
	v_pk_mul_f32 v[90:91], v[90:91], v[86:87]
	v_cvt_pk_bf16_f32 v86, v92, v93
	v_cvt_pk_bf16_f32 v87, v90, v91
	ds_read_b64_tr_b16 v[90:91], v126
	ds_read_b64_tr_b16 v[94:95], v126 offset:32
	ds_read_b64_tr_b16 v[88:89], v128
	ds_read_b64_tr_b16 v[92:93], v128 offset:32
	ds_read_b64_tr_b16 v[102:103], v128 offset:64
	ds_read_b64_tr_b16 v[104:105], v126 offset:64
	ds_read_b64_tr_b16 v[106:107], v128 offset:96
	ds_read_b64_tr_b16 v[108:109], v126 offset:96
	s_waitcnt lgkmcnt(0)
; __device__ __forceinline__ float bperm_f(int src_lane, float v) { return __builtin_bit_cast(float, __builtin_amdgcn_ds_bpermute(src_lane << 2, __builtin_bit_cast(int, v))); }
; template <int KIND>
; __device__ __forceinline__ void w_m3_core(const bf16x8 (&Qf)[4][2], const bf16x8 (&Kf)[4][2], const bf16x8 (&Sf)[4][2], const LAS bf16_t* vT, float lg,
;                                           const bf16_t* gsrc, const float* nw, bf16_t* ydst, int lo, int fq) {
;     ...
;         for (int kk2 = 0; kk2 < 2; ++kk2) {
;             if (2 * kk2 > nb) continue;
;             float pv[8];
; #pragma unroll
;             for (int hh = 0; hh < 2; ++hh) { const int mb = 2 * kk2 + hh;
;                 if (mb <= nb) { f32x4 s = {0.f, 0.f, 0.f, 0.f};
;                     s = __builtin_amdgcn_mfma_f32_16x16x32_bf16(Kf[mb][0], Qf[nb][0], s, 0, 0, 0); s = __builtin_amdgcn_mfma_f32_16x16x32_bf16(Kf[mb][1], Qf[nb][1], s, 0, 0, 0);
; #pragma unroll
;                     for (int r = 0; r < 4; ++r) { const int m = 16 * mb + 4 * fq + r, n = 16 * nb + lo; float v = s[r];
;                         if (KIND == 0) v *= __expf((float)(n - m) * lg);
;                         if (mb == nb) v = (m <= n) ? v : 0.f;
;                         pv[4 * hh + r] = v; }
;                 } else {
; #pragma unroll
;                     for (int r = 0; r < 4; ++r) pv[4 * hh + r] = 0.f; }
;             }
;             const bf16x8 Pf = pack_frag(pv);
; #pragma unroll
;             for (int eb = 0; eb < 4; ++eb)
;                 O[eb] = __builtin_amdgcn_mfma_f32_16x16x32_bf16(tr_frag(vT, 32 * kk2 + 4 * fq, 32 * kk2 + 16 + 4 * fq, 16 * eb, lo), Pf, O[eb], 0, 0, 0);
;         }
; #pragma unroll
;         for (int kk = 0; kk < 2; ++kk)
; #pragma unroll
;             for (int eb = 0; eb < 4; ++eb) O2[eb] = __builtin_amdgcn_mfma_f32_16x16x32_bf16(Sf[eb][kk], Qf[nb][kk], O2[eb], 0, 0, 0);
;         const float osc = KIND == 0 ? __expf((float)(16 * nb + lo + 1) * lg) : 1.0f;
; #pragma unroll
;         for (int eb = 0; eb < 4; ++eb) O[eb] = O[eb] + O2[eb] * osc;
;         float ss = 0.f;
; #pragma unroll
;         for (int eb = 0; eb < 4; ++eb) ss += (O[eb][0] * O[eb][0] + O[eb][1] * O[eb][1]) + (O[eb][2] * O[eb][2] + O[eb][3] * O[eb][3]);
;         { const int ln = (fq << 4) | lo; ss += bperm_f(ln ^ 16, ss); ss += bperm_f(ln ^ 32, ss); }
;         const float rs = rsqrtf(ss * (1.0f / 64.0f) + EPS);
	v_mfma_f32_16x16x32_bf16 v[88:91], v[88:91], v[84:87], 0
	v_mfma_f32_16x16x32_bf16 v[92:95], v[92:95], v[84:87], 0
	v_mfma_f32_16x16x32_bf16 v[102:105], v[102:105], v[84:87], 0
	v_mfma_f32_16x16x32_bf16 v[84:87], v[106:109], v[84:87], 0
	v_mfma_f32_16x16x32_bf16 v[106:109], v[44:47], v[80:83], 0
	v_mfma_f32_16x16x32_bf16 v[108:111], v[48:51], v[76:79], v[106:109]
	s_nop 6
	v_add_u32_e32 v107, 33, v124
	v_mul_f32_e32 v0, v139, v108
	v_cndmask_b32_e64 v2, v0, 0, vcc
	v_sub_u32_e32 v0, v136, v107
	v_cvt_f32_i32_e32 v0, v0
	v_cmp_ge_i32_e64 s[38:39], v136, v107
	v_add_u32_e32 v106, 35, v124
	v_add_u32_e32 v108, 34, v124
	v_mul_f32_e32 v0, v135, v0
	v_mul_f32_e32 v0, 0x3fb8aa3b, v0
	v_exp_f32_e32 v0, v0
	v_sub_u32_e32 v1, v136, v106
	v_cvt_f32_i32_e32 v1, v1
	v_mul_f32_e32 v0, v0, v109
	v_cndmask_b32_e64 v109, 0, v0, s[38:39]
	v_sub_u32_e32 v0, v136, v108
	v_cvt_f32_i32_e32 v0, v0
	v_mul_f32_e32 v1, v135, v1
	v_mul_f32_e32 v1, 0x3fb8aa3b, v1
	v_exp_f32_e32 v1, v1
	v_mul_f32_e32 v0, v135, v0
	v_mul_f32_e32 v0, 0x3fb8aa3b, v0
	v_exp_f32_e32 v0, v0
	v_cmp_ge_i32_e64 s[38:39], v136, v108
	v_pk_mul_f32 v[110:111], v[0:1], v[110:111]
	s_nop 0
	v_cvt_pk_bf16_f32 v1, v110, v111
	ds_read_b64_tr_b16 v[110:111], v128 offset:4608
	ds_read_b64_tr_b16 v[112:113], v126 offset:4608
	v_cvt_pk_bf16_f32 v0, v2, v109
	v_cndmask_b32_e64 v2, 0, v1, s[38:39]
	v_lshrrev_b32_e32 v1, 16, v1
	v_cmp_ge_i32_e64 s[38:39], v136, v106
	s_nop 1
	v_cndmask_b32_e64 v1, 0, v1, s[38:39]
	v_perm_b32 v1, v1, v2, s53
	v_mov_b32_e32 v2, v3
	s_waitcnt lgkmcnt(0)
	s_nop 0
	v_mfma_f32_16x16x32_bf16 v[88:91], v[110:113], v[0:3], v[88:91]
	ds_read_b64_tr_b16 v[110:111], v128 offset:4640
	ds_read_b64_tr_b16 v[112:113], v126 offset:4640
	s_waitcnt lgkmcnt(0)
	v_mfma_f32_16x16x32_bf16 v[110:113], v[110:113], v[0:3], v[92:95]
	s_nop 2
	ds_read_b64_tr_b16 v[92:93], v128 offset:4672
	ds_read_b64_tr_b16 v[94:95], v126 offset:4672
	s_waitcnt lgkmcnt(0)
	v_mfma_f32_16x16x32_bf16 v[118:121], v[92:95], v[0:3], v[102:105]
	ds_read_b64_tr_b16 v[92:93], v128 offset:4704
	ds_read_b64_tr_b16 v[94:95], v126 offset:4704
	s_waitcnt lgkmcnt(0)
	v_mfma_f32_16x16x32_bf16 v[144:147], v[92:95], v[0:3], v[84:87]
	v_add_u32_e32 v0, 33, v133
	v_cvt_f32_ubyte0_e32 v0, v0
	v_mul_f32_e32 v0, v135, v0
	v_mfma_f32_16x16x32_bf16 v[84:87], v[20:23], v[80:83], 0
	v_mul_f32_e32 v0, 0x3fb8aa3b, v0
	v_exp_f32_e32 v2, v0
	v_mfma_f32_16x16x32_bf16 v[92:95], v[24:27], v[80:83], 0
	v_mfma_f32_16x16x32_bf16 v[102:105], v[36:39], v[80:83], 0
	v_mfma_f32_16x16x32_bf16 v[80:83], v[40:43], v[80:83], 0
	v_mfma_f32_16x16x32_bf16 v[84:87], v[12:15], v[76:79], v[84:87]
	v_mfma_f32_16x16x32_bf16 v[148:151], v[16:19], v[76:79], v[92:95]
	v_mfma_f32_16x16x32_bf16 v[152:155], v[28:31], v[76:79], v[102:105]
	s_nop 5
	v_fma_f32 v94, v2, v86, v90
	v_fma_f32 v95, v2, v87, v91
	v_pk_fma_f32 v[92:93], v[2:3], v[148:149], v[110:111] op_sel_hi:[0,1,1]
	v_mfma_f32_16x16x32_bf16 v[76:79], v[32:35], v[76:79], v[80:83]
	v_fma_f32 v102, v2, v84, v88
	v_fma_f32 v103, v2, v85, v89
	v_pk_fma_f32 v[88:89], v[2:3], v[150:151], v[112:113] op_sel_hi:[0,1,1]
	v_pk_fma_f32 v[84:85], v[2:3], v[154:155], v[120:121] op_sel_hi:[0,1,1]
	v_pk_fma_f32 v[86:87], v[2:3], v[152:153], v[118:119] op_sel_hi:[0,1,1]
	s_nop 2
	v_pk_fma_f32 v[0:1], v[2:3], v[78:79], v[146:147] op_sel_hi:[0,1,1]
	v_pk_fma_f32 v[82:83], v[2:3], v[76:77], v[144:145] op_sel_hi:[0,1,1]
	v_pk_mul_f32 v[76:77], v[94:95], v[94:95]
	v_pk_mul_f32 v[78:79], v[102:103], v[102:103]
	v_mul_f32_e32 v2, v82, v82
	v_pk_mov_b32 v[80:81], v[78:79], v[76:77] op_sel:[1,0]
	v_mov_b32_e32 v79, v77
	v_pk_add_f32 v[76:77], v[80:81], v[78:79]
	v_pk_mul_f32 v[78:79], v[88:89], v[88:89]
	v_pk_mul_f32 v[80:81], v[92:93], v[92:93]
	v_pk_add_f32 v[76:77], v[76:77], v[76:77] op_sel:[0,1] op_sel_hi:[1,0]
	v_pk_mov_b32 v[90:91], v[80:81], v[78:79] op_sel:[1,0]
	v_mov_b32_e32 v81, v79
	v_pk_add_f32 v[78:79], v[90:91], v[80:81]
	v_mul_f32_e32 v80, v83, v83
	v_pk_add_f32 v[78:79], v[78:79], v[78:79] op_sel:[0,1] op_sel_hi:[1,0]
	v_mov_b32_e32 v77, v2
	v_mov_b32_e32 v79, v80
	v_mul_f32_e32 v2, v87, v87
	v_mul_f32_e32 v81, v0, v0
	v_pk_add_f32 v[76:77], v[76:77], v[78:79]
	v_pk_fma_f32 v[78:79], v[86:87], v[86:87], v[2:3] op_sel_hi:[1,1,0]
	v_mul_f32_e32 v2, v85, v85
	v_mul_f32_e32 v90, v1, v1
	v_mov_b32_e32 v79, v81
	v_pk_fma_f32 v[80:81], v[84:85], v[84:85], v[2:3] op_sel_hi:[1,1,0]
	s_nop 0
	v_mov_b32_e32 v81, v90
	v_pk_add_f32 v[78:79], v[78:79], v[80:81]
	s_nop 0
	v_pk_add_f32 v[76:77], v[76:77], v[78:79]
	s_nop 0
	v_add_f32_e32 v2, v76, v77
	ds_bpermute_b32 v76, v138, v2
	s_waitcnt lgkmcnt(0)
	v_add_f32_e32 v2, v2, v76
	ds_bpermute_b32 v76, v137, v2
	s_waitcnt lgkmcnt(0)
	v_add_f32_e32 v2, v2, v76
	v_fmamk_f32 v2, v2, 0x3c800000, v200
	v_cmp_gt_f32_e64 s[38:39], s29, v2
	v_mul_f32_e32 v76, 0x4b800000, v2
	s_nop 0
	v_cndmask_b32_e64 v2, v2, v76, s[38:39]
	v_rsq_f32_e32 v2, v2
	s_nop 0
	v_mul_f32_e32 v76, 0x45800000, v2
	v_cndmask_b32_e64 v80, v2, v76, s[38:39]
	v_mad_u64_u32 v[76:77], s[20:21], v136, s72, v[98:99]
	v_lshl_add_u64 v[90:91], v[76:77], 0, v[96:97]
	v_mov_b64_e32 v[110:111], v[238:239]
	v_mov_b64_e32 v[76:77], v[184:185]
	v_mov_b64_e32 v[78:79], v[186:187]
	v_lshlrev_b32_e32 v2, 11, v136
	v_lshl_add_u64 v[104:105], s[40:41], 0, v[2:3]
	v_pk_mul_f32 v[102:103], v[102:103], v[80:81] op_sel_hi:[1,0]
	v_pk_mul_f32 v[94:95], v[94:95], v[80:81] op_sel_hi:[1,0]
	v_pk_mul_f32 v[92:93], v[92:93], v[80:81] op_sel_hi:[1,0]
	v_pk_mul_f32 v[88:89], v[88:89], v[80:81] op_sel_hi:[1,0]
	v_pk_mul_f32 v[86:87], v[86:87], v[80:81] op_sel_hi:[1,0]
	s_waitcnt lgkmcnt(0)
; __device__ __forceinline__ unsigned pk2(float lo, float hi) { const f32x2_t v = {lo, hi}; const bf16x2_t b = __builtin_convertvector(v, bf16x2_t); return __builtin_bit_cast(unsigned, b); }
; __device__ __forceinline__ float sigmoidf_(float x) { return __builtin_amdgcn_rcpf(1.0f + __expf(-x)); }
; template <int KIND>
; __device__ __forceinline__ void w_m3_core(const bf16x8 (&Qf)[4][2], const bf16x8 (&Kf)[4][2], const bf16x8 (&Sf)[4][2], const LAS bf16_t* vT, float lg,
;                                           const bf16_t* gsrc, const float* nw, bf16_t* ydst, int lo, int fq) {
;     ...
;                     s = __builtin_amdgcn_mfma_f32_16x16x32_bf16(Kf[mb][0], Qf[nb][0], s, 0, 0, 0); s = __builtin_amdgcn_mfma_f32_16x16x32_bf16(Kf[mb][1], Qf[nb][1], s, 0, 0, 0);
; #pragma unroll
;                     for (int r = 0; r < 4; ++r) { const int m = 16 * mb + 4 * fq + r, n = 16 * nb + lo; float v = s[r];
;                         if (KIND == 0) v *= __expf((float)(n - m) * lg);
;                         if (mb == nb) v = (m <= n) ? v : 0.f;
;                         pv[4 * hh + r] = v; }
;     ...
;         const size_t n = 16 * nb + lo;
; #pragma unroll
;         for (int eb = 0; eb < 4; ++eb) { const int e0 = 16 * eb + 4 * fq;
;             const unsigned long long gw_ = *(const unsigned long long*)(gsrc + n * NIN + e0); const f32x4 w4 = *(const f32x4*)(nw + e0);
;             const float g0 = __uint_as_float((unsigned)gw_ << 16), g1 = __uint_as_float((unsigned)gw_ & 0xffff0000u), g2 = __uint_as_float((unsigned)(gw_ >> 32) << 16), g3 = __uint_as_float((unsigned)(gw_ >> 32) & 0xffff0000u);
;             const float o0 = O[eb][0] * rs * w4[0] * (g0 * sigmoidf_(g0)), o1 = O[eb][1] * rs * w4[1] * (g1 * sigmoidf_(g1));
;             const float o2 = O[eb][2] * rs * w4[2] * (g2 * sigmoidf_(g2)), o3 = O[eb][3] * rs * w4[3] * (g3 * sigmoidf_(g3));
;             *(unsigned long long*)(ydst + n * DM + e0) = (unsigned long long)pk2(o0, o1) | ((unsigned long long)pk2(o2, o3) << 32); }
	v_lshlrev_b32_e32 v112, 16, v110
	v_mul_f32_e32 v2, 0xbfb8aa3b, v112
	v_exp_f32_e32 v2, v2
	v_and_b32_e32 v113, 0xffff0000, v110
	v_lshlrev_b32_e32 v110, 16, v111
	v_and_b32_e32 v111, 0xffff0000, v111
	v_add_f32_e32 v2, 1.0, v2
	v_rcp_f32_e32 v118, v2
	v_mul_f32_e32 v2, 0xbfb8aa3b, v113
	v_exp_f32_e32 v2, v2
	v_pk_mul_f32 v[76:77], v[76:77], v[102:103]
	v_pk_mul_f32 v[78:79], v[78:79], v[94:95]
	v_add_f32_e32 v2, 1.0, v2
	v_rcp_f32_e32 v119, v2
	v_mul_f32_e32 v2, 0xbfb8aa3b, v110
	v_exp_f32_e32 v2, v2
	v_pk_mul_f32 v[102:103], v[118:119], v[112:113]
	s_nop 0
	v_pk_mul_f32 v[76:77], v[102:103], v[76:77]
	v_add_f32_e32 v2, 1.0, v2
	v_rcp_f32_e32 v102, v2
	v_mul_f32_e32 v2, 0xbfb8aa3b, v111
	v_exp_f32_e32 v2, v2
	s_nop 0
	v_add_f32_e32 v2, 1.0, v2
	v_rcp_f32_e32 v103, v2
	s_nop 0
	v_pk_mul_f32 v[94:95], v[102:103], v[110:111]
	s_nop 0
	v_pk_mul_f32 v[78:79], v[94:95], v[78:79]
	v_cvt_pk_bf16_f32 v94, v76, v77
	v_cvt_pk_bf16_f32 v95, v78, v79
	v_lshl_add_u64 v[76:77], v[104:105], 0, v[96:97]
	global_store_dwordx2 v[76:77], v[94:95], off offset:1024
	v_mov_b64_e32 v[78:79], v[240:241]
	v_mov_b64_e32 v[102:103], v[188:189]
	v_mov_b64_e32 v[104:105], v[190:191]
	s_waitcnt lgkmcnt(0)
	v_lshlrev_b32_e32 v94, 16, v78
	v_mul_f32_e32 v2, 0xbfb8aa3b, v94
	v_exp_f32_e32 v2, v2
	v_and_b32_e32 v95, 0xffff0000, v78
	v_lshlrev_b32_e32 v78, 16, v79
	v_and_b32_e32 v79, 0xffff0000, v79
	v_add_f32_e32 v2, 1.0, v2
	v_rcp_f32_e32 v110, v2
	v_mul_f32_e32 v2, 0xbfb8aa3b, v95
	v_exp_f32_e32 v2, v2
	v_pk_mul_f32 v[92:93], v[102:103], v[92:93]
	v_pk_mul_f32 v[88:89], v[104:105], v[88:89]
	v_mul_f32_e32 v102, v84, v80
	v_add_f32_e32 v2, 1.0, v2
	v_rcp_f32_e32 v111, v2
	v_mul_f32_e32 v2, 0xbfb8aa3b, v78
	v_exp_f32_e32 v2, v2
	v_pk_mul_f32 v[94:95], v[110:111], v[94:95]
	s_nop 0
	v_pk_mul_f32 v[92:93], v[94:95], v[92:93]
	v_add_f32_e32 v2, 1.0, v2
	v_rcp_f32_e32 v94, v2
	v_mul_f32_e32 v2, 0xbfb8aa3b, v79
	v_exp_f32_e32 v2, v2
	s_nop 0
	v_add_f32_e32 v2, 1.0, v2
	v_rcp_f32_e32 v95, v2
	s_nop 0
	v_pk_mul_f32 v[78:79], v[94:95], v[78:79]
	s_nop 0
	v_pk_mul_f32 v[78:79], v[78:79], v[88:89]
	v_cvt_pk_bf16_f32 v88, v92, v93
	v_cvt_pk_bf16_f32 v89, v78, v79
	global_store_dwordx2 v[76:77], v[88:89], off offset:1056
	v_mov_b64_e32 v[78:79], v[242:243]
	v_mov_b64_e32 v[92:93], v[192:193]
	v_mov_b64_e32 v[94:95], v[194:195]
	s_waitcnt lgkmcnt(0)
	v_lshlrev_b32_e32 v88, 16, v78
	v_mul_f32_e32 v2, 0xbfb8aa3b, v88
	v_exp_f32_e32 v2, v2
	v_and_b32_e32 v89, 0xffff0000, v78
	v_lshlrev_b32_e32 v103, 16, v79
	v_and_b32_e32 v79, 0xffff0000, v79
	v_add_f32_e32 v2, 1.0, v2
	v_rcp_f32_e32 v104, v2
	v_mul_f32_e32 v2, 0xbfb8aa3b, v89
	v_exp_f32_e32 v2, v2
	v_pk_mul_f32 v[86:87], v[92:93], v[86:87]
	v_mul_f32_e32 v78, v85, v80
	v_mov_b32_e32 v84, v95
	v_add_f32_e32 v2, 1.0, v2
	v_rcp_f32_e32 v105, v2
	v_mul_f32_e32 v2, 0xbfb8aa3b, v103
	v_exp_f32_e32 v2, v2
	v_mul_f32_e32 v92, v0, v80
	v_pk_mul_f32 v[88:89], v[104:105], v[88:89]
	v_add_f32_e32 v2, 1.0, v2
	v_pk_mul_f32 v[86:87], v[88:89], v[86:87]
	v_rcp_f32_e32 v89, v2
	v_mul_f32_e32 v2, 0xbfb8aa3b, v79
	v_exp_f32_e32 v2, v2
	v_mov_b32_e32 v88, v94
	v_pk_mul_f32 v[88:89], v[88:89], v[102:103]
	v_add_f32_e32 v2, 1.0, v2
	v_rcp_f32_e32 v85, v2
	s_nop 0
	v_pk_mul_f32 v[78:79], v[84:85], v[78:79]
	v_cvt_pk_bf16_f32 v84, v86, v87
	v_mov_b32_e32 v86, v88
	v_mov_b32_e32 v87, v78
	v_mov_b32_e32 v78, v89
	v_pk_mul_f32 v[78:79], v[86:87], v[78:79]
	v_mul_f32_e32 v88, v82, v80
	v_cvt_pk_bf16_f32 v85, v78, v79
	global_store_dwordx2 v[76:77], v[84:85], off offset:1088
	v_mov_b64_e32 v[78:79], v[244:245]
	s_nop 0
	v_mov_b64_e32 v[84:85], v[196:197]
	v_mov_b64_e32 v[86:87], v[198:199]
	v_mul_f32_e32 v90, v83, v80
	s_waitcnt lgkmcnt(0)
	v_lshlrev_b32_e32 v89, 16, v78
	v_lshlrev_b32_e32 v93, 16, v79
	v_mul_f32_e32 v2, 0xbfb8aa3b, v89
	v_mul_f32_e32 v0, 0xbfb8aa3b, v93
	v_exp_f32_e32 v2, v2
	v_exp_f32_e32 v0, v0
	v_and_b32_e32 v91, 0xffff0000, v78
	v_and_b32_e32 v79, 0xffff0000, v79
	v_add_f32_e32 v2, 1.0, v2
	v_add_f32_e32 v0, 1.0, v0
	v_rcp_f32_e32 v95, v2
	v_mul_f32_e32 v2, 0xbfb8aa3b, v91
	v_mov_b32_e32 v82, v85
	v_rcp_f32_e32 v85, v0
	v_mul_f32_e32 v0, 0xbfb8aa3b, v79
	v_exp_f32_e32 v2, v2
	v_exp_f32_e32 v0, v0
	v_mul_f32_e32 v78, v1, v80
	v_mov_b32_e32 v94, v84
	v_add_f32_e32 v2, 1.0, v2
	v_add_f32_e32 v0, 1.0, v0
	v_rcp_f32_e32 v83, v2
	v_rcp_f32_e32 v1, v0
	v_mov_b32_e32 v84, v86
	v_mov_b32_e32 v0, v87
	v_pk_mul_f32 v[88:89], v[94:95], v[88:89]
	v_pk_mul_f32 v[82:83], v[82:83], v[90:91]
	v_pk_mul_f32 v[84:85], v[84:85], v[92:93]
	v_pk_mul_f32 v[0:1], v[0:1], v[78:79]
	v_mov_b32_e32 v78, v88
	v_mov_b32_e32 v79, v82
	v_mov_b32_e32 v82, v89
	v_mov_b32_e32 v80, v84
	v_mov_b32_e32 v81, v0
	v_mov_b32_e32 v0, v85
	v_pk_mul_f32 v[78:79], v[78:79], v[82:83]
	v_pk_mul_f32 v[0:1], v[80:81], v[0:1]
	v_cvt_pk_bf16_f32 v78, v78, v79
	v_cvt_pk_bf16_f32 v79, v0, v1
	global_store_dwordx2 v[76:77], v[78:79], off offset:1120
	v_sub_u32_e32 v2, v134, v124
	v_add_u32_e32 v1, v134, v143
	v_cvt_f32_i32_e32 v0, v2
	v_cvt_f32_i32_e32 v1, v1
	v_mfma_f32_16x16x32_bf16 v[64:67], v[64:67], v[8:11], 0
	v_mul_f32_e32 v0, v135, v0
	v_mul_f32_e32 v1, v135, v1
	v_mul_f32_e32 v0, 0x3fb8aa3b, v0
	v_mul_f32_e32 v1, 0x3fb8aa3b, v1
	v_mfma_f32_16x16x32_bf16 v[64:67], v[72:75], v[4:7], v[64:67]
	v_exp_f32_e32 v0, v0
	v_exp_f32_e32 v1, v1
	v_mfma_f32_16x16x32_bf16 v[60:63], v[60:63], v[8:11], 0
	v_mfma_f32_16x16x32_bf16 v[60:63], v[68:71], v[4:7], v[60:63]
	s_nop 3
	v_mul_f32_e64 v0, v0, v64
	v_mul_f32_e64 v1, v1, v65
	v_sub_u32_e32 v64, v134, v142
	v_cvt_pk_bf16_f32 v68, v0, v1
	v_subrev_u32_e32 v0, 32, v2
	v_sub_u32_e32 v1, v134, v107
	v_cvt_f32_i32_e32 v0, v0
	v_cvt_f32_i32_e32 v1, v1
; __device__ __forceinline__ float bperm_f(int src_lane, float v) { return __builtin_bit_cast(float, __builtin_amdgcn_ds_bpermute(src_lane << 2, __builtin_bit_cast(int, v))); }
; template <int KIND>
; __device__ __forceinline__ void w_m3_core(const bf16x8 (&Qf)[4][2], const bf16x8 (&Kf)[4][2], const bf16x8 (&Sf)[4][2], const LAS bf16_t* vT, float lg,
;                                           const bf16_t* gsrc, const float* nw, bf16_t* ydst, int lo, int fq) {
;     ...
;         for (int kk2 = 0; kk2 < 2; ++kk2) {
;             if (2 * kk2 > nb) continue;
;             float pv[8];
; #pragma unroll
;             for (int hh = 0; hh < 2; ++hh) { const int mb = 2 * kk2 + hh;
;                 if (mb <= nb) { f32x4 s = {0.f, 0.f, 0.f, 0.f};
;                     s = __builtin_amdgcn_mfma_f32_16x16x32_bf16(Kf[mb][0], Qf[nb][0], s, 0, 0, 0); s = __builtin_amdgcn_mfma_f32_16x16x32_bf16(Kf[mb][1], Qf[nb][1], s, 0, 0, 0);
; #pragma unroll
;                     for (int r = 0; r < 4; ++r) { const int m = 16 * mb + 4 * fq + r, n = 16 * nb + lo; float v = s[r];
;                         if (KIND == 0) v *= __expf((float)(n - m) * lg);
;                         if (mb == nb) v = (m <= n) ? v : 0.f;
;                         pv[4 * hh + r] = v; }
;                 } else {
; #pragma unroll
;                     for (int r = 0; r < 4; ++r) pv[4 * hh + r] = 0.f; }
;             }
;             const bf16x8 Pf = pack_frag(pv);
; #pragma unroll
;             for (int eb = 0; eb < 4; ++eb)
;                 O[eb] = __builtin_amdgcn_mfma_f32_16x16x32_bf16(tr_frag(vT, 32 * kk2 + 4 * fq, 32 * kk2 + 16 + 4 * fq, 16 * eb, lo), Pf, O[eb], 0, 0, 0);
;         }
; #pragma unroll
;         for (int kk = 0; kk < 2; ++kk)
; #pragma unroll
;             for (int eb = 0; eb < 4; ++eb) O2[eb] = __builtin_amdgcn_mfma_f32_16x16x32_bf16(Sf[eb][kk], Qf[nb][kk], O2[eb], 0, 0, 0);
;         const float osc = KIND == 0 ? __expf((float)(16 * nb + lo + 1) * lg) : 1.0f;
; #pragma unroll
;         for (int eb = 0; eb < 4; ++eb) O[eb] = O[eb] + O2[eb] * osc;
;         float ss = 0.f;
; #pragma unroll
;         for (int eb = 0; eb < 4; ++eb) ss += (O[eb][0] * O[eb][0] + O[eb][1] * O[eb][1]) + (O[eb][2] * O[eb][2] + O[eb][3] * O[eb][3]);
;         { const int ln = (fq << 4) | lo; ss += bperm_f(ln ^ 16, ss); ss += bperm_f(ln ^ 32, ss); }
;         const float rs = rsqrtf(ss * (1.0f / 64.0f) + EPS);
	v_mfma_f32_16x16x32_bf16 v[44:47], v[44:47], v[8:11], 0
	v_sub_u32_e32 v2, v134, v108
	v_mul_f32_e32 v0, v135, v0
	v_mul_f32_e32 v1, v135, v1
	v_cvt_f32_i32_e32 v2, v2
	v_mul_f32_e32 v0, 0x3fb8aa3b, v0
	v_mul_f32_e32 v1, 0x3fb8aa3b, v1
	v_mfma_f32_16x16x32_bf16 v[44:47], v[48:51], v[4:7], v[44:47]
	v_exp_f32_e32 v0, v0
	v_exp_f32_e32 v1, v1
	v_mul_f32_e32 v2, v135, v2
	v_mul_f32_e32 v2, 0x3fb8aa3b, v2
	v_sub_u32_e32 v65, v134, v141
	s_nop 2
	v_pk_mul_f32 v[0:1], v[0:1], v[44:45]
	v_exp_f32_e32 v44, v2
	v_sub_u32_e32 v2, v134, v106
	v_cvt_f32_i32_e32 v2, v2
	v_cvt_f32_i32_e32 v64, v64
	v_cvt_f32_i32_e32 v65, v65
	v_mfma_f32_16x16x32_bf16 v[20:23], v[20:23], v[8:11], 0
	v_mul_f32_e32 v2, v135, v2
	v_mul_f32_e32 v2, 0x3fb8aa3b, v2
	v_exp_f32_e32 v45, v2
	v_mul_f32_e32 v64, v135, v64
	v_mul_f32_e32 v65, v135, v65
	v_mul_f32_e32 v64, 0x3fb8aa3b, v64
	v_pk_mul_f32 v[48:49], v[44:45], v[46:47]
	v_mfma_f32_16x16x32_bf16 v[44:47], v[52:55], v[8:11], 0
	v_mul_f32_e32 v65, 0x3fb8aa3b, v65
	v_exp_f32_e32 v64, v64
	v_exp_f32_e32 v65, v65
	v_mfma_f32_16x16x32_bf16 v[44:47], v[56:59], v[4:7], v[44:47]
	v_mul_f32_e64 v64, v64, v66
	v_mul_f32_e64 v65, v65, v67
	v_sub_u32_e32 v66, v134, v140
	v_sub_u32_e32 v67, v134, v115
	s_nop 3
	v_mul_f32_e32 v2, v139, v44
	v_add_u32_e32 v44, 49, v124
	v_sub_u32_e32 v50, v134, v44
	v_cvt_f32_i32_e32 v50, v50
	v_cvt_f32_i32_e32 v66, v66
	v_cvt_f32_i32_e32 v67, v67
	v_cndmask_b32_e64 v2, v2, 0, vcc
	v_mul_f32_e32 v50, v135, v50
	v_mul_f32_e32 v50, 0x3fb8aa3b, v50
	v_exp_f32_e32 v50, v50
	v_cmp_ge_i32_e32 vcc, v134, v44
	v_add_u32_e32 v44, 50, v124
	v_mul_f32_e32 v66, v135, v66
	v_mul_f32_e32 v45, v50, v45
	v_cndmask_b32_e32 v50, 0, v45, vcc
	v_sub_u32_e32 v45, v134, v44
	v_cvt_f32_i32_e32 v45, v45
	v_mul_f32_e32 v67, v135, v67
	v_mul_f32_e32 v66, 0x3fb8aa3b, v66
	v_mul_f32_e32 v67, 0x3fb8aa3b, v67
	v_exp_f32_e32 v66, v66
	v_exp_f32_e32 v67, v67
	v_mul_f32_e32 v45, v135, v45
	v_mul_f32_e32 v45, 0x3fb8aa3b, v45
	v_exp_f32_e32 v45, v45
	v_pk_mul_f32 v[60:61], v[66:67], v[60:61]
	v_sub_u32_e32 v66, v134, v116
	v_sub_u32_e32 v67, v134, v114
	v_cvt_f32_i32_e32 v66, v66
	v_cvt_f32_i32_e32 v67, v67
	v_mul_f32_e32 v45, v45, v46
	v_cmp_ge_i32_e32 vcc, v134, v44
	v_add_u32_e32 v44, 51, v124
	v_mul_f32_e32 v66, v135, v66
	v_cndmask_b32_e32 v51, 0, v45, vcc
	v_sub_u32_e32 v45, v134, v44
	v_mul_f32_e32 v67, v135, v67
	v_cvt_f32_i32_e32 v45, v45
	v_mul_f32_e32 v66, 0x3fb8aa3b, v66
	v_mul_f32_e32 v67, 0x3fb8aa3b, v67
	v_exp_f32_e32 v66, v66
	v_exp_f32_e32 v67, v67
	v_mul_f32_e32 v45, v135, v45
	v_mul_f32_e32 v45, 0x3fb8aa3b, v45
	v_exp_f32_e32 v45, v45
	v_pk_mul_f32 v[62:63], v[66:67], v[62:63]
	v_cvt_pk_bf16_f32 v69, v64, v65
	v_cvt_pk_bf16_f32 v70, v60, v61
	v_cvt_pk_bf16_f32 v71, v62, v63
	ds_read_b64_tr_b16 v[62:63], v126
	ds_read_b64_tr_b16 v[66:67], v126 offset:32
	ds_read_b64_tr_b16 v[60:61], v128
	ds_read_b64_tr_b16 v[64:65], v128 offset:32
	v_mul_f32_e32 v45, v45, v47
	v_cmp_ge_i32_e32 vcc, v134, v44
	s_waitcnt lgkmcnt(0)
	v_mfma_f32_16x16x32_bf16 v[72:75], v[60:63], v[68:71], 0
	v_cndmask_b32_e32 v47, 0, v45, vcc
	v_cvt_pk_bf16_f32 v45, v48, v49
	v_cvt_pk_bf16_f32 v46, v2, v50
	v_mfma_f32_16x16x32_bf16 v[60:63], v[64:67], v[68:71], 0
	ds_read_b64_tr_b16 v[64:65], v128 offset:64
	ds_read_b64_tr_b16 v[66:67], v126 offset:64
	ds_read_b64_tr_b16 v[76:77], v128 offset:96
	ds_read_b64_tr_b16 v[78:79], v126 offset:96
	v_cvt_pk_bf16_f32 v47, v51, v47
	ds_read_b64_tr_b16 v[48:49], v128 offset:4608
	ds_read_b64_tr_b16 v[50:51], v126 offset:4608
	ds_read_b64_tr_b16 v[52:53], v128 offset:4640
	ds_read_b64_tr_b16 v[54:55], v126 offset:4640
	v_cvt_pk_bf16_f32 v44, v0, v1
	ds_read_b64_tr_b16 v[56:57], v128 offset:4672
	ds_read_b64_tr_b16 v[58:59], v126 offset:4672
	s_waitcnt lgkmcnt(0)
	v_mfma_f32_16x16x32_bf16 v[52:55], v[52:55], v[44:47], v[60:63]
	s_nop 2
	ds_read_b64_tr_b16 v[60:61], v128 offset:4704
	ds_read_b64_tr_b16 v[62:63], v126 offset:4704
	v_add_u32_e32 v0, 49, v133
	v_cvt_f32_ubyte0_e32 v0, v0
	v_mfma_f32_16x16x32_bf16 v[64:67], v[64:67], v[68:71], 0
	v_mul_f32_e32 v0, v135, v0
	v_mul_f32_e32 v0, 0x3fb8aa3b, v0
	v_exp_f32_e32 v2, v0
	v_mfma_f32_16x16x32_bf16 v[68:71], v[76:79], v[68:71], 0
	v_mfma_f32_16x16x32_bf16 v[24:27], v[24:27], v[8:11], 0
	v_mfma_f32_16x16x32_bf16 v[36:39], v[36:39], v[8:11], 0
	v_mfma_f32_16x16x32_bf16 v[8:11], v[40:43], v[8:11], 0
	v_mfma_f32_16x16x32_bf16 v[48:51], v[48:51], v[44:47], v[72:75]
	v_mfma_f32_16x16x32_bf16 v[12:15], v[12:15], v[4:7], v[20:23]
	v_mfma_f32_16x16x32_bf16 v[56:59], v[56:59], v[44:47], v[64:67]
	s_waitcnt lgkmcnt(0)
	v_mfma_f32_16x16x32_bf16 v[44:47], v[60:63], v[44:47], v[68:71]
	s_nop 4
	v_fma_f32 v22, v2, v14, v50
	v_fma_f32 v23, v2, v15, v51
	v_mfma_f32_16x16x32_bf16 v[18:21], v[16:19], v[4:7], v[24:27]
	v_mfma_f32_16x16x32_bf16 v[26:29], v[28:31], v[4:7], v[36:39]
	s_nop 1
	v_fma_f32 v24, v2, v12, v48
	v_fma_f32 v25, v2, v13, v49
	s_nop 2
	v_pk_fma_f32 v[16:17], v[2:3], v[20:21], v[54:55] op_sel_hi:[0,1,1]
	v_pk_fma_f32 v[18:19], v[2:3], v[18:19], v[52:53] op_sel_hi:[0,1,1]
	v_mfma_f32_16x16x32_bf16 v[4:7], v[32:35], v[4:7], v[8:11]
	v_fma_f32 v12, v2, v28, v58
	v_fma_f32 v13, v2, v29, v59
	s_nop 5
	v_pk_fma_f32 v[0:1], v[2:3], v[6:7], v[46:47] op_sel_hi:[0,1,1]
	v_pk_fma_f32 v[10:11], v[2:3], v[4:5], v[44:45] op_sel_hi:[0,1,1]
	v_pk_mul_f32 v[4:5], v[22:23], v[22:23]
	v_pk_mul_f32 v[6:7], v[24:25], v[24:25]
	v_pk_fma_f32 v[14:15], v[2:3], v[26:27], v[56:57] op_sel_hi:[0,1,1]
	v_pk_mov_b32 v[8:9], v[6:7], v[4:5] op_sel:[1,0]
	v_mov_b32_e32 v7, v5
	v_pk_add_f32 v[4:5], v[8:9], v[6:7]
	v_pk_mul_f32 v[6:7], v[16:17], v[16:17]
	v_pk_mul_f32 v[8:9], v[18:19], v[18:19]
	v_mul_f32_e32 v2, v10, v10
	v_pk_mov_b32 v[20:21], v[8:9], v[6:7] op_sel:[1,0]
	v_mov_b32_e32 v9, v7
	v_pk_add_f32 v[6:7], v[20:21], v[8:9]
	v_mul_f32_e32 v8, v11, v11
	v_pk_add_f32 v[4:5], v[4:5], v[4:5] op_sel:[0,1] op_sel_hi:[1,0]
	v_pk_add_f32 v[6:7], v[6:7], v[6:7] op_sel:[0,1] op_sel_hi:[1,0]
	v_mov_b32_e32 v5, v2
	v_mov_b32_e32 v7, v8
	v_mul_f32_e32 v2, v15, v15
	v_mul_f32_e32 v9, v0, v0
	v_pk_add_f32 v[4:5], v[4:5], v[6:7]
	v_pk_fma_f32 v[6:7], v[14:15], v[14:15], v[2:3] op_sel_hi:[1,1,0]
	v_mul_f32_e32 v2, v13, v13
	v_mul_f32_e32 v20, v1, v1
	v_mov_b32_e32 v7, v9
	v_pk_fma_f32 v[8:9], v[12:13], v[12:13], v[2:3] op_sel_hi:[1,1,0]
	s_nop 0
	v_mov_b32_e32 v9, v20
	v_pk_add_f32 v[6:7], v[6:7], v[8:9]
	s_nop 0
	v_pk_add_f32 v[4:5], v[4:5], v[6:7]
	s_nop 0
	v_add_f32_e32 v2, v4, v5
	ds_bpermute_b32 v4, v138, v2
	s_waitcnt lgkmcnt(0)
; __device__ __forceinline__ unsigned pk2(float lo, float hi) { const f32x2_t v = {lo, hi}; const bf16x2_t b = __builtin_convertvector(v, bf16x2_t); return __builtin_bit_cast(unsigned, b); }
; __device__ __forceinline__ float sigmoidf_(float x) { return __builtin_amdgcn_rcpf(1.0f + __expf(-x)); }
; template <int KIND>
; __device__ __forceinline__ void w_m3_core(const bf16x8 (&Qf)[4][2], const bf16x8 (&Kf)[4][2], const bf16x8 (&Sf)[4][2], const LAS bf16_t* vT, float lg,
;                                           const bf16_t* gsrc, const float* nw, bf16_t* ydst, int lo, int fq) {
;     ...
;         const size_t n = 16 * nb + lo;
; #pragma unroll
;         for (int eb = 0; eb < 4; ++eb) { const int e0 = 16 * eb + 4 * fq;
;             const unsigned long long gw_ = *(const unsigned long long*)(gsrc + n * NIN + e0); const f32x4 w4 = *(const f32x4*)(nw + e0);
;             const float g0 = __uint_as_float((unsigned)gw_ << 16), g1 = __uint_as_float((unsigned)gw_ & 0xffff0000u), g2 = __uint_as_float((unsigned)(gw_ >> 32) << 16), g3 = __uint_as_float((unsigned)(gw_ >> 32) & 0xffff0000u);
;             const float o0 = O[eb][0] * rs * w4[0] * (g0 * sigmoidf_(g0)), o1 = O[eb][1] * rs * w4[1] * (g1 * sigmoidf_(g1));
;             const float o2 = O[eb][2] * rs * w4[2] * (g2 * sigmoidf_(g2)), o3 = O[eb][3] * rs * w4[3] * (g3 * sigmoidf_(g3));
;             *(unsigned long long*)(ydst + n * DM + e0) = (unsigned long long)pk2(o0, o1) | ((unsigned long long)pk2(o2, o3) << 32); }
	v_add_f32_e32 v2, v2, v4
	ds_bpermute_b32 v4, v137, v2
	s_waitcnt lgkmcnt(0)
	v_add_f32_e32 v2, v2, v4
	v_fmamk_f32 v2, v2, 0x3c800000, v200
	v_cmp_gt_f32_e32 vcc, s29, v2
	v_mul_f32_e32 v4, 0x4b800000, v2
	s_nop 0
	v_cndmask_b32_e32 v2, v2, v4, vcc
	v_rsq_f32_e32 v2, v2
	s_nop 0
	v_mul_f32_e32 v4, 0x45800000, v2
	v_cndmask_b32_e32 v8, v2, v4, vcc
	v_mad_u64_u32 v[4:5], s[20:21], v134, s72, v[98:99]
	v_lshl_add_u64 v[20:21], v[4:5], 0, v[96:97]
	v_mov_b64_e32 v[28:29], v[246:247]
	v_mov_b64_e32 v[4:5], v[184:185]
	v_mov_b64_e32 v[6:7], v[186:187]
	v_lshlrev_b32_e32 v2, 11, v134
	v_lshl_add_u64 v[26:27], s[40:41], 0, v[2:3]
	v_pk_mul_f32 v[24:25], v[24:25], v[8:9] op_sel_hi:[1,0]
	v_pk_mul_f32 v[22:23], v[22:23], v[8:9] op_sel_hi:[1,0]
	v_pk_mul_f32 v[18:19], v[18:19], v[8:9] op_sel_hi:[1,0]
	v_pk_mul_f32 v[16:17], v[16:17], v[8:9] op_sel_hi:[1,0]
	v_pk_mul_f32 v[14:15], v[14:15], v[8:9] op_sel_hi:[1,0]
	s_waitcnt lgkmcnt(0)
	v_lshlrev_b32_e32 v30, 16, v28
	v_mul_f32_e32 v2, 0xbfb8aa3b, v30
	v_exp_f32_e32 v2, v2
	v_and_b32_e32 v31, 0xffff0000, v28
	v_lshlrev_b32_e32 v28, 16, v29
	v_and_b32_e32 v29, 0xffff0000, v29
	v_add_f32_e32 v2, 1.0, v2
	v_rcp_f32_e32 v32, v2
	v_mul_f32_e32 v2, 0xbfb8aa3b, v31
	v_exp_f32_e32 v2, v2
	v_pk_mul_f32 v[4:5], v[4:5], v[24:25]
	v_pk_mul_f32 v[6:7], v[6:7], v[22:23]
	v_add_f32_e32 v2, 1.0, v2
	v_rcp_f32_e32 v33, v2
	v_mul_f32_e32 v2, 0xbfb8aa3b, v28
	v_exp_f32_e32 v2, v2
	v_pk_mul_f32 v[24:25], v[32:33], v[30:31]
	s_nop 0
	v_pk_mul_f32 v[4:5], v[24:25], v[4:5]
	v_add_f32_e32 v2, 1.0, v2
	v_rcp_f32_e32 v24, v2
	v_mul_f32_e32 v2, 0xbfb8aa3b, v29
	v_exp_f32_e32 v2, v2
	s_nop 0
	v_add_f32_e32 v2, 1.0, v2
	v_rcp_f32_e32 v25, v2
	s_nop 0
	v_pk_mul_f32 v[22:23], v[24:25], v[28:29]
	s_nop 0
	v_pk_mul_f32 v[6:7], v[22:23], v[6:7]
	v_cvt_pk_bf16_f32 v22, v4, v5
	v_cvt_pk_bf16_f32 v23, v6, v7
	v_lshl_add_u64 v[4:5], v[26:27], 0, v[96:97]
	global_store_dwordx2 v[4:5], v[22:23], off offset:1024
	v_mov_b64_e32 v[6:7], v[248:249]
	s_nop 0
	v_mov_b64_e32 v[22:23], v[188:189]
	v_mov_b64_e32 v[24:25], v[190:191]
	s_waitcnt lgkmcnt(0)
	v_lshlrev_b32_e32 v26, 16, v6
	v_mul_f32_e32 v2, 0xbfb8aa3b, v26
	v_exp_f32_e32 v2, v2
	v_and_b32_e32 v27, 0xffff0000, v6
	v_lshlrev_b32_e32 v6, 16, v7
	v_and_b32_e32 v7, 0xffff0000, v7
	v_add_f32_e32 v2, 1.0, v2
	v_rcp_f32_e32 v28, v2
	v_mul_f32_e32 v2, 0xbfb8aa3b, v27
	v_exp_f32_e32 v2, v2
	v_pk_mul_f32 v[18:19], v[22:23], v[18:19]
	v_pk_mul_f32 v[16:17], v[24:25], v[16:17]
	v_mul_f32_e32 v24, v12, v8
	v_add_f32_e32 v2, 1.0, v2
	v_rcp_f32_e32 v29, v2
	v_mul_f32_e32 v2, 0xbfb8aa3b, v6
	v_exp_f32_e32 v2, v2
	v_pk_mul_f32 v[22:23], v[28:29], v[26:27]
	s_nop 0
	v_pk_mul_f32 v[18:19], v[22:23], v[18:19]
	v_add_f32_e32 v2, 1.0, v2
	v_rcp_f32_e32 v22, v2
	v_mul_f32_e32 v2, 0xbfb8aa3b, v7
	v_exp_f32_e32 v2, v2
	s_nop 0
	v_add_f32_e32 v2, 1.0, v2
	v_rcp_f32_e32 v23, v2
	s_nop 0
	v_pk_mul_f32 v[6:7], v[22:23], v[6:7]
	s_nop 0
	v_pk_mul_f32 v[6:7], v[6:7], v[16:17]
	v_cvt_pk_bf16_f32 v16, v18, v19
	v_cvt_pk_bf16_f32 v17, v6, v7
	global_store_dwordx2 v[4:5], v[16:17], off offset:1056
	v_mov_b64_e32 v[6:7], v[250:251]
	s_nop 0
	v_mov_b64_e32 v[16:17], v[192:193]
	v_mov_b64_e32 v[18:19], v[194:195]
	s_waitcnt lgkmcnt(0)
	v_lshlrev_b32_e32 v22, 16, v6
	v_mul_f32_e32 v2, 0xbfb8aa3b, v22
	v_exp_f32_e32 v2, v2
	v_and_b32_e32 v23, 0xffff0000, v6
	v_lshlrev_b32_e32 v25, 16, v7
	v_and_b32_e32 v7, 0xffff0000, v7
	v_add_f32_e32 v2, 1.0, v2
	v_rcp_f32_e32 v26, v2
	v_mul_f32_e32 v2, 0xbfb8aa3b, v23
	v_exp_f32_e32 v2, v2
	v_pk_mul_f32 v[14:15], v[16:17], v[14:15]
	v_mul_f32_e32 v6, v13, v8
	v_mov_b32_e32 v12, v19
	v_add_f32_e32 v2, 1.0, v2
	v_rcp_f32_e32 v27, v2
	v_mul_f32_e32 v2, 0xbfb8aa3b, v25
	v_exp_f32_e32 v2, v2
	v_pk_mul_f32 v[16:17], v[26:27], v[22:23]
	s_nop 0
	v_pk_mul_f32 v[14:15], v[16:17], v[14:15]
	v_add_f32_e32 v2, 1.0, v2
	v_rcp_f32_e32 v17, v2
	v_mul_f32_e32 v2, 0xbfb8aa3b, v7
	v_exp_f32_e32 v2, v2
	v_mov_b32_e32 v16, v18
	v_pk_mul_f32 v[16:17], v[16:17], v[24:25]
	v_mul_f32_e32 v18, v11, v8
	v_add_f32_e32 v2, 1.0, v2
	v_rcp_f32_e32 v13, v2
	s_nop 0
	v_pk_mul_f32 v[6:7], v[12:13], v[6:7]
	v_cvt_pk_bf16_f32 v12, v14, v15
	v_mov_b32_e32 v14, v16
	v_mov_b32_e32 v15, v6
	v_mov_b32_e32 v6, v17
	v_pk_mul_f32 v[6:7], v[14:15], v[6:7]
	v_mul_f32_e32 v16, v10, v8
	v_cvt_pk_bf16_f32 v13, v6, v7
	global_store_dwordx2 v[4:5], v[12:13], off offset:1088
	v_mov_b64_e32 v[6:7], v[252:253]
	s_nop 0
	v_mov_b64_e32 v[12:13], v[196:197]
	v_mov_b64_e32 v[14:15], v[198:199]
	v_mul_f32_e32 v20, v0, v8
	s_waitcnt lgkmcnt(0)
	v_lshlrev_b32_e32 v17, 16, v6
	v_lshlrev_b32_e32 v21, 16, v7
	v_mul_f32_e32 v2, 0xbfb8aa3b, v17
	v_mul_f32_e32 v0, 0xbfb8aa3b, v21
	v_exp_f32_e32 v2, v2
	v_exp_f32_e32 v0, v0
	v_and_b32_e32 v19, 0xffff0000, v6
	v_and_b32_e32 v7, 0xffff0000, v7
	v_add_f32_e32 v2, 1.0, v2
	v_add_f32_e32 v0, 1.0, v0
	v_rcp_f32_e32 v23, v2
	v_mul_f32_e32 v2, 0xbfb8aa3b, v19
	v_mov_b32_e32 v10, v13
	v_rcp_f32_e32 v13, v0
	v_mul_f32_e32 v0, 0xbfb8aa3b, v7
	v_exp_f32_e32 v2, v2
	v_exp_f32_e32 v0, v0
	v_mul_f32_e32 v6, v1, v8
	v_mov_b32_e32 v22, v12
	v_add_f32_e32 v2, 1.0, v2
	v_add_f32_e32 v0, 1.0, v0
	v_rcp_f32_e32 v11, v2
	v_rcp_f32_e32 v1, v0
	v_mov_b32_e32 v12, v14
	v_mov_b32_e32 v0, v15
	v_pk_mul_f32 v[16:17], v[22:23], v[16:17]
	v_pk_mul_f32 v[10:11], v[10:11], v[18:19]
	v_pk_mul_f32 v[12:13], v[12:13], v[20:21]
	v_pk_mul_f32 v[0:1], v[0:1], v[6:7]
	v_mov_b32_e32 v6, v16
	v_mov_b32_e32 v7, v10
	v_mov_b32_e32 v10, v17
	v_mov_b32_e32 v8, v12
	v_mov_b32_e32 v9, v0
	v_mov_b32_e32 v0, v13
	v_pk_mul_f32 v[6:7], v[6:7], v[10:11]
	v_pk_mul_f32 v[0:1], v[8:9], v[0:1]
	v_cvt_pk_bf16_f32 v6, v6, v7
	v_cvt_pk_bf16_f32 v7, v0, v1
	global_store_dwordx2 v[4:5], v[6:7], off offset:1120
	s_waitcnt lgkmcnt(0)
	s_branch .LBB0_186
; __device__ __forceinline__ void ld8bf(const bf16_t* p, float (&o)[8]) { unpack8(*(const u32x4*)p, o); }
; __device__ __forceinline__ float sigmoidf_(float x) { return __builtin_amdgcn_rcpf(1.0f + __expf(-x)); }
; __device__ __forceinline__ bf16x8 pack_frag(const float (&v)[8]) { return __builtin_bit_cast(bf16x8, pack8(v)); }
; template <int KIND>
; __device__ __forceinline__ void w_m3_core(const bf16x8 (&Qf)[4][2], const bf16x8 (&Kf)[4][2], const bf16x8 (&Sf)[4][2], const LAS bf16_t* vT, float lg,
;                                           const bf16_t* gsrc, const float* nw, bf16_t* ydst, int lo, int fq) {
;     ...
;             const unsigned long long gw_ = *(const unsigned long long*)(gsrc + n * NIN + e0); const f32x4 w4 = *(const f32x4*)(nw + e0);
; __device__ __forceinline__ void w_hg_m3(const Args& a, int l, unsigned char* ws, const bf16_t* proj, bf16_t* y, LAS unsigned char* wl, int b, int ck_, int h, int lane) {
;     ...
;         for (int tb = 0; tb < 4; ++tb) { float fp[8], qv[8], a1[8], a2[8];
;             ld8bf(fsrc + (size_t)(16 * tb + lo) * NIN, fp); ld8bf(proj + (size_t)(row0 + 16 * tb + lo) * NIN + C_HQ + 64 * h + 32 * kk + 8 * fq, qv);
; #pragma unroll
;             for (int j = 0; j < 8; ++j) { float lf, key; hg_lf_key(fp[j], lbv[j], lf, key);
;                 const float q = qv[j] * sigmoidf_(qv[j]); a1[j] = q * __expf(bb[tb][j] - r31[j]); a2[j] = key * __expf(r31[j] - bb[tb][j]); }
;             Qf[tb][kk] = pack_frag(a1); Kf[tb][kk] = pack_frag(a2); }
.LBB0_189:
	s_or_b64 exec, exec, s[34:35]
	v_and_b32_e32 v196, 15, v132
	v_lshrrev_b32_e32 v197, 4, v132
	v_mul_u32_u24_e32 v196, 0x1800, v196
	v_lshl_add_u32 v196, v197, 3, v196
	v_add_u32_e32 v196, s88, v196
	v_add_u32_e32 v196, 0x1600, v196
	v_mov_b32_e32 v197, 0
	v_mov_b32_e32 v198, s67
	v_mov_b32_e32 v199, s68
	v_lshl_add_u64 v[198:199], v[198:199], 0, v[196:197]
	global_load_dwordx2 v[222:223], v[198:199], off
	global_load_dwordx2 v[224:225], v[198:199], off offset:32
	global_load_dwordx2 v[226:227], v[198:199], off offset:64
	global_load_dwordx2 v[228:229], v[198:199], off offset:96
	v_add_u32_e32 v196, 0x18000, v196
	v_mov_b32_e32 v198, s67
	v_mov_b32_e32 v199, s68
	v_lshl_add_u64 v[198:199], v[198:199], 0, v[196:197]
	global_load_dwordx2 v[230:231], v[198:199], off
	global_load_dwordx2 v[232:233], v[198:199], off offset:32
	global_load_dwordx2 v[234:235], v[198:199], off offset:64
	global_load_dwordx2 v[236:237], v[198:199], off offset:96
	v_add_u32_e32 v196, 0x18000, v196
	v_mov_b32_e32 v198, s67
	v_mov_b32_e32 v199, s68
	v_lshl_add_u64 v[198:199], v[198:199], 0, v[196:197]
	global_load_dwordx2 v[238:239], v[198:199], off
	global_load_dwordx2 v[240:241], v[198:199], off offset:32
	global_load_dwordx2 v[242:243], v[198:199], off offset:64
	global_load_dwordx2 v[244:245], v[198:199], off offset:96
	v_add_u32_e32 v196, 0x18000, v196
	v_mov_b32_e32 v198, s67
	v_mov_b32_e32 v199, s68
	v_lshl_add_u64 v[198:199], v[198:199], 0, v[196:197]
	global_load_dwordx2 v[246:247], v[198:199], off
	global_load_dwordx2 v[248:249], v[198:199], off offset:32
	global_load_dwordx2 v[250:251], v[198:199], off offset:64
	global_load_dwordx2 v[252:253], v[198:199], off offset:96
	s_mov_b64 s[20:21], 0x1000
	v_lshl_add_u64 v[38:39], v[64:65], 0, s[20:21]
	v_lshl_add_u64 v[64:65], v[66:67], 0, s[20:21]
	v_mul_f32_e32 v52, 0x3fb8aa3b, v98
	v_lshlrev_b32_e32 v67, 16, v4
	v_or_b32_e32 v186, 60, v70
	v_lshl_add_u64 v[70:71], v[54:55], 0, s[20:21]
	v_exp_f32_e32 v81, v52
	v_mul_f32_e32 v52, 0x3fb8aa3b, v97
	v_and_b32_e32 v4, 0xffff0000, v4
	v_mul_f32_e64 v54, |v67|, s26
	v_exp_f32_e32 v80, v52
	v_mul_f32_e32 v52, 0x3fb8aa3b, v94
	v_exp_f32_e32 v54, v54
	v_mul_f32_e64 v55, |v4|, s26
	v_exp_f32_e32 v83, v52
	v_mul_f32_e32 v52, 0x3fb8aa3b, v93
	v_exp_f32_e32 v55, v55
	v_exp_f32_e32 v82, v52
	v_mul_f32_e32 v52, 0x3fb8aa3b, v90
	v_exp_f32_e32 v85, v52
	v_mul_f32_e32 v52, 0x3fb8aa3b, v89
	v_add_f32_e32 v53, v151, v153
	v_exp_f32_e32 v84, v52
	v_mul_f32_e32 v52, 0x3fb8aa3b, v74
	v_add_f32_e32 v145, v53, v145
	v_add_f32_e32 v53, 1.0, v54
	v_lshl_add_u64 v[78:79], v[62:63], 0, s[20:21]
	v_exp_f32_e32 v87, v52
	v_mul_f32_e32 v52, 0x3fb8aa3b, v73
	v_rcp_f32_e32 v62, v53
	v_add_f32_e32 v53, 1.0, v55
	v_exp_f32_e32 v86, v52
	v_add_f32_e32 v52, v152, v154
	v_rcp_f32_e32 v63, v53
	v_add_f32_e32 v66, v52, v146
	v_sub_f32_e32 v52, v73, v66
	v_sub_f32_e32 v53, v74, v145
	v_mul_f32_e32 v52, 0x3fb8aa3b, v52
	v_mul_f32_e32 v53, 0x3fb8aa3b, v53
	v_exp_f32_e32 v52, v52
	v_exp_f32_e32 v53, v53
	v_pk_mul_f32 v[54:55], v[54:55], v[62:63]
	v_cmp_le_f32_e32 vcc, 0, v4
	v_pk_add_f32 v[42:43], v[42:43], 1.0 op_sel_hi:[1,0] neg_lo:[1,0] neg_hi:[1,0]
	s_lshl_b32 s20, s90, 2
	v_cndmask_b32_e32 v55, v63, v55, vcc
	v_cmp_le_f32_e32 vcc, 0, v67
	s_lshl_b32 s21, s71, 9
	s_add_i32 s20, s20, s21
	v_cndmask_b32_e32 v54, v62, v54, vcc
	v_pk_mul_f32 v[54:55], v[42:43], v[54:55]
	s_mov_b64 s[34:35], 0x18000
	v_pk_mul_f32 v[52:53], v[52:53], v[54:55]
	s_add_i32 s20, s20, s70
	v_cvt_pk_bf16_f32 v4, v52, v53
	v_pk_add_f32 v[52:53], v[44:45], 1.0 op_sel_hi:[1,0] neg_lo:[1,0] neg_hi:[1,0]
	v_add_f32_e32 v44, v148, v150
	v_add_f32_e32 v67, v44, v139
	v_lshlrev_b32_e32 v139, 16, v5
	v_and_b32_e32 v5, 0xffff0000, v5
	v_mul_f32_e64 v54, |v139|, s26
	v_exp_f32_e32 v54, v54
	v_mul_f32_e64 v55, |v5|, s26
	v_exp_f32_e32 v55, v55
	v_add_f32_e32 v45, v147, v149
	v_add_f32_e32 v138, v45, v138
	v_add_f32_e32 v45, 1.0, v54
	v_rcp_f32_e32 v62, v45
	v_add_f32_e32 v45, 1.0, v55
	v_rcp_f32_e32 v63, v45
	v_sub_f32_e32 v44, v89, v67
	v_sub_f32_e32 v45, v90, v138
	v_mul_f32_e32 v44, 0x3fb8aa3b, v44
	v_mul_f32_e32 v45, 0x3fb8aa3b, v45
	v_exp_f32_e32 v44, v44
	v_exp_f32_e32 v45, v45
	v_pk_mul_f32 v[54:55], v[54:55], v[62:63]
	v_cmp_le_f32_e32 vcc, 0, v5
	v_lshl_add_u64 v[36:37], v[48:49], 0, s[34:35]
	s_mov_b64 s[34:35], 0x30000
	v_cndmask_b32_e32 v55, v63, v55, vcc
	v_cmp_le_f32_e32 vcc, 0, v139
	v_lshlrev_b32_e32 v139, 16, v6
	v_and_b32_e32 v6, 0xffff0000, v6
	v_cndmask_b32_e32 v54, v62, v54, vcc
	v_pk_mul_f32 v[54:55], v[52:53], v[54:55]
	v_cmp_le_f32_e32 vcc, 0, v6
	v_pk_mul_f32 v[44:45], v[44:45], v[54:55]
	v_pk_add_f32 v[54:55], v[46:47], 1.0 op_sel_hi:[1,0] neg_lo:[1,0] neg_hi:[1,0]
	v_mul_f32_e64 v46, |v139|, s26
	v_exp_f32_e32 v46, v46
	v_mul_f32_e64 v47, |v6|, s26
	v_exp_f32_e32 v47, v47
	v_cvt_pk_bf16_f32 v5, v44, v45
	v_add_f32_e32 v45, v140, v142
	v_add_f32_e32 v131, v45, v131
	v_add_f32_e32 v45, 1.0, v46
	v_rcp_f32_e32 v62, v45
	v_add_f32_e32 v45, 1.0, v47
	v_add_f32_e32 v44, v141, v143
	v_rcp_f32_e32 v63, v45
	v_add_f32_e32 v133, v44, v133
	v_sub_f32_e32 v44, v93, v133
	v_sub_f32_e32 v45, v94, v131
	v_mul_f32_e32 v44, 0x3fb8aa3b, v44
	v_mul_f32_e32 v45, 0x3fb8aa3b, v45
	v_exp_f32_e32 v44, v44
	v_exp_f32_e32 v45, v45
	v_pk_mul_f32 v[46:47], v[46:47], v[62:63]
	s_ashr_i32 s21, s20, 31
	v_cndmask_b32_e32 v47, v63, v47, vcc
	v_cmp_le_f32_e32 vcc, 0, v139
	v_lshl_add_u64 v[76:77], v[48:49], 0, s[34:35]
	v_or_b32_e32 v128, 16, v114
	v_cndmask_b32_e32 v46, v62, v46, vcc
	v_pk_mul_f32 v[46:47], v[54:55], v[46:47]
	v_or_b32_e32 v127, 32, v114
	v_pk_mul_f32 v[44:45], v[44:45], v[46:47]
	v_or_b32_e32 v126, 48, v114
; __device__ __forceinline__ void ld8bf(const bf16_t* p, float (&o)[8]) { unpack8(*(const u32x4*)p, o); }
; __device__ __forceinline__ float sigmoidf_(float x) { return __builtin_amdgcn_rcpf(1.0f + __expf(-x)); }
; __device__ __forceinline__ bf16x8 pack_frag(const float (&v)[8]) { return __builtin_bit_cast(bf16x8, pack8(v)); }
; __device__ __forceinline__ void hg_lf_key(float fp, float lb, float& lf, float& key) {
;     const float e = __expf(-fabsf(fp));
;     const float rc = __builtin_amdgcn_rcpf(1.0f + e);
;     const float sp = fp >= 0.f ? rc : e * rc;
;     const float sn = fp >= 0.f ? e * rc : rc;
;     const float lsig = (fp >= 0.f ? 0.f : fp) + __logf(rc);
;     lf = (lb == 0.f) ? lsig : __logf(lb + (1.0f - lb) * sp); key = (1.0f - lb) * sn;
; }
; __device__ __forceinline__ void w_hg_m3(const Args& a, int l, unsigned char* ws, const bf16_t* proj, bf16_t* y, LAS unsigned char* wl, int b, int ck_, int h, int lane) {
;     ...
;         for (int tb = 0; tb < 4; ++tb) { float fp[8], qv[8], a1[8], a2[8];
;             ld8bf(fsrc + (size_t)(16 * tb + lo) * NIN, fp); ld8bf(proj + (size_t)(row0 + 16 * tb + lo) * NIN + C_HQ + 64 * h + 32 * kk + 8 * fq, qv);
; #pragma unroll
;             for (int j = 0; j < 8; ++j) { float lf, key; hg_lf_key(fp[j], lbv[j], lf, key);
;                 const float q = qv[j] * sigmoidf_(qv[j]); a1[j] = q * __expf(bb[tb][j] - r31[j]); a2[j] = key * __expf(r31[j] - bb[tb][j]); }
;             Qf[tb][kk] = pack_frag(a1); Kf[tb][kk] = pack_frag(a2); }
	v_cvt_pk_bf16_f32 v6, v44, v45
	v_add_f32_e32 v45, v134, v136
	v_lshlrev_b32_e32 v134, 16, v7
	v_and_b32_e32 v7, 0xffff0000, v7
	v_mul_f32_e64 v46, |v134|, s26
	v_exp_f32_e32 v46, v46
	v_mul_f32_e64 v47, |v7|, s26
	v_exp_f32_e32 v47, v47
	v_add_f32_e32 v125, v45, v125
	v_add_f32_e32 v45, 1.0, v46
	v_rcp_f32_e32 v62, v45
	v_add_f32_e32 v45, 1.0, v47
	v_add_f32_e32 v44, v135, v137
	v_rcp_f32_e32 v63, v45
	v_add_f32_e32 v129, v44, v129
	v_sub_f32_e32 v44, v97, v129
	v_sub_f32_e32 v45, v98, v125
	v_mul_f32_e32 v44, 0x3fb8aa3b, v44
	v_mul_f32_e32 v45, 0x3fb8aa3b, v45
	v_exp_f32_e32 v44, v44
	v_exp_f32_e32 v45, v45
	v_pk_mul_f32 v[46:47], v[46:47], v[62:63]
	v_cmp_le_f32_e32 vcc, 0, v7
	s_lshl_b64 s[40:41], s[20:21], 13
	s_nop 0
	v_cndmask_b32_e32 v47, v63, v47, vcc
	v_cmp_le_f32_e32 vcc, 0, v134
	s_nop 1
	v_cndmask_b32_e32 v46, v62, v46, vcc
	v_pk_mul_f32 v[46:47], v[40:41], v[46:47]
	s_nop 0
	v_pk_mul_f32 v[44:45], v[44:45], v[46:47]
	s_nop 0
	v_cvt_pk_bf16_f32 v7, v44, v45
	v_sub_f32_e32 v44, v66, v73
	v_mul_f32_e32 v46, 0x3fb8aa3b, v44
	v_lshlrev_b32_e32 v44, 16, v8
	v_and_b32_e32 v45, 0xffff0000, v8
	v_mul_f32_e32 v8, 0xbfb8aa3b, v44
	v_exp_f32_e32 v8, v8
	v_mul_f32_e32 v47, 0xbfb8aa3b, v45
	v_exp_f32_e32 v47, v47
	v_lshlrev_b32_e32 v66, 16, v9
	v_add_f32_e32 v8, 1.0, v8
	v_rcp_f32_e32 v62, v8
	v_add_f32_e32 v8, 1.0, v47
	v_rcp_f32_e32 v63, v8
	v_sub_f32_e32 v8, v145, v74
	v_mul_f32_e32 v8, 0x3fb8aa3b, v8
	v_exp_f32_e32 v47, v8
	v_sub_f32_e32 v8, v67, v89
	v_and_b32_e32 v67, 0xffff0000, v9
	v_mul_f32_e32 v9, 0xbfb8aa3b, v66
	v_pk_mul_f32 v[44:45], v[62:63], v[44:45]
	v_exp_f32_e32 v9, v9
	v_mul_f32_e32 v63, 0xbfb8aa3b, v67
	v_exp_f32_e32 v63, v63
	v_mul_f32_e32 v8, 0x3fb8aa3b, v8
	v_add_f32_e32 v9, 1.0, v9
	v_exp_f32_e32 v62, v8
	v_sub_f32_e32 v8, v138, v90
	v_rcp_f32_e32 v134, v9
	v_add_f32_e32 v9, 1.0, v63
	v_exp_f32_e32 v46, v46
	v_mul_f32_e32 v8, 0x3fb8aa3b, v8
	v_rcp_f32_e32 v135, v9
	v_exp_f32_e32 v63, v8
	v_pk_mul_f32 v[8:9], v[46:47], v[44:45]
	v_pk_mul_f32 v[44:45], v[134:135], v[66:67]
	s_nop 0
	v_pk_mul_f32 v[44:45], v[62:63], v[44:45]
	v_cvt_pk_bf16_f32 v8, v8, v9
	v_cvt_pk_bf16_f32 v9, v44, v45
	v_sub_f32_e32 v44, v133, v93
	v_mul_f32_e32 v46, 0x3fb8aa3b, v44
	v_lshlrev_b32_e32 v44, 16, v10
	v_and_b32_e32 v45, 0xffff0000, v10
	v_mul_f32_e32 v10, 0xbfb8aa3b, v44
	v_exp_f32_e32 v10, v10
	v_mul_f32_e32 v47, 0xbfb8aa3b, v45
	v_exp_f32_e32 v47, v47
	v_lshlrev_b32_e32 v66, 16, v11
	v_add_f32_e32 v10, 1.0, v10
	v_rcp_f32_e32 v62, v10
	v_add_f32_e32 v10, 1.0, v47
	v_rcp_f32_e32 v63, v10
	v_and_b32_e32 v67, 0xffff0000, v11
	v_mul_f32_e32 v11, 0xbfb8aa3b, v66
	v_exp_f32_e32 v11, v11
	v_pk_mul_f32 v[44:45], v[62:63], v[44:45]
	v_mul_f32_e32 v63, 0xbfb8aa3b, v67
	v_sub_f32_e32 v10, v131, v94
	v_exp_f32_e32 v63, v63
	v_mul_f32_e32 v10, 0x3fb8aa3b, v10
	v_exp_f32_e32 v47, v10
	v_sub_f32_e32 v10, v129, v97
	v_mul_f32_e32 v10, 0x3fb8aa3b, v10
	v_add_f32_e32 v11, 1.0, v11
	v_exp_f32_e32 v62, v10
	v_sub_f32_e32 v10, v125, v98
	v_rcp_f32_e32 v134, v11
	v_add_f32_e32 v11, 1.0, v63
	v_exp_f32_e32 v46, v46
	v_mul_f32_e32 v10, 0x3fb8aa3b, v10
	v_rcp_f32_e32 v135, v11
	v_exp_f32_e32 v63, v10
	v_pk_mul_f32 v[10:11], v[46:47], v[44:45]
	v_pk_mul_f32 v[44:45], v[134:135], v[66:67]
	s_nop 0
	v_pk_mul_f32 v[44:45], v[62:63], v[44:45]
	v_cvt_pk_bf16_f32 v10, v10, v11
	v_cvt_pk_bf16_f32 v11, v44, v45
	v_sub_f32_e32 v44, v97, v121
	v_lshlrev_b32_e32 v66, 16, v31
	v_mul_f32_e32 v46, 0x3fb8aa3b, v44
	v_and_b32_e32 v31, 0xffff0000, v31
	v_mul_f32_e64 v44, |v66|, s26
	v_exp_f32_e32 v44, v44
	v_mul_f32_e64 v45, |v31|, s26
	v_exp_f32_e32 v45, v45
	v_cmp_le_f32_e32 vcc, 0, v31
	v_add_f32_e32 v47, 1.0, v44
	v_rcp_f32_e32 v62, v47
	v_add_f32_e32 v47, 1.0, v45
	v_rcp_f32_e32 v63, v47
	v_and_b32_e32 v67, 0xffff0000, v15
	v_sub_f32_e32 v31, v121, v97
	v_sub_f32_e32 v47, v98, v122
	v_pk_mul_f32 v[44:45], v[44:45], v[62:63]
	v_mul_f32_e32 v31, 0x3fb8aa3b, v31
	v_cndmask_b32_e32 v45, v63, v45, vcc
	v_cmp_le_f32_e32 vcc, 0, v66
	v_lshlrev_b32_e32 v66, 16, v15
	v_mul_f32_e32 v15, 0xbfb8aa3b, v66
	v_exp_f32_e32 v15, v15
	v_mul_f32_e32 v63, 0xbfb8aa3b, v67
	v_exp_f32_e32 v63, v63
	v_mul_f32_e32 v47, 0x3fb8aa3b, v47
	v_add_f32_e32 v15, 1.0, v15
	v_cndmask_b32_e32 v44, v62, v44, vcc
	v_exp_f32_e32 v62, v31
	v_sub_f32_e32 v31, v122, v98
	v_rcp_f32_e32 v134, v15
	v_add_f32_e32 v15, 1.0, v63
	v_lshlrev_b32_e32 v121, 16, v30
	v_exp_f32_e32 v46, v46
	v_exp_f32_e32 v47, v47
	v_mul_f32_e32 v31, 0x3fb8aa3b, v31
	v_rcp_f32_e32 v135, v15
	v_and_b32_e32 v122, 0xffff0000, v30
	v_mul_f32_e64 v30, |v121|, s26
	v_exp_f32_e32 v63, v31
	v_exp_f32_e32 v30, v30
	v_mul_f32_e64 v31, |v122|, s26
	v_exp_f32_e32 v31, v31
	v_pk_mul_f32 v[44:45], v[40:41], v[44:45]
	v_sub_f32_e32 v15, v93, v118
	v_pk_mul_f32 v[44:45], v[46:47], v[44:45]
	v_pk_mul_f32 v[46:47], v[134:135], v[66:67]
	v_mul_f32_e32 v15, 0x3fb8aa3b, v15
	v_pk_mul_f32 v[46:47], v[62:63], v[46:47]
	v_exp_f32_e32 v62, v15
	v_add_f32_e32 v15, 1.0, v30
	v_rcp_f32_e32 v66, v15
	v_add_f32_e32 v15, 1.0, v31
	v_rcp_f32_e32 v67, v15
	v_sub_f32_e32 v15, v94, v119
	v_mul_f32_e32 v15, 0x3fb8aa3b, v15
	v_exp_f32_e32 v63, v15
	v_pk_mul_f32 v[30:31], v[30:31], v[66:67]
	v_cmp_le_f32_e32 vcc, 0, v122
	v_sub_f32_e32 v15, v118, v93
	v_mul_f32_e32 v15, 0x3fb8aa3b, v15
	v_cndmask_b32_e32 v31, v67, v31, vcc
	v_cmp_le_f32_e32 vcc, 0, v121
	v_lshlrev_b32_e32 v118, 16, v14
	v_lshlrev_b32_e32 v134, 16, v13
	v_cndmask_b32_e32 v30, v66, v30, vcc
	v_exp_f32_e32 v66, v15
	v_sub_f32_e32 v15, v119, v94
	v_and_b32_e32 v119, 0xffff0000, v14
	v_mul_f32_e32 v14, 0xbfb8aa3b, v118
	v_mul_f32_e32 v67, 0xbfb8aa3b, v119
	v_exp_f32_e32 v14, v14
	v_exp_f32_e32 v67, v67
; __device__ __forceinline__ void ld8bf(const bf16_t* p, float (&o)[8]) { unpack8(*(const u32x4*)p, o); }
; __device__ __forceinline__ float sigmoidf_(float x) { return __builtin_amdgcn_rcpf(1.0f + __expf(-x)); }
; __device__ __forceinline__ bf16x8 pack_frag(const float (&v)[8]) { return __builtin_bit_cast(bf16x8, pack8(v)); }
; __device__ __forceinline__ void hg_lf_key(float fp, float lb, float& lf, float& key) {
;     const float e = __expf(-fabsf(fp));
;     const float rc = __builtin_amdgcn_rcpf(1.0f + e);
;     const float sp = fp >= 0.f ? rc : e * rc;
;     const float sn = fp >= 0.f ? e * rc : rc;
;     const float lsig = (fp >= 0.f ? 0.f : fp) + __logf(rc);
;     lf = (lb == 0.f) ? lsig : __logf(lb + (1.0f - lb) * sp); key = (1.0f - lb) * sn;
; }
; __device__ __forceinline__ void w_hg_m3(const Args& a, int l, unsigned char* ws, const bf16_t* proj, bf16_t* y, LAS unsigned char* wl, int b, int ck_, int h, int lane) {
;     ...
;         for (int tb = 0; tb < 4; ++tb) { float fp[8], qv[8], a1[8], a2[8];
;             ld8bf(fsrc + (size_t)(16 * tb + lo) * NIN, fp); ld8bf(proj + (size_t)(row0 + 16 * tb + lo) * NIN + C_HQ + 64 * h + 32 * kk + 8 * fq, qv);
; #pragma unroll
;             for (int j = 0; j < 8; ++j) { float lf, key; hg_lf_key(fp[j], lbv[j], lf, key);
;                 const float q = qv[j] * sigmoidf_(qv[j]); a1[j] = q * __expf(bb[tb][j] - r31[j]); a2[j] = key * __expf(r31[j] - bb[tb][j]); }
;             Qf[tb][kk] = pack_frag(a1); Kf[tb][kk] = pack_frag(a2); }
	v_mul_f32_e32 v121, 0x3fb8aa3b, v15
	v_pk_mul_f32 v[30:31], v[54:55], v[30:31]
	v_add_f32_e32 v14, 1.0, v14
	v_add_f32_e32 v15, 1.0, v67
	v_rcp_f32_e32 v14, v14
	v_rcp_f32_e32 v15, v15
	v_exp_f32_e32 v67, v121
	v_pk_mul_f32 v[30:31], v[62:63], v[30:31]
	v_lshlrev_b32_e32 v121, 16, v29
	v_pk_mul_f32 v[14:15], v[14:15], v[118:119]
	v_and_b32_e32 v29, 0xffff0000, v29
	v_pk_mul_f32 v[62:63], v[66:67], v[14:15]
	v_sub_f32_e32 v14, v89, v115
	v_mul_f32_e32 v66, 0x3fb8aa3b, v14
	v_mul_f32_e64 v14, |v121|, s26
	v_exp_f32_e32 v14, v14
	v_mul_f32_e64 v15, |v29|, s26
	v_exp_f32_e32 v15, v15
	v_and_b32_e32 v135, 0xffff0000, v13
	v_add_f32_e32 v67, 1.0, v14
	v_rcp_f32_e32 v118, v67
	v_add_f32_e32 v67, 1.0, v15
	v_rcp_f32_e32 v119, v67
	v_mul_f32_e32 v13, 0xbfb8aa3b, v134
	v_cmp_le_f32_e32 vcc, 0, v29
	v_sub_f32_e32 v29, v115, v89
	v_exp_f32_e32 v13, v13
	v_mul_f32_e32 v115, 0xbfb8aa3b, v135
	v_exp_f32_e32 v115, v115
	v_pk_mul_f32 v[14:15], v[14:15], v[118:119]
	v_sub_f32_e32 v67, v90, v116
	v_cndmask_b32_e32 v15, v119, v15, vcc
	v_cmp_le_f32_e32 vcc, 0, v121
	v_mul_f32_e32 v29, 0x3fb8aa3b, v29
	v_add_f32_e32 v13, 1.0, v13
	v_mul_f32_e32 v67, 0x3fb8aa3b, v67
	v_cndmask_b32_e32 v14, v118, v14, vcc
	v_exp_f32_e32 v118, v29
	v_sub_f32_e32 v29, v116, v90
	v_rcp_f32_e32 v136, v13
	v_add_f32_e32 v13, 1.0, v115
	v_lshlrev_b32_e32 v115, 16, v28
	v_exp_f32_e32 v66, v66
	v_exp_f32_e32 v67, v67
	v_mul_f32_e32 v29, 0x3fb8aa3b, v29
	v_rcp_f32_e32 v137, v13
	v_and_b32_e32 v116, 0xffff0000, v28
	v_mul_f32_e64 v28, |v115|, s26
	v_exp_f32_e32 v119, v29
	v_exp_f32_e32 v28, v28
	v_mul_f32_e64 v29, |v116|, s26
	v_exp_f32_e32 v29, v29
	v_pk_mul_f32 v[14:15], v[52:53], v[14:15]
	v_sub_f32_e32 v13, v73, v111
	v_pk_mul_f32 v[14:15], v[66:67], v[14:15]
	v_pk_mul_f32 v[66:67], v[136:137], v[134:135]
	v_mul_f32_e32 v13, 0x3fb8aa3b, v13
	v_pk_mul_f32 v[66:67], v[118:119], v[66:67]
	v_exp_f32_e32 v118, v13
	v_add_f32_e32 v13, 1.0, v28
	v_rcp_f32_e32 v134, v13
	v_add_f32_e32 v13, 1.0, v29
	v_rcp_f32_e32 v135, v13
	v_sub_f32_e32 v13, v74, v112
	v_mul_f32_e32 v13, 0x3fb8aa3b, v13
	v_lshlrev_b32_e32 v136, 16, v12
	v_and_b32_e32 v137, 0xffff0000, v12
	v_exp_f32_e32 v119, v13
	v_sub_f32_e32 v13, v111, v73
	v_mul_f32_e32 v12, 0xbfb8aa3b, v136
	v_mul_f32_e32 v111, 0xbfb8aa3b, v137
	v_exp_f32_e32 v12, v12
	v_exp_f32_e32 v111, v111
	v_pk_mul_f32 v[28:29], v[28:29], v[134:135]
	v_cmp_le_f32_e32 vcc, 0, v116
	v_mul_f32_e32 v13, 0x3fb8aa3b, v13
	v_add_f32_e32 v12, 1.0, v12
	v_cndmask_b32_e32 v29, v135, v29, vcc
	v_cmp_le_f32_e32 vcc, 0, v115
	v_rcp_f32_e32 v12, v12
	s_nop 0
	v_cndmask_b32_e32 v28, v134, v28, vcc
	v_exp_f32_e32 v134, v13
	v_sub_f32_e32 v13, v112, v74
	v_mul_f32_e32 v112, 0x3fb8aa3b, v13
	v_add_f32_e32 v13, 1.0, v111
	v_rcp_f32_e32 v13, v13
	v_exp_f32_e32 v135, v112
	v_pk_mul_f32 v[28:29], v[42:43], v[28:29]
	v_pk_mul_f32 v[12:13], v[12:13], v[136:137]
	v_pk_mul_f32 v[28:29], v[118:119], v[28:29]
	v_pk_mul_f32 v[118:119], v[134:135], v[12:13]
	v_cvt_pk_bf16_f32 v12, v28, v29
	v_cvt_pk_bf16_f32 v13, v14, v15
	v_cvt_pk_bf16_f32 v15, v44, v45
	v_cvt_pk_bf16_f32 v29, v66, v67
	v_sub_f32_e32 v44, v97, v107
	v_lshlrev_b32_e32 v66, 16, v35
	v_cvt_pk_bf16_f32 v14, v30, v31
	v_cvt_pk_bf16_f32 v31, v46, v47
	v_mul_f32_e32 v46, 0x3fb8aa3b, v44
	v_and_b32_e32 v35, 0xffff0000, v35
	v_mul_f32_e64 v44, |v66|, s26
	v_exp_f32_e32 v44, v44
	v_mul_f32_e64 v45, |v35|, s26
	v_exp_f32_e32 v45, v45
	v_cvt_pk_bf16_f32 v30, v62, v63
	v_add_f32_e32 v47, 1.0, v44
	v_rcp_f32_e32 v62, v47
	v_add_f32_e32 v47, 1.0, v45
	v_rcp_f32_e32 v63, v47
	v_cmp_le_f32_e32 vcc, 0, v35
	v_and_b32_e32 v67, 0xffff0000, v19
	v_sub_f32_e32 v35, v107, v97
	v_pk_mul_f32 v[44:45], v[44:45], v[62:63]
	v_sub_f32_e32 v47, v98, v109
	v_cndmask_b32_e32 v45, v63, v45, vcc
	v_cmp_le_f32_e32 vcc, 0, v66
	v_lshlrev_b32_e32 v66, 16, v19
	v_mul_f32_e32 v19, 0xbfb8aa3b, v66
	v_exp_f32_e32 v19, v19
	v_mul_f32_e32 v63, 0xbfb8aa3b, v67
	v_exp_f32_e32 v63, v63
	v_mul_f32_e32 v35, 0x3fb8aa3b, v35
	v_add_f32_e32 v19, 1.0, v19
	v_cvt_pk_bf16_f32 v28, v118, v119
	v_mul_f32_e32 v47, 0x3fb8aa3b, v47
	v_cndmask_b32_e32 v44, v62, v44, vcc
	v_exp_f32_e32 v62, v35
	v_sub_f32_e32 v35, v109, v98
	v_rcp_f32_e32 v118, v19
	v_add_f32_e32 v19, 1.0, v63
	v_lshlrev_b32_e32 v107, 16, v34
	v_exp_f32_e32 v46, v46
	v_exp_f32_e32 v47, v47
	v_mul_f32_e32 v35, 0x3fb8aa3b, v35
	v_rcp_f32_e32 v119, v19
	v_and_b32_e32 v109, 0xffff0000, v34
	v_mul_f32_e64 v34, |v107|, s26
	v_exp_f32_e32 v63, v35
	v_exp_f32_e32 v34, v34
	v_mul_f32_e64 v35, |v109|, s26
	v_exp_f32_e32 v35, v35
	v_pk_mul_f32 v[44:45], v[40:41], v[44:45]
	v_sub_f32_e32 v19, v93, v104
	v_pk_mul_f32 v[44:45], v[46:47], v[44:45]
	v_pk_mul_f32 v[46:47], v[118:119], v[66:67]
	v_mul_f32_e32 v19, 0x3fb8aa3b, v19
	v_pk_mul_f32 v[62:63], v[62:63], v[46:47]
	v_exp_f32_e32 v46, v19
	v_add_f32_e32 v19, 1.0, v34
	v_rcp_f32_e32 v66, v19
	v_add_f32_e32 v19, 1.0, v35
	v_rcp_f32_e32 v67, v19
	v_sub_f32_e32 v19, v94, v105
	v_mul_f32_e32 v19, 0x3fb8aa3b, v19
	v_exp_f32_e32 v47, v19
	v_pk_mul_f32 v[34:35], v[34:35], v[66:67]
	v_cmp_le_f32_e32 vcc, 0, v109
	v_sub_f32_e32 v19, v104, v93
	v_mul_f32_e32 v19, 0x3fb8aa3b, v19
	v_cndmask_b32_e32 v35, v67, v35, vcc
	v_cmp_le_f32_e32 vcc, 0, v107
	v_lshlrev_b32_e32 v104, 16, v18
	v_lshlrev_b32_e32 v118, 16, v17
	v_cndmask_b32_e32 v34, v66, v34, vcc
	v_exp_f32_e32 v66, v19
	v_sub_f32_e32 v19, v105, v94
	v_and_b32_e32 v105, 0xffff0000, v18
	v_mul_f32_e32 v18, 0xbfb8aa3b, v104
	v_mul_f32_e32 v67, 0xbfb8aa3b, v105
	v_exp_f32_e32 v18, v18
	v_exp_f32_e32 v67, v67
	v_mul_f32_e32 v107, 0x3fb8aa3b, v19
	v_pk_mul_f32 v[34:35], v[54:55], v[34:35]
	v_add_f32_e32 v18, 1.0, v18
	v_add_f32_e32 v19, 1.0, v67
; __device__ __forceinline__ void ld8bf(const bf16_t* p, float (&o)[8]) { unpack8(*(const u32x4*)p, o); }
; __device__ __forceinline__ float sigmoidf_(float x) { return __builtin_amdgcn_rcpf(1.0f + __expf(-x)); }
; __device__ __forceinline__ bf16x8 pack_frag(const float (&v)[8]) { return __builtin_bit_cast(bf16x8, pack8(v)); }
; __device__ __forceinline__ void hg_lf_key(float fp, float lb, float& lf, float& key) {
;     const float e = __expf(-fabsf(fp));
;     const float rc = __builtin_amdgcn_rcpf(1.0f + e);
;     const float sp = fp >= 0.f ? rc : e * rc;
;     const float sn = fp >= 0.f ? e * rc : rc;
;     const float lsig = (fp >= 0.f ? 0.f : fp) + __logf(rc);
;     lf = (lb == 0.f) ? lsig : __logf(lb + (1.0f - lb) * sp); key = (1.0f - lb) * sn;
; }
; __device__ __forceinline__ void w_hg_m3(const Args& a, int l, unsigned char* ws, const bf16_t* proj, bf16_t* y, LAS unsigned char* wl, int b, int ck_, int h, int lane) {
;     ...
;         for (int tb = 0; tb < 4; ++tb) { float fp[8], qv[8], a1[8], a2[8];
;             ld8bf(fsrc + (size_t)(16 * tb + lo) * NIN, fp); ld8bf(proj + (size_t)(row0 + 16 * tb + lo) * NIN + C_HQ + 64 * h + 32 * kk + 8 * fq, qv);
; #pragma unroll
;             for (int j = 0; j < 8; ++j) { float lf, key; hg_lf_key(fp[j], lbv[j], lf, key);
;                 const float q = qv[j] * sigmoidf_(qv[j]); a1[j] = q * __expf(bb[tb][j] - r31[j]); a2[j] = key * __expf(r31[j] - bb[tb][j]); }
;             Qf[tb][kk] = pack_frag(a1); Kf[tb][kk] = pack_frag(a2); }
	v_rcp_f32_e32 v18, v18
	v_rcp_f32_e32 v19, v19
	v_exp_f32_e32 v67, v107
	v_pk_mul_f32 v[34:35], v[46:47], v[34:35]
	v_lshlrev_b32_e32 v107, 16, v33
	v_pk_mul_f32 v[18:19], v[18:19], v[104:105]
	v_and_b32_e32 v33, 0xffff0000, v33
	v_pk_mul_f32 v[46:47], v[66:67], v[18:19]
	v_sub_f32_e32 v18, v89, v101
	v_mul_f32_e32 v66, 0x3fb8aa3b, v18
	v_mul_f32_e64 v18, |v107|, s26
	v_exp_f32_e32 v18, v18
	v_mul_f32_e64 v19, |v33|, s26
	v_exp_f32_e32 v19, v19
	v_and_b32_e32 v119, 0xffff0000, v17
	v_add_f32_e32 v67, 1.0, v18
	v_rcp_f32_e32 v104, v67
	v_add_f32_e32 v67, 1.0, v19
	v_rcp_f32_e32 v105, v67
	v_mul_f32_e32 v17, 0xbfb8aa3b, v118
	v_cmp_le_f32_e32 vcc, 0, v33
	v_sub_f32_e32 v33, v101, v89
	v_exp_f32_e32 v17, v17
	v_mul_f32_e32 v101, 0xbfb8aa3b, v119
	v_exp_f32_e32 v101, v101
	v_pk_mul_f32 v[18:19], v[18:19], v[104:105]
	v_sub_f32_e32 v67, v90, v102
	v_cndmask_b32_e32 v19, v105, v19, vcc
	v_cmp_le_f32_e32 vcc, 0, v107
	v_mul_f32_e32 v33, 0x3fb8aa3b, v33
	v_add_f32_e32 v17, 1.0, v17
	v_mul_f32_e32 v67, 0x3fb8aa3b, v67
	v_cndmask_b32_e32 v18, v104, v18, vcc
	v_exp_f32_e32 v104, v33
	v_sub_f32_e32 v33, v102, v90
	v_rcp_f32_e32 v134, v17
	v_add_f32_e32 v17, 1.0, v101
	v_lshlrev_b32_e32 v101, 16, v32
	v_exp_f32_e32 v66, v66
	v_exp_f32_e32 v67, v67
	v_mul_f32_e32 v33, 0x3fb8aa3b, v33
	v_rcp_f32_e32 v135, v17
	v_and_b32_e32 v102, 0xffff0000, v32
	v_mul_f32_e64 v32, |v101|, s26
	v_exp_f32_e32 v105, v33
	v_exp_f32_e32 v32, v32
	v_mul_f32_e64 v33, |v102|, s26
	v_exp_f32_e32 v33, v33
	v_pk_mul_f32 v[18:19], v[52:53], v[18:19]
	v_sub_f32_e32 v17, v73, v99
	v_pk_mul_f32 v[18:19], v[66:67], v[18:19]
	v_pk_mul_f32 v[66:67], v[134:135], v[118:119]
	v_mul_f32_e32 v17, 0x3fb8aa3b, v17
	v_pk_mul_f32 v[66:67], v[104:105], v[66:67]
	v_exp_f32_e32 v104, v17
	v_add_f32_e32 v17, 1.0, v32
	v_rcp_f32_e32 v118, v17
	v_add_f32_e32 v17, 1.0, v33
	v_rcp_f32_e32 v119, v17
	v_sub_f32_e32 v17, v74, v100
	v_mul_f32_e32 v17, 0x3fb8aa3b, v17
	v_exp_f32_e32 v105, v17
	v_pk_mul_f32 v[32:33], v[32:33], v[118:119]
	v_cmp_le_f32_e32 vcc, 0, v102
	v_sub_f32_e32 v17, v99, v73
	v_mul_f32_e32 v17, 0x3fb8aa3b, v17
	v_cndmask_b32_e32 v33, v119, v33, vcc
	v_cmp_le_f32_e32 vcc, 0, v101
	v_and_b32_e32 v101, 0xffff0000, v16
	v_mul_f32_e32 v99, 0xbfb8aa3b, v101
	v_cndmask_b32_e32 v32, v118, v32, vcc
	v_exp_f32_e32 v118, v17
	v_sub_f32_e32 v17, v100, v74
	v_lshlrev_b32_e32 v100, 16, v16
	v_mul_f32_e32 v16, 0xbfb8aa3b, v100
	v_exp_f32_e32 v16, v16
	v_exp_f32_e32 v99, v99
	v_mul_f32_e32 v102, 0x3fb8aa3b, v17
	v_exp_f32_e32 v119, v102
	v_add_f32_e32 v16, 1.0, v16
	v_add_f32_e32 v17, 1.0, v99
	v_rcp_f32_e32 v16, v16
	v_rcp_f32_e32 v17, v17
	v_pk_mul_f32 v[32:33], v[42:43], v[32:33]
	v_cvt_pk_bf16_f32 v46, v46, v47
	v_pk_mul_f32 v[32:33], v[104:105], v[32:33]
	v_pk_mul_f32 v[16:17], v[16:17], v[100:101]
	v_cvt_pk_bf16_f32 v47, v62, v63
	v_pk_mul_f32 v[100:101], v[118:119], v[16:17]
	v_cvt_pk_bf16_f32 v16, v32, v33
	v_cvt_pk_bf16_f32 v17, v18, v19
	v_cvt_pk_bf16_f32 v19, v44, v45
	v_cvt_pk_bf16_f32 v45, v66, v67
	v_sub_f32_e32 v32, v97, v95
	v_lshlrev_b32_e32 v66, 16, v27
	v_cvt_pk_bf16_f32 v18, v34, v35
	v_mul_f32_e32 v34, 0x3fb8aa3b, v32
	v_and_b32_e32 v27, 0xffff0000, v27
	v_mul_f32_e64 v32, |v66|, s26
	v_exp_f32_e32 v32, v32
	v_mul_f32_e64 v33, |v27|, s26
	v_exp_f32_e32 v33, v33
	v_cmp_le_f32_e32 vcc, 0, v27
	v_add_f32_e32 v35, 1.0, v32
	v_rcp_f32_e32 v62, v35
	v_add_f32_e32 v35, 1.0, v33
	v_rcp_f32_e32 v63, v35
	v_and_b32_e32 v67, 0xffff0000, v23
	v_sub_f32_e32 v27, v95, v97
	v_sub_f32_e32 v35, v98, v96
	v_pk_mul_f32 v[32:33], v[32:33], v[62:63]
	v_mul_f32_e32 v27, 0x3fb8aa3b, v27
	v_cndmask_b32_e32 v33, v63, v33, vcc
	v_cmp_le_f32_e32 vcc, 0, v66
	v_lshlrev_b32_e32 v66, 16, v23
	v_mul_f32_e32 v23, 0xbfb8aa3b, v66
	v_exp_f32_e32 v23, v23
	v_mul_f32_e32 v63, 0xbfb8aa3b, v67
	v_exp_f32_e32 v63, v63
	v_mul_f32_e32 v35, 0x3fb8aa3b, v35
	v_add_f32_e32 v23, 1.0, v23
	v_cndmask_b32_e32 v32, v62, v32, vcc
	v_exp_f32_e32 v62, v27
	v_sub_f32_e32 v27, v96, v98
	v_rcp_f32_e32 v96, v23
	v_add_f32_e32 v23, 1.0, v63
	v_exp_f32_e32 v34, v34
	v_exp_f32_e32 v35, v35
	v_rcp_f32_e32 v97, v23
	v_pk_mul_f32 v[32:33], v[40:41], v[32:33]
	v_mul_f32_e32 v27, 0x3fb8aa3b, v27
	v_pk_mul_f32 v[32:33], v[34:35], v[32:33]
	v_pk_mul_f32 v[34:35], v[96:97], v[66:67]
	v_lshlrev_b32_e32 v66, 16, v26
	v_and_b32_e32 v67, 0xffff0000, v26
	v_mul_f32_e64 v26, |v66|, s26
	v_exp_f32_e32 v63, v27
	v_exp_f32_e32 v26, v26
	v_mul_f32_e64 v27, |v67|, s26
	v_exp_f32_e32 v27, v27
	v_sub_f32_e32 v23, v93, v91
	v_mul_f32_e32 v23, 0x3fb8aa3b, v23
	v_exp_f32_e32 v40, v23
	v_add_f32_e32 v23, 1.0, v26
	v_pk_mul_f32 v[34:35], v[62:63], v[34:35]
	v_rcp_f32_e32 v62, v23
	v_add_f32_e32 v23, 1.0, v27
	v_rcp_f32_e32 v63, v23
	v_cmp_le_f32_e32 vcc, 0, v67
	v_and_b32_e32 v67, 0xffff0000, v22
	v_sub_f32_e32 v23, v94, v92
	v_pk_mul_f32 v[26:27], v[26:27], v[62:63]
	v_mul_f32_e32 v23, 0x3fb8aa3b, v23
	v_cndmask_b32_e32 v27, v63, v27, vcc
	v_cmp_le_f32_e32 vcc, 0, v66
	v_lshlrev_b32_e32 v66, 16, v22
	v_mul_f32_e32 v22, 0xbfb8aa3b, v66
	v_mul_f32_e32 v63, 0xbfb8aa3b, v67
	v_exp_f32_e32 v22, v22
	v_exp_f32_e32 v63, v63
	v_exp_f32_e32 v41, v23
	v_sub_f32_e32 v23, v91, v93
	v_mul_f32_e32 v23, 0x3fb8aa3b, v23
	v_cndmask_b32_e32 v26, v62, v26, vcc
	v_exp_f32_e32 v62, v23
	v_sub_f32_e32 v23, v92, v94
	v_mul_f32_e32 v91, 0x3fb8aa3b, v23
	v_add_f32_e32 v22, 1.0, v22
	v_add_f32_e32 v23, 1.0, v63
	v_rcp_f32_e32 v22, v22
	v_rcp_f32_e32 v23, v23
	v_exp_f32_e32 v63, v91
	v_pk_mul_f32 v[26:27], v[54:55], v[26:27]
	v_cvt_pk_bf16_f32 v44, v100, v101
	v_pk_mul_f32 v[22:23], v[22:23], v[66:67]
	v_pk_mul_f32 v[26:27], v[40:41], v[26:27]
	v_pk_mul_f32 v[40:41], v[62:63], v[22:23]
; __device__ __forceinline__ float sigmoidf_(float x) { return __builtin_amdgcn_rcpf(1.0f + __expf(-x)); }
; __device__ __forceinline__ bf16x8 pack_frag(const float (&v)[8]) { return __builtin_bit_cast(bf16x8, pack8(v)); }
; __device__ __forceinline__ float row_sum_incl(float v) { v += dpp_shr0<1>(v); v += dpp_shr0<2>(v); v += dpp_shr0<4>(v); v += dpp_shr0<8>(v); return v; }
; __device__ __forceinline__ float bcast15(float v, int lane) { return bperm_f((lane & 48) | 15, v); }
; __device__ __forceinline__ void w_hg_scan(const float (&lbv)[8], const bf16_t* fsrc, int lane, float (&bb)[4][8], float (&r31)[8], float (&r63)[8]) {
;     ...
;     for (int tb = 0; tb < 4; ++tb) {
; #pragma unroll
;         for (int j = 0; j < 8; ++j) { const float v = row_sum_incl(bb[tb][j]) + carry[j]; bb[tb][j] = v; carry[j] = bcast15(v, lane); if (tb == 1) r31[j] = carry[j]; if (tb == 3) r63[j] = carry[j]; }
;         __builtin_amdgcn_sched_barrier(0);
;     }
; __device__ __forceinline__ void w_hg_m3(const Args& a, int l, unsigned char* ws, const bf16_t* proj, bf16_t* y, LAS unsigned char* wl, int b, int ck_, int h, int lane) {
;     ...
;             for (int j = 0; j < 8; ++j) { float lf, key; hg_lf_key(fp[j], lbv[j], lf, key);
;                 const float q = qv[j] * sigmoidf_(qv[j]); a1[j] = q * __expf(bb[tb][j] - r31[j]); a2[j] = key * __expf(r31[j] - bb[tb][j]); }
;             Qf[tb][kk] = pack_frag(a1); Kf[tb][kk] = pack_frag(a2); }
	v_sub_f32_e32 v22, v89, v75
	v_lshlrev_b32_e32 v66, 16, v25
	v_mul_f32_e32 v54, 0x3fb8aa3b, v22
	v_and_b32_e32 v25, 0xffff0000, v25
	v_mul_f32_e64 v22, |v66|, s26
	v_exp_f32_e32 v22, v22
	v_mul_f32_e64 v23, |v25|, s26
	v_exp_f32_e32 v23, v23
	v_cmp_le_f32_e32 vcc, 0, v25
	v_add_f32_e32 v55, 1.0, v22
	v_rcp_f32_e32 v62, v55
	v_add_f32_e32 v55, 1.0, v23
	v_rcp_f32_e32 v63, v55
	v_and_b32_e32 v67, 0xffff0000, v21
	v_sub_f32_e32 v25, v75, v89
	v_mul_f32_e32 v25, 0x3fb8aa3b, v25
	v_pk_mul_f32 v[22:23], v[22:23], v[62:63]
	v_sub_f32_e32 v55, v90, v88
	v_cndmask_b32_e32 v23, v63, v23, vcc
	v_cmp_le_f32_e32 vcc, 0, v66
	v_lshlrev_b32_e32 v66, 16, v21
	v_mul_f32_e32 v21, 0xbfb8aa3b, v66
	v_exp_f32_e32 v21, v21
	v_mul_f32_e32 v63, 0xbfb8aa3b, v67
	v_exp_f32_e32 v63, v63
	v_cndmask_b32_e32 v22, v62, v22, vcc
	v_add_f32_e32 v21, 1.0, v21
	v_exp_f32_e32 v62, v25
	v_sub_f32_e32 v25, v88, v90
	v_rcp_f32_e32 v88, v21
	v_add_f32_e32 v21, 1.0, v63
	v_rcp_f32_e32 v89, v21
	v_pk_mul_f32 v[22:23], v[52:53], v[22:23]
	v_mul_f32_e32 v55, 0x3fb8aa3b, v55
	v_mul_f32_e32 v25, 0x3fb8aa3b, v25
	v_pk_mul_f32 v[52:53], v[88:89], v[66:67]
	v_lshlrev_b32_e32 v66, 16, v24
	v_and_b32_e32 v67, 0xffff0000, v24
	v_mul_f32_e64 v24, |v66|, s26
	v_exp_f32_e32 v54, v54
	v_exp_f32_e32 v55, v55
	v_exp_f32_e32 v63, v25
	v_exp_f32_e32 v24, v24
	v_mul_f32_e64 v25, |v67|, s26
	v_exp_f32_e32 v25, v25
	v_sub_f32_e32 v21, v73, v2
	v_mul_f32_e32 v21, 0x3fb8aa3b, v21
	v_pk_mul_f32 v[22:23], v[54:55], v[22:23]
	v_pk_mul_f32 v[54:55], v[62:63], v[52:53]
	v_exp_f32_e32 v52, v21
	v_add_f32_e32 v21, 1.0, v24
	v_rcp_f32_e32 v62, v21
	v_add_f32_e32 v21, 1.0, v25
	v_rcp_f32_e32 v63, v21
	v_sub_f32_e32 v21, v74, v72
	v_cmp_le_f32_e32 vcc, 0, v67
	v_mul_f32_e32 v21, 0x3fb8aa3b, v21
	v_pk_mul_f32 v[24:25], v[24:25], v[62:63]
	v_and_b32_e32 v67, 0xffff0000, v20
	v_cndmask_b32_e32 v25, v63, v25, vcc
	v_cmp_le_f32_e32 vcc, 0, v66
	v_lshlrev_b32_e32 v66, 16, v20
	v_exp_f32_e32 v53, v21
	v_mul_f32_e32 v20, 0xbfb8aa3b, v66
	v_mul_f32_e32 v21, 0xbfb8aa3b, v67
	v_exp_f32_e32 v20, v20
	v_exp_f32_e32 v21, v21
	v_sub_f32_e32 v2, v2, v73
	v_mul_f32_e32 v2, 0x3fb8aa3b, v2
	v_cndmask_b32_e32 v24, v62, v24, vcc
	v_exp_f32_e32 v62, v2
	v_sub_f32_e32 v2, v72, v74
	v_add_f32_e32 v20, 1.0, v20
	v_add_f32_e32 v21, 1.0, v21
	v_mul_f32_e32 v2, 0x3fb8aa3b, v2
	v_rcp_f32_e32 v20, v20
	v_rcp_f32_e32 v21, v21
	v_exp_f32_e32 v63, v2
	v_pk_mul_f32 v[24:25], v[42:43], v[24:25]
	v_add_f32_dpp v2, v103, v103 row_shr:1 row_mask:0xf bank_mask:0xf bound_ctrl:1
	v_pk_mul_f32 v[24:25], v[52:53], v[24:25]
	v_pk_mul_f32 v[20:21], v[20:21], v[66:67]
	v_cvt_pk_bf16_f32 v53, v54, v55
	v_pk_mul_f32 v[42:43], v[62:63], v[20:21]
	v_cvt_pk_bf16_f32 v20, v24, v25
	v_cvt_pk_bf16_f32 v21, v22, v23
	v_cvt_pk_bf16_f32 v22, v26, v27
	v_cvt_pk_bf16_f32 v23, v32, v33
	v_cvt_pk_bf16_f32 v55, v34, v35
	v_add_f32_dpp v24, v106, v106 row_shr:1 row_mask:0xf bank_mask:0xf bound_ctrl:1
	v_add_f32_dpp v25, v110, v110 row_shr:1 row_mask:0xf bank_mask:0xf bound_ctrl:1
	v_add_f32_dpp v26, v113, v113 row_shr:1 row_mask:0xf bank_mask:0xf bound_ctrl:1
	v_add_f32_dpp v27, v117, v117 row_shr:1 row_mask:0xf bank_mask:0xf bound_ctrl:1
	v_add_f32_dpp v32, v120, v120 row_shr:1 row_mask:0xf bank_mask:0xf bound_ctrl:1
	v_add_f32_dpp v33, v123, v123 row_shr:1 row_mask:0xf bank_mask:0xf bound_ctrl:1
	v_add_f32_dpp v34, v124, v124 row_shr:1 row_mask:0xf bank_mask:0xf bound_ctrl:1
	v_add_f32_dpp v2, v2, v2 row_shr:2 row_mask:0xf bank_mask:0xf bound_ctrl:1
	v_add_f32_dpp v24, v24, v24 row_shr:2 row_mask:0xf bank_mask:0xf bound_ctrl:1
	v_add_f32_dpp v25, v25, v25 row_shr:2 row_mask:0xf bank_mask:0xf bound_ctrl:1
	v_add_f32_dpp v26, v26, v26 row_shr:2 row_mask:0xf bank_mask:0xf bound_ctrl:1
	v_add_f32_dpp v27, v27, v27 row_shr:2 row_mask:0xf bank_mask:0xf bound_ctrl:1
	v_add_f32_dpp v32, v32, v32 row_shr:2 row_mask:0xf bank_mask:0xf bound_ctrl:1
	v_add_f32_dpp v33, v33, v33 row_shr:2 row_mask:0xf bank_mask:0xf bound_ctrl:1
	v_add_f32_dpp v34, v34, v34 row_shr:2 row_mask:0xf bank_mask:0xf bound_ctrl:1
	v_add_f32_dpp v2, v2, v2 row_shr:4 row_mask:0xf bank_mask:0xf bound_ctrl:1
	v_add_f32_dpp v24, v24, v24 row_shr:4 row_mask:0xf bank_mask:0xf bound_ctrl:1
	v_add_f32_dpp v25, v25, v25 row_shr:4 row_mask:0xf bank_mask:0xf bound_ctrl:1
	v_add_f32_dpp v26, v26, v26 row_shr:4 row_mask:0xf bank_mask:0xf bound_ctrl:1
	v_add_f32_dpp v27, v27, v27 row_shr:4 row_mask:0xf bank_mask:0xf bound_ctrl:1
	v_add_f32_dpp v32, v32, v32 row_shr:4 row_mask:0xf bank_mask:0xf bound_ctrl:1
	v_add_f32_dpp v33, v33, v33 row_shr:4 row_mask:0xf bank_mask:0xf bound_ctrl:1
	v_add_f32_dpp v34, v34, v34 row_shr:4 row_mask:0xf bank_mask:0xf bound_ctrl:1
	v_add_f32_dpp v2, v2, v2 row_shr:8 row_mask:0xf bank_mask:0xf bound_ctrl:1
	v_add_f32_dpp v24, v24, v24 row_shr:8 row_mask:0xf bank_mask:0xf bound_ctrl:1
	v_add_f32_dpp v25, v25, v25 row_shr:8 row_mask:0xf bank_mask:0xf bound_ctrl:1
	v_add_f32_dpp v26, v26, v26 row_shr:8 row_mask:0xf bank_mask:0xf bound_ctrl:1
	v_add_f32_dpp v27, v27, v27 row_shr:8 row_mask:0xf bank_mask:0xf bound_ctrl:1
	v_add_f32_dpp v32, v32, v32 row_shr:8 row_mask:0xf bank_mask:0xf bound_ctrl:1
	v_add_f32_dpp v33, v33, v33 row_shr:8 row_mask:0xf bank_mask:0xf bound_ctrl:1
	v_add_f32_dpp v34, v34, v34 row_shr:8 row_mask:0xf bank_mask:0xf bound_ctrl:1
	v_cvt_pk_bf16_f32 v52, v42, v43
	v_cvt_pk_bf16_f32 v54, v40, v41
	v_add_f32_e32 v41, 0, v2
	v_add_f32_e32 v43, 0, v24
	v_add_f32_e32 v74, 0, v25
	v_add_f32_e32 v75, 0, v26
	v_add_f32_e32 v121, 0, v27
	v_add_f32_e32 v119, 0, v32
	v_add_f32_e32 v63, 0, v33
	v_add_f32_e32 v62, 0, v34
	ds_bpermute_b32 v2, v186, v41
	ds_bpermute_b32 v24, v186, v43
	ds_bpermute_b32 v25, v186, v74
	ds_bpermute_b32 v26, v186, v75
	ds_bpermute_b32 v27, v186, v121
	ds_bpermute_b32 v32, v186, v119
	ds_bpermute_b32 v33, v186, v63
	ds_bpermute_b32 v34, v186, v62
	v_add_f32_dpp v35, v130, v130 row_shr:1 row_mask:0xf bank_mask:0xf bound_ctrl:1
	s_nop 1
	v_add_f32_dpp v35, v35, v35 row_shr:2 row_mask:0xf bank_mask:0xf bound_ctrl:1
	s_nop 1
	v_add_f32_dpp v35, v35, v35 row_shr:4 row_mask:0xf bank_mask:0xf bound_ctrl:1
	s_nop 1
	v_add_f32_dpp v35, v35, v35 row_shr:8 row_mask:0xf bank_mask:0xf bound_ctrl:1
	s_waitcnt lgkmcnt(7)
; __device__ __forceinline__ float bperm_f(int src_lane, float v) { return __builtin_bit_cast(float, __builtin_amdgcn_ds_bpermute(src_lane << 2, __builtin_bit_cast(int, v))); }
; __device__ __forceinline__ float row_sum_incl(float v) { v += dpp_shr0<1>(v); v += dpp_shr0<2>(v); v += dpp_shr0<4>(v); v += dpp_shr0<8>(v); return v; }
; __device__ __forceinline__ float bcast15(float v, int lane) { return bperm_f((lane & 48) | 15, v); }
; __device__ __forceinline__ void w_hg_scan(const float (&lbv)[8], const bf16_t* fsrc, int lane, float (&bb)[4][8], float (&r31)[8], float (&r63)[8]) {
;     ...
;     float carry[8];
; #pragma unroll
;     for (int j = 0; j < 8; ++j) carry[j] = 0.f;
; #pragma unroll
;     for (int tb = 0; tb < 4; ++tb) {
; #pragma unroll
;         for (int j = 0; j < 8; ++j) { const float v = row_sum_incl(bb[tb][j]) + carry[j]; bb[tb][j] = v; carry[j] = bcast15(v, lane); if (tb == 1) r31[j] = carry[j]; if (tb == 3) r63[j] = carry[j]; }
;         __builtin_amdgcn_sched_barrier(0);
;     }
	v_add_f32_e32 v118, v35, v2
	ds_bpermute_b32 v2, v186, v118
	v_add_f32_dpp v35, v144, v144 row_shr:1 row_mask:0xf bank_mask:0xf bound_ctrl:1
	s_nop 1
	v_add_f32_dpp v35, v35, v35 row_shr:2 row_mask:0xf bank_mask:0xf bound_ctrl:1
	s_nop 1
	v_add_f32_dpp v35, v35, v35 row_shr:4 row_mask:0xf bank_mask:0xf bound_ctrl:1
	s_nop 1
	v_add_f32_dpp v35, v35, v35 row_shr:8 row_mask:0xf bank_mask:0xf bound_ctrl:1
	s_waitcnt lgkmcnt(7)
	v_add_f32_e32 v117, v35, v24
	v_add_f32_dpp v24, v155, v155 row_shr:1 row_mask:0xf bank_mask:0xf bound_ctrl:1
	ds_bpermute_b32 v88, v186, v117
	s_nop 0
	v_add_f32_dpp v24, v24, v24 row_shr:2 row_mask:0xf bank_mask:0xf bound_ctrl:1
	s_nop 1
	v_add_f32_dpp v24, v24, v24 row_shr:4 row_mask:0xf bank_mask:0xf bound_ctrl:1
	s_nop 1
	v_add_f32_dpp v24, v24, v24 row_shr:8 row_mask:0xf bank_mask:0xf bound_ctrl:1
	s_waitcnt lgkmcnt(7)
	v_add_f32_e32 v116, v24, v25
	ds_bpermute_b32 v89, v186, v116
	v_add_f32_dpp v24, v156, v156 row_shr:1 row_mask:0xf bank_mask:0xf bound_ctrl:1
	s_nop 1
	v_add_f32_dpp v24, v24, v24 row_shr:2 row_mask:0xf bank_mask:0xf bound_ctrl:1
	s_nop 1
	v_add_f32_dpp v24, v24, v24 row_shr:4 row_mask:0xf bank_mask:0xf bound_ctrl:1
	s_nop 1
	v_add_f32_dpp v24, v24, v24 row_shr:8 row_mask:0xf bank_mask:0xf bound_ctrl:1
	s_waitcnt lgkmcnt(7)
	v_add_f32_e32 v115, v24, v26
	ds_bpermute_b32 v90, v186, v115
	v_add_f32_dpp v24, v157, v157 row_shr:1 row_mask:0xf bank_mask:0xf bound_ctrl:1
	s_nop 1
	v_add_f32_dpp v24, v24, v24 row_shr:2 row_mask:0xf bank_mask:0xf bound_ctrl:1
	s_nop 1
	v_add_f32_dpp v24, v24, v24 row_shr:4 row_mask:0xf bank_mask:0xf bound_ctrl:1
	s_nop 1
	v_add_f32_dpp v24, v24, v24 row_shr:8 row_mask:0xf bank_mask:0xf bound_ctrl:1
	s_waitcnt lgkmcnt(7)
	v_add_f32_e32 v113, v24, v27
	ds_bpermute_b32 v91, v186, v113
	v_add_f32_dpp v24, v158, v158 row_shr:1 row_mask:0xf bank_mask:0xf bound_ctrl:1
	s_nop 1
	v_add_f32_dpp v24, v24, v24 row_shr:2 row_mask:0xf bank_mask:0xf bound_ctrl:1
	s_nop 1
	v_add_f32_dpp v24, v24, v24 row_shr:4 row_mask:0xf bank_mask:0xf bound_ctrl:1
	s_nop 1
	v_add_f32_dpp v24, v24, v24 row_shr:8 row_mask:0xf bank_mask:0xf bound_ctrl:1
	s_waitcnt lgkmcnt(7)
	v_add_f32_e32 v112, v24, v32
	ds_bpermute_b32 v92, v186, v112
	v_add_f32_dpp v24, v159, v159 row_shr:1 row_mask:0xf bank_mask:0xf bound_ctrl:1
	s_nop 1
	v_add_f32_dpp v24, v24, v24 row_shr:2 row_mask:0xf bank_mask:0xf bound_ctrl:1
	s_nop 1
	v_add_f32_dpp v24, v24, v24 row_shr:4 row_mask:0xf bank_mask:0xf bound_ctrl:1
	s_nop 1
	v_add_f32_dpp v24, v24, v24 row_shr:8 row_mask:0xf bank_mask:0xf bound_ctrl:1
	s_waitcnt lgkmcnt(7)
	v_add_f32_e32 v111, v24, v33
	ds_bpermute_b32 v93, v186, v111
	v_add_f32_dpp v24, v160, v160 row_shr:1 row_mask:0xf bank_mask:0xf bound_ctrl:1
	s_nop 1
	v_add_f32_dpp v24, v24, v24 row_shr:2 row_mask:0xf bank_mask:0xf bound_ctrl:1
	s_nop 1
	v_add_f32_dpp v24, v24, v24 row_shr:4 row_mask:0xf bank_mask:0xf bound_ctrl:1
	s_nop 1
	v_add_f32_dpp v24, v24, v24 row_shr:8 row_mask:0xf bank_mask:0xf bound_ctrl:1
	s_waitcnt lgkmcnt(7)
	v_add_f32_e32 v110, v24, v34
	ds_bpermute_b32 v94, v186, v110
	v_add_f32_dpp v24, v161, v161 row_shr:1 row_mask:0xf bank_mask:0xf bound_ctrl:1
	v_add_f32_dpp v25, v162, v162 row_shr:1 row_mask:0xf bank_mask:0xf bound_ctrl:1
	v_add_f32_dpp v26, v163, v163 row_shr:1 row_mask:0xf bank_mask:0xf bound_ctrl:1
	v_add_f32_dpp v27, v169, v169 row_shr:1 row_mask:0xf bank_mask:0xf bound_ctrl:1
	v_add_f32_dpp v32, v174, v174 row_shr:1 row_mask:0xf bank_mask:0xf bound_ctrl:1
	v_add_f32_dpp v33, v175, v175 row_shr:1 row_mask:0xf bank_mask:0xf bound_ctrl:1
	v_add_f32_dpp v34, v176, v176 row_shr:1 row_mask:0xf bank_mask:0xf bound_ctrl:1
	v_add_f32_dpp v35, v177, v177 row_shr:1 row_mask:0xf bank_mask:0xf bound_ctrl:1
	v_add_f32_dpp v24, v24, v24 row_shr:2 row_mask:0xf bank_mask:0xf bound_ctrl:1
	v_add_f32_dpp v25, v25, v25 row_shr:2 row_mask:0xf bank_mask:0xf bound_ctrl:1
	v_add_f32_dpp v26, v26, v26 row_shr:2 row_mask:0xf bank_mask:0xf bound_ctrl:1
	v_add_f32_dpp v27, v27, v27 row_shr:2 row_mask:0xf bank_mask:0xf bound_ctrl:1
	v_add_f32_dpp v32, v32, v32 row_shr:2 row_mask:0xf bank_mask:0xf bound_ctrl:1
	v_add_f32_dpp v33, v33, v33 row_shr:2 row_mask:0xf bank_mask:0xf bound_ctrl:1
	v_add_f32_dpp v34, v34, v34 row_shr:2 row_mask:0xf bank_mask:0xf bound_ctrl:1
	v_add_f32_dpp v35, v35, v35 row_shr:2 row_mask:0xf bank_mask:0xf bound_ctrl:1
	v_add_f32_dpp v24, v24, v24 row_shr:4 row_mask:0xf bank_mask:0xf bound_ctrl:1
	v_add_f32_dpp v25, v25, v25 row_shr:4 row_mask:0xf bank_mask:0xf bound_ctrl:1
	v_add_f32_dpp v26, v26, v26 row_shr:4 row_mask:0xf bank_mask:0xf bound_ctrl:1
	v_add_f32_dpp v27, v27, v27 row_shr:4 row_mask:0xf bank_mask:0xf bound_ctrl:1
	v_add_f32_dpp v32, v32, v32 row_shr:4 row_mask:0xf bank_mask:0xf bound_ctrl:1
	v_add_f32_dpp v33, v33, v33 row_shr:4 row_mask:0xf bank_mask:0xf bound_ctrl:1
	v_add_f32_dpp v34, v34, v34 row_shr:4 row_mask:0xf bank_mask:0xf bound_ctrl:1
	v_add_f32_dpp v35, v35, v35 row_shr:4 row_mask:0xf bank_mask:0xf bound_ctrl:1
	v_add_f32_dpp v24, v24, v24 row_shr:8 row_mask:0xf bank_mask:0xf bound_ctrl:1
	v_add_f32_dpp v25, v25, v25 row_shr:8 row_mask:0xf bank_mask:0xf bound_ctrl:1
	v_add_f32_dpp v26, v26, v26 row_shr:8 row_mask:0xf bank_mask:0xf bound_ctrl:1
	v_add_f32_dpp v27, v27, v27 row_shr:8 row_mask:0xf bank_mask:0xf bound_ctrl:1
	v_add_f32_dpp v32, v32, v32 row_shr:8 row_mask:0xf bank_mask:0xf bound_ctrl:1
	v_add_f32_dpp v33, v33, v33 row_shr:8 row_mask:0xf bank_mask:0xf bound_ctrl:1
	v_add_f32_dpp v34, v34, v34 row_shr:8 row_mask:0xf bank_mask:0xf bound_ctrl:1
	v_add_f32_dpp v35, v35, v35 row_shr:8 row_mask:0xf bank_mask:0xf bound_ctrl:1
	s_waitcnt lgkmcnt(7)
; __device__ __forceinline__ void ld8bf(const bf16_t* p, float (&o)[8]) { unpack8(*(const u32x4*)p, o); }
; __device__ __forceinline__ float sigmoidf_(float x) { return __builtin_amdgcn_rcpf(1.0f + __expf(-x)); }
; __device__ __forceinline__ bf16x8 pack_frag(const float (&v)[8]) { return __builtin_bit_cast(bf16x8, pack8(v)); }
; __device__ __forceinline__ void hg_lf_key(float fp, float lb, float& lf, float& key) {
;     const float e = __expf(-fabsf(fp));
;     const float rc = __builtin_amdgcn_rcpf(1.0f + e);
;     const float sp = fp >= 0.f ? rc : e * rc;
;     const float sn = fp >= 0.f ? e * rc : rc;
;     const float lsig = (fp >= 0.f ? 0.f : fp) + __logf(rc);
;     lf = (lb == 0.f) ? lsig : __logf(lb + (1.0f - lb) * sp); key = (1.0f - lb) * sn;
; }
; __device__ __forceinline__ void w_hg_m3(const Args& a, int l, unsigned char* ws, const bf16_t* proj, bf16_t* y, LAS unsigned char* wl, int b, int ck_, int h, int lane) {
;     ...
;         for (int tb = 0; tb < 4; ++tb) { float fp[8], qv[8], a1[8], a2[8];
;             ld8bf(fsrc + (size_t)(16 * tb + lo) * NIN, fp); ld8bf(proj + (size_t)(row0 + 16 * tb + lo) * NIN + C_HQ + 64 * h + 32 * kk + 8 * fq, qv);
; #pragma unroll
;             for (int j = 0; j < 8; ++j) { float lf, key; hg_lf_key(fp[j], lbv[j], lf, key);
;                 const float q = qv[j] * sigmoidf_(qv[j]); a1[j] = q * __expf(bb[tb][j] - r31[j]); a2[j] = key * __expf(r31[j] - bb[tb][j]); }
;             Qf[tb][kk] = pack_frag(a1); Kf[tb][kk] = pack_frag(a2); }
	v_add_f32_e32 v109, v24, v2
	s_waitcnt lgkmcnt(6)
	v_add_f32_e32 v107, v25, v88
	s_waitcnt lgkmcnt(5)
	v_add_f32_e32 v106, v26, v89
	s_waitcnt lgkmcnt(4)
	v_add_f32_e32 v105, v27, v90
	s_waitcnt lgkmcnt(3)
	v_add_f32_e32 v104, v32, v91
	s_waitcnt lgkmcnt(2)
	v_add_f32_e32 v103, v33, v92
	s_waitcnt lgkmcnt(1)
	v_add_f32_e32 v67, v34, v93
	s_waitcnt lgkmcnt(0)
	v_add_f32_e32 v66, v35, v94
	ds_bpermute_b32 v24, v186, v109
	ds_bpermute_b32 v25, v186, v107
	ds_bpermute_b32 v26, v186, v106
	ds_bpermute_b32 v27, v186, v105
	ds_bpermute_b32 v32, v186, v104
	ds_bpermute_b32 v33, v186, v103
	ds_bpermute_b32 v34, v186, v67
	ds_bpermute_b32 v35, v186, v66
	v_add_f32_dpp v40, v178, v178 row_shr:1 row_mask:0xf bank_mask:0xf bound_ctrl:1
	s_nop 1
	v_add_f32_dpp v40, v40, v40 row_shr:2 row_mask:0xf bank_mask:0xf bound_ctrl:1
	s_nop 1
	v_add_f32_dpp v40, v40, v40 row_shr:4 row_mask:0xf bank_mask:0xf bound_ctrl:1
	s_nop 1
	v_add_f32_dpp v40, v40, v40 row_shr:8 row_mask:0xf bank_mask:0xf bound_ctrl:1
	s_waitcnt lgkmcnt(7)
	v_add_f32_e32 v102, v40, v24
	v_add_f32_dpp v24, v179, v179 row_shr:1 row_mask:0xf bank_mask:0xf bound_ctrl:1
	s_nop 1
	v_add_f32_dpp v24, v24, v24 row_shr:2 row_mask:0xf bank_mask:0xf bound_ctrl:1
	s_nop 1
	v_add_f32_dpp v24, v24, v24 row_shr:4 row_mask:0xf bank_mask:0xf bound_ctrl:1
	s_nop 1
	v_add_f32_dpp v24, v24, v24 row_shr:8 row_mask:0xf bank_mask:0xf bound_ctrl:1
	s_waitcnt lgkmcnt(6)
	v_add_f32_e32 v101, v24, v25
	v_add_f32_dpp v24, v180, v180 row_shr:1 row_mask:0xf bank_mask:0xf bound_ctrl:1
	s_nop 1
	v_add_f32_dpp v24, v24, v24 row_shr:2 row_mask:0xf bank_mask:0xf bound_ctrl:1
	s_nop 1
	v_add_f32_dpp v24, v24, v24 row_shr:4 row_mask:0xf bank_mask:0xf bound_ctrl:1
	s_nop 1
	v_add_f32_dpp v24, v24, v24 row_shr:8 row_mask:0xf bank_mask:0xf bound_ctrl:1
	s_waitcnt lgkmcnt(5)
	v_add_f32_e32 v100, v24, v26
	v_add_f32_dpp v24, v181, v181 row_shr:1 row_mask:0xf bank_mask:0xf bound_ctrl:1
	s_nop 1
	v_add_f32_dpp v24, v24, v24 row_shr:2 row_mask:0xf bank_mask:0xf bound_ctrl:1
	s_nop 1
	v_add_f32_dpp v24, v24, v24 row_shr:4 row_mask:0xf bank_mask:0xf bound_ctrl:1
	s_nop 1
	v_add_f32_dpp v24, v24, v24 row_shr:8 row_mask:0xf bank_mask:0xf bound_ctrl:1
	s_waitcnt lgkmcnt(4)
	v_add_f32_e32 v99, v24, v27
	v_add_f32_dpp v24, v182, v182 row_shr:1 row_mask:0xf bank_mask:0xf bound_ctrl:1
	s_nop 1
	v_add_f32_dpp v24, v24, v24 row_shr:2 row_mask:0xf bank_mask:0xf bound_ctrl:1
	s_nop 1
	v_add_f32_dpp v24, v24, v24 row_shr:4 row_mask:0xf bank_mask:0xf bound_ctrl:1
	s_nop 1
	v_add_f32_dpp v24, v24, v24 row_shr:8 row_mask:0xf bank_mask:0xf bound_ctrl:1
	s_waitcnt lgkmcnt(3)
	v_add_f32_e32 v98, v24, v32
	v_add_f32_dpp v24, v183, v183 row_shr:1 row_mask:0xf bank_mask:0xf bound_ctrl:1
	s_nop 1
	v_add_f32_dpp v24, v24, v24 row_shr:2 row_mask:0xf bank_mask:0xf bound_ctrl:1
	s_nop 1
	v_add_f32_dpp v24, v24, v24 row_shr:4 row_mask:0xf bank_mask:0xf bound_ctrl:1
	s_nop 1
	v_add_f32_dpp v24, v24, v24 row_shr:8 row_mask:0xf bank_mask:0xf bound_ctrl:1
	s_waitcnt lgkmcnt(2)
	v_add_f32_e32 v97, v24, v33
	v_add_f32_dpp v24, v184, v184 row_shr:1 row_mask:0xf bank_mask:0xf bound_ctrl:1
	s_nop 1
	v_add_f32_dpp v24, v24, v24 row_shr:2 row_mask:0xf bank_mask:0xf bound_ctrl:1
	s_nop 1
	v_add_f32_dpp v24, v24, v24 row_shr:4 row_mask:0xf bank_mask:0xf bound_ctrl:1
	s_nop 1
	v_add_f32_dpp v24, v24, v24 row_shr:8 row_mask:0xf bank_mask:0xf bound_ctrl:1
	s_waitcnt lgkmcnt(1)
	v_add_f32_e32 v96, v24, v34
	v_add_f32_dpp v24, v185, v185 row_shr:1 row_mask:0xf bank_mask:0xf bound_ctrl:1
	s_nop 1
	v_add_f32_dpp v24, v24, v24 row_shr:2 row_mask:0xf bank_mask:0xf bound_ctrl:1
	s_nop 1
	v_add_f32_dpp v24, v24, v24 row_shr:4 row_mask:0xf bank_mask:0xf bound_ctrl:1
	s_nop 1
	v_add_f32_dpp v24, v24, v24 row_shr:8 row_mask:0xf bank_mask:0xf bound_ctrl:1
	s_waitcnt lgkmcnt(0)
	v_add_f32_e32 v95, v24, v35
	global_load_dwordx4 v[24:27], v[60:61], off
	global_load_dwordx4 v[32:35], v[70:71], off offset:64
	global_load_dwordx4 v[134:137], v[48:49], off offset:64
	global_load_dwordx4 v[138:141], v[78:79], off offset:64
	global_load_dwordx4 v[142:145], v[36:37], off offset:64
	global_load_dwordx4 v[146:149], v[38:39], off offset:64
	global_load_dwordx4 v[150:153], v[76:77], off offset:64
	global_load_dwordx4 v[122:125], v[64:65], off offset:64
	v_pk_add_f32 v[70:71], v[56:57], 1.0 op_sel_hi:[1,0] neg_lo:[1,0] neg_hi:[1,0]
	v_sub_f32_e32 v40, v41, v2
	v_sub_f32_e32 v41, v2, v41
	v_mul_f32_e32 v41, 0x3fb8aa3b, v41
	v_exp_f32_e32 v42, v41
	v_sub_f32_e32 v41, v43, v88
	v_mul_f32_e32 v40, 0x3fb8aa3b, v40
	v_mul_f32_e32 v41, 0x3fb8aa3b, v41
	v_exp_f32_e32 v40, v40
	v_exp_f32_e32 v41, v41
	v_pk_add_f32 v[72:73], v[58:59], 1.0 op_sel_hi:[1,0] neg_lo:[1,0] neg_hi:[1,0]
	s_waitcnt vmcnt(0) lgkmcnt(0)
; __device__ __forceinline__ void ld8bf(const bf16_t* p, float (&o)[8]) { unpack8(*(const u32x4*)p, o); }
; __device__ __forceinline__ float sigmoidf_(float x) { return __builtin_amdgcn_rcpf(1.0f + __expf(-x)); }
; __device__ __forceinline__ bf16x8 pack_frag(const float (&v)[8]) { return __builtin_bit_cast(bf16x8, pack8(v)); }
; __device__ __forceinline__ void hg_lf_key(float fp, float lb, float& lf, float& key) {
;     const float e = __expf(-fabsf(fp));
;     const float rc = __builtin_amdgcn_rcpf(1.0f + e);
;     const float sp = fp >= 0.f ? rc : e * rc;
;     const float sn = fp >= 0.f ? e * rc : rc;
;     const float lsig = (fp >= 0.f ? 0.f : fp) + __logf(rc);
;     lf = (lb == 0.f) ? lsig : __logf(lb + (1.0f - lb) * sp); key = (1.0f - lb) * sn;
; }
; __device__ __forceinline__ void w_hg_m3(const Args& a, int l, unsigned char* ws, const bf16_t* proj, bf16_t* y, LAS unsigned char* wl, int b, int ck_, int h, int lane) {
;     ...
;         for (int tb = 0; tb < 4; ++tb) { float fp[8], qv[8], a1[8], a2[8];
;             ld8bf(fsrc + (size_t)(16 * tb + lo) * NIN, fp); ld8bf(proj + (size_t)(row0 + 16 * tb + lo) * NIN + C_HQ + 64 * h + 32 * kk + 8 * fq, qv);
; #pragma unroll
;             for (int j = 0; j < 8; ++j) { float lf, key; hg_lf_key(fp[j], lbv[j], lf, key);
;                 const float q = qv[j] * sigmoidf_(qv[j]); a1[j] = q * __expf(bb[tb][j] - r31[j]); a2[j] = key * __expf(r31[j] - bb[tb][j]); }
;             Qf[tb][kk] = pack_frag(a1); Kf[tb][kk] = pack_frag(a2); }
	v_lshlrev_b32_e32 v56, 16, v32
	v_and_b32_e32 v57, 0xffff0000, v32
	v_mul_f32_e32 v32, 0xbfb8aa3b, v56
	v_exp_f32_e32 v32, v32
	s_nop 0
	v_add_f32_e32 v32, 1.0, v32
	v_rcp_f32_e32 v60, v32
	v_mul_f32_e32 v32, 0xbfb8aa3b, v57
	v_exp_f32_e32 v32, v32
	s_nop 0
	v_add_f32_e32 v32, 1.0, v32
	v_rcp_f32_e32 v61, v32
	v_sub_f32_e32 v32, v88, v43
	v_mul_f32_e32 v32, 0x3fb8aa3b, v32
	v_exp_f32_e32 v43, v32
	v_pk_mul_f32 v[56:57], v[60:61], v[56:57]
	v_lshlrev_b32_e32 v32, 16, v24
	v_pk_mul_f32 v[40:41], v[40:41], v[56:57]
	v_mul_f32_e64 v56, |v32|, s26
	v_exp_f32_e32 v56, v56
	v_and_b32_e32 v24, 0xffff0000, v24
	v_cmp_le_f32_e32 vcc, 0, v32
	v_cmp_le_f32_e64 s[38:39], 0, v24
	v_add_f32_e32 v57, 1.0, v56
	v_rcp_f32_e32 v60, v57
	v_mul_f32_e64 v57, |v24|, s26
	v_exp_f32_e32 v57, v57
	v_sub_f32_e32 v24, v74, v89
	v_mul_f32_e32 v24, 0x3fb8aa3b, v24
	v_lshlrev_b32_e32 v32, 16, v33
	v_add_f32_e32 v61, 1.0, v57
	v_rcp_f32_e32 v61, v61
	v_and_b32_e32 v33, 0xffff0000, v33
	v_pk_mul_f32 v[56:57], v[56:57], v[60:61]
	s_nop 0
	v_cndmask_b32_e64 v57, v61, v57, s[38:39]
	v_cndmask_b32_e32 v56, v60, v56, vcc
	v_pk_mul_f32 v[56:57], v[70:71], v[56:57]
	s_nop 0
	v_pk_mul_f32 v[42:43], v[42:43], v[56:57]
	v_exp_f32_e32 v56, v24
	v_sub_f32_e32 v24, v89, v74
	v_mul_f32_e32 v24, 0x3fb8aa3b, v24
	v_exp_f32_e32 v58, v24
	v_sub_f32_e32 v24, v75, v90
	v_mul_f32_e32 v24, 0x3fb8aa3b, v24
	v_exp_f32_e32 v57, v24
	v_mul_f32_e32 v24, 0xbfb8aa3b, v32
	v_exp_f32_e32 v24, v24
	s_nop 0
	v_add_f32_e32 v24, 1.0, v24
	v_rcp_f32_e32 v60, v24
	v_mul_f32_e32 v24, 0xbfb8aa3b, v33
	v_exp_f32_e32 v24, v24
	s_nop 0
	v_add_f32_e32 v24, 1.0, v24
	v_rcp_f32_e32 v61, v24
	v_sub_f32_e32 v24, v90, v75
	v_mul_f32_e32 v24, 0x3fb8aa3b, v24
	v_exp_f32_e32 v59, v24
	v_pk_mul_f32 v[32:33], v[60:61], v[32:33]
	v_lshlrev_b32_e32 v60, 16, v25
	v_mul_f32_e64 v24, |v60|, s26
	v_exp_f32_e32 v24, v24
	v_and_b32_e32 v61, 0xffff0000, v25
	v_pk_mul_f32 v[32:33], v[56:57], v[32:33]
	v_cmp_le_f32_e32 vcc, 0, v60
	v_add_f32_e32 v25, 1.0, v24
	v_rcp_f32_e32 v56, v25
	v_mul_f32_e64 v25, |v61|, s26
	v_exp_f32_e32 v25, v25
	v_cmp_le_f32_e64 s[38:39], 0, v61
	v_pk_add_f32 v[74:75], v[50:51], 1.0 op_sel_hi:[1,0] neg_lo:[1,0] neg_hi:[1,0]
	v_add_f32_e32 v57, 1.0, v25
	v_rcp_f32_e32 v57, v57
	s_nop 0
	v_pk_mul_f32 v[24:25], v[24:25], v[56:57]
	s_nop 0
	v_cndmask_b32_e64 v25, v57, v25, s[38:39]
	v_cndmask_b32_e32 v24, v56, v24, vcc
	v_pk_mul_f32 v[24:25], v[72:73], v[24:25]
	s_nop 0
	v_pk_mul_f32 v[56:57], v[58:59], v[24:25]
	v_lshlrev_b32_e32 v58, 16, v34
	v_and_b32_e32 v59, 0xffff0000, v34
	v_mul_f32_e32 v34, 0xbfb8aa3b, v58
	v_exp_f32_e32 v34, v34
	v_sub_f32_e32 v25, v91, v121
	v_mul_f32_e32 v25, 0x3fb8aa3b, v25
	v_sub_f32_e32 v24, v121, v91
	v_add_f32_e32 v34, 1.0, v34
	v_rcp_f32_e32 v60, v34
	v_mul_f32_e32 v34, 0xbfb8aa3b, v59
	v_exp_f32_e32 v34, v34
	v_exp_f32_e32 v50, v25
	v_sub_f32_e32 v25, v119, v92
	v_mul_f32_e32 v24, 0x3fb8aa3b, v24
	v_add_f32_e32 v34, 1.0, v34
	v_mul_f32_e32 v25, 0x3fb8aa3b, v25
	v_rcp_f32_e32 v61, v34
	v_exp_f32_e32 v24, v24
	v_exp_f32_e32 v25, v25
	v_sub_f32_e32 v34, v92, v119
	v_mul_f32_e32 v34, 0x3fb8aa3b, v34
	v_pk_mul_f32 v[58:59], v[60:61], v[58:59]
	v_exp_f32_e32 v51, v34
	v_lshlrev_b32_e32 v34, 16, v26
	v_pk_mul_f32 v[24:25], v[24:25], v[58:59]
	v_mul_f32_e64 v58, |v34|, s26
	v_exp_f32_e32 v58, v58
	v_and_b32_e32 v26, 0xffff0000, v26
	v_cmp_le_f32_e32 vcc, 0, v34
	v_cmp_le_f32_e64 s[38:39], 0, v26
	v_add_f32_e32 v59, 1.0, v58
	v_rcp_f32_e32 v60, v59
	v_mul_f32_e64 v59, |v26|, s26
	v_exp_f32_e32 v59, v59
	v_sub_f32_e32 v26, v63, v93
	v_mul_f32_e32 v26, 0x3fb8aa3b, v26
	v_add_f32_e32 v61, 1.0, v59
	v_rcp_f32_e32 v61, v61
	s_nop 0
	v_pk_mul_f32 v[58:59], v[58:59], v[60:61]
	s_nop 0
	v_cndmask_b32_e64 v59, v61, v59, s[38:39]
	v_cndmask_b32_e32 v58, v60, v58, vcc
	v_pk_mul_f32 v[58:59], v[74:75], v[58:59]
	v_lshlrev_b32_e32 v60, 16, v35
	v_pk_mul_f32 v[50:51], v[50:51], v[58:59]
	v_exp_f32_e32 v58, v26
	v_sub_f32_e32 v26, v93, v63
	v_mul_f32_e32 v26, 0x3fb8aa3b, v26
	v_exp_f32_e32 v34, v26
	v_sub_f32_e32 v26, v62, v94
	v_mul_f32_e32 v26, 0x3fb8aa3b, v26
	v_exp_f32_e32 v59, v26
	v_mul_f32_e32 v26, 0xbfb8aa3b, v60
	v_exp_f32_e32 v26, v26
	v_and_b32_e32 v61, 0xffff0000, v35
	v_and_b32_e32 v63, 0xffff0000, v27
	v_cmp_le_f32_e64 s[38:39], 0, v63
	v_add_f32_e32 v26, 1.0, v26
	v_rcp_f32_e32 v120, v26
	v_mul_f32_e32 v26, 0xbfb8aa3b, v61
	v_exp_f32_e32 v26, v26
	s_nop 0
	v_add_f32_e32 v26, 1.0, v26
	v_rcp_f32_e32 v121, v26
	v_sub_f32_e32 v26, v94, v62
	v_mul_f32_e32 v26, 0x3fb8aa3b, v26
	v_lshlrev_b32_e32 v62, 16, v27
	v_exp_f32_e32 v35, v26
	v_mul_f32_e64 v26, |v62|, s26
	v_exp_f32_e32 v26, v26
	v_pk_mul_f32 v[60:61], v[120:121], v[60:61]
	v_cmp_le_f32_e32 vcc, 0, v62
	v_pk_mul_f32 v[58:59], v[58:59], v[60:61]
	v_add_f32_e32 v27, 1.0, v26
	v_rcp_f32_e32 v60, v27
	v_mul_f32_e64 v27, |v63|, s26
	v_exp_f32_e32 v27, v27
	v_cvt_pk_bf16_f32 v62, v24, v25
	v_cvt_pk_bf16_f32 v24, v42, v43
	v_cvt_pk_bf16_f32 v25, v56, v57
	v_add_f32_e32 v61, 1.0, v27
	v_rcp_f32_e32 v61, v61
	v_cvt_pk_bf16_f32 v63, v58, v59
	v_pk_mul_f32 v[26:27], v[26:27], v[60:61]
	s_nop 0
	v_cndmask_b32_e64 v27, v61, v27, s[38:39]
	v_cndmask_b32_e32 v26, v60, v26, vcc
	v_pk_mul_f32 v[26:27], v[68:69], v[26:27]
	v_cvt_pk_bf16_f32 v60, v40, v41
	v_pk_mul_f32 v[34:35], v[34:35], v[26:27]
	v_cvt_pk_bf16_f32 v61, v32, v33
	v_cvt_pk_bf16_f32 v27, v34, v35
	v_mov_b64_e32 v[32:33], v[134:135]
	v_mov_b64_e32 v[34:35], v[136:137]
	v_mov_b64_e32 v[40:41], v[138:139]
	v_mov_b64_e32 v[42:43], v[140:141]
	v_sub_f32_e32 v49, v2, v118
	v_mul_f32_e32 v49, 0x3fb8aa3b, v49
	v_cvt_pk_bf16_f32 v26, v50, v51
	v_sub_f32_e32 v48, v118, v2
	v_exp_f32_e32 v50, v49
	v_sub_f32_e32 v49, v117, v88
	v_mul_f32_e32 v48, 0x3fb8aa3b, v48
	v_mul_f32_e32 v49, 0x3fb8aa3b, v49
	v_exp_f32_e32 v48, v48
	v_exp_f32_e32 v49, v49
	s_waitcnt vmcnt(0) lgkmcnt(0)
; __device__ __forceinline__ void ld8bf(const bf16_t* p, float (&o)[8]) { unpack8(*(const u32x4*)p, o); }
; __device__ __forceinline__ float sigmoidf_(float x) { return __builtin_amdgcn_rcpf(1.0f + __expf(-x)); }
; __device__ __forceinline__ bf16x8 pack_frag(const float (&v)[8]) { return __builtin_bit_cast(bf16x8, pack8(v)); }
; __device__ __forceinline__ void hg_lf_key(float fp, float lb, float& lf, float& key) {
;     const float e = __expf(-fabsf(fp));
;     const float rc = __builtin_amdgcn_rcpf(1.0f + e);
;     const float sp = fp >= 0.f ? rc : e * rc;
;     const float sn = fp >= 0.f ? e * rc : rc;
;     const float lsig = (fp >= 0.f ? 0.f : fp) + __logf(rc);
;     lf = (lb == 0.f) ? lsig : __logf(lb + (1.0f - lb) * sp); key = (1.0f - lb) * sn;
; }
; __device__ __forceinline__ void w_hg_m3(const Args& a, int l, unsigned char* ws, const bf16_t* proj, bf16_t* y, LAS unsigned char* wl, int b, int ck_, int h, int lane) {
;     ...
;         for (int tb = 0; tb < 4; ++tb) { float fp[8], qv[8], a1[8], a2[8];
;             ld8bf(fsrc + (size_t)(16 * tb + lo) * NIN, fp); ld8bf(proj + (size_t)(row0 + 16 * tb + lo) * NIN + C_HQ + 64 * h + 32 * kk + 8 * fq, qv);
; #pragma unroll
;             for (int j = 0; j < 8; ++j) { float lf, key; hg_lf_key(fp[j], lbv[j], lf, key);
;                 const float q = qv[j] * sigmoidf_(qv[j]); a1[j] = q * __expf(bb[tb][j] - r31[j]); a2[j] = key * __expf(r31[j] - bb[tb][j]); }
;             Qf[tb][kk] = pack_frag(a1); Kf[tb][kk] = pack_frag(a2); }
	v_lshlrev_b32_e32 v56, 16, v40
	v_and_b32_e32 v57, 0xffff0000, v40
	v_mul_f32_e32 v40, 0xbfb8aa3b, v56
	v_exp_f32_e32 v40, v40
	s_nop 0
	v_add_f32_e32 v40, 1.0, v40
	v_rcp_f32_e32 v58, v40
	v_mul_f32_e32 v40, 0xbfb8aa3b, v57
	v_exp_f32_e32 v40, v40
	s_nop 0
	v_add_f32_e32 v40, 1.0, v40
	v_rcp_f32_e32 v59, v40
	v_sub_f32_e32 v40, v88, v117
	v_mul_f32_e32 v40, 0x3fb8aa3b, v40
	v_exp_f32_e32 v51, v40
	v_pk_mul_f32 v[56:57], v[58:59], v[56:57]
	v_lshlrev_b32_e32 v40, 16, v32
	v_pk_mul_f32 v[48:49], v[48:49], v[56:57]
	v_mul_f32_e64 v56, |v40|, s26
	v_exp_f32_e32 v56, v56
	v_and_b32_e32 v32, 0xffff0000, v32
	v_cmp_le_f32_e32 vcc, 0, v40
	v_cmp_le_f32_e64 s[38:39], 0, v32
	v_add_f32_e32 v57, 1.0, v56
	v_rcp_f32_e32 v58, v57
	v_mul_f32_e64 v57, |v32|, s26
	v_exp_f32_e32 v57, v57
	v_sub_f32_e32 v32, v116, v89
	v_mul_f32_e32 v32, 0x3fb8aa3b, v32
	v_cvt_pk_bf16_f32 v48, v48, v49
	v_add_f32_e32 v59, 1.0, v57
	v_rcp_f32_e32 v59, v59
	s_nop 0
	v_pk_mul_f32 v[56:57], v[56:57], v[58:59]
	s_nop 0
	v_cndmask_b32_e64 v57, v59, v57, s[38:39]
	v_cndmask_b32_e32 v56, v58, v56, vcc
	v_pk_mul_f32 v[56:57], v[70:71], v[56:57]
	v_lshlrev_b32_e32 v58, 16, v41
	v_pk_mul_f32 v[56:57], v[50:51], v[56:57]
	v_exp_f32_e32 v50, v32
	v_sub_f32_e32 v32, v89, v116
	v_mul_f32_e32 v32, 0x3fb8aa3b, v32
	v_exp_f32_e32 v40, v32
	v_sub_f32_e32 v32, v115, v90
	v_mul_f32_e32 v32, 0x3fb8aa3b, v32
	v_exp_f32_e32 v51, v32
	v_mul_f32_e32 v32, 0xbfb8aa3b, v58
	v_exp_f32_e32 v32, v32
	v_and_b32_e32 v59, 0xffff0000, v41
	v_add_f32_e32 v32, 1.0, v32
	v_rcp_f32_e32 v78, v32
	v_mul_f32_e32 v32, 0xbfb8aa3b, v59
	v_exp_f32_e32 v32, v32
	s_nop 0
	v_add_f32_e32 v32, 1.0, v32
	v_rcp_f32_e32 v79, v32
	v_sub_f32_e32 v32, v90, v115
	v_mul_f32_e32 v32, 0x3fb8aa3b, v32
	v_exp_f32_e32 v41, v32
	v_pk_mul_f32 v[58:59], v[78:79], v[58:59]
	v_lshlrev_b32_e32 v78, 16, v33
	v_mul_f32_e64 v32, |v78|, s26
	v_exp_f32_e32 v32, v32
	v_and_b32_e32 v79, 0xffff0000, v33
	v_pk_mul_f32 v[50:51], v[50:51], v[58:59]
	v_cmp_le_f32_e32 vcc, 0, v78
	v_add_f32_e32 v33, 1.0, v32
	v_rcp_f32_e32 v58, v33
	v_mul_f32_e64 v33, |v79|, s26
	v_exp_f32_e32 v33, v33
	v_lshlrev_b32_e32 v78, 16, v42
	v_cmp_le_f32_e64 s[38:39], 0, v79
	v_and_b32_e32 v79, 0xffff0000, v42
	v_mul_f32_e32 v42, 0xbfb8aa3b, v78
	v_add_f32_e32 v59, 1.0, v33
	v_exp_f32_e32 v42, v42
	v_rcp_f32_e32 v59, v59
	v_cvt_pk_bf16_f32 v49, v50, v51
	v_add_f32_e32 v42, 1.0, v42
	v_pk_mul_f32 v[32:33], v[32:33], v[58:59]
	v_rcp_f32_e32 v116, v42
	v_mul_f32_e32 v42, 0xbfb8aa3b, v79
	v_cndmask_b32_e64 v33, v59, v33, s[38:39]
	v_cndmask_b32_e32 v32, v58, v32, vcc
	v_exp_f32_e32 v42, v42
	v_pk_mul_f32 v[32:33], v[72:73], v[32:33]
	v_add_f32_e32 v42, 1.0, v42
	v_pk_mul_f32 v[40:41], v[40:41], v[32:33]
	v_sub_f32_e32 v33, v91, v113
	v_mul_f32_e32 v33, 0x3fb8aa3b, v33
	v_sub_f32_e32 v32, v113, v91
	v_exp_f32_e32 v58, v33
	v_sub_f32_e32 v33, v112, v92
	v_mul_f32_e32 v32, 0x3fb8aa3b, v32
	v_mul_f32_e32 v33, 0x3fb8aa3b, v33
	v_rcp_f32_e32 v117, v42
	v_exp_f32_e32 v32, v32
	v_exp_f32_e32 v33, v33
	v_sub_f32_e32 v42, v92, v112
	v_mul_f32_e32 v42, 0x3fb8aa3b, v42
	v_pk_mul_f32 v[78:79], v[116:117], v[78:79]
	v_exp_f32_e32 v59, v42
	v_lshlrev_b32_e32 v42, 16, v34
	v_pk_mul_f32 v[32:33], v[32:33], v[78:79]
	v_mul_f32_e64 v78, |v42|, s26
	v_exp_f32_e32 v78, v78
	v_and_b32_e32 v34, 0xffff0000, v34
	v_cmp_le_f32_e32 vcc, 0, v42
	v_cmp_le_f32_e64 s[38:39], 0, v34
	v_add_f32_e32 v79, 1.0, v78
	v_rcp_f32_e32 v112, v79
	v_mul_f32_e64 v79, |v34|, s26
	v_exp_f32_e32 v79, v79
	v_sub_f32_e32 v34, v111, v93
	v_mul_f32_e32 v34, 0x3fb8aa3b, v34
	v_cvt_pk_bf16_f32 v50, v32, v33
	v_add_f32_e32 v113, 1.0, v79
	v_rcp_f32_e32 v113, v113
	v_cvt_pk_bf16_f32 v33, v40, v41
	v_cvt_pk_bf16_f32 v32, v56, v57
	v_sub_f32_e32 v57, v2, v109
	v_pk_mul_f32 v[78:79], v[78:79], v[112:113]
	v_mul_f32_e32 v57, 0x3fb8aa3b, v57
	v_cndmask_b32_e64 v79, v113, v79, s[38:39]
	v_cndmask_b32_e32 v78, v112, v78, vcc
	v_pk_mul_f32 v[78:79], v[74:75], v[78:79]
	v_lshlrev_b32_e32 v112, 16, v43
	v_pk_mul_f32 v[58:59], v[58:59], v[78:79]
	v_exp_f32_e32 v78, v34
	v_sub_f32_e32 v34, v93, v111
	v_mul_f32_e32 v34, 0x3fb8aa3b, v34
	v_exp_f32_e32 v42, v34
	v_sub_f32_e32 v34, v110, v94
	v_mul_f32_e32 v34, 0x3fb8aa3b, v34
	v_exp_f32_e32 v79, v34
	v_mul_f32_e32 v34, 0xbfb8aa3b, v112
	v_exp_f32_e32 v34, v34
	v_and_b32_e32 v113, 0xffff0000, v43
	v_sub_f32_e32 v56, v109, v2
	v_mul_f32_e32 v56, 0x3fb8aa3b, v56
	v_add_f32_e32 v34, 1.0, v34
	v_rcp_f32_e32 v116, v34
	v_mul_f32_e32 v34, 0xbfb8aa3b, v113
	v_exp_f32_e32 v34, v34
	v_exp_f32_e32 v56, v56
	v_add_f32_e32 v34, 1.0, v34
	v_rcp_f32_e32 v117, v34
	v_sub_f32_e32 v34, v94, v110
	v_mul_f32_e32 v34, 0x3fb8aa3b, v34
	v_exp_f32_e32 v43, v34
	v_pk_mul_f32 v[112:113], v[116:117], v[112:113]
	s_nop 0
	v_pk_mul_f32 v[78:79], v[78:79], v[112:113]
	v_lshlrev_b32_e32 v112, 16, v35
	v_mul_f32_e64 v34, |v112|, s26
	v_exp_f32_e32 v34, v34
	v_and_b32_e32 v113, 0xffff0000, v35
	v_cmp_le_f32_e32 vcc, 0, v112
	v_cmp_le_f32_e64 s[38:39], 0, v113
	v_add_f32_e32 v35, 1.0, v34
	v_rcp_f32_e32 v110, v35
	v_mul_f32_e64 v35, |v113|, s26
	v_exp_f32_e32 v35, v35
	v_cvt_pk_bf16_f32 v51, v78, v79
	v_add_f32_e32 v111, 1.0, v35
	v_rcp_f32_e32 v111, v111
	s_nop 0
	v_pk_mul_f32 v[34:35], v[34:35], v[110:111]
	s_nop 0
	v_cndmask_b32_e64 v35, v111, v35, s[38:39]
	v_cndmask_b32_e32 v34, v110, v34, vcc
	v_pk_mul_f32 v[34:35], v[68:69], v[34:35]
	s_nop 0
	v_pk_mul_f32 v[42:43], v[42:43], v[34:35]
	v_cvt_pk_bf16_f32 v34, v58, v59
	v_cvt_pk_bf16_f32 v35, v42, v43
	v_mov_b64_e32 v[40:41], v[142:143]
	v_mov_b64_e32 v[42:43], v[144:145]
	s_nop 0
	v_mov_b64_e32 v[36:37], v[146:147]
	v_mov_b64_e32 v[38:39], v[148:149]
	v_exp_f32_e32 v58, v57
	v_sub_f32_e32 v57, v107, v88
	v_mul_f32_e32 v57, 0x3fb8aa3b, v57
	v_exp_f32_e32 v57, v57
	s_waitcnt vmcnt(0) lgkmcnt(0)
; __device__ __forceinline__ void ld8bf(const bf16_t* p, float (&o)[8]) { unpack8(*(const u32x4*)p, o); }
; __device__ __forceinline__ float sigmoidf_(float x) { return __builtin_amdgcn_rcpf(1.0f + __expf(-x)); }
; __device__ __forceinline__ bf16x8 pack_frag(const float (&v)[8]) { return __builtin_bit_cast(bf16x8, pack8(v)); }
; __device__ __forceinline__ void hg_lf_key(float fp, float lb, float& lf, float& key) {
;     const float e = __expf(-fabsf(fp));
;     const float rc = __builtin_amdgcn_rcpf(1.0f + e);
;     const float sp = fp >= 0.f ? rc : e * rc;
;     const float sn = fp >= 0.f ? e * rc : rc;
;     const float lsig = (fp >= 0.f ? 0.f : fp) + __logf(rc);
;     lf = (lb == 0.f) ? lsig : __logf(lb + (1.0f - lb) * sp); key = (1.0f - lb) * sn;
; }
; __device__ __forceinline__ void w_hg_m3(const Args& a, int l, unsigned char* ws, const bf16_t* proj, bf16_t* y, LAS unsigned char* wl, int b, int ck_, int h, int lane) {
;     ...
;         for (int tb = 0; tb < 4; ++tb) { float fp[8], qv[8], a1[8], a2[8];
;             ld8bf(fsrc + (size_t)(16 * tb + lo) * NIN, fp); ld8bf(proj + (size_t)(row0 + 16 * tb + lo) * NIN + C_HQ + 64 * h + 32 * kk + 8 * fq, qv);
; #pragma unroll
;             for (int j = 0; j < 8; ++j) { float lf, key; hg_lf_key(fp[j], lbv[j], lf, key);
;                 const float q = qv[j] * sigmoidf_(qv[j]); a1[j] = q * __expf(bb[tb][j] - r31[j]); a2[j] = key * __expf(r31[j] - bb[tb][j]); }
;             Qf[tb][kk] = pack_frag(a1); Kf[tb][kk] = pack_frag(a2); }
	v_and_b32_e32 v109, 0xffff0000, v41
	v_lshlrev_b32_e32 v78, 16, v36
	v_and_b32_e32 v79, 0xffff0000, v36
	v_mul_f32_e32 v36, 0xbfb8aa3b, v78
	v_exp_f32_e32 v36, v36
	s_nop 0
	v_add_f32_e32 v36, 1.0, v36
	v_rcp_f32_e32 v110, v36
	v_mul_f32_e32 v36, 0xbfb8aa3b, v79
	v_exp_f32_e32 v36, v36
	s_nop 0
	v_add_f32_e32 v36, 1.0, v36
	v_rcp_f32_e32 v111, v36
	v_sub_f32_e32 v36, v88, v107
	v_mul_f32_e32 v36, 0x3fb8aa3b, v36
	v_exp_f32_e32 v59, v36
	v_pk_mul_f32 v[78:79], v[110:111], v[78:79]
	v_lshlrev_b32_e32 v36, 16, v40
	v_pk_mul_f32 v[56:57], v[56:57], v[78:79]
	v_mul_f32_e64 v78, |v36|, s26
	v_exp_f32_e32 v78, v78
	v_and_b32_e32 v40, 0xffff0000, v40
	v_cmp_le_f32_e32 vcc, 0, v36
	v_cmp_le_f32_e64 s[38:39], 0, v40
	v_add_f32_e32 v79, 1.0, v78
	v_rcp_f32_e32 v110, v79
	v_mul_f32_e64 v79, |v40|, s26
	v_exp_f32_e32 v79, v79
	v_sub_f32_e32 v36, v106, v89
	v_mul_f32_e32 v36, 0x3fb8aa3b, v36
	v_sub_f32_e32 v40, v105, v90
	v_add_f32_e32 v107, 1.0, v79
	v_rcp_f32_e32 v111, v107
	v_and_b32_e32 v107, 0xffff0000, v37
	v_mul_f32_e32 v40, 0x3fb8aa3b, v40
	v_pk_mul_f32 v[78:79], v[78:79], v[110:111]
	s_nop 0
	v_cndmask_b32_e64 v79, v111, v79, s[38:39]
	v_cndmask_b32_e32 v78, v110, v78, vcc
	v_pk_mul_f32 v[78:79], v[70:71], v[78:79]
	v_cmp_le_f32_e64 s[38:39], 0, v109
	v_pk_mul_f32 v[58:59], v[58:59], v[78:79]
	v_exp_f32_e32 v78, v36
	v_sub_f32_e32 v36, v89, v106
	v_lshlrev_b32_e32 v106, 16, v37
	v_mul_f32_e32 v37, 0xbfb8aa3b, v106
	v_exp_f32_e32 v37, v37
	v_exp_f32_e32 v79, v40
	v_mul_f32_e32 v36, 0x3fb8aa3b, v36
	v_exp_f32_e32 v36, v36
	v_add_f32_e32 v37, 1.0, v37
	v_rcp_f32_e32 v110, v37
	v_mul_f32_e32 v37, 0xbfb8aa3b, v107
	v_exp_f32_e32 v37, v37
	s_nop 0
	v_add_f32_e32 v37, 1.0, v37
	v_rcp_f32_e32 v111, v37
	v_sub_f32_e32 v37, v90, v105
	v_lshlrev_b32_e32 v105, 16, v41
	v_mul_f32_e64 v40, |v105|, s26
	v_exp_f32_e32 v40, v40
	v_pk_mul_f32 v[106:107], v[110:111], v[106:107]
	v_mul_f32_e32 v37, 0x3fb8aa3b, v37
	v_pk_mul_f32 v[78:79], v[78:79], v[106:107]
	v_add_f32_e32 v41, 1.0, v40
	v_rcp_f32_e32 v106, v41
	v_mul_f32_e64 v41, |v109|, s26
	v_exp_f32_e32 v41, v41
	v_exp_f32_e32 v37, v37
	v_cmp_le_f32_e32 vcc, 0, v105
	v_and_b32_e32 v105, 0xffff0000, v38
	v_add_f32_e32 v107, 1.0, v41
	v_rcp_f32_e32 v107, v107
	s_nop 0
	v_pk_mul_f32 v[40:41], v[40:41], v[106:107]
	s_nop 0
	v_cndmask_b32_e64 v41, v107, v41, s[38:39]
	v_cndmask_b32_e32 v40, v106, v40, vcc
	v_pk_mul_f32 v[40:41], v[72:73], v[40:41]
	s_nop 0
	v_pk_mul_f32 v[106:107], v[36:37], v[40:41]
	v_sub_f32_e32 v36, v104, v91
	v_sub_f32_e32 v37, v91, v104
	v_lshlrev_b32_e32 v104, 16, v38
	v_mul_f32_e32 v38, 0xbfb8aa3b, v104
	v_exp_f32_e32 v38, v38
	v_mul_f32_e32 v37, 0x3fb8aa3b, v37
	v_exp_f32_e32 v40, v37
	v_sub_f32_e32 v37, v103, v92
	v_add_f32_e32 v38, 1.0, v38
	v_rcp_f32_e32 v110, v38
	v_mul_f32_e32 v38, 0xbfb8aa3b, v105
	v_exp_f32_e32 v38, v38
	v_mul_f32_e32 v36, 0x3fb8aa3b, v36
	v_mul_f32_e32 v37, 0x3fb8aa3b, v37
	v_exp_f32_e32 v36, v36
	v_add_f32_e32 v38, 1.0, v38
	v_rcp_f32_e32 v111, v38
	v_exp_f32_e32 v37, v37
	v_sub_f32_e32 v38, v92, v103
	v_mul_f32_e32 v38, 0x3fb8aa3b, v38
	v_exp_f32_e32 v41, v38
	v_lshlrev_b32_e32 v38, 16, v42
	v_pk_mul_f32 v[104:105], v[110:111], v[104:105]
	v_mul_f32_e64 v103, |v38|, s26
	v_pk_mul_f32 v[36:37], v[36:37], v[104:105]
	v_exp_f32_e32 v104, v103
	v_and_b32_e32 v42, 0xffff0000, v42
	v_cmp_le_f32_e32 vcc, 0, v38
	v_cmp_le_f32_e64 s[38:39], 0, v42
	v_add_f32_e32 v103, 1.0, v104
	v_rcp_f32_e32 v110, v103
	v_mul_f32_e64 v103, |v42|, s26
	v_exp_f32_e32 v105, v103
	v_sub_f32_e32 v38, v67, v93
	v_mul_f32_e32 v38, 0x3fb8aa3b, v38
	v_add_f32_e32 v103, 1.0, v105
	v_rcp_f32_e32 v111, v103
	s_nop 0
	v_pk_mul_f32 v[104:105], v[104:105], v[110:111]
	s_nop 0
	v_cndmask_b32_e32 v104, v110, v104, vcc
	v_lshlrev_b32_e32 v110, 16, v39
	v_cndmask_b32_e64 v105, v111, v105, s[38:39]
	v_and_b32_e32 v111, 0xffff0000, v39
	v_mul_f32_e32 v39, 0xbfb8aa3b, v110
	v_exp_f32_e32 v39, v39
	v_pk_mul_f32 v[104:105], v[74:75], v[104:105]
	v_add_f32_e32 v39, 1.0, v39
	v_rcp_f32_e32 v112, v39
	v_mul_f32_e32 v39, 0xbfb8aa3b, v111
	v_exp_f32_e32 v39, v39
	v_pk_mul_f32 v[104:105], v[40:41], v[104:105]
	v_sub_f32_e32 v41, v66, v94
	v_mul_f32_e32 v41, 0x3fb8aa3b, v41
	v_add_f32_e32 v39, 1.0, v39
	v_rcp_f32_e32 v113, v39
	v_exp_f32_e32 v40, v38
	v_exp_f32_e32 v41, v41
	v_sub_f32_e32 v39, v94, v66
	v_pk_mul_f32 v[110:111], v[112:113], v[110:111]
	v_lshlrev_b32_e32 v66, 16, v43
	v_pk_mul_f32 v[110:111], v[40:41], v[110:111]
	v_mul_f32_e64 v40, |v66|, s26
	v_exp_f32_e32 v40, v40
	v_sub_f32_e32 v38, v93, v67
	v_and_b32_e32 v67, 0xffff0000, v43
	v_mul_f32_e32 v38, 0x3fb8aa3b, v38
	v_add_f32_e32 v41, 1.0, v40
	v_rcp_f32_e32 v42, v41
	v_mul_f32_e64 v41, |v67|, s26
	v_exp_f32_e32 v41, v41
	v_mul_f32_e32 v39, 0x3fb8aa3b, v39
	v_exp_f32_e32 v38, v38
	v_exp_f32_e32 v39, v39
	v_add_f32_e32 v43, 1.0, v41
	v_rcp_f32_e32 v43, v43
	v_cmp_le_f32_e32 vcc, 0, v66
	v_cmp_le_f32_e64 s[38:39], 0, v67
	v_pk_mul_f32 v[40:41], v[40:41], v[42:43]
	s_nop 0
	v_cndmask_b32_e64 v41, v43, v41, s[38:39]
	v_cndmask_b32_e32 v40, v42, v40, vcc
	v_pk_mul_f32 v[40:41], v[68:69], v[40:41]
	v_cvt_pk_bf16_f32 v42, v36, v37
	v_pk_mul_f32 v[66:67], v[38:39], v[40:41]
	v_cvt_pk_bf16_f32 v40, v56, v57
	v_cvt_pk_bf16_f32 v36, v58, v59
	v_cvt_pk_bf16_f32 v39, v66, v67
	v_mov_b64_e32 v[56:57], v[150:151]
	v_mov_b64_e32 v[58:59], v[152:153]
	s_nop 0
	v_mov_b64_e32 v[64:65], v[122:123]
	v_mov_b64_e32 v[66:67], v[124:125]
	v_sub_f32_e32 v76, v102, v2
	v_sub_f32_e32 v77, v2, v102
	v_cvt_pk_bf16_f32 v38, v104, v105
	v_mul_f32_e32 v77, 0x3fb8aa3b, v77
	v_cvt_pk_bf16_f32 v41, v78, v79
	v_exp_f32_e32 v78, v77
	v_sub_f32_e32 v77, v101, v88
	v_mul_f32_e32 v76, 0x3fb8aa3b, v76
	v_mul_f32_e32 v77, 0x3fb8aa3b, v77
	v_exp_f32_e32 v76, v76
	v_exp_f32_e32 v77, v77
	v_mul_f32_e32 v2, 0x3fb8aa3b, v2
	v_cvt_pk_bf16_f32 v37, v106, v107
	v_cvt_pk_bf16_f32 v43, v110, v111
	s_waitcnt vmcnt(0) lgkmcnt(0)
; __device__ __forceinline__ void ld8bf(const bf16_t* p, float (&o)[8]) { unpack8(*(const u32x4*)p, o); }
; __device__ __forceinline__ float sigmoidf_(float x) { return __builtin_amdgcn_rcpf(1.0f + __expf(-x)); }
; __device__ __forceinline__ const float* in_ptr(const Args& a, int i) { asm volatile("" : "+s"(i)); return a.in[i]; }
; #define WAVE_LDS_FENCE() asm volatile("s_waitcnt lgkmcnt(0)" ::: "memory")
; __device__ __forceinline__ bf16x8 pack_frag(const float (&v)[8]) { return __builtin_bit_cast(bf16x8, pack8(v)); }
; __device__ __forceinline__ void w_hg_m3(const Args& a, int l, unsigned char* ws, const bf16_t* proj, bf16_t* y, LAS unsigned char* wl, int b, int ck_, int h, int lane) {
;     ...
;         for (int tb = 0; tb < 4; ++tb) { float fp[8], qv[8], a1[8], a2[8];
;             ld8bf(fsrc + (size_t)(16 * tb + lo) * NIN, fp); ld8bf(proj + (size_t)(row0 + 16 * tb + lo) * NIN + C_HQ + 64 * h + 32 * kk + 8 * fq, qv);
; #pragma unroll
;             for (int j = 0; j < 8; ++j) { float lf, key; hg_lf_key(fp[j], lbv[j], lf, key);
;                 const float q = qv[j] * sigmoidf_(qv[j]); a1[j] = q * __expf(bb[tb][j] - r31[j]); a2[j] = key * __expf(r31[j] - bb[tb][j]); }
;             Qf[tb][kk] = pack_frag(a1); Kf[tb][kk] = pack_frag(a2); }
; #pragma unroll
;         for (int j = 0; j < 8; ++j) er[kk][j] = __expf(r31[j]);
;         __builtin_amdgcn_sched_barrier(0);
;     }
; #pragma unroll
;     for (int kk = 0; kk < 2; ++kk)
; #pragma unroll
;         for (int eb = 0; eb < 4; ++eb) { float sv[8]; ld8bf(Sb + (16 * eb + lo) * 64 + 32 * kk + 8 * fq, sv);
; #pragma unroll
;             for (int j = 0; j < 8; ++j) sv[j] *= er[kk][j];
;             Sf[eb][kk] = pack_frag(sv); }
;     WAVE_LDS_FENCE();
;     w_m3_core<1>(Qf, Kf, Sf, vT, 0.f, proj + (size_t)row0 * NIN + C_HG + 64 * h, in_ptr(a, I_HNW) + l * 256 + 64 * h, y + (size_t)row0 * DM + 768 + 64 * h, lo, fq);
	v_lshlrev_b32_e32 v102, 16, v64
	v_and_b32_e32 v103, 0xffff0000, v64
	v_mul_f32_e32 v64, 0xbfb8aa3b, v102
	v_exp_f32_e32 v64, v64
	s_nop 0
	v_add_f32_e32 v64, 1.0, v64
	v_rcp_f32_e32 v104, v64
	v_mul_f32_e32 v64, 0xbfb8aa3b, v103
	v_exp_f32_e32 v64, v64
	s_nop 0
	v_add_f32_e32 v64, 1.0, v64
	v_rcp_f32_e32 v105, v64
	v_sub_f32_e32 v64, v88, v101
	v_mul_f32_e32 v64, 0x3fb8aa3b, v64
	v_exp_f32_e32 v79, v64
	v_lshlrev_b32_e32 v64, 16, v56
	v_pk_mul_f32 v[102:103], v[104:105], v[102:103]
	v_mul_f32_e64 v101, |v64|, s26
	v_pk_mul_f32 v[76:77], v[76:77], v[102:103]
	v_exp_f32_e32 v102, v101
	v_and_b32_e32 v56, 0xffff0000, v56
	v_cmp_le_f32_e32 vcc, 0, v64
	v_cmp_le_f32_e64 s[38:39], 0, v56
	v_add_f32_e32 v101, 1.0, v102
	v_rcp_f32_e32 v104, v101
	v_mul_f32_e64 v101, |v56|, s26
	v_exp_f32_e32 v103, v101
	v_sub_f32_e32 v56, v100, v89
	v_mul_f32_e32 v56, 0x3fb8aa3b, v56
	v_lshlrev_b32_e32 v64, 16, v65
	v_add_f32_e32 v101, 1.0, v103
	v_rcp_f32_e32 v105, v101
	v_and_b32_e32 v65, 0xffff0000, v65
	v_pk_mul_f32 v[102:103], v[102:103], v[104:105]
	s_nop 0
	v_cndmask_b32_e64 v103, v105, v103, s[38:39]
	v_cndmask_b32_e32 v102, v104, v102, vcc
	v_pk_mul_f32 v[70:71], v[70:71], v[102:103]
	s_nop 0
	v_pk_mul_f32 v[70:71], v[78:79], v[70:71]
	v_exp_f32_e32 v78, v56
	v_sub_f32_e32 v56, v89, v100
	v_mul_f32_e32 v56, 0x3fb8aa3b, v56
	v_exp_f32_e32 v100, v56
	v_sub_f32_e32 v56, v99, v90
	v_mul_f32_e32 v56, 0x3fb8aa3b, v56
	v_exp_f32_e32 v79, v56
	v_mul_f32_e32 v56, 0xbfb8aa3b, v64
	v_exp_f32_e32 v56, v56
	s_nop 0
	v_add_f32_e32 v56, 1.0, v56
	v_rcp_f32_e32 v102, v56
	v_mul_f32_e32 v56, 0xbfb8aa3b, v65
	v_exp_f32_e32 v56, v56
	s_nop 0
	v_add_f32_e32 v56, 1.0, v56
	v_rcp_f32_e32 v103, v56
	v_sub_f32_e32 v56, v90, v99
	v_mul_f32_e32 v56, 0x3fb8aa3b, v56
	v_lshlrev_b32_e32 v99, 16, v57
	v_exp_f32_e32 v101, v56
	v_mul_f32_e64 v56, |v99|, s26
	v_exp_f32_e32 v56, v56
	v_pk_mul_f32 v[64:65], v[102:103], v[64:65]
	v_and_b32_e32 v102, 0xffff0000, v57
	v_pk_mul_f32 v[64:65], v[78:79], v[64:65]
	v_add_f32_e32 v57, 1.0, v56
	v_rcp_f32_e32 v78, v57
	v_mul_f32_e64 v57, |v102|, s26
	v_exp_f32_e32 v57, v57
	v_cmp_le_f32_e32 vcc, 0, v99
	v_cmp_le_f32_e64 s[38:39], 0, v102
	v_and_b32_e32 v99, 0xffff0000, v66
	v_add_f32_e32 v79, 1.0, v57
	v_rcp_f32_e32 v79, v79
	s_nop 0
	v_pk_mul_f32 v[56:57], v[56:57], v[78:79]
	s_nop 0
	v_cndmask_b32_e64 v57, v79, v57, s[38:39]
	v_cndmask_b32_e32 v56, v78, v56, vcc
	v_pk_mul_f32 v[56:57], v[72:73], v[56:57]
	s_nop 0
	v_pk_mul_f32 v[72:73], v[100:101], v[56:57]
	v_sub_f32_e32 v56, v98, v91
	v_sub_f32_e32 v57, v91, v98
	v_lshlrev_b32_e32 v98, 16, v66
	v_mul_f32_e32 v66, 0xbfb8aa3b, v98
	v_exp_f32_e32 v66, v66
	v_mul_f32_e32 v57, 0x3fb8aa3b, v57
	v_exp_f32_e32 v78, v57
	v_sub_f32_e32 v57, v97, v92
	v_add_f32_e32 v66, 1.0, v66
	v_rcp_f32_e32 v100, v66
	v_mul_f32_e32 v66, 0xbfb8aa3b, v99
	v_exp_f32_e32 v66, v66
	v_mul_f32_e32 v56, 0x3fb8aa3b, v56
	v_mul_f32_e32 v57, 0x3fb8aa3b, v57
	v_exp_f32_e32 v56, v56
	v_add_f32_e32 v66, 1.0, v66
	v_rcp_f32_e32 v101, v66
	v_exp_f32_e32 v57, v57
	v_lshlrev_b32_e32 v66, 16, v58
	v_and_b32_e32 v58, 0xffff0000, v58
	v_pk_mul_f32 v[98:99], v[100:101], v[98:99]
	v_cmp_le_f32_e32 vcc, 0, v66
	v_pk_mul_f32 v[98:99], v[56:57], v[98:99]
	v_sub_f32_e32 v56, v92, v97
	v_mul_f32_e32 v56, 0x3fb8aa3b, v56
	v_exp_f32_e32 v79, v56
	v_mul_f32_e64 v56, |v66|, s26
	v_exp_f32_e32 v56, v56
	v_cmp_le_f32_e64 s[38:39], 0, v58
	v_add_f32_e32 v57, 1.0, v56
	v_rcp_f32_e32 v100, v57
	v_mul_f32_e64 v57, |v58|, s26
	v_exp_f32_e32 v57, v57
	s_nop 0
	v_add_f32_e32 v97, 1.0, v57
	v_rcp_f32_e32 v101, v97
	s_nop 0
	v_pk_mul_f32 v[56:57], v[56:57], v[100:101]
	s_nop 0
	v_cndmask_b32_e64 v57, v101, v57, s[38:39]
	v_cndmask_b32_e32 v56, v100, v56, vcc
	v_pk_mul_f32 v[56:57], v[74:75], v[56:57]
	v_exp_f32_e32 v100, v2
	v_pk_mul_f32 v[74:75], v[78:79], v[56:57]
	v_lshlrev_b32_e32 v78, 16, v67
	v_mul_f32_e32 v58, 0xbfb8aa3b, v78
	v_exp_f32_e32 v58, v58
	v_and_b32_e32 v79, 0xffff0000, v67
	v_sub_f32_e32 v56, v96, v93
	v_sub_f32_e32 v57, v93, v96
	v_add_f32_e32 v58, 1.0, v58
	v_rcp_f32_e32 v96, v58
	v_mul_f32_e32 v58, 0xbfb8aa3b, v79
	v_exp_f32_e32 v58, v58
	v_mul_f32_e32 v57, 0x3fb8aa3b, v57
	v_exp_f32_e32 v66, v57
	v_sub_f32_e32 v57, v95, v94
	v_add_f32_e32 v58, 1.0, v58
	v_mul_f32_e32 v56, 0x3fb8aa3b, v56
	v_mul_f32_e32 v57, 0x3fb8aa3b, v57
	v_rcp_f32_e32 v97, v58
	v_exp_f32_e32 v56, v56
	v_exp_f32_e32 v57, v57
	v_mul_f32_e32 v2, 0x3fb8aa3b, v88
	v_pk_mul_f32 v[78:79], v[96:97], v[78:79]
	v_and_b32_e32 v96, 0xffff0000, v59
	v_pk_mul_f32 v[78:79], v[56:57], v[78:79]
	v_sub_f32_e32 v56, v94, v95
	v_mul_f32_e32 v56, 0x3fb8aa3b, v56
	v_lshlrev_b32_e32 v95, 16, v59
	v_exp_f32_e32 v67, v56
	v_mul_f32_e64 v56, |v95|, s26
	v_exp_f32_e32 v56, v56
	v_exp_f32_e32 v101, v2
	v_mul_f32_e32 v2, 0x3fb8aa3b, v89
	v_exp_f32_e32 v102, v2
	v_add_f32_e32 v57, 1.0, v56
	v_rcp_f32_e32 v58, v57
	v_mul_f32_e64 v57, |v96|, s26
	v_exp_f32_e32 v57, v57
	v_mul_f32_e32 v2, 0x3fb8aa3b, v90
	v_cmp_le_f32_e32 vcc, 0, v95
	v_cmp_le_f32_e64 s[38:39], 0, v96
	v_add_f32_e32 v59, 1.0, v57
	v_rcp_f32_e32 v59, v59
	v_exp_f32_e32 v103, v2
	v_mul_f32_e32 v2, 0x3fb8aa3b, v91
	v_exp_f32_e32 v104, v2
	v_pk_mul_f32 v[56:57], v[56:57], v[58:59]
	v_mul_f32_e32 v2, 0x3fb8aa3b, v92
	v_cndmask_b32_e64 v57, v59, v57, s[38:39]
	v_cndmask_b32_e32 v56, v58, v56, vcc
	v_pk_mul_f32 v[56:57], v[68:69], v[56:57]
	v_exp_f32_e32 v105, v2
	v_mul_f32_e32 v2, 0x3fb8aa3b, v93
	v_pk_mul_f32 v[66:67], v[66:67], v[56:57]
	v_exp_f32_e32 v106, v2
	v_mul_f32_e32 v2, 0x3fb8aa3b, v94
	v_cvt_pk_bf16_f32 v56, v76, v77
	v_cvt_pk_bf16_f32 v57, v64, v65
	v_cvt_pk_bf16_f32 v58, v98, v99
	v_cvt_pk_bf16_f32 v59, v78, v79
	v_cvt_pk_bf16_f32 v68, v70, v71
	v_cvt_pk_bf16_f32 v69, v72, v73
	v_cvt_pk_bf16_f32 v70, v74, v75
	v_cvt_pk_bf16_f32 v71, v66, v67
	v_exp_f32_e32 v107, v2
	s_add_u32 s20, s80, s40
	s_addc_u32 s21, s81, s41
	v_lshl_add_u64 v[94:95], v[0:1], 1, s[20:21]
	v_lshlrev_b32_e32 v2, 7, v114
	v_lshl_add_u64 v[0:1], v[94:95], 0, v[2:3]
	global_load_dwordx4 v[146:149], v[0:1], off
	global_load_dwordx4 v[150:153], v[0:1], off offset:2048
	global_load_dwordx4 v[122:125], v[0:1], off offset:64
	global_load_dwordx4 v[134:137], v[0:1], off offset:2112
	v_mov_b32_e32 v130, 0x1000
	v_mov_b32_e32 v131, 0
	v_lshl_add_u64 v[186:187], v[0:1], 0, v[130:131]
	global_load_dwordx4 v[188:191], v[186:187], off
	global_load_dwordx4 v[192:195], v[186:187], off offset:2048
	global_load_dwordx4 v[196:199], v[186:187], off offset:64
	v_or_b32_e32 v92, 0x1000, v2
	v_mov_b32_e32 v93, v3
	v_or_b32_e32 v2, 0x1800, v2
	s_add_u32 s20, s67, s88
	v_lshlrev_b32_e32 v120, 2, v108
	s_addc_u32 s21, s68, 0
	v_cmp_gt_i32_e64 s[40:41], v120, v114
	s_add_u32 s48, s20, 0x1600
	s_mov_b32 s20, 12
	s_addc_u32 s49, s21, 0
	v_cmp_lt_i32_e64 s[42:43], v120, v114
	v_ashrrev_i32_e32 v121, 31, v120
	s_waitcnt vmcnt(0)
; __device__ __forceinline__ void ld8bf(const bf16_t* p, float (&o)[8]) { unpack8(*(const u32x4*)p, o); }
; __device__ __forceinline__ const float* in_ptr(const Args& a, int i) { asm volatile("" : "+s"(i)); return a.in[i]; }
; #define WAVE_LDS_FENCE() asm volatile("s_waitcnt lgkmcnt(0)" ::: "memory")
; __device__ __forceinline__ bf16x8 pack_frag(const float (&v)[8]) { return __builtin_bit_cast(bf16x8, pack8(v)); }
; template <int KIND>
; __device__ __forceinline__ void w_m3_core(const bf16x8 (&Qf)[4][2], const bf16x8 (&Kf)[4][2], const bf16x8 (&Sf)[4][2], const LAS bf16_t* vT, float lg,
;                                           const bf16_t* gsrc, const float* nw, bf16_t* ydst, int lo, int fq) {
;     ...
;                     s = __builtin_amdgcn_mfma_f32_16x16x32_bf16(Kf[mb][0], Qf[nb][0], s, 0, 0, 0); s = __builtin_amdgcn_mfma_f32_16x16x32_bf16(Kf[mb][1], Qf[nb][1], s, 0, 0, 0);
; __device__ __forceinline__ void w_hg_m3(const Args& a, int l, unsigned char* ws, const bf16_t* proj, bf16_t* y, LAS unsigned char* wl, int b, int ck_, int h, int lane) {
;     ...
; #pragma unroll
;     for (int kk = 0; kk < 2; ++kk)
; #pragma unroll
;         for (int eb = 0; eb < 4; ++eb) { float sv[8]; ld8bf(Sb + (16 * eb + lo) * 64 + 32 * kk + 8 * fq, sv);
; #pragma unroll
;             for (int j = 0; j < 8; ++j) sv[j] *= er[kk][j];
;             Sf[eb][kk] = pack_frag(sv); }
;     WAVE_LDS_FENCE();
;     w_m3_core<1>(Qf, Kf, Sf, vT, 0.f, proj + (size_t)row0 * NIN + C_HG + 64 * h, in_ptr(a, I_HNW) + l * 256 + 64 * h, y + (size_t)row0 * DM + 768 + 64 * h, lo, fq);
	v_mov_b64_e32 v[64:65], v[146:147]
	v_mov_b64_e32 v[66:67], v[148:149]
	v_lshlrev_b32_e32 v72, 16, v64
	v_and_b32_e32 v73, 0xffff0000, v64
	v_lshlrev_b32_e32 v64, 16, v65
	v_and_b32_e32 v65, 0xffff0000, v65
	v_pk_mul_f32 v[74:75], v[84:85], v[64:65]
	v_lshlrev_b32_e32 v64, 16, v66
	v_and_b32_e32 v65, 0xffff0000, v66
	v_pk_mul_f32 v[72:73], v[86:87], v[72:73]
	v_pk_mul_f32 v[76:77], v[82:83], v[64:65]
	v_lshlrev_b32_e32 v64, 16, v67
	v_and_b32_e32 v65, 0xffff0000, v67
	v_pk_mul_f32 v[78:79], v[80:81], v[64:65]
	v_cvt_pk_bf16_f32 v64, v72, v73
	v_cvt_pk_bf16_f32 v65, v74, v75
	v_mov_b64_e32 v[72:73], v[150:151]
	v_mov_b64_e32 v[74:75], v[152:153]
	v_cvt_pk_bf16_f32 v66, v76, v77
	v_cvt_pk_bf16_f32 v67, v78, v79
	s_waitcnt vmcnt(0)
	v_lshlrev_b32_e32 v76, 16, v72
	v_and_b32_e32 v77, 0xffff0000, v72
	v_lshlrev_b32_e32 v72, 16, v73
	v_and_b32_e32 v73, 0xffff0000, v73
	v_pk_mul_f32 v[78:79], v[84:85], v[72:73]
	v_lshlrev_b32_e32 v72, 16, v74
	v_and_b32_e32 v73, 0xffff0000, v74
	v_pk_mul_f32 v[76:77], v[86:87], v[76:77]
	v_pk_mul_f32 v[88:89], v[82:83], v[72:73]
	v_lshlrev_b32_e32 v72, 16, v75
	v_and_b32_e32 v73, 0xffff0000, v75
	v_pk_mul_f32 v[90:91], v[80:81], v[72:73]
	v_cvt_pk_bf16_f32 v72, v76, v77
	v_lshl_add_u64 v[76:77], v[94:95], 0, v[92:93]
	v_cvt_pk_bf16_f32 v73, v78, v79
	v_mov_b64_e32 v[76:77], v[188:189]
	v_mov_b64_e32 v[78:79], v[190:191]
	v_cvt_pk_bf16_f32 v74, v88, v89
	v_cvt_pk_bf16_f32 v75, v90, v91
	s_waitcnt vmcnt(0)
	v_lshlrev_b32_e32 v88, 16, v76
	v_and_b32_e32 v89, 0xffff0000, v76
	v_lshlrev_b32_e32 v76, 16, v77
	v_and_b32_e32 v77, 0xffff0000, v77
	v_pk_mul_f32 v[90:91], v[84:85], v[76:77]
	v_lshlrev_b32_e32 v76, 16, v78
	v_and_b32_e32 v77, 0xffff0000, v78
	v_pk_mul_f32 v[88:89], v[86:87], v[88:89]
	v_pk_mul_f32 v[96:97], v[82:83], v[76:77]
	v_lshlrev_b32_e32 v76, 16, v79
	v_and_b32_e32 v77, 0xffff0000, v79
	v_pk_mul_f32 v[98:99], v[80:81], v[76:77]
	v_cvt_pk_bf16_f32 v76, v88, v89
	v_lshl_add_u64 v[88:89], v[94:95], 0, v[2:3]
	v_cvt_pk_bf16_f32 v77, v90, v91
	v_mov_b64_e32 v[88:89], v[192:193]
	v_mov_b64_e32 v[90:91], v[194:195]
	v_cvt_pk_bf16_f32 v78, v96, v97
	v_cvt_pk_bf16_f32 v79, v98, v99
	v_mfma_f32_16x16x32_bf16 v[116:119], v[72:75], v[52:55], 0
	s_waitcnt vmcnt(0)
	v_lshlrev_b32_e32 v96, 16, v88
	v_and_b32_e32 v97, 0xffff0000, v88
	v_lshlrev_b32_e32 v88, 16, v89
	v_and_b32_e32 v89, 0xffff0000, v89
	v_pk_mul_f32 v[84:85], v[84:85], v[88:89]
	v_lshlrev_b32_e32 v88, 16, v90
	v_and_b32_e32 v89, 0xffff0000, v90
	v_pk_mul_f32 v[86:87], v[86:87], v[96:97]
	v_pk_mul_f32 v[82:83], v[82:83], v[88:89]
	v_lshlrev_b32_e32 v88, 16, v91
	v_and_b32_e32 v89, 0xffff0000, v91
	v_pk_mul_f32 v[88:89], v[80:81], v[88:89]
	v_cvt_pk_bf16_f32 v80, v86, v87
	v_cvt_pk_bf16_f32 v81, v84, v85
	v_mov_b64_e32 v[84:85], v[122:123]
	v_mov_b64_e32 v[86:87], v[124:125]
	v_cvt_pk_bf16_f32 v82, v82, v83
	v_cvt_pk_bf16_f32 v83, v88, v89
	v_lshl_add_u64 v[96:97], v[94:95], 0, 64
	v_mfma_f32_16x16x32_bf16 v[138:141], v[76:79], v[52:55], 0
	s_waitcnt vmcnt(0)
	v_lshlrev_b32_e32 v88, 16, v84
	v_and_b32_e32 v89, 0xffff0000, v84
	v_lshlrev_b32_e32 v84, 16, v85
	v_and_b32_e32 v85, 0xffff0000, v85
	v_pk_mul_f32 v[90:91], v[102:103], v[84:85]
	v_lshlrev_b32_e32 v84, 16, v86
	v_and_b32_e32 v85, 0xffff0000, v86
	v_pk_mul_f32 v[88:89], v[100:101], v[88:89]
	v_pk_mul_f32 v[94:95], v[104:105], v[84:85]
	v_lshlrev_b32_e32 v84, 16, v87
	v_and_b32_e32 v85, 0xffff0000, v87
	v_pk_mul_f32 v[98:99], v[106:107], v[84:85]
	v_cvt_pk_bf16_f32 v84, v88, v89
	v_cvt_pk_bf16_f32 v85, v90, v91
	v_mov_b64_e32 v[88:89], v[134:135]
	v_mov_b64_e32 v[90:91], v[136:137]
	v_cvt_pk_bf16_f32 v86, v94, v95
	v_cvt_pk_bf16_f32 v87, v98, v99
	s_waitcnt vmcnt(0)
	v_lshlrev_b32_e32 v0, 16, v88
	v_and_b32_e32 v1, 0xffff0000, v88
	v_lshlrev_b32_e32 v88, 16, v89
	v_and_b32_e32 v89, 0xffff0000, v89
	v_pk_mul_f32 v[94:95], v[102:103], v[88:89]
	v_lshlrev_b32_e32 v88, 16, v90
	v_and_b32_e32 v89, 0xffff0000, v90
	v_pk_mul_f32 v[0:1], v[100:101], v[0:1]
	v_pk_mul_f32 v[98:99], v[104:105], v[88:89]
	v_lshlrev_b32_e32 v88, 16, v91
	v_and_b32_e32 v89, 0xffff0000, v91
	v_pk_mul_f32 v[110:111], v[106:107], v[88:89]
	v_cvt_pk_bf16_f32 v88, v0, v1
	v_lshl_add_u64 v[0:1], v[96:97], 0, v[92:93]
	v_cvt_pk_bf16_f32 v89, v94, v95
	v_mov_b64_e32 v[92:93], v[196:197]
	v_mov_b64_e32 v[94:95], v[198:199]
	v_cvt_pk_bf16_f32 v90, v98, v99
	v_cvt_pk_bf16_f32 v91, v110, v111
	s_waitcnt vmcnt(0)
	v_lshlrev_b32_e32 v0, 16, v92
	v_and_b32_e32 v1, 0xffff0000, v92
	v_lshlrev_b32_e32 v92, 16, v93
	v_and_b32_e32 v93, 0xffff0000, v93
	v_pk_mul_f32 v[98:99], v[102:103], v[92:93]
	v_lshlrev_b32_e32 v92, 16, v94
	v_and_b32_e32 v93, 0xffff0000, v94
	v_pk_mul_f32 v[0:1], v[100:101], v[0:1]
	v_pk_mul_f32 v[110:111], v[104:105], v[92:93]
	v_lshlrev_b32_e32 v92, 16, v95
	v_and_b32_e32 v93, 0xffff0000, v95
	v_pk_mul_f32 v[112:113], v[106:107], v[92:93]
	v_cvt_pk_bf16_f32 v92, v0, v1
	v_lshl_add_u64 v[0:1], v[96:97], 0, v[2:3]
	v_cvt_pk_bf16_f32 v93, v98, v99
	global_load_dwordx4 v[96:99], v[0:1], off
	v_or_b32_e32 v2, 2, v120
	s_waitcnt lgkmcnt(0)
	s_ashr_i32 s21, s20, 31
	v_cmp_gt_i32_e64 s[38:39], v2, v114
	s_lshl_b64 s[20:21], s[20:21], 3
	s_add_u32 s20, s0, s20
	s_addc_u32 s21, s1, s21
	v_cvt_pk_bf16_f32 v94, v110, v111
	s_load_dwordx2 s[20:21], s[20:21], 0x0
	v_cvt_pk_bf16_f32 v95, v112, v113
	v_mfma_f32_16x16x32_bf16 v[142:145], v[88:91], v[60:63], v[116:119]
	s_lshl_b64 s[34:35], s[36:37], 2
	s_waitcnt lgkmcnt(0)
; template <int KIND>
; __device__ __forceinline__ void w_m3_core(const bf16x8 (&Qf)[4][2], const bf16x8 (&Kf)[4][2], const bf16x8 (&Sf)[4][2], const LAS bf16_t* vT, float lg,
;                                           const bf16_t* gsrc, const float* nw, bf16_t* ydst, int lo, int fq) {
;     ...
;     for (int nb = 0; nb < 4; ++nb) {
;         f32x4 O[4], O2[4];
; #pragma unroll
;         for (int eb = 0; eb < 4; ++eb) { O[eb] = (f32x4){0.f, 0.f, 0.f, 0.f}; O2[eb] = (f32x4){0.f, 0.f, 0.f, 0.f}; }
; #pragma unroll
;         for (int kk2 = 0; kk2 < 2; ++kk2) {
;             if (2 * kk2 > nb) continue;
;             float pv[8];
; #pragma unroll
;             for (int hh = 0; hh < 2; ++hh) { const int mb = 2 * kk2 + hh;
;                 if (mb <= nb) { f32x4 s = {0.f, 0.f, 0.f, 0.f};
;                     s = __builtin_amdgcn_mfma_f32_16x16x32_bf16(Kf[mb][0], Qf[nb][0], s, 0, 0, 0); s = __builtin_amdgcn_mfma_f32_16x16x32_bf16(Kf[mb][1], Qf[nb][1], s, 0, 0, 0);
; #pragma unroll
;                     for (int r = 0; r < 4; ++r) { const int m = 16 * mb + 4 * fq + r, n = 16 * nb + lo; float v = s[r];
;                         if (KIND == 0) v *= __expf((float)(n - m) * lg);
;                         if (mb == nb) v = (m <= n) ? v : 0.f;
;                         pv[4 * hh + r] = v; }
;                 } else {
; #pragma unroll
;                     for (int r = 0; r < 4; ++r) pv[4 * hh + r] = 0.f; }
;             }
;             const bf16x8 Pf = pack_frag(pv);
; #pragma unroll
;             for (int eb = 0; eb < 4; ++eb)
;                 O[eb] = __builtin_amdgcn_mfma_f32_16x16x32_bf16(tr_frag(vT, 32 * kk2 + 4 * fq, 32 * kk2 + 16 + 4 * fq, 16 * eb, lo), Pf, O[eb], 0, 0, 0);
;         }
; #pragma unroll
;         for (int kk = 0; kk < 2; ++kk)
; #pragma unroll
;             for (int eb = 0; eb < 4; ++eb) O2[eb] = __builtin_amdgcn_mfma_f32_16x16x32_bf16(Sf[eb][kk], Qf[nb][kk], O2[eb], 0, 0, 0);
;         const float osc = KIND == 0 ? __expf((float)(16 * nb + lo + 1) * lg) : 1.0f;
; #pragma unroll
;         for (int eb = 0; eb < 4; ++eb) O[eb] = O[eb] + O2[eb] * osc;
;         float ss = 0.f;
; #pragma unroll
;         for (int eb = 0; eb < 4; ++eb) ss += (O[eb][0] * O[eb][0] + O[eb][1] * O[eb][1]) + (O[eb][2] * O[eb][2] + O[eb][3] * O[eb][3]);
;         { const int ln = (fq << 4) | lo; ss += bperm_f(ln ^ 16, ss); ss += bperm_f(ln ^ 32, ss); }
	s_add_u32 s27, s20, s34
	v_mfma_f32_16x16x32_bf16 v[138:141], v[92:95], v[60:63], v[138:141]
	s_addc_u32 s35, s21, s35
	s_lshl_b64 s[20:21], s[24:25], 2
	s_add_u32 s34, s27, s20
	s_addc_u32 s35, s35, s21
	v_lshl_add_u64 v[186:187], v[120:121], 2, s[34:35]
	global_load_dwordx4 v[146:149], v[186:187], off
	global_load_dwordx4 v[150:153], v[186:187], off offset:64
	global_load_dwordx4 v[188:191], v[186:187], off offset:128
	global_load_dwordx4 v[192:195], v[186:187], off offset:192
	s_lshl_b64 s[20:21], s[86:87], 11
	s_add_u32 s20, s10, s20
	s_addc_u32 s21, s11, s21
	s_add_u32 s46, s20, s88
	s_addc_u32 s47, s21, 0
	s_waitcnt vmcnt(0)
	v_lshlrev_b32_e32 v0, 16, v96
	v_and_b32_e32 v1, 0xffff0000, v96
	v_lshlrev_b32_e32 v96, 16, v97
	v_and_b32_e32 v97, 0xffff0000, v97
	v_pk_mul_f32 v[0:1], v[100:101], v[0:1]
	v_pk_mul_f32 v[100:101], v[102:103], v[96:97]
	v_lshlrev_b32_e32 v96, 16, v98
	v_and_b32_e32 v97, 0xffff0000, v98
	v_pk_mul_f32 v[102:103], v[104:105], v[96:97]
	v_lshlrev_b32_e32 v96, 16, v99
	v_and_b32_e32 v97, 0xffff0000, v99
	v_pk_mul_f32 v[104:105], v[106:107], v[96:97]
	v_cvt_pk_bf16_f32 v97, v100, v101
	v_cvt_pk_bf16_f32 v98, v102, v103
	v_mfma_f32_16x16x32_bf16 v[100:103], v[20:23], v[52:55], 0
	v_cvt_pk_bf16_f32 v96, v0, v1
	v_lshrrev_b32_e32 v0, 2, v114
	v_lshlrev_b32_e32 v1, 3, v114
	v_mfma_f32_16x16x32_bf16 v[100:103], v[24:27], v[60:63], v[100:103]
	v_cvt_pk_bf16_f32 v99, v104, v105
	v_or_b32_e32 v104, v120, v0
	v_lshlrev_b32_e32 v0, 2, v114
	v_and_b32_e32 v105, 24, v1
	v_lshlrev_b32_e32 v1, 6, v108
	v_bitop3_b32 v130, v1, 64, v0 bitop3:0x36
	v_bitop3_b32 v129, v1, s96, v0 bitop3:0x36
	s_nop 0
	v_cndmask_b32_e64 v0, v100, 0, s[40:41]
	v_or_b32_e32 v100, 3, v120
	v_cmp_gt_i32_e32 vcc, v100, v114
	v_cndmask_b32_e64 v1, 0, v101, s[42:43]
	v_cndmask_b32_e64 v2, v102, 0, s[38:39]
	v_cndmask_b32_e64 v100, v103, 0, vcc
	v_cvt_pk_bf16_f32 v0, v0, v1
	v_cvt_pk_bf16_f32 v1, v2, v100
	v_mul_lo_u32 v100, v104, s23
	v_add3_u32 v131, s2, v105, v100
	ds_read_b64_tr_b16 v[102:103], v131 offset:2304
	ds_read_b64_tr_b16 v[100:101], v131
	ds_read_b64_tr_b16 v[104:105], v131 offset:32
	ds_read_b64_tr_b16 v[106:107], v131 offset:2336
	ds_read_b64_tr_b16 v[108:109], v131 offset:64
	ds_read_b64_tr_b16 v[110:111], v131 offset:2368
	v_mov_b32_e32 v2, v3
	s_waitcnt lgkmcnt(0)
	s_nop 0
	v_mfma_f32_16x16x32_bf16 v[122:125], v[108:111], v[0:3], 0
	ds_read_b64_tr_b16 v[108:109], v131 offset:96
	ds_read_b64_tr_b16 v[110:111], v131 offset:2400
	s_waitcnt lgkmcnt(0)
	v_mfma_f32_16x16x32_bf16 v[134:137], v[108:111], v[0:3], 0
	v_mfma_f32_16x16x32_bf16 v[108:111], v[64:67], v[52:55], 0
	v_mfma_f32_16x16x32_bf16 v[52:55], v[80:83], v[52:55], 0
	v_mfma_f32_16x16x32_bf16 v[100:103], v[100:103], v[0:3], 0
	v_mfma_f32_16x16x32_bf16 v[108:111], v[84:87], v[60:63], v[108:111]
	v_mfma_f32_16x16x32_bf16 v[104:107], v[104:107], v[0:3], 0
	v_mfma_f32_16x16x32_bf16 v[52:55], v[96:99], v[60:63], v[52:55]
	s_nop 5
	v_add_f32_e64 v116, v102, v110
	v_add_f32_e64 v117, v103, v111
	v_pk_add_f32 v[118:119], v[100:101], v[108:109]
	v_pk_add_f32 v[112:113], v[104:105], v[142:143]
	v_pk_add_f32 v[110:111], v[106:107], v[144:145]
	v_pk_add_f32 v[108:109], v[122:123], v[138:139]
	v_pk_add_f32 v[0:1], v[136:137], v[54:55]
	v_pk_add_f32 v[104:105], v[134:135], v[52:53]
	v_pk_mul_f32 v[52:53], v[116:117], v[116:117]
	v_pk_mul_f32 v[54:55], v[118:119], v[118:119]
	v_mul_f32_e32 v2, v104, v104
	v_pk_mov_b32 v[60:61], v[54:55], v[52:53] op_sel:[1,0]
	v_mov_b32_e32 v55, v53
	v_pk_add_f32 v[52:53], v[60:61], v[54:55]
	v_pk_mul_f32 v[54:55], v[110:111], v[110:111]
	v_pk_mul_f32 v[60:61], v[112:113], v[112:113]
	v_pk_add_f32 v[52:53], v[52:53], v[52:53] op_sel:[0,1] op_sel_hi:[1,0]
	v_pk_mov_b32 v[62:63], v[60:61], v[54:55] op_sel:[1,0]
	v_mov_b32_e32 v61, v55
	v_pk_add_f32 v[54:55], v[62:63], v[60:61]
	v_mul_f32_e32 v60, v105, v105
	v_pk_add_f32 v[54:55], v[54:55], v[54:55] op_sel:[0,1] op_sel_hi:[1,0]
	v_pk_add_f32 v[106:107], v[124:125], v[140:141]
	v_mov_b32_e32 v53, v2
	v_mov_b32_e32 v55, v60
	v_mul_f32_e32 v2, v109, v109
	v_mul_f32_e32 v61, v0, v0
	v_pk_add_f32 v[52:53], v[52:53], v[54:55]
	v_pk_fma_f32 v[54:55], v[108:109], v[108:109], v[2:3] op_sel_hi:[1,1,0]
	v_mul_f32_e32 v2, v107, v107
	v_mul_f32_e32 v62, v1, v1
	v_mov_b32_e32 v55, v61
	v_pk_fma_f32 v[60:61], v[106:107], v[106:107], v[2:3] op_sel_hi:[1,1,0]
	v_mov_b64_e32 v[100:101], s[48:49]
	v_mov_b32_e32 v61, v62
	v_pk_add_f32 v[54:55], v[54:55], v[60:61]
	v_lshlrev_b64 v[62:63], 1, v[120:121]
	v_pk_add_f32 v[52:53], v[52:53], v[54:55]
	v_lshl_add_u64 v[60:61], v[120:121], 2, s[34:35]
	v_add_f32_e32 v2, v52, v53
	ds_bpermute_b32 v52, v130, v2
	s_waitcnt lgkmcnt(0)
	v_add_f32_e32 v2, v2, v52
	ds_bpermute_b32 v52, v129, v2
	s_waitcnt lgkmcnt(0)
	v_add_f32_e32 v2, v2, v52
	v_fmamk_f32 v2, v2, 0x3c800000, v200
	v_cmp_gt_f32_e64 s[44:45], s29, v2
	v_mul_f32_e32 v52, 0x4b800000, v2
	s_nop 0
	v_cndmask_b32_e64 v2, v2, v52, s[44:45]
	v_rsq_f32_e32 v2, v2
	s_nop 0
	v_mul_f32_e32 v52, 0x45800000, v2
	v_cndmask_b32_e64 v102, v2, v52, s[44:45]
	v_mad_u64_u32 v[52:53], s[20:21], v114, s72, v[100:101]
	v_lshlrev_b32_e32 v2, 11, v114
	v_lshl_add_u64 v[114:115], v[52:53], 0, v[62:63]
	v_mov_b64_e32 v[124:125], v[222:223]
	v_mov_b64_e32 v[52:53], v[146:147]
	v_mov_b64_e32 v[54:55], v[148:149]
	v_lshl_add_u64 v[122:123], s[46:47], 0, v[2:3]
	v_pk_mul_f32 v[118:119], v[118:119], v[102:103] op_sel_hi:[1,0]
	v_pk_mul_f32 v[116:117], v[116:117], v[102:103] op_sel_hi:[1,0]
	v_pk_mul_f32 v[112:113], v[112:113], v[102:103] op_sel_hi:[1,0]
	v_pk_mul_f32 v[110:111], v[110:111], v[102:103] op_sel_hi:[1,0]
	s_waitcnt lgkmcnt(0)
; __device__ __forceinline__ float bperm_f(int src_lane, float v) { return __builtin_bit_cast(float, __builtin_amdgcn_ds_bpermute(src_lane << 2, __builtin_bit_cast(int, v))); }
; template <int KIND>
; __device__ __forceinline__ void w_m3_core(const bf16x8 (&Qf)[4][2], const bf16x8 (&Kf)[4][2], const bf16x8 (&Sf)[4][2], const LAS bf16_t* vT, float lg,
;                                           const bf16_t* gsrc, const float* nw, bf16_t* ydst, int lo, int fq) {
;     ...
;                     s = __builtin_amdgcn_mfma_f32_16x16x32_bf16(Kf[mb][0], Qf[nb][0], s, 0, 0, 0); s = __builtin_amdgcn_mfma_f32_16x16x32_bf16(Kf[mb][1], Qf[nb][1], s, 0, 0, 0);
; #pragma unroll
;                     for (int r = 0; r < 4; ++r) { const int m = 16 * mb + 4 * fq + r, n = 16 * nb + lo; float v = s[r];
;                         if (KIND == 0) v *= __expf((float)(n - m) * lg);
;                         if (mb == nb) v = (m <= n) ? v : 0.f;
;                         pv[4 * hh + r] = v; }
;                 } else {
; #pragma unroll
;                     for (int r = 0; r < 4; ++r) pv[4 * hh + r] = 0.f; }
;             }
;             const bf16x8 Pf = pack_frag(pv);
; #pragma unroll
;             for (int eb = 0; eb < 4; ++eb)
;                 O[eb] = __builtin_amdgcn_mfma_f32_16x16x32_bf16(tr_frag(vT, 32 * kk2 + 4 * fq, 32 * kk2 + 16 + 4 * fq, 16 * eb, lo), Pf, O[eb], 0, 0, 0);
;         }
; #pragma unroll
;         for (int kk = 0; kk < 2; ++kk)
; #pragma unroll
;             for (int eb = 0; eb < 4; ++eb) O2[eb] = __builtin_amdgcn_mfma_f32_16x16x32_bf16(Sf[eb][kk], Qf[nb][kk], O2[eb], 0, 0, 0);
;         const float osc = KIND == 0 ? __expf((float)(16 * nb + lo + 1) * lg) : 1.0f;
; #pragma unroll
;         for (int eb = 0; eb < 4; ++eb) O[eb] = O[eb] + O2[eb] * osc;
;         float ss = 0.f;
; #pragma unroll
;         for (int eb = 0; eb < 4; ++eb) ss += (O[eb][0] * O[eb][0] + O[eb][1] * O[eb][1]) + (O[eb][2] * O[eb][2] + O[eb][3] * O[eb][3]);
;         { const int ln = (fq << 4) | lo; ss += bperm_f(ln ^ 16, ss); ss += bperm_f(ln ^ 32, ss); }
;         const float rs = rsqrtf(ss * (1.0f / 64.0f) + EPS);
;         const size_t n = 16 * nb + lo;
; #pragma unroll
;         for (int eb = 0; eb < 4; ++eb) { const int e0 = 16 * eb + 4 * fq;
;             const unsigned long long gw_ = *(const unsigned long long*)(gsrc + n * NIN + e0); const f32x4 w4 = *(const f32x4*)(nw + e0);
	v_lshlrev_b32_e32 v120, 16, v124
	v_mul_f32_e32 v2, 0xbfb8aa3b, v120
	v_exp_f32_e32 v2, v2
	v_and_b32_e32 v121, 0xffff0000, v124
	v_lshlrev_b32_e32 v124, 16, v125
	v_and_b32_e32 v125, 0xffff0000, v125
	v_add_f32_e32 v2, 1.0, v2
	v_rcp_f32_e32 v134, v2
	v_mul_f32_e32 v2, 0xbfb8aa3b, v121
	v_exp_f32_e32 v2, v2
	v_pk_mul_f32 v[52:53], v[52:53], v[118:119]
	v_pk_mul_f32 v[54:55], v[54:55], v[116:117]
	v_add_f32_e32 v2, 1.0, v2
	v_rcp_f32_e32 v135, v2
	v_mul_f32_e32 v2, 0xbfb8aa3b, v124
	v_exp_f32_e32 v2, v2
	v_pk_mul_f32 v[118:119], v[134:135], v[120:121]
	s_nop 0
	v_pk_mul_f32 v[52:53], v[118:119], v[52:53]
	v_add_f32_e32 v2, 1.0, v2
	v_rcp_f32_e32 v118, v2
	v_mul_f32_e32 v2, 0xbfb8aa3b, v125
	v_exp_f32_e32 v2, v2
	s_nop 0
	v_add_f32_e32 v2, 1.0, v2
	v_rcp_f32_e32 v119, v2
	s_nop 0
	v_pk_mul_f32 v[116:117], v[118:119], v[124:125]
	s_nop 0
	v_pk_mul_f32 v[54:55], v[116:117], v[54:55]
	v_cvt_pk_bf16_f32 v116, v52, v53
	v_cvt_pk_bf16_f32 v117, v54, v55
	v_lshl_add_u64 v[52:53], v[122:123], 0, v[62:63]
	global_store_dwordx2 v[52:53], v[116:117], off offset:1536
	v_mov_b64_e32 v[54:55], v[224:225]
	s_nop 0
	v_mov_b64_e32 v[116:117], v[150:151]
	v_mov_b64_e32 v[118:119], v[152:153]
	s_waitcnt lgkmcnt(0)
	v_lshlrev_b32_e32 v120, 16, v54
	v_mul_f32_e32 v2, 0xbfb8aa3b, v120
	v_exp_f32_e32 v2, v2
	v_and_b32_e32 v121, 0xffff0000, v54
	v_lshlrev_b32_e32 v54, 16, v55
	v_and_b32_e32 v55, 0xffff0000, v55
	v_add_f32_e32 v2, 1.0, v2
	v_rcp_f32_e32 v122, v2
	v_mul_f32_e32 v2, 0xbfb8aa3b, v121
	v_exp_f32_e32 v2, v2
	v_pk_mul_f32 v[112:113], v[116:117], v[112:113]
	v_pk_mul_f32 v[110:111], v[118:119], v[110:111]
	v_mul_f32_e32 v118, v109, v102
	v_add_f32_e32 v2, 1.0, v2
	v_rcp_f32_e32 v123, v2
	v_mul_f32_e32 v2, 0xbfb8aa3b, v54
	v_exp_f32_e32 v2, v2
	v_pk_mul_f32 v[116:117], v[122:123], v[120:121]
	s_nop 0
	v_pk_mul_f32 v[112:113], v[116:117], v[112:113]
	v_add_f32_e32 v2, 1.0, v2
	v_rcp_f32_e32 v116, v2
	v_mul_f32_e32 v2, 0xbfb8aa3b, v55
	v_exp_f32_e32 v2, v2
	v_mul_f32_e32 v120, v106, v102
	v_add_f32_e32 v2, 1.0, v2
	v_rcp_f32_e32 v117, v2
	s_nop 0
	v_pk_mul_f32 v[54:55], v[116:117], v[54:55]
	s_nop 0
	v_pk_mul_f32 v[54:55], v[54:55], v[110:111]
	v_cvt_pk_bf16_f32 v110, v112, v113
	v_cvt_pk_bf16_f32 v111, v54, v55
	global_store_dwordx2 v[52:53], v[110:111], off offset:1568
	v_mov_b64_e32 v[54:55], v[226:227]
	s_nop 0
	v_mov_b64_e32 v[110:111], v[188:189]
	v_mov_b64_e32 v[112:113], v[190:191]
	v_mul_f32_e32 v116, v108, v102
	s_waitcnt lgkmcnt(0)
	v_lshlrev_b32_e32 v117, 16, v54
	v_mul_f32_e32 v2, 0xbfb8aa3b, v117
	v_exp_f32_e32 v2, v2
	v_and_b32_e32 v119, 0xffff0000, v54
	v_lshlrev_b32_e32 v121, 16, v55
	v_and_b32_e32 v55, 0xffff0000, v55
	v_add_f32_e32 v2, 1.0, v2
	v_rcp_f32_e32 v123, v2
	v_mul_f32_e32 v2, 0xbfb8aa3b, v119
	v_exp_f32_e32 v2, v2
	v_mov_b32_e32 v108, v111
	v_mul_f32_e32 v54, v107, v102
	v_mov_b32_e32 v122, v110
	v_add_f32_e32 v2, 1.0, v2
	v_rcp_f32_e32 v109, v2
	v_mul_f32_e32 v2, 0xbfb8aa3b, v121
	v_exp_f32_e32 v2, v2
	v_pk_mul_f32 v[116:117], v[122:123], v[116:117]
	v_pk_mul_f32 v[108:109], v[108:109], v[118:119]
	v_mov_b32_e32 v110, v112
	v_add_f32_e32 v2, 1.0, v2
	v_rcp_f32_e32 v111, v2
	v_mul_f32_e32 v2, 0xbfb8aa3b, v55
	v_exp_f32_e32 v2, v2
	v_mov_b32_e32 v106, v113
	v_pk_mul_f32 v[110:111], v[110:111], v[120:121]
	v_mul_f32_e32 v112, v105, v102
	v_add_f32_e32 v2, 1.0, v2
	v_rcp_f32_e32 v107, v2
	s_nop 0
	v_pk_mul_f32 v[54:55], v[106:107], v[54:55]
	v_mov_b32_e32 v106, v116
	v_mov_b32_e32 v107, v108
	v_mov_b32_e32 v108, v117
	v_pk_mul_f32 v[106:107], v[106:107], v[108:109]
	v_mov_b32_e32 v108, v110
	v_mov_b32_e32 v109, v54
	v_mov_b32_e32 v54, v111
	v_pk_mul_f32 v[54:55], v[108:109], v[54:55]
	v_cvt_pk_bf16_f32 v106, v106, v107
	v_cvt_pk_bf16_f32 v107, v54, v55
	global_store_dwordx2 v[52:53], v[106:107], off offset:1600
	v_mov_b64_e32 v[54:55], v[228:229]
	s_nop 0
	v_mov_b64_e32 v[106:107], v[192:193]
	v_mov_b64_e32 v[108:109], v[194:195]
	v_mul_f32_e32 v114, v0, v102
	v_mul_f32_e32 v110, v104, v102
	s_waitcnt lgkmcnt(0)
	v_lshlrev_b32_e32 v111, 16, v54
	v_lshlrev_b32_e32 v115, 16, v55
	v_mul_f32_e32 v2, 0xbfb8aa3b, v111
	v_mul_f32_e32 v0, 0xbfb8aa3b, v115
	v_exp_f32_e32 v2, v2
	v_exp_f32_e32 v0, v0
	v_and_b32_e32 v113, 0xffff0000, v54
	v_and_b32_e32 v55, 0xffff0000, v55
	v_add_f32_e32 v2, 1.0, v2
	v_add_f32_e32 v0, 1.0, v0
	v_rcp_f32_e32 v117, v2
	v_mul_f32_e32 v2, 0xbfb8aa3b, v113
	v_mov_b32_e32 v104, v107
	v_rcp_f32_e32 v107, v0
	v_mul_f32_e32 v0, 0xbfb8aa3b, v55
	v_exp_f32_e32 v2, v2
	v_exp_f32_e32 v0, v0
	v_mul_f32_e32 v54, v1, v102
	v_mov_b32_e32 v116, v106
	v_add_f32_e32 v2, 1.0, v2
	v_add_f32_e32 v0, 1.0, v0
	v_rcp_f32_e32 v105, v2
	v_rcp_f32_e32 v1, v0
	v_mov_b32_e32 v106, v108
	v_mov_b32_e32 v0, v109
	v_pk_mul_f32 v[110:111], v[116:117], v[110:111]
	v_pk_mul_f32 v[104:105], v[104:105], v[112:113]
	v_pk_mul_f32 v[106:107], v[106:107], v[114:115]
	v_pk_mul_f32 v[0:1], v[0:1], v[54:55]
	v_mov_b32_e32 v54, v110
	v_mov_b32_e32 v55, v104
	v_mov_b32_e32 v104, v111
	v_mov_b32_e32 v102, v106
	v_mov_b32_e32 v103, v0
	v_mov_b32_e32 v0, v107
	v_pk_mul_f32 v[54:55], v[54:55], v[104:105]
	v_pk_mul_f32 v[0:1], v[102:103], v[0:1]
	v_cvt_pk_bf16_f32 v54, v54, v55
	v_cvt_pk_bf16_f32 v55, v0, v1
	global_store_dwordx2 v[52:53], v[54:55], off offset:1632
	v_mfma_f32_16x16x32_bf16 v[102:105], v[16:19], v[44:47], 0
	v_mfma_f32_16x16x32_bf16 v[52:55], v[20:23], v[44:47], 0
	v_mfma_f32_16x16x32_bf16 v[102:105], v[32:35], v[48:51], v[102:105]
	v_mfma_f32_16x16x32_bf16 v[52:55], v[24:27], v[48:51], v[52:55]
	v_mfma_f32_16x16x32_bf16 v[134:137], v[76:79], v[44:47], 0
	s_nop 5
	v_cndmask_b32_e64 v0, v102, 0, s[40:41]
	v_cndmask_b32_e64 v2, v104, 0, s[38:39]
	v_cndmask_b32_e64 v102, v105, 0, vcc
	v_cndmask_b32_e64 v1, 0, v103, s[42:43]
	v_cvt_pk_bf16_f32 v52, v52, v53
	v_cvt_pk_bf16_f32 v53, v54, v55
	v_cvt_pk_bf16_f32 v55, v2, v102
	ds_read_b64_tr_b16 v[104:105], v131 offset:2304
	ds_read_b64_tr_b16 v[102:103], v131
	ds_read_b64_tr_b16 v[106:107], v131 offset:32
	ds_read_b64_tr_b16 v[108:109], v131 offset:2336
	v_cvt_pk_bf16_f32 v54, v0, v1
	v_mfma_f32_16x16x32_bf16 v[134:137], v[92:95], v[48:51], v[134:137]
	s_waitcnt lgkmcnt(0)
; __device__ __forceinline__ float bperm_f(int src_lane, float v) { return __builtin_bit_cast(float, __builtin_amdgcn_ds_bpermute(src_lane << 2, __builtin_bit_cast(int, v))); }
; template <int KIND>
; __device__ __forceinline__ void w_m3_core(const bf16x8 (&Qf)[4][2], const bf16x8 (&Kf)[4][2], const bf16x8 (&Sf)[4][2], const LAS bf16_t* vT, float lg,
;                                           const bf16_t* gsrc, const float* nw, bf16_t* ydst, int lo, int fq) {
;     ...
;                     s = __builtin_amdgcn_mfma_f32_16x16x32_bf16(Kf[mb][0], Qf[nb][0], s, 0, 0, 0); s = __builtin_amdgcn_mfma_f32_16x16x32_bf16(Kf[mb][1], Qf[nb][1], s, 0, 0, 0);
; #pragma unroll
;                     for (int r = 0; r < 4; ++r) { const int m = 16 * mb + 4 * fq + r, n = 16 * nb + lo; float v = s[r];
;                         if (KIND == 0) v *= __expf((float)(n - m) * lg);
;                         if (mb == nb) v = (m <= n) ? v : 0.f;
;                         pv[4 * hh + r] = v; }
;                 } else {
; #pragma unroll
;                     for (int r = 0; r < 4; ++r) pv[4 * hh + r] = 0.f; }
;             }
;             const bf16x8 Pf = pack_frag(pv);
; #pragma unroll
;             for (int eb = 0; eb < 4; ++eb)
;                 O[eb] = __builtin_amdgcn_mfma_f32_16x16x32_bf16(tr_frag(vT, 32 * kk2 + 4 * fq, 32 * kk2 + 16 + 4 * fq, 16 * eb, lo), Pf, O[eb], 0, 0, 0);
;         }
; #pragma unroll
;         for (int kk = 0; kk < 2; ++kk)
; #pragma unroll
;             for (int eb = 0; eb < 4; ++eb) O2[eb] = __builtin_amdgcn_mfma_f32_16x16x32_bf16(Sf[eb][kk], Qf[nb][kk], O2[eb], 0, 0, 0);
;         const float osc = KIND == 0 ? __expf((float)(16 * nb + lo + 1) * lg) : 1.0f;
; #pragma unroll
;         for (int eb = 0; eb < 4; ++eb) O[eb] = O[eb] + O2[eb] * osc;
;         float ss = 0.f;
; #pragma unroll
;         for (int eb = 0; eb < 4; ++eb) ss += (O[eb][0] * O[eb][0] + O[eb][1] * O[eb][1]) + (O[eb][2] * O[eb][2] + O[eb][3] * O[eb][3]);
;         { const int ln = (fq << 4) | lo; ss += bperm_f(ln ^ 16, ss); ss += bperm_f(ln ^ 32, ss); }
;         const float rs = rsqrtf(ss * (1.0f / 64.0f) + EPS);
;         const size_t n = 16 * nb + lo;
; #pragma unroll
;         for (int eb = 0; eb < 4; ++eb) { const int e0 = 16 * eb + 4 * fq;
;             const unsigned long long gw_ = *(const unsigned long long*)(gsrc + n * NIN + e0); const f32x4 w4 = *(const f32x4*)(nw + e0);
	v_mfma_f32_16x16x32_bf16 v[112:115], v[106:109], v[52:55], 0
	ds_read_b64_tr_b16 v[106:107], v131 offset:64
	ds_read_b64_tr_b16 v[108:109], v131 offset:2368
	s_waitcnt lgkmcnt(0)
	v_mfma_f32_16x16x32_bf16 v[116:119], v[106:109], v[52:55], 0
	ds_read_b64_tr_b16 v[106:107], v131 offset:96
	ds_read_b64_tr_b16 v[108:109], v131 offset:2400
	v_mfma_f32_16x16x32_bf16 v[102:105], v[102:105], v[52:55], 0
	s_waitcnt lgkmcnt(0)
	v_mfma_f32_16x16x32_bf16 v[120:123], v[106:109], v[52:55], 0
	v_mfma_f32_16x16x32_bf16 v[52:55], v[64:67], v[44:47], 0
	v_mfma_f32_16x16x32_bf16 v[106:109], v[72:75], v[44:47], 0
	v_mfma_f32_16x16x32_bf16 v[44:47], v[80:83], v[44:47], 0
	v_mfma_f32_16x16x32_bf16 v[52:55], v[84:87], v[48:51], v[52:55]
	v_mfma_f32_16x16x32_bf16 v[44:47], v[96:99], v[48:51], v[44:47]
	v_mfma_f32_16x16x32_bf16 v[138:141], v[88:91], v[48:51], v[106:109]
	s_nop 5
	v_add_f32_e64 v110, v102, v52
	v_add_f32_e64 v111, v103, v53
	v_pk_add_f32 v[0:1], v[122:123], v[46:47]
	v_pk_add_f32 v[50:51], v[120:121], v[44:45]
	v_pk_add_f32 v[108:109], v[104:105], v[54:55]
	v_pk_mul_f32 v[46:47], v[110:111], v[110:111]
	v_pk_mul_f32 v[44:45], v[108:109], v[108:109]
	v_pk_add_f32 v[104:105], v[114:115], v[140:141]
	v_pk_add_f32 v[106:107], v[112:113], v[138:139]
	v_pk_mov_b32 v[48:49], v[46:47], v[44:45] op_sel:[1,0]
	v_mov_b32_e32 v47, v45
	v_pk_add_f32 v[44:45], v[48:49], v[46:47]
	v_pk_mul_f32 v[46:47], v[104:105], v[104:105]
	v_pk_mul_f32 v[48:49], v[106:107], v[106:107]
	v_pk_add_f32 v[54:55], v[116:117], v[134:135]
	v_pk_mov_b32 v[102:103], v[48:49], v[46:47] op_sel:[1,0]
	v_mov_b32_e32 v49, v47
	v_pk_add_f32 v[46:47], v[102:103], v[48:49]
	v_mul_f32_e32 v2, v50, v50
	v_mul_f32_e32 v48, v51, v51
	v_pk_add_f32 v[44:45], v[44:45], v[44:45] op_sel:[0,1] op_sel_hi:[1,0]
	v_pk_add_f32 v[46:47], v[46:47], v[46:47] op_sel:[0,1] op_sel_hi:[1,0]
	v_pk_add_f32 v[52:53], v[118:119], v[136:137]
	v_mov_b32_e32 v45, v2
	v_mov_b32_e32 v47, v48
	v_mul_f32_e32 v2, v55, v55
	v_mul_f32_e32 v49, v0, v0
	v_pk_add_f32 v[44:45], v[44:45], v[46:47]
	v_pk_fma_f32 v[46:47], v[54:55], v[54:55], v[2:3] op_sel_hi:[1,1,0]
	v_mul_f32_e32 v2, v53, v53
	v_mul_f32_e32 v102, v1, v1
	v_mov_b32_e32 v47, v49
	v_pk_fma_f32 v[48:49], v[52:53], v[52:53], v[2:3] op_sel_hi:[1,1,0]
	s_nop 0
	v_mov_b32_e32 v49, v102
	v_pk_add_f32 v[46:47], v[46:47], v[48:49]
	s_nop 0
	v_pk_add_f32 v[44:45], v[44:45], v[46:47]
	s_nop 0
	v_add_f32_e32 v2, v44, v45
	ds_bpermute_b32 v44, v130, v2
	s_waitcnt lgkmcnt(0)
	v_add_f32_e32 v2, v2, v44
	ds_bpermute_b32 v44, v129, v2
	s_waitcnt lgkmcnt(0)
	v_add_f32_e32 v2, v2, v44
	v_fmamk_f32 v2, v2, 0x3c800000, v200
	v_cmp_gt_f32_e64 s[44:45], s29, v2
	v_mul_f32_e32 v44, 0x4b800000, v2
	s_nop 0
	v_cndmask_b32_e64 v2, v2, v44, s[44:45]
	v_rsq_f32_e32 v2, v2
	s_nop 0
	v_mul_f32_e32 v44, 0x45800000, v2
	v_cndmask_b32_e64 v48, v2, v44, s[44:45]
	v_mad_u64_u32 v[44:45], s[20:21], v128, s72, v[100:101]
	v_lshl_add_u64 v[102:103], v[44:45], 0, v[62:63]
	v_mov_b64_e32 v[114:115], v[230:231]
	v_mov_b64_e32 v[44:45], v[146:147]
	v_mov_b64_e32 v[46:47], v[148:149]
	v_lshlrev_b32_e32 v2, 11, v128
	v_lshl_add_u64 v[112:113], s[46:47], 0, v[2:3]
	v_pk_mul_f32 v[110:111], v[110:111], v[48:49] op_sel_hi:[1,0]
	v_pk_mul_f32 v[108:109], v[108:109], v[48:49] op_sel_hi:[1,0]
	v_pk_mul_f32 v[106:107], v[106:107], v[48:49] op_sel_hi:[1,0]
	v_pk_mul_f32 v[104:105], v[104:105], v[48:49] op_sel_hi:[1,0]
	s_waitcnt lgkmcnt(0)
	v_lshlrev_b32_e32 v116, 16, v114
	v_mul_f32_e32 v2, 0xbfb8aa3b, v116
	v_exp_f32_e32 v2, v2
	v_and_b32_e32 v117, 0xffff0000, v114
	v_lshlrev_b32_e32 v114, 16, v115
	v_and_b32_e32 v115, 0xffff0000, v115
	v_add_f32_e32 v2, 1.0, v2
	v_rcp_f32_e32 v118, v2
	v_mul_f32_e32 v2, 0xbfb8aa3b, v117
	v_exp_f32_e32 v2, v2
	v_pk_mul_f32 v[44:45], v[44:45], v[110:111]
	v_pk_mul_f32 v[46:47], v[46:47], v[108:109]
	v_add_f32_e32 v2, 1.0, v2
	v_rcp_f32_e32 v119, v2
	v_mul_f32_e32 v2, 0xbfb8aa3b, v114
	v_exp_f32_e32 v2, v2
	v_pk_mul_f32 v[110:111], v[118:119], v[116:117]
	s_nop 0
	v_pk_mul_f32 v[44:45], v[110:111], v[44:45]
	v_add_f32_e32 v2, 1.0, v2
	v_rcp_f32_e32 v110, v2
	v_mul_f32_e32 v2, 0xbfb8aa3b, v115
	v_exp_f32_e32 v2, v2
	s_nop 0
	v_add_f32_e32 v2, 1.0, v2
	v_rcp_f32_e32 v111, v2
	s_nop 0
	v_pk_mul_f32 v[108:109], v[110:111], v[114:115]
	s_nop 0
	v_pk_mul_f32 v[46:47], v[108:109], v[46:47]
	v_cvt_pk_bf16_f32 v108, v44, v45
	v_cvt_pk_bf16_f32 v109, v46, v47
	v_lshl_add_u64 v[44:45], v[112:113], 0, v[62:63]
	global_store_dwordx2 v[44:45], v[108:109], off offset:1536
	v_mov_b64_e32 v[46:47], v[232:233]
	s_nop 0
	v_mov_b64_e32 v[108:109], v[150:151]
	v_mov_b64_e32 v[110:111], v[152:153]
	s_waitcnt lgkmcnt(0)
	v_lshlrev_b32_e32 v112, 16, v46
	v_mul_f32_e32 v2, 0xbfb8aa3b, v112
	v_exp_f32_e32 v2, v2
	v_and_b32_e32 v113, 0xffff0000, v46
	v_lshlrev_b32_e32 v46, 16, v47
	v_and_b32_e32 v47, 0xffff0000, v47
	v_add_f32_e32 v2, 1.0, v2
	v_rcp_f32_e32 v114, v2
	v_mul_f32_e32 v2, 0xbfb8aa3b, v113
	v_exp_f32_e32 v2, v2
	v_pk_mul_f32 v[106:107], v[108:109], v[106:107]
	v_pk_mul_f32 v[104:105], v[110:111], v[104:105]
	v_mul_f32_e32 v110, v55, v48
	v_add_f32_e32 v2, 1.0, v2
	v_rcp_f32_e32 v115, v2
	v_mul_f32_e32 v2, 0xbfb8aa3b, v46
	v_exp_f32_e32 v2, v2
	v_pk_mul_f32 v[108:109], v[114:115], v[112:113]
	s_nop 0
	v_pk_mul_f32 v[106:107], v[108:109], v[106:107]
	v_add_f32_e32 v2, 1.0, v2
	v_rcp_f32_e32 v108, v2
	v_mul_f32_e32 v2, 0xbfb8aa3b, v47
	v_exp_f32_e32 v2, v2
	v_mul_f32_e32 v112, v52, v48
	v_add_f32_e32 v2, 1.0, v2
	v_rcp_f32_e32 v109, v2
	s_nop 0
	v_pk_mul_f32 v[46:47], v[108:109], v[46:47]
	s_nop 0
	v_pk_mul_f32 v[46:47], v[46:47], v[104:105]
	v_cvt_pk_bf16_f32 v104, v106, v107
	v_cvt_pk_bf16_f32 v105, v46, v47
	global_store_dwordx2 v[44:45], v[104:105], off offset:1568
	v_mov_b64_e32 v[46:47], v[234:235]
	s_nop 0
	v_mov_b64_e32 v[104:105], v[188:189]
	v_mov_b64_e32 v[106:107], v[190:191]
	v_mul_f32_e32 v108, v54, v48
	s_waitcnt lgkmcnt(0)
; __device__ __forceinline__ float bperm_f(int src_lane, float v) { return __builtin_bit_cast(float, __builtin_amdgcn_ds_bpermute(src_lane << 2, __builtin_bit_cast(int, v))); }
; template <int KIND>
; __device__ __forceinline__ void w_m3_core(const bf16x8 (&Qf)[4][2], const bf16x8 (&Kf)[4][2], const bf16x8 (&Sf)[4][2], const LAS bf16_t* vT, float lg,
;                                           const bf16_t* gsrc, const float* nw, bf16_t* ydst, int lo, int fq) {
;     ...
;                     s = __builtin_amdgcn_mfma_f32_16x16x32_bf16(Kf[mb][0], Qf[nb][0], s, 0, 0, 0); s = __builtin_amdgcn_mfma_f32_16x16x32_bf16(Kf[mb][1], Qf[nb][1], s, 0, 0, 0);
; #pragma unroll
;                     for (int r = 0; r < 4; ++r) { const int m = 16 * mb + 4 * fq + r, n = 16 * nb + lo; float v = s[r];
;                         if (KIND == 0) v *= __expf((float)(n - m) * lg);
;                         if (mb == nb) v = (m <= n) ? v : 0.f;
;                         pv[4 * hh + r] = v; }
;                 } else {
; #pragma unroll
;                     for (int r = 0; r < 4; ++r) pv[4 * hh + r] = 0.f; }
;             }
;             const bf16x8 Pf = pack_frag(pv);
; #pragma unroll
;             for (int eb = 0; eb < 4; ++eb)
;                 O[eb] = __builtin_amdgcn_mfma_f32_16x16x32_bf16(tr_frag(vT, 32 * kk2 + 4 * fq, 32 * kk2 + 16 + 4 * fq, 16 * eb, lo), Pf, O[eb], 0, 0, 0);
;         }
; #pragma unroll
;         for (int kk = 0; kk < 2; ++kk)
; #pragma unroll
;             for (int eb = 0; eb < 4; ++eb) O2[eb] = __builtin_amdgcn_mfma_f32_16x16x32_bf16(Sf[eb][kk], Qf[nb][kk], O2[eb], 0, 0, 0);
;         const float osc = KIND == 0 ? __expf((float)(16 * nb + lo + 1) * lg) : 1.0f;
; #pragma unroll
;         for (int eb = 0; eb < 4; ++eb) O[eb] = O[eb] + O2[eb] * osc;
;         float ss = 0.f;
; #pragma unroll
;         for (int eb = 0; eb < 4; ++eb) ss += (O[eb][0] * O[eb][0] + O[eb][1] * O[eb][1]) + (O[eb][2] * O[eb][2] + O[eb][3] * O[eb][3]);
;         { const int ln = (fq << 4) | lo; ss += bperm_f(ln ^ 16, ss); ss += bperm_f(ln ^ 32, ss); }
;         const float rs = rsqrtf(ss * (1.0f / 64.0f) + EPS);
;         const size_t n = 16 * nb + lo;
; #pragma unroll
;         for (int eb = 0; eb < 4; ++eb) { const int e0 = 16 * eb + 4 * fq;
;             const unsigned long long gw_ = *(const unsigned long long*)(gsrc + n * NIN + e0); const f32x4 w4 = *(const f32x4*)(nw + e0);
	v_lshlrev_b32_e32 v109, 16, v46
	v_mul_f32_e32 v2, 0xbfb8aa3b, v109
	v_exp_f32_e32 v2, v2
	v_and_b32_e32 v111, 0xffff0000, v46
	v_lshlrev_b32_e32 v113, 16, v47
	v_and_b32_e32 v47, 0xffff0000, v47
	v_add_f32_e32 v2, 1.0, v2
	v_rcp_f32_e32 v115, v2
	v_mul_f32_e32 v2, 0xbfb8aa3b, v111
	v_exp_f32_e32 v2, v2
	v_mov_b32_e32 v54, v105
	v_mul_f32_e32 v46, v53, v48
	v_mov_b32_e32 v114, v104
	v_add_f32_e32 v2, 1.0, v2
	v_rcp_f32_e32 v55, v2
	v_mul_f32_e32 v2, 0xbfb8aa3b, v113
	v_exp_f32_e32 v2, v2
	v_pk_mul_f32 v[108:109], v[114:115], v[108:109]
	v_pk_mul_f32 v[54:55], v[54:55], v[110:111]
	v_mov_b32_e32 v104, v106
	v_add_f32_e32 v2, 1.0, v2
	v_rcp_f32_e32 v105, v2
	v_mul_f32_e32 v2, 0xbfb8aa3b, v47
	v_exp_f32_e32 v2, v2
	v_mov_b32_e32 v52, v107
	v_pk_mul_f32 v[104:105], v[104:105], v[112:113]
	v_mul_f32_e32 v106, v0, v48
	v_add_f32_e32 v2, 1.0, v2
	v_rcp_f32_e32 v53, v2
	s_nop 0
	v_pk_mul_f32 v[46:47], v[52:53], v[46:47]
	v_mov_b32_e32 v52, v108
	v_mov_b32_e32 v53, v54
	v_mov_b32_e32 v54, v109
	v_pk_mul_f32 v[52:53], v[52:53], v[54:55]
	v_mov_b32_e32 v54, v104
	v_mov_b32_e32 v55, v46
	v_mov_b32_e32 v46, v105
	v_pk_mul_f32 v[46:47], v[54:55], v[46:47]
	v_cvt_pk_bf16_f32 v52, v52, v53
	v_cvt_pk_bf16_f32 v53, v46, v47
	global_store_dwordx2 v[44:45], v[52:53], off offset:1600
	v_mov_b64_e32 v[46:47], v[236:237]
	s_nop 0
	v_mov_b64_e32 v[52:53], v[192:193]
	v_mov_b64_e32 v[54:55], v[194:195]
	v_mul_f32_e32 v102, v50, v48
	v_mul_f32_e32 v104, v51, v48
	s_waitcnt lgkmcnt(0)
	v_lshlrev_b32_e32 v103, 16, v46
	v_lshlrev_b32_e32 v107, 16, v47
	v_mul_f32_e32 v2, 0xbfb8aa3b, v103
	v_mul_f32_e32 v0, 0xbfb8aa3b, v107
	v_exp_f32_e32 v2, v2
	v_exp_f32_e32 v0, v0
	v_and_b32_e32 v105, 0xffff0000, v46
	v_and_b32_e32 v47, 0xffff0000, v47
	v_add_f32_e32 v2, 1.0, v2
	v_add_f32_e32 v0, 1.0, v0
	v_rcp_f32_e32 v109, v2
	v_mul_f32_e32 v2, 0xbfb8aa3b, v105
	v_mov_b32_e32 v50, v53
	v_rcp_f32_e32 v53, v0
	v_mul_f32_e32 v0, 0xbfb8aa3b, v47
	v_exp_f32_e32 v2, v2
	v_exp_f32_e32 v0, v0
	v_mul_f32_e32 v46, v1, v48
	v_mov_b32_e32 v108, v52
	v_add_f32_e32 v2, 1.0, v2
	v_add_f32_e32 v0, 1.0, v0
	v_rcp_f32_e32 v51, v2
	v_rcp_f32_e32 v1, v0
	v_mov_b32_e32 v52, v54
	v_mov_b32_e32 v0, v55
	v_pk_mul_f32 v[102:103], v[108:109], v[102:103]
	v_pk_mul_f32 v[50:51], v[50:51], v[104:105]
	v_pk_mul_f32 v[52:53], v[52:53], v[106:107]
	v_pk_mul_f32 v[0:1], v[0:1], v[46:47]
	v_mov_b32_e32 v46, v102
	v_mov_b32_e32 v47, v50
	v_mov_b32_e32 v50, v103
	v_mov_b32_e32 v48, v52
	v_mov_b32_e32 v49, v0
	v_mov_b32_e32 v0, v53
	v_pk_mul_f32 v[46:47], v[46:47], v[50:51]
	v_pk_mul_f32 v[0:1], v[48:49], v[0:1]
	v_cvt_pk_bf16_f32 v46, v46, v47
	v_cvt_pk_bf16_f32 v47, v0, v1
	global_store_dwordx2 v[44:45], v[46:47], off offset:1632
	v_mfma_f32_16x16x32_bf16 v[44:47], v[20:23], v[28:31], 0
	v_mfma_f32_16x16x32_bf16 v[48:51], v[16:19], v[28:31], 0
	v_mfma_f32_16x16x32_bf16 v[44:47], v[24:27], v[40:43], v[44:47]
	v_mfma_f32_16x16x32_bf16 v[48:51], v[32:35], v[40:43], v[48:51]
	s_nop 6
	v_cvt_pk_bf16_f32 v44, v44, v45
	v_cvt_pk_bf16_f32 v45, v46, v47
	v_cvt_pk_bf16_f32 v46, v48, v49
	v_cvt_pk_bf16_f32 v47, v50, v51
	ds_read_b64_tr_b16 v[50:51], v131 offset:2304
	ds_read_b64_tr_b16 v[48:49], v131
	ds_read_b64_tr_b16 v[52:53], v131 offset:32
	ds_read_b64_tr_b16 v[54:55], v131 offset:2336
	ds_read_b64_tr_b16 v[102:103], v131 offset:64
	ds_read_b64_tr_b16 v[104:105], v131 offset:2368
	ds_read_b64_tr_b16 v[106:107], v131 offset:96
	ds_read_b64_tr_b16 v[108:109], v131 offset:2400
	s_waitcnt lgkmcnt(0)
	v_mfma_f32_16x16x32_bf16 v[48:51], v[48:51], v[44:47], 0
	v_mfma_f32_16x16x32_bf16 v[52:55], v[52:55], v[44:47], 0
	v_mfma_f32_16x16x32_bf16 v[102:105], v[102:105], v[44:47], 0
	v_mfma_f32_16x16x32_bf16 v[44:47], v[106:109], v[44:47], 0
	v_mfma_f32_16x16x32_bf16 v[106:109], v[12:15], v[28:31], 0
	v_mfma_f32_16x16x32_bf16 v[106:109], v[36:39], v[40:43], v[106:109]
	s_nop 7
	v_cndmask_b32_e64 v0, v106, 0, s[40:41]
	v_cndmask_b32_e64 v1, 0, v107, s[42:43]
	v_cndmask_b32_e64 v2, v108, 0, s[38:39]
	v_cndmask_b32_e64 v106, v109, 0, vcc
	v_cvt_pk_bf16_f32 v0, v0, v1
	v_cvt_pk_bf16_f32 v1, v2, v106
	ds_read_b64_tr_b16 v[106:107], v131 offset:4608
	ds_read_b64_tr_b16 v[108:109], v131 offset:6912
	v_mov_b32_e32 v2, v3
	s_waitcnt lgkmcnt(0)
	s_nop 0
	v_mfma_f32_16x16x32_bf16 v[48:51], v[106:109], v[0:3], v[48:51]
	ds_read_b64_tr_b16 v[106:107], v131 offset:4640
	ds_read_b64_tr_b16 v[108:109], v131 offset:6944
	s_waitcnt lgkmcnt(0)
	v_mfma_f32_16x16x32_bf16 v[106:109], v[106:109], v[0:3], v[52:55]
	s_nop 2
	ds_read_b64_tr_b16 v[52:53], v131 offset:4672
	ds_read_b64_tr_b16 v[54:55], v131 offset:6976
	s_waitcnt lgkmcnt(0)
	v_mfma_f32_16x16x32_bf16 v[110:113], v[52:55], v[0:3], v[102:105]
	ds_read_b64_tr_b16 v[52:53], v131 offset:4704
	ds_read_b64_tr_b16 v[54:55], v131 offset:7008
	s_waitcnt lgkmcnt(0)
; __device__ __forceinline__ unsigned pk2(float lo, float hi) { const f32x2_t v = {lo, hi}; const bf16x2_t b = __builtin_convertvector(v, bf16x2_t); return __builtin_bit_cast(unsigned, b); }
; __device__ __forceinline__ float sigmoidf_(float x) { return __builtin_amdgcn_rcpf(1.0f + __expf(-x)); }
; __device__ __forceinline__ float bperm_f(int src_lane, float v) { return __builtin_bit_cast(float, __builtin_amdgcn_ds_bpermute(src_lane << 2, __builtin_bit_cast(int, v))); }
; template <int KIND>
; __device__ __forceinline__ void w_m3_core(const bf16x8 (&Qf)[4][2], const bf16x8 (&Kf)[4][2], const bf16x8 (&Sf)[4][2], const LAS bf16_t* vT, float lg,
;                                           const bf16_t* gsrc, const float* nw, bf16_t* ydst, int lo, int fq) {
;     ...
; #pragma unroll
;         for (int kk = 0; kk < 2; ++kk)
; #pragma unroll
;             for (int eb = 0; eb < 4; ++eb) O2[eb] = __builtin_amdgcn_mfma_f32_16x16x32_bf16(Sf[eb][kk], Qf[nb][kk], O2[eb], 0, 0, 0);
;         const float osc = KIND == 0 ? __expf((float)(16 * nb + lo + 1) * lg) : 1.0f;
; #pragma unroll
;         for (int eb = 0; eb < 4; ++eb) O[eb] = O[eb] + O2[eb] * osc;
;         float ss = 0.f;
; #pragma unroll
;         for (int eb = 0; eb < 4; ++eb) ss += (O[eb][0] * O[eb][0] + O[eb][1] * O[eb][1]) + (O[eb][2] * O[eb][2] + O[eb][3] * O[eb][3]);
;         { const int ln = (fq << 4) | lo; ss += bperm_f(ln ^ 16, ss); ss += bperm_f(ln ^ 32, ss); }
;         const float rs = rsqrtf(ss * (1.0f / 64.0f) + EPS);
;         const size_t n = 16 * nb + lo;
; #pragma unroll
;         for (int eb = 0; eb < 4; ++eb) { const int e0 = 16 * eb + 4 * fq;
;             const unsigned long long gw_ = *(const unsigned long long*)(gsrc + n * NIN + e0); const f32x4 w4 = *(const f32x4*)(nw + e0);
;             const float g0 = __uint_as_float((unsigned)gw_ << 16), g1 = __uint_as_float((unsigned)gw_ & 0xffff0000u), g2 = __uint_as_float((unsigned)(gw_ >> 32) << 16), g3 = __uint_as_float((unsigned)(gw_ >> 32) & 0xffff0000u);
;             const float o0 = O[eb][0] * rs * w4[0] * (g0 * sigmoidf_(g0)), o1 = O[eb][1] * rs * w4[1] * (g1 * sigmoidf_(g1));
;             const float o2 = O[eb][2] * rs * w4[2] * (g2 * sigmoidf_(g2)), o3 = O[eb][3] * rs * w4[3] * (g3 * sigmoidf_(g3));
;             *(unsigned long long*)(ydst + n * DM + e0) = (unsigned long long)pk2(o0, o1) | ((unsigned long long)pk2(o2, o3) << 32); }
	v_mfma_f32_16x16x32_bf16 v[114:117], v[52:55], v[0:3], v[44:47]
	v_mfma_f32_16x16x32_bf16 v[44:47], v[64:67], v[28:31], 0
	v_mfma_f32_16x16x32_bf16 v[52:55], v[72:75], v[28:31], 0
	v_mfma_f32_16x16x32_bf16 v[102:105], v[76:79], v[28:31], 0
	v_mfma_f32_16x16x32_bf16 v[28:31], v[80:83], v[28:31], 0
	v_mfma_f32_16x16x32_bf16 v[44:47], v[84:87], v[40:43], v[44:47]
	v_mfma_f32_16x16x32_bf16 v[28:31], v[96:99], v[40:43], v[28:31]
	v_mfma_f32_16x16x32_bf16 v[118:121], v[88:91], v[40:43], v[52:55]
	v_mfma_f32_16x16x32_bf16 v[122:125], v[92:95], v[40:43], v[102:105]
	s_nop 4
	v_add_f32_e64 v54, v50, v46
	v_add_f32_e64 v55, v51, v47
	v_pk_add_f32 v[0:1], v[116:117], v[30:31]
	v_pk_add_f32 v[42:43], v[114:115], v[28:29]
	v_pk_add_f32 v[102:103], v[48:49], v[44:45]
	v_pk_mul_f32 v[28:29], v[54:55], v[54:55]
	v_pk_mul_f32 v[30:31], v[102:103], v[102:103]
	v_pk_add_f32 v[50:51], v[108:109], v[120:121]
	v_pk_add_f32 v[52:53], v[106:107], v[118:119]
	v_pk_mov_b32 v[40:41], v[30:31], v[28:29] op_sel:[1,0]
	v_mov_b32_e32 v31, v29
	v_pk_add_f32 v[28:29], v[40:41], v[30:31]
	v_pk_mul_f32 v[30:31], v[50:51], v[50:51]
	v_pk_mul_f32 v[40:41], v[52:53], v[52:53]
	v_pk_add_f32 v[46:47], v[110:111], v[122:123]
	v_pk_mov_b32 v[48:49], v[40:41], v[30:31] op_sel:[1,0]
	v_mov_b32_e32 v41, v31
	v_pk_add_f32 v[30:31], v[48:49], v[40:41]
	v_mul_f32_e32 v2, v42, v42
	v_mul_f32_e32 v40, v43, v43
	v_pk_add_f32 v[28:29], v[28:29], v[28:29] op_sel:[0,1] op_sel_hi:[1,0]
	v_pk_add_f32 v[30:31], v[30:31], v[30:31] op_sel:[0,1] op_sel_hi:[1,0]
	v_pk_add_f32 v[44:45], v[112:113], v[124:125]
	v_mov_b32_e32 v29, v2
	v_mov_b32_e32 v31, v40
	v_mul_f32_e32 v2, v47, v47
	v_mul_f32_e32 v41, v0, v0
	v_pk_add_f32 v[28:29], v[28:29], v[30:31]
	v_pk_fma_f32 v[30:31], v[46:47], v[46:47], v[2:3] op_sel_hi:[1,1,0]
	v_mul_f32_e32 v2, v45, v45
	v_mul_f32_e32 v48, v1, v1
	v_mov_b32_e32 v31, v41
	v_pk_fma_f32 v[40:41], v[44:45], v[44:45], v[2:3] op_sel_hi:[1,1,0]
	s_nop 0
	v_mov_b32_e32 v41, v48
	v_pk_add_f32 v[30:31], v[30:31], v[40:41]
	s_nop 0
	v_pk_add_f32 v[28:29], v[28:29], v[30:31]
	s_nop 0
	v_add_f32_e32 v2, v28, v29
	ds_bpermute_b32 v28, v130, v2
	s_waitcnt lgkmcnt(0)
	v_add_f32_e32 v2, v2, v28
	ds_bpermute_b32 v28, v129, v2
	s_waitcnt lgkmcnt(0)
	v_add_f32_e32 v2, v2, v28
	v_fmamk_f32 v2, v2, 0x3c800000, v200
	v_cmp_gt_f32_e64 s[44:45], s29, v2
	v_mul_f32_e32 v28, 0x4b800000, v2
	s_nop 0
	v_cndmask_b32_e64 v2, v2, v28, s[44:45]
	v_rsq_f32_e32 v2, v2
	s_nop 0
	v_mul_f32_e32 v28, 0x45800000, v2
	v_cndmask_b32_e64 v40, v2, v28, s[44:45]
	v_mad_u64_u32 v[28:29], s[20:21], v127, s72, v[100:101]
	v_lshl_add_u64 v[48:49], v[28:29], 0, v[62:63]
	v_mov_b64_e32 v[106:107], v[238:239]
	v_mov_b64_e32 v[28:29], v[146:147]
	v_mov_b64_e32 v[30:31], v[148:149]
	v_lshlrev_b32_e32 v2, 11, v127
	v_lshl_add_u64 v[104:105], s[46:47], 0, v[2:3]
	v_pk_mul_f32 v[102:103], v[102:103], v[40:41] op_sel_hi:[1,0]
	v_pk_mul_f32 v[54:55], v[54:55], v[40:41] op_sel_hi:[1,0]
	v_pk_mul_f32 v[52:53], v[52:53], v[40:41] op_sel_hi:[1,0]
	v_pk_mul_f32 v[50:51], v[50:51], v[40:41] op_sel_hi:[1,0]
	s_waitcnt lgkmcnt(0)
	v_lshlrev_b32_e32 v108, 16, v106
	v_mul_f32_e32 v2, 0xbfb8aa3b, v108
	v_exp_f32_e32 v2, v2
	v_and_b32_e32 v109, 0xffff0000, v106
	v_lshlrev_b32_e32 v106, 16, v107
	v_and_b32_e32 v107, 0xffff0000, v107
	v_add_f32_e32 v2, 1.0, v2
	v_rcp_f32_e32 v110, v2
	v_mul_f32_e32 v2, 0xbfb8aa3b, v109
	v_exp_f32_e32 v2, v2
	v_pk_mul_f32 v[28:29], v[28:29], v[102:103]
	v_pk_mul_f32 v[30:31], v[30:31], v[54:55]
	v_add_f32_e32 v2, 1.0, v2
	v_rcp_f32_e32 v111, v2
	v_mul_f32_e32 v2, 0xbfb8aa3b, v106
	v_exp_f32_e32 v2, v2
	v_pk_mul_f32 v[102:103], v[110:111], v[108:109]
	s_nop 0
	v_pk_mul_f32 v[28:29], v[102:103], v[28:29]
	v_add_f32_e32 v2, 1.0, v2
	v_rcp_f32_e32 v102, v2
	v_mul_f32_e32 v2, 0xbfb8aa3b, v107
	v_exp_f32_e32 v2, v2
	s_nop 0
	v_add_f32_e32 v2, 1.0, v2
	v_rcp_f32_e32 v103, v2
	s_nop 0
	v_pk_mul_f32 v[54:55], v[102:103], v[106:107]
	s_nop 0
	v_pk_mul_f32 v[30:31], v[54:55], v[30:31]
	v_cvt_pk_bf16_f32 v54, v28, v29
	v_cvt_pk_bf16_f32 v55, v30, v31
	v_lshl_add_u64 v[28:29], v[104:105], 0, v[62:63]
	global_store_dwordx2 v[28:29], v[54:55], off offset:1536
	v_mov_b64_e32 v[30:31], v[240:241]
	v_mov_b64_e32 v[102:103], v[150:151]
	v_mov_b64_e32 v[104:105], v[152:153]
	s_waitcnt lgkmcnt(0)
	v_lshlrev_b32_e32 v54, 16, v30
	v_mul_f32_e32 v2, 0xbfb8aa3b, v54
	v_exp_f32_e32 v2, v2
	v_and_b32_e32 v55, 0xffff0000, v30
	v_lshlrev_b32_e32 v30, 16, v31
	v_and_b32_e32 v31, 0xffff0000, v31
	v_add_f32_e32 v2, 1.0, v2
	v_rcp_f32_e32 v106, v2
	v_mul_f32_e32 v2, 0xbfb8aa3b, v55
	v_exp_f32_e32 v2, v2
	v_pk_mul_f32 v[52:53], v[102:103], v[52:53]
	v_pk_mul_f32 v[50:51], v[104:105], v[50:51]
	v_mul_f32_e32 v102, v47, v40
	v_add_f32_e32 v2, 1.0, v2
	v_rcp_f32_e32 v107, v2
	v_mul_f32_e32 v2, 0xbfb8aa3b, v30
	v_exp_f32_e32 v2, v2
	v_mul_f32_e32 v104, v44, v40
	v_pk_mul_f32 v[54:55], v[106:107], v[54:55]
	v_add_f32_e32 v2, 1.0, v2
	v_pk_mul_f32 v[52:53], v[54:55], v[52:53]
	v_rcp_f32_e32 v54, v2
	v_mul_f32_e32 v2, 0xbfb8aa3b, v31
	v_exp_f32_e32 v2, v2
	s_nop 0
	v_add_f32_e32 v2, 1.0, v2
	v_rcp_f32_e32 v55, v2
	s_nop 0
	v_pk_mul_f32 v[30:31], v[54:55], v[30:31]
	s_nop 0
	v_pk_mul_f32 v[30:31], v[30:31], v[50:51]
	v_cvt_pk_bf16_f32 v50, v52, v53
	v_cvt_pk_bf16_f32 v51, v30, v31
	global_store_dwordx2 v[28:29], v[50:51], off offset:1568
	v_mov_b64_e32 v[30:31], v[242:243]
	s_nop 0
	v_mov_b64_e32 v[50:51], v[188:189]
	v_mov_b64_e32 v[52:53], v[190:191]
	v_mul_f32_e32 v54, v46, v40
	s_waitcnt lgkmcnt(0)
; __device__ __forceinline__ float bperm_f(int src_lane, float v) { return __builtin_bit_cast(float, __builtin_amdgcn_ds_bpermute(src_lane << 2, __builtin_bit_cast(int, v))); }
; template <int KIND>
; __device__ __forceinline__ void w_m3_core(const bf16x8 (&Qf)[4][2], const bf16x8 (&Kf)[4][2], const bf16x8 (&Sf)[4][2], const LAS bf16_t* vT, float lg,
;                                           const bf16_t* gsrc, const float* nw, bf16_t* ydst, int lo, int fq) {
;     ...
;                     s = __builtin_amdgcn_mfma_f32_16x16x32_bf16(Kf[mb][0], Qf[nb][0], s, 0, 0, 0); s = __builtin_amdgcn_mfma_f32_16x16x32_bf16(Kf[mb][1], Qf[nb][1], s, 0, 0, 0);
; #pragma unroll
;                     for (int r = 0; r < 4; ++r) { const int m = 16 * mb + 4 * fq + r, n = 16 * nb + lo; float v = s[r];
;                         if (KIND == 0) v *= __expf((float)(n - m) * lg);
;                         if (mb == nb) v = (m <= n) ? v : 0.f;
;                         pv[4 * hh + r] = v; }
;                 } else {
; #pragma unroll
;                     for (int r = 0; r < 4; ++r) pv[4 * hh + r] = 0.f; }
;             }
;             const bf16x8 Pf = pack_frag(pv);
; #pragma unroll
;             for (int eb = 0; eb < 4; ++eb)
;                 O[eb] = __builtin_amdgcn_mfma_f32_16x16x32_bf16(tr_frag(vT, 32 * kk2 + 4 * fq, 32 * kk2 + 16 + 4 * fq, 16 * eb, lo), Pf, O[eb], 0, 0, 0);
;         }
; #pragma unroll
;         for (int kk = 0; kk < 2; ++kk)
; #pragma unroll
;             for (int eb = 0; eb < 4; ++eb) O2[eb] = __builtin_amdgcn_mfma_f32_16x16x32_bf16(Sf[eb][kk], Qf[nb][kk], O2[eb], 0, 0, 0);
;         const float osc = KIND == 0 ? __expf((float)(16 * nb + lo + 1) * lg) : 1.0f;
; #pragma unroll
;         for (int eb = 0; eb < 4; ++eb) O[eb] = O[eb] + O2[eb] * osc;
;         float ss = 0.f;
; #pragma unroll
;         for (int eb = 0; eb < 4; ++eb) ss += (O[eb][0] * O[eb][0] + O[eb][1] * O[eb][1]) + (O[eb][2] * O[eb][2] + O[eb][3] * O[eb][3]);
;         { const int ln = (fq << 4) | lo; ss += bperm_f(ln ^ 16, ss); ss += bperm_f(ln ^ 32, ss); }
;         const float rs = rsqrtf(ss * (1.0f / 64.0f) + EPS);
;         const size_t n = 16 * nb + lo;
; #pragma unroll
;         for (int eb = 0; eb < 4; ++eb) { const int e0 = 16 * eb + 4 * fq;
;             const unsigned long long gw_ = *(const unsigned long long*)(gsrc + n * NIN + e0); const f32x4 w4 = *(const f32x4*)(nw + e0);
	v_lshlrev_b32_e32 v55, 16, v30
	v_mul_f32_e32 v2, 0xbfb8aa3b, v55
	v_exp_f32_e32 v2, v2
	v_and_b32_e32 v103, 0xffff0000, v30
	v_lshlrev_b32_e32 v105, 16, v31
	v_and_b32_e32 v31, 0xffff0000, v31
	v_add_f32_e32 v2, 1.0, v2
	v_rcp_f32_e32 v107, v2
	v_mul_f32_e32 v2, 0xbfb8aa3b, v103
	v_exp_f32_e32 v2, v2
	v_mov_b32_e32 v46, v51
	v_mul_f32_e32 v30, v45, v40
	v_mov_b32_e32 v106, v50
	v_add_f32_e32 v2, 1.0, v2
	v_rcp_f32_e32 v47, v2
	v_mul_f32_e32 v2, 0xbfb8aa3b, v105
	v_exp_f32_e32 v2, v2
	v_pk_mul_f32 v[54:55], v[106:107], v[54:55]
	v_pk_mul_f32 v[46:47], v[46:47], v[102:103]
	v_mov_b32_e32 v50, v52
	v_add_f32_e32 v2, 1.0, v2
	v_rcp_f32_e32 v51, v2
	v_mul_f32_e32 v2, 0xbfb8aa3b, v31
	v_exp_f32_e32 v2, v2
	v_mov_b32_e32 v44, v53
	v_pk_mul_f32 v[50:51], v[50:51], v[104:105]
	v_mul_f32_e32 v52, v0, v40
	v_add_f32_e32 v2, 1.0, v2
	v_rcp_f32_e32 v45, v2
	s_nop 0
	v_pk_mul_f32 v[30:31], v[44:45], v[30:31]
	v_mov_b32_e32 v44, v54
	v_mov_b32_e32 v45, v46
	v_mov_b32_e32 v46, v55
	v_pk_mul_f32 v[44:45], v[44:45], v[46:47]
	v_mov_b32_e32 v46, v50
	v_mov_b32_e32 v47, v30
	v_mov_b32_e32 v30, v51
	v_pk_mul_f32 v[30:31], v[46:47], v[30:31]
	v_cvt_pk_bf16_f32 v44, v44, v45
	v_cvt_pk_bf16_f32 v45, v30, v31
	global_store_dwordx2 v[28:29], v[44:45], off offset:1600
	v_mov_b64_e32 v[30:31], v[244:245]
	s_nop 0
	v_mov_b64_e32 v[44:45], v[192:193]
	v_mov_b64_e32 v[46:47], v[194:195]
	v_mul_f32_e32 v48, v42, v40
	v_mul_f32_e32 v50, v43, v40
	s_waitcnt lgkmcnt(0)
	v_lshlrev_b32_e32 v49, 16, v30
	v_lshlrev_b32_e32 v53, 16, v31
	v_mul_f32_e32 v2, 0xbfb8aa3b, v49
	v_mul_f32_e32 v0, 0xbfb8aa3b, v53
	v_exp_f32_e32 v2, v2
	v_exp_f32_e32 v0, v0
	v_and_b32_e32 v51, 0xffff0000, v30
	v_and_b32_e32 v31, 0xffff0000, v31
	v_add_f32_e32 v2, 1.0, v2
	v_add_f32_e32 v0, 1.0, v0
	v_rcp_f32_e32 v55, v2
	v_mul_f32_e32 v2, 0xbfb8aa3b, v51
	v_mov_b32_e32 v42, v45
	v_rcp_f32_e32 v45, v0
	v_mul_f32_e32 v0, 0xbfb8aa3b, v31
	v_exp_f32_e32 v2, v2
	v_exp_f32_e32 v0, v0
	v_mul_f32_e32 v30, v1, v40
	v_mov_b32_e32 v54, v44
	v_add_f32_e32 v2, 1.0, v2
	v_add_f32_e32 v0, 1.0, v0
	v_rcp_f32_e32 v43, v2
	v_rcp_f32_e32 v1, v0
	v_mov_b32_e32 v44, v46
	v_mov_b32_e32 v0, v47
	v_pk_mul_f32 v[48:49], v[54:55], v[48:49]
	v_pk_mul_f32 v[42:43], v[42:43], v[50:51]
	v_pk_mul_f32 v[44:45], v[44:45], v[52:53]
	v_pk_mul_f32 v[0:1], v[0:1], v[30:31]
	v_mov_b32_e32 v30, v48
	v_mov_b32_e32 v31, v42
	v_mov_b32_e32 v42, v49
	v_mov_b32_e32 v40, v44
	v_mov_b32_e32 v41, v0
	v_mov_b32_e32 v0, v45
	v_pk_mul_f32 v[30:31], v[30:31], v[42:43]
	v_pk_mul_f32 v[0:1], v[40:41], v[0:1]
	v_cvt_pk_bf16_f32 v30, v30, v31
	v_cvt_pk_bf16_f32 v31, v0, v1
	global_store_dwordx2 v[28:29], v[30:31], off offset:1632
	v_mfma_f32_16x16x32_bf16 v[20:23], v[20:23], v[8:11], 0
	v_mfma_f32_16x16x32_bf16 v[20:23], v[24:27], v[56:59], v[20:23]
	ds_read_b64_tr_b16 v[26:27], v131 offset:2304
	ds_read_b64_tr_b16 v[24:25], v131
	v_mfma_f32_16x16x32_bf16 v[16:19], v[16:19], v[8:11], 0
	v_mfma_f32_16x16x32_bf16 v[16:19], v[32:35], v[56:59], v[16:19]
	s_nop 3
	v_cvt_pk_bf16_f32 v20, v20, v21
	v_cvt_pk_bf16_f32 v21, v22, v23
	v_mfma_f32_16x16x32_bf16 v[12:15], v[12:15], v[8:11], 0
	v_mfma_f32_16x16x32_bf16 v[4:7], v[4:7], v[8:11], 0
	v_cvt_pk_bf16_f32 v22, v16, v17
	v_cvt_pk_bf16_f32 v23, v18, v19
	v_mfma_f32_16x16x32_bf16 v[4:7], v[68:71], v[56:59], v[4:7]
	s_waitcnt lgkmcnt(0)
	v_mfma_f32_16x16x32_bf16 v[16:19], v[24:27], v[20:23], 0
	ds_read_b64_tr_b16 v[24:25], v131 offset:32
	ds_read_b64_tr_b16 v[26:27], v131 offset:2336
	ds_read_b64_tr_b16 v[28:29], v131 offset:64
	ds_read_b64_tr_b16 v[32:33], v131 offset:96
	ds_read_b64_tr_b16 v[30:31], v131 offset:2368
	ds_read_b64_tr_b16 v[34:35], v131 offset:2400
	v_mfma_f32_16x16x32_bf16 v[12:15], v[36:39], v[56:59], v[12:15]
	v_cndmask_b32_e64 v0, v4, 0, s[40:41]
	v_cndmask_b32_e64 v1, 0, v5, s[42:43]
	ds_read_b64_tr_b16 v[36:37], v131 offset:4608
	ds_read_b64_tr_b16 v[38:39], v131 offset:6912
	s_waitcnt lgkmcnt(0)
	v_mfma_f32_16x16x32_bf16 v[24:27], v[24:27], v[20:23], 0
	s_nop 1
	v_cvt_pk_bf16_f32 v4, v12, v13
	v_cvt_pk_bf16_f32 v5, v14, v15
	v_cndmask_b32_e64 v2, v6, 0, s[38:39]
	v_mfma_f32_16x16x32_bf16 v[28:31], v[28:31], v[20:23], 0
	v_cndmask_b32_e64 v7, v7, 0, vcc
	v_cvt_pk_bf16_f32 v6, v0, v1
	v_cvt_pk_bf16_f32 v7, v2, v7
	v_mfma_f32_16x16x32_bf16 v[12:15], v[32:35], v[20:23], 0
	ds_read_b64_tr_b16 v[20:21], v131 offset:6944
	v_mad_u64_u32 v[0:1], s[20:21], v126, s72, v[100:101]
	v_mfma_f32_16x16x32_bf16 v[32:35], v[36:39], v[4:7], v[16:19]
	s_nop 2
	ds_read_b64_tr_b16 v[18:19], v131 offset:4640
	ds_read_b64_tr_b16 v[16:17], v131 offset:4672
	s_waitcnt lgkmcnt(0)
	v_mfma_f32_16x16x32_bf16 v[20:23], v[18:21], v[4:7], v[24:27]
	ds_read_b64_tr_b16 v[18:19], v131 offset:6976
	s_nop 1
	ds_read_b64_tr_b16 v[24:25], v131 offset:4704
	ds_read_b64_tr_b16 v[26:27], v131 offset:7008
	s_waitcnt lgkmcnt(0)
; __device__ __forceinline__ unsigned pk2(float lo, float hi) { const f32x2_t v = {lo, hi}; const bf16x2_t b = __builtin_convertvector(v, bf16x2_t); return __builtin_bit_cast(unsigned, b); }
; __device__ __forceinline__ float sigmoidf_(float x) { return __builtin_amdgcn_rcpf(1.0f + __expf(-x)); }
; __device__ __forceinline__ float bperm_f(int src_lane, float v) { return __builtin_bit_cast(float, __builtin_amdgcn_ds_bpermute(src_lane << 2, __builtin_bit_cast(int, v))); }
; template <int KIND>
; __device__ __forceinline__ void w_m3_core(const bf16x8 (&Qf)[4][2], const bf16x8 (&Kf)[4][2], const bf16x8 (&Sf)[4][2], const LAS bf16_t* vT, float lg,
;                                           const bf16_t* gsrc, const float* nw, bf16_t* ydst, int lo, int fq) {
;     ...
; #pragma unroll
;         for (int kk = 0; kk < 2; ++kk)
; #pragma unroll
;             for (int eb = 0; eb < 4; ++eb) O2[eb] = __builtin_amdgcn_mfma_f32_16x16x32_bf16(Sf[eb][kk], Qf[nb][kk], O2[eb], 0, 0, 0);
;         const float osc = KIND == 0 ? __expf((float)(16 * nb + lo + 1) * lg) : 1.0f;
; #pragma unroll
;         for (int eb = 0; eb < 4; ++eb) O[eb] = O[eb] + O2[eb] * osc;
;         float ss = 0.f;
; #pragma unroll
;         for (int eb = 0; eb < 4; ++eb) ss += (O[eb][0] * O[eb][0] + O[eb][1] * O[eb][1]) + (O[eb][2] * O[eb][2] + O[eb][3] * O[eb][3]);
;         { const int ln = (fq << 4) | lo; ss += bperm_f(ln ^ 16, ss); ss += bperm_f(ln ^ 32, ss); }
;         const float rs = rsqrtf(ss * (1.0f / 64.0f) + EPS);
;         const size_t n = 16 * nb + lo;
; #pragma unroll
;         for (int eb = 0; eb < 4; ++eb) { const int e0 = 16 * eb + 4 * fq;
;             const unsigned long long gw_ = *(const unsigned long long*)(gsrc + n * NIN + e0); const f32x4 w4 = *(const f32x4*)(nw + e0);
;             const float g0 = __uint_as_float((unsigned)gw_ << 16), g1 = __uint_as_float((unsigned)gw_ & 0xffff0000u), g2 = __uint_as_float((unsigned)(gw_ >> 32) << 16), g3 = __uint_as_float((unsigned)(gw_ >> 32) & 0xffff0000u);
;             const float o0 = O[eb][0] * rs * w4[0] * (g0 * sigmoidf_(g0)), o1 = O[eb][1] * rs * w4[1] * (g1 * sigmoidf_(g1));
;             const float o2 = O[eb][2] * rs * w4[2] * (g2 * sigmoidf_(g2)), o3 = O[eb][3] * rs * w4[3] * (g3 * sigmoidf_(g3));
;             *(unsigned long long*)(ydst + n * DM + e0) = (unsigned long long)pk2(o0, o1) | ((unsigned long long)pk2(o2, o3) << 32); }
	v_mfma_f32_16x16x32_bf16 v[16:19], v[16:19], v[4:7], v[28:31]
	v_mfma_f32_16x16x32_bf16 v[12:15], v[24:27], v[4:7], v[12:15]
	v_lshl_add_u64 v[6:7], v[0:1], 0, v[62:63]
	v_mov_b64_e32 v[44:45], v[246:247]
	v_mov_b64_e32 v[40:41], v[146:147]
	v_mov_b64_e32 v[42:43], v[148:149]
	v_mfma_f32_16x16x32_bf16 v[24:27], v[64:67], v[8:11], 0
	v_mfma_f32_16x16x32_bf16 v[28:31], v[72:75], v[8:11], 0
	v_mfma_f32_16x16x32_bf16 v[36:39], v[76:79], v[8:11], 0
	v_mfma_f32_16x16x32_bf16 v[8:11], v[80:83], v[8:11], 0
	v_mfma_f32_16x16x32_bf16 v[24:27], v[84:87], v[56:59], v[24:27]
	v_mfma_f32_16x16x32_bf16 v[8:11], v[96:99], v[56:59], v[8:11]
	v_mfma_f32_16x16x32_bf16 v[28:31], v[88:91], v[56:59], v[28:31]
	s_nop 5
	v_add_f32_e64 v26, v34, v26
	v_add_f32_e64 v27, v35, v27
	v_pk_add_f32 v[32:33], v[32:33], v[24:25]
	v_pk_add_f32 v[0:1], v[14:15], v[10:11]
	v_pk_add_f32 v[4:5], v[12:13], v[8:9]
	v_pk_mul_f32 v[8:9], v[26:27], v[26:27]
	v_pk_mul_f32 v[10:11], v[32:33], v[32:33]
	v_pk_add_f32 v[30:31], v[22:23], v[30:31]
	v_mfma_f32_16x16x32_bf16 v[22:25], v[92:95], v[56:59], v[36:39]
	v_add_f32_e64 v20, v20, v28
	v_add_f32_e64 v21, v21, v29
	v_pk_mov_b32 v[12:13], v[10:11], v[8:9] op_sel:[1,0]
	v_mov_b32_e32 v11, v9
	v_pk_add_f32 v[8:9], v[12:13], v[10:11]
	v_pk_mul_f32 v[10:11], v[30:31], v[30:31]
	v_pk_mul_f32 v[12:13], v[20:21], v[20:21]
	s_nop 0
	v_pk_add_f32 v[16:17], v[16:17], v[22:23]
	v_pk_mov_b32 v[14:15], v[12:13], v[10:11] op_sel:[1,0]
	v_mov_b32_e32 v13, v11
	v_pk_add_f32 v[10:11], v[14:15], v[12:13]
	v_mul_f32_e32 v2, v4, v4
	v_mul_f32_e32 v12, v5, v5
	v_pk_add_f32 v[8:9], v[8:9], v[8:9] op_sel:[0,1] op_sel_hi:[1,0]
	v_pk_add_f32 v[10:11], v[10:11], v[10:11] op_sel:[0,1] op_sel_hi:[1,0]
	v_pk_add_f32 v[18:19], v[18:19], v[24:25]
	v_mov_b32_e32 v9, v2
	v_mov_b32_e32 v11, v12
	v_mul_f32_e32 v2, v17, v17
	v_mul_f32_e32 v13, v0, v0
	v_pk_add_f32 v[8:9], v[8:9], v[10:11]
	v_pk_fma_f32 v[10:11], v[16:17], v[16:17], v[2:3] op_sel_hi:[1,1,0]
	v_mul_f32_e32 v2, v19, v19
	v_mul_f32_e32 v14, v1, v1
	v_mov_b32_e32 v11, v13
	v_pk_fma_f32 v[12:13], v[18:19], v[18:19], v[2:3] op_sel_hi:[1,1,0]
	s_waitcnt lgkmcnt(0)
	v_and_b32_e32 v15, 0xffff0000, v45
	v_mov_b32_e32 v13, v14
	v_pk_add_f32 v[10:11], v[10:11], v[12:13]
	v_lshlrev_b32_e32 v12, 16, v44
	v_pk_add_f32 v[8:9], v[8:9], v[10:11]
	v_and_b32_e32 v13, 0xffff0000, v44
	v_add_f32_e32 v2, v8, v9
	ds_bpermute_b32 v8, v130, v2
	v_mul_f32_e32 v9, 0xbfb8aa3b, v13
	v_exp_f32_e32 v9, v9
	v_lshlrev_b32_e32 v14, 16, v45
	s_waitcnt lgkmcnt(0)
	v_add_f32_e32 v2, v2, v8
	ds_bpermute_b32 v8, v129, v2
	s_waitcnt lgkmcnt(0)
	v_add_f32_e32 v2, v2, v8
	v_fmamk_f32 v2, v2, 0x3c800000, v200
	v_mul_f32_e32 v8, 0x4b800000, v2
	v_cmp_gt_f32_e32 vcc, s29, v2
	s_nop 1
	v_cndmask_b32_e32 v2, v2, v8, vcc
	v_rsq_f32_e32 v2, v2
	s_nop 0
	v_mul_f32_e32 v8, 0x45800000, v2
	v_cndmask_b32_e32 v8, v2, v8, vcc
	v_lshlrev_b32_e32 v2, 11, v126
	v_lshl_add_u64 v[10:11], s[46:47], 0, v[2:3]
	v_mul_f32_e32 v2, 0xbfb8aa3b, v12
	v_exp_f32_e32 v2, v2
	v_pk_mul_f32 v[24:25], v[32:33], v[8:9] op_sel_hi:[1,0]
	v_lshl_add_u64 v[10:11], v[10:11], 0, v[62:63]
	v_pk_mul_f32 v[24:25], v[40:41], v[24:25]
	v_add_f32_e32 v2, 1.0, v2
	v_rcp_f32_e32 v22, v2
	v_add_f32_e32 v2, 1.0, v9
	v_rcp_f32_e32 v23, v2
	v_mul_f32_e32 v2, 0xbfb8aa3b, v14
	v_exp_f32_e32 v2, v2
	v_mul_f32_e32 v9, 0xbfb8aa3b, v15
	v_exp_f32_e32 v9, v9
	v_pk_mul_f32 v[12:13], v[22:23], v[12:13]
	v_add_f32_e32 v2, 1.0, v2
	v_rcp_f32_e32 v22, v2
	v_add_f32_e32 v2, 1.0, v9
	v_rcp_f32_e32 v23, v2
	v_pk_mul_f32 v[12:13], v[12:13], v[24:25]
	v_pk_mul_f32 v[24:25], v[26:27], v[8:9] op_sel_hi:[1,0]
	v_cvt_pk_bf16_f32 v12, v12, v13
	v_pk_mul_f32 v[24:25], v[42:43], v[24:25]
	v_pk_mul_f32 v[14:15], v[22:23], v[14:15]
	v_pk_mul_f32 v[20:21], v[20:21], v[8:9] op_sel_hi:[1,0]
	v_pk_mul_f32 v[14:15], v[14:15], v[24:25]
	v_pk_mul_f32 v[24:25], v[30:31], v[8:9] op_sel_hi:[1,0]
	v_cvt_pk_bf16_f32 v13, v14, v15
	global_store_dwordx2 v[10:11], v[12:13], off offset:1536
	v_mov_b64_e32 v[22:23], v[248:249]
	s_nop 0
	v_mov_b64_e32 v[12:13], v[150:151]
	v_mov_b64_e32 v[14:15], v[152:153]
	v_mul_f32_e32 v16, v16, v8
	v_mul_f32_e32 v18, v18, v8
	v_mul_f32_e32 v4, v4, v8
	v_mul_f32_e32 v0, v0, v8
	s_waitcnt lgkmcnt(0)
; __device__ __forceinline__ unsigned pk2(float lo, float hi) { const f32x2_t v = {lo, hi}; const bf16x2_t b = __builtin_convertvector(v, bf16x2_t); return __builtin_bit_cast(unsigned, b); }
; __device__ __forceinline__ float sigmoidf_(float x) { return __builtin_amdgcn_rcpf(1.0f + __expf(-x)); }
; template <int KIND>
; __device__ __forceinline__ void w_m3_core(const bf16x8 (&Qf)[4][2], const bf16x8 (&Kf)[4][2], const bf16x8 (&Sf)[4][2], const LAS bf16_t* vT, float lg,
;                                           const bf16_t* gsrc, const float* nw, bf16_t* ydst, int lo, int fq) {
;     ...
;         for (int eb = 0; eb < 4; ++eb) { const int e0 = 16 * eb + 4 * fq;
;             const unsigned long long gw_ = *(const unsigned long long*)(gsrc + n * NIN + e0); const f32x4 w4 = *(const f32x4*)(nw + e0);
;             const float g0 = __uint_as_float((unsigned)gw_ << 16), g1 = __uint_as_float((unsigned)gw_ & 0xffff0000u), g2 = __uint_as_float((unsigned)(gw_ >> 32) << 16), g3 = __uint_as_float((unsigned)(gw_ >> 32) & 0xffff0000u);
;             const float o0 = O[eb][0] * rs * w4[0] * (g0 * sigmoidf_(g0)), o1 = O[eb][1] * rs * w4[1] * (g1 * sigmoidf_(g1));
;             const float o2 = O[eb][2] * rs * w4[2] * (g2 * sigmoidf_(g2)), o3 = O[eb][3] * rs * w4[3] * (g3 * sigmoidf_(g3));
;             *(unsigned long long*)(ydst + n * DM + e0) = (unsigned long long)pk2(o0, o1) | ((unsigned long long)pk2(o2, o3) << 32); }
	v_lshlrev_b32_e32 v26, 16, v22
	v_and_b32_e32 v27, 0xffff0000, v22
	v_lshlrev_b32_e32 v22, 16, v23
	v_and_b32_e32 v23, 0xffff0000, v23
	v_mul_f32_e32 v2, 0xbfb8aa3b, v26
	v_mul_f32_e32 v9, 0xbfb8aa3b, v27
	v_mul_f32_e32 v28, 0xbfb8aa3b, v22
	v_mul_f32_e32 v29, 0xbfb8aa3b, v23
	v_exp_f32_e32 v2, v2
	v_exp_f32_e32 v9, v9
	v_exp_f32_e32 v28, v28
	v_exp_f32_e32 v29, v29
	v_add_f32_e32 v2, 1.0, v2
	v_add_f32_e32 v9, 1.0, v9
	v_add_f32_e32 v30, 1.0, v28
	v_add_f32_e32 v31, 1.0, v29
	v_rcp_f32_e32 v28, v2
	v_rcp_f32_e32 v29, v9
	v_rcp_f32_e32 v30, v30
	v_rcp_f32_e32 v31, v31
	v_pk_mul_f32 v[12:13], v[12:13], v[20:21]
	v_pk_mul_f32 v[14:15], v[14:15], v[24:25]
	v_pk_mul_f32 v[20:21], v[28:29], v[26:27]
	v_pk_mul_f32 v[22:23], v[30:31], v[22:23]
	v_pk_mul_f32 v[12:13], v[20:21], v[12:13]
	v_pk_mul_f32 v[14:15], v[22:23], v[14:15]
	v_cvt_pk_bf16_f32 v12, v12, v13
	v_cvt_pk_bf16_f32 v13, v14, v15
	global_store_dwordx2 v[10:11], v[12:13], off offset:1568
	v_mov_b64_e32 v[20:21], v[250:251]
	s_nop 0
	v_mov_b64_e32 v[12:13], v[188:189]
	v_mov_b64_e32 v[14:15], v[190:191]
	v_mul_f32_e32 v22, v17, v8
	v_mul_f32_e32 v24, v19, v8
	s_waitcnt lgkmcnt(0)
	v_lshlrev_b32_e32 v17, 16, v20
	v_and_b32_e32 v23, 0xffff0000, v20
	v_lshlrev_b32_e32 v19, 16, v21
	v_and_b32_e32 v25, 0xffff0000, v21
	v_mov_b32_e32 v20, v13
	v_mov_b32_e32 v26, v15
	v_mul_f32_e32 v2, 0xbfb8aa3b, v17
	v_mul_f32_e32 v9, 0xbfb8aa3b, v23
	v_mul_f32_e32 v13, 0xbfb8aa3b, v19
	v_mul_f32_e32 v15, 0xbfb8aa3b, v25
	v_exp_f32_e32 v2, v2
	v_exp_f32_e32 v9, v9
	v_exp_f32_e32 v13, v13
	v_exp_f32_e32 v15, v15
	v_add_f32_e32 v2, 1.0, v2
	v_add_f32_e32 v9, 1.0, v9
	v_add_f32_e32 v27, 1.0, v13
	v_add_f32_e32 v28, 1.0, v15
	v_rcp_f32_e32 v13, v2
	v_rcp_f32_e32 v21, v9
	v_rcp_f32_e32 v15, v27
	v_rcp_f32_e32 v27, v28
	v_pk_mul_f32 v[12:13], v[12:13], v[16:17]
	v_pk_mul_f32 v[16:17], v[20:21], v[22:23]
	v_pk_mul_f32 v[14:15], v[14:15], v[18:19]
	v_pk_mul_f32 v[18:19], v[26:27], v[24:25]
	v_mov_b32_e32 v20, v12
	v_mov_b32_e32 v21, v16
	v_mov_b32_e32 v16, v13
	v_mov_b32_e32 v12, v14
	v_mov_b32_e32 v13, v18
	v_mov_b32_e32 v18, v15
	v_pk_mul_f32 v[14:15], v[20:21], v[16:17]
	v_pk_mul_f32 v[12:13], v[12:13], v[18:19]
	v_cvt_pk_bf16_f32 v14, v14, v15
	v_cvt_pk_bf16_f32 v15, v12, v13
	global_store_dwordx2 v[10:11], v[14:15], off offset:1600
	v_mov_b64_e32 v[6:7], v[252:253]
	s_nop 0
	v_mov_b64_e32 v[12:13], v[192:193]
	v_mov_b64_e32 v[14:15], v[194:195]
	v_mul_f32_e32 v16, v5, v8
	v_mul_f32_e32 v8, v1, v8
	s_waitcnt lgkmcnt(0)
	v_lshlrev_b32_e32 v5, 16, v6
	v_and_b32_e32 v17, 0xffff0000, v6
	v_lshlrev_b32_e32 v1, 16, v7
	v_and_b32_e32 v9, 0xffff0000, v7
	v_mov_b32_e32 v6, v12
	v_mov_b32_e32 v12, v13
	v_mov_b32_e32 v18, v15
	v_mul_f32_e32 v2, 0xbfb8aa3b, v5
	v_mul_f32_e32 v7, 0xbfb8aa3b, v17
	v_mul_f32_e32 v13, 0xbfb8aa3b, v1
	v_mul_f32_e32 v15, 0xbfb8aa3b, v9
	v_exp_f32_e32 v2, v2
	v_exp_f32_e32 v7, v7
	v_exp_f32_e32 v13, v13
	v_exp_f32_e32 v15, v15
	v_add_f32_e32 v2, 1.0, v2
	v_add_f32_e32 v19, 1.0, v7
	v_add_f32_e32 v20, 1.0, v13
	v_add_f32_e32 v21, 1.0, v15
	v_rcp_f32_e32 v7, v2
	v_rcp_f32_e32 v13, v19
	v_rcp_f32_e32 v15, v20
	v_rcp_f32_e32 v19, v21
	v_pk_mul_f32 v[4:5], v[6:7], v[4:5]
	v_pk_mul_f32 v[6:7], v[12:13], v[16:17]
	v_pk_mul_f32 v[0:1], v[14:15], v[0:1]
	v_pk_mul_f32 v[8:9], v[18:19], v[8:9]
	v_mov_b32_e32 v12, v4
	v_mov_b32_e32 v13, v6
	v_mov_b32_e32 v6, v5
	v_mov_b32_e32 v4, v0
	v_mov_b32_e32 v5, v8
	v_mov_b32_e32 v8, v1
	v_pk_mul_f32 v[0:1], v[12:13], v[6:7]
	v_pk_mul_f32 v[4:5], v[4:5], v[8:9]
	v_cvt_pk_bf16_f32 v0, v0, v1
	v_cvt_pk_bf16_f32 v1, v4, v5
	global_store_dwordx2 v[10:11], v[0:1], off offset:1632
	s_waitcnt lgkmcnt(0)

; #define LAS __attribute__((address_space(3)))
; __device__ __forceinline__ void ld8bf(const bf16_t* p, float (&o)[8]) { unpack8(*(const u32x4*)p, o); }
; __device__ __forceinline__ void w_hg_m3(const Args& a, int l, unsigned char* ws, const bf16_t* proj, bf16_t* y, LAS unsigned char* wl, int b, int ck_, int h, int lane) {
;     LAS bf16_t* vT = (LAS bf16_t*)wl;
;     const int row0 = b * SEQ + 64 * ck_, lo = lane & 15, fq = lane >> 4;
;     w_store_vT(vT, proj + (size_t)row0 * NIN + C_HI + 64 * h, lane);
;     bf16x8 Qf[4][2], Kf[4][2], Sf[4][2]; float er[2][8];
;     const bf16_t* Sb = (const bf16_t*)((const unsigned char*)a.out + OUT_SBH) + (size_t)((b * NCH + ck_) * 4 + h) * 4096;
; #pragma unroll
;     for (int kk = 0; kk < 2; ++kk) { float bb[4][8], r31[8], r63[8], lbv[8];
; #pragma unroll
;         for (int j = 0; j < 8; ++j) lbv[j] = hg_lb(a, l, 64 * h + 32 * kk + 8 * fq + j);
;         const bf16_t* fsrc = proj + (size_t)row0 * NIN + C_HF + 64 * h + 32 * kk + 8 * fq;
;         w_hg_scan(lbv, fsrc, lane, bb, r31, r63);
; #pragma unroll
;         for (int tb = 0; tb < 4; ++tb) { float fp[8], qv[8], a1[8], a2[8];
;             ld8bf(fsrc + (size_t)(16 * tb + lo) * NIN, fp); ld8bf(proj + (size_t)(row0 + 16 * tb + lo) * NIN + C_HQ + 64 * h + 32 * kk + 8 * fq, qv);
.LBB0_191:
	s_lshr_b32 s20, s66, 8
	s_lshr_b32 s21, s66, 9
	s_add_i32 s20, s20, s66
	s_and_b32 s21, s21, 12
	s_add_i32 s20, s20, s21
	s_and_b32 s70, s20, 15
	s_cmp_lt_u32 s70, 12
	s_cbranch_scc1 .LBB0_190
	s_ashr_i32 s21, s66, 31
	s_ashr_i32 s20, s66, 4
	s_lshr_b32 s21, s21, 25
	s_add_i32 s21, s20, s21
	s_ashr_i32 s71, s21, 7
	s_and_b32 s21, s21, 0xffffff80
	s_sub_i32 s90, s20, s21
	s_lshl_b32 s20, s71, 13
	s_lshl_b32 s21, s90, 6
	s_add_i32 s86, s21, s20
	s_add_i32 s70, s70, -12
	s_mul_i32 s21, s86, 0x1800
	s_mul_hi_i32 s20, s86, 0x1800
	s_add_u32 s67, s8, s21
	v_mov_b32_e32 v10, v132
	s_addc_u32 s68, s9, s20
	s_lshl_b32 s24, s70, 6
	s_lshl_b32 s20, s70, 7
	s_add_u32 s20, s67, s20
	v_lshlrev_b32_e32 v0, 4, v10
	s_addc_u32 s21, s68, 0
	v_and_b32_e32 v2, 0x70, v0
	v_lshl_add_u64 v[0:1], s[20:21], 0, v[2:3]
	s_mov_b64 s[20:21], 0x1400
	v_ashrrev_i32_e32 v8, 3, v10
	v_lshl_add_u64 v[0:1], v[0:1], 0, s[20:21]
	v_mad_i64_i32 v[4:5], s[20:21], v8, s72, v[0:1]
	global_load_dwordx4 v[60:63], v[4:5], off
	v_add_u32_e32 v4, 8, v8
	v_mad_i64_i32 v[4:5], s[20:21], v4, s72, v[0:1]
	global_load_dwordx4 v[64:67], v[4:5], off
	v_add_u32_e32 v4, 16, v8
	v_mad_i64_i32 v[4:5], s[20:21], v4, s72, v[0:1]
	global_load_dwordx4 v[70:73], v[4:5], off
	v_add_u32_e32 v4, 24, v8
	v_mad_i64_i32 v[4:5], s[20:21], v4, s72, v[0:1]
	global_load_dwordx4 v[74:77], v[4:5], off
	v_add_u32_e32 v4, 32, v8
	v_mad_i64_i32 v[4:5], s[20:21], v4, s72, v[0:1]
	global_load_dwordx4 v[78:81], v[4:5], off
	v_add_u32_e32 v4, 40, v8
	v_mad_i64_i32 v[4:5], s[20:21], v4, s72, v[0:1]
	global_load_dwordx4 v[88:91], v[4:5], off
	v_add_u32_e32 v4, 48, v8
	v_mad_i64_i32 v[4:5], s[20:21], v4, s72, v[0:1]
	global_load_dwordx4 v[92:95], v[4:5], off
	v_add_u32_e32 v4, 56, v8
	v_mad_i64_i32 v[0:1], s[20:21], v4, s72, v[0:1]
	global_load_dwordx4 v[96:99], v[0:1], off
	v_and_b32_e32 v196, 15, v10
	v_lshrrev_b32_e32 v197, 4, v10
	v_mul_u32_u24_e32 v196, 0x1800, v196
	v_lshl_add_u32 v196, v197, 4, v196
	s_lshl_b32 s20, s24, 1
	s_addk_i32 s20, 0x1200
	v_add_u32_e32 v196, s20, v196
	v_add_co_u32_e32 v198, vcc, s67, v196
	v_mov_b32_e32 v199, s68
	s_nop 0
	v_addc_co_u32_e32 v199, vcc, 0, v199, vcc
	global_load_dwordx4 v[222:225], v[198:199], off
	global_load_dwordx4 v[238:241], v[198:199], off offset:64
	v_add_u32_e32 v196, 0x18000, v196
	v_add_co_u32_e32 v198, vcc, s67, v196
	v_mov_b32_e32 v199, s68
	s_nop 0
	v_addc_co_u32_e32 v199, vcc, 0, v199, vcc
	global_load_dwordx4 v[226:229], v[198:199], off
	global_load_dwordx4 v[242:245], v[198:199], off offset:64
	v_add_u32_e32 v196, 0x18000, v196
	v_add_co_u32_e32 v198, vcc, s67, v196
	v_mov_b32_e32 v199, s68
	s_nop 0
	v_addc_co_u32_e32 v199, vcc, 0, v199, vcc
	global_load_dwordx4 v[230:233], v[198:199], off
	global_load_dwordx4 v[246:249], v[198:199], off offset:64
	v_add_u32_e32 v196, 0x18000, v196
	v_add_co_u32_e32 v198, vcc, s67, v196
	v_mov_b32_e32 v199, s68
	s_nop 0
	v_addc_co_u32_e32 v199, vcc, 0, v199, vcc
	global_load_dwordx4 v[234:237], v[198:199], off
	global_load_dwordx4 v[250:253], v[198:199], off offset:64
	v_mul_lo_u32 v9, v8, s23
	v_add3_u32 v2, s2, v2, v9
	v_ashrrev_i32_e32 v108, 4, v10
	v_mov_b32_e32 v43, 0
	s_and_b64 vcc, exec, s[14:15]
	v_mov_b32_e32 v42, 0
	v_mov_b32_e32 v154, v2
	v_lshlrev_b32_e32 v0, 3, v108
	v_add_u32_e32 v36, s24, v0
	v_ashrrev_i32_e32 v37, 31, v36
	s_cbranch_vccnz .LBB0_466
	v_cndmask_b32_e64 v1, 0, 1, s[14:15]
	v_cmp_ne_u32_e64 s[38:39], 1, v1
	s_andn2_b64 vcc, exec, s[14:15]
	s_cbranch_vccz .LBB0_467

; __device__ __forceinline__ void ld8bf(const bf16_t* p, float (&o)[8]) { unpack8(*(const u32x4*)p, o); }
; __device__ __forceinline__ float sigmoidf_(float x) { return __builtin_amdgcn_rcpf(1.0f + __expf(-x)); }
; __device__ __forceinline__ const float* in_ptr(const Args& a, int i) { asm volatile("" : "+s"(i)); return a.in[i]; }
; __device__ __forceinline__ float hg_lb(const Args& a, int l, int ch) {
;     if (l == 0) return 0.f;
;     const float* hb = in_ptr(a, I_HLB); return sigmoidf_(hb[256 + ch] - hb[ch]);
; __device__ __forceinline__ void hg_lf_key(float fp, float lb, float& lf, float& key) {
;     const float e = __expf(-fabsf(fp));
;     const float rc = __builtin_amdgcn_rcpf(1.0f + e);
;     const float sp = fp >= 0.f ? rc : e * rc;
;     const float sn = fp >= 0.f ? e * rc : rc;
;     const float lsig = (fp >= 0.f ? 0.f : fp) + __logf(rc);
;     lf = (lb == 0.f) ? lsig : __logf(lb + (1.0f - lb) * sp); key = (1.0f - lb) * sn;
; }
; __device__ __forceinline__ void w_hg_scan(const float (&lbv)[8], const bf16_t* fsrc, int lane, float (&bb)[4][8], float (&r31)[8], float (&r63)[8]) {
;     const int lo = lane & 15;
; #pragma unroll
;     for (int tb = 0; tb < 4; ++tb) { float fp[8]; ld8bf(fsrc + (size_t)(16 * tb + lo) * NIN, fp);
; #pragma unroll
;         for (int j = 0; j < 8; ++j) { float key; hg_lf_key(fp[j], lbv[j], bb[tb][j], key); } }
.LBB0_200:
	s_mov_b32 s20, 11
	s_ashr_i32 s21, s20, 31
	s_lshl_b64 s[20:21], s[20:21], 3
	s_add_u32 s20, s0, s20
	s_addc_u32 s21, s1, s21
	s_load_dwordx2 s[20:21], s[20:21], 0x0
	s_waitcnt lgkmcnt(0)
	v_lshl_add_u64 v[4:5], v[36:37], 2, s[20:21]
	v_mov_b32_e32 v1, v127
	v_mov_b32_e32 v2, v193
	s_waitcnt vmcnt(0)
	v_sub_f32_e32 v1, v1, v2
	v_mul_f32_e32 v1, 0xbfb8aa3b, v1
	v_exp_f32_e32 v1, v1
	s_nop 0
	v_add_f32_e32 v1, 1.0, v1
	v_rcp_f32_e32 v11, v1
.LBB0_201:
	s_lshl_b32 s88, s24, 1
	v_and_b32_e32 v114, 15, v10
	s_add_u32 s20, s67, s88
	s_addc_u32 s21, s68, 0
	v_ashrrev_i32_e32 v1, 31, v0
	v_mul_u32_u24_e32 v2, 0xc00, v114
	v_lshl_add_u64 v[4:5], v[0:1], 1, s[20:21]
	v_lshlrev_b32_e32 v2, 1, v2
	v_lshl_add_u64 v[8:9], v[4:5], 0, v[2:3]
	v_add_co_u32_e32 v4, vcc, s73, v8
	v_cmp_neq_f32_e64 s[40:41], 0, v42
	s_nop 0
	v_addc_co_u32_e32 v5, vcc, 0, v9, vcc
	s_waitcnt vmcnt(0)
	ds_write_b128 v154, v[60:63]
	ds_write_b128 v154, v[64:67] offset:1152
	ds_write_b128 v154, v[70:73] offset:2304
	ds_write_b128 v154, v[74:77] offset:3456
	ds_write_b128 v154, v[78:81] offset:4608
	ds_write_b128 v154, v[88:91] offset:5760
	ds_write_b128 v154, v[92:95] offset:6912
	ds_write_b128 v154, v[96:99] offset:8064
	v_mov_b64_e32 v[4:5], v[222:223]
	v_mov_b64_e32 v[6:7], v[224:225]
	v_sub_f32_e32 v20, 1.0, v42
	s_waitcnt vmcnt(0) lgkmcnt(0)
	v_lshlrev_b32_e32 v13, 16, v4
	v_mul_f32_e64 v2, |v13|, s26
	v_exp_f32_e32 v15, v2
	v_cmp_le_f32_e32 vcc, 0, v13
	v_add_f32_e32 v2, 1.0, v15
	v_rcp_f32_e32 v14, v2
	s_and_saveexec_b64 s[20:21], s[40:41]
	s_xor_b64 s[34:35], exec, s[20:21]
	s_cbranch_execz .LBB0_203
	v_mul_f32_e32 v2, v15, v14
	v_cndmask_b32_e32 v2, v2, v14, vcc
	v_fma_f32 v2, v20, v2, v42
	v_cmp_gt_f32_e64 s[42:43], s29, v2
	s_nop 1
	v_cndmask_b32_e64 v13, 0, 32, s[42:43]
	v_ldexp_f32 v2, v2, v13
	v_log_f32_e32 v2, v2
	s_nop 0
	v_mul_f32_e32 v13, 0x3f317217, v2
	v_fma_f32 v13, v2, s17, -v13
	v_fmac_f32_e32 v13, 0x3377d1cf, v2
	v_fmac_f32_e32 v13, 0x3f317217, v2
	v_cmp_lt_f32_e64 s[44:45], |v2|, s22
	s_nop 1
	v_cndmask_b32_e64 v2, v2, v13, s[44:45]
	v_cndmask_b32_e64 v13, 0, v203, s[42:43]
	v_sub_f32_e32 v2, v2, v13

; __device__ __forceinline__ void ld8bf(const bf16_t* p, float (&o)[8]) { unpack8(*(const u32x4*)p, o); }
; __device__ __forceinline__ void hg_lf_key(float fp, float lb, float& lf, float& key) {
;     const float e = __expf(-fabsf(fp));
;     const float rc = __builtin_amdgcn_rcpf(1.0f + e);
;     const float sp = fp >= 0.f ? rc : e * rc;
;     const float sn = fp >= 0.f ? e * rc : rc;
;     const float lsig = (fp >= 0.f ? 0.f : fp) + __logf(rc);
;     lf = (lb == 0.f) ? lsig : __logf(lb + (1.0f - lb) * sp); key = (1.0f - lb) * sn;
; }
; __device__ __forceinline__ void w_hg_scan(const float (&lbv)[8], const bf16_t* fsrc, int lane, float (&bb)[4][8], float (&r31)[8], float (&r63)[8]) {
;     const int lo = lane & 15;
; #pragma unroll
;     for (int tb = 0; tb < 4; ++tb) { float fp[8]; ld8bf(fsrc + (size_t)(16 * tb + lo) * NIN, fp);
; #pragma unroll
;         for (int j = 0; j < 8; ++j) { float key; hg_lf_key(fp[j], lbv[j], bb[tb][j], key); } }
.LBB0_233:
	s_or_b64 exec, exec, s[34:35]
	s_mov_b64 s[20:21], 0x1200
	v_lshl_add_u64 v[52:53], v[8:9], 0, s[20:21]
	v_add_co_u32_e32 v4, vcc, 0x18000, v52
	s_nop 1
	v_addc_co_u32_e32 v5, vcc, 0, v53, vcc
	v_mov_b64_e32 v[4:5], v[226:227]
	v_mov_b64_e32 v[6:7], v[228:229]
	s_waitcnt vmcnt(0) lgkmcnt(0)
	v_lshlrev_b32_e32 v9, 16, v4
	v_mul_f32_e64 v8, |v9|, s26
	v_exp_f32_e32 v27, v8
	v_cmp_le_f32_e32 vcc, 0, v9
	v_add_f32_e32 v8, 1.0, v27
	v_rcp_f32_e32 v26, v8
	s_and_saveexec_b64 s[20:21], s[40:41]
	s_xor_b64 s[34:35], exec, s[20:21]
	s_cbranch_execz .LBB0_235
	v_mul_f32_e32 v8, v27, v26
	v_cndmask_b32_e32 v8, v8, v26, vcc
	v_fma_f32 v8, v20, v8, v42
	v_cmp_gt_f32_e64 s[56:57], s29, v8
	s_nop 1
	v_cndmask_b32_e64 v9, 0, 32, s[56:57]
	v_ldexp_f32 v8, v8, v9
	v_log_f32_e32 v8, v8
	s_nop 0
	v_mul_f32_e32 v9, 0x3f317217, v8
	v_fma_f32 v9, v8, s17, -v9
	v_fmac_f32_e32 v9, 0x3377d1cf, v8
	v_fmac_f32_e32 v9, 0x3f317217, v8
	v_cmp_lt_f32_e64 s[58:59], |v8|, s22
	s_nop 1
	v_cndmask_b32_e64 v8, v8, v9, s[58:59]
	v_cndmask_b32_e64 v9, 0, v203, s[56:57]
	v_sub_f32_e32 v8, v8, v9

; __device__ __forceinline__ void ld8bf(const bf16_t* p, float (&o)[8]) { unpack8(*(const u32x4*)p, o); }
; __device__ __forceinline__ void hg_lf_key(float fp, float lb, float& lf, float& key) {
;     const float e = __expf(-fabsf(fp));
;     const float rc = __builtin_amdgcn_rcpf(1.0f + e);
;     const float sp = fp >= 0.f ? rc : e * rc;
;     const float sn = fp >= 0.f ? e * rc : rc;
;     const float lsig = (fp >= 0.f ? 0.f : fp) + __logf(rc);
;     lf = (lb == 0.f) ? lsig : __logf(lb + (1.0f - lb) * sp); key = (1.0f - lb) * sn;
; }
; __device__ __forceinline__ void w_hg_scan(const float (&lbv)[8], const bf16_t* fsrc, int lane, float (&bb)[4][8], float (&r31)[8], float (&r63)[8]) {
;     const int lo = lane & 15;
; #pragma unroll
;     for (int tb = 0; tb < 4; ++tb) { float fp[8]; ld8bf(fsrc + (size_t)(16 * tb + lo) * NIN, fp);
; #pragma unroll
;         for (int j = 0; j < 8; ++j) { float key; hg_lf_key(fp[j], lbv[j], bb[tb][j], key); } }
.LBB0_265:
	s_or_b64 exec, exec, s[34:35]
	v_add_co_u32_e32 v4, vcc, 0x30000, v52
	s_nop 1
	v_addc_co_u32_e32 v5, vcc, 0, v53, vcc
	v_mov_b64_e32 v[4:5], v[230:231]
	v_mov_b64_e32 v[6:7], v[232:233]
	s_waitcnt vmcnt(0) lgkmcnt(0)
	v_lshlrev_b32_e32 v33, 16, v4
	v_mul_f32_e64 v32, |v33|, s26
	v_exp_f32_e32 v35, v32
	v_cmp_le_f32_e32 vcc, 0, v33
	v_add_f32_e32 v32, 1.0, v35
	v_rcp_f32_e32 v34, v32
	s_and_saveexec_b64 s[20:21], s[40:41]
	s_xor_b64 s[34:35], exec, s[20:21]
	s_cbranch_execz .LBB0_267
	v_mul_f32_e32 v32, v35, v34
	v_cndmask_b32_e32 v32, v32, v34, vcc
	v_fma_f32 v32, v20, v32, v42
	v_cmp_gt_f32_e64 s[56:57], s29, v32
	s_nop 1
	v_cndmask_b32_e64 v33, 0, 32, s[56:57]
	v_ldexp_f32 v32, v32, v33
	v_log_f32_e32 v32, v32
	s_nop 0
	v_mul_f32_e32 v33, 0x3f317217, v32
	v_fma_f32 v33, v32, s17, -v33
	v_fmac_f32_e32 v33, 0x3377d1cf, v32
	v_fmac_f32_e32 v33, 0x3f317217, v32
	v_cmp_lt_f32_e64 s[58:59], |v32|, s22
	s_nop 1
	v_cndmask_b32_e64 v32, v32, v33, s[58:59]
	v_cndmask_b32_e64 v33, 0, v203, s[56:57]
	v_sub_f32_e32 v32, v32, v33

; __device__ __forceinline__ void ld8bf(const bf16_t* p, float (&o)[8]) { unpack8(*(const u32x4*)p, o); }
; __device__ __forceinline__ void hg_lf_key(float fp, float lb, float& lf, float& key) {
;     const float e = __expf(-fabsf(fp));
;     const float rc = __builtin_amdgcn_rcpf(1.0f + e);
;     const float sp = fp >= 0.f ? rc : e * rc;
;     const float sn = fp >= 0.f ? e * rc : rc;
;     const float lsig = (fp >= 0.f ? 0.f : fp) + __logf(rc);
;     lf = (lb == 0.f) ? lsig : __logf(lb + (1.0f - lb) * sp); key = (1.0f - lb) * sn;
; }
; __device__ __forceinline__ void w_hg_scan(const float (&lbv)[8], const bf16_t* fsrc, int lane, float (&bb)[4][8], float (&r31)[8], float (&r63)[8]) {
;     const int lo = lane & 15;
; #pragma unroll
;     for (int tb = 0; tb < 4; ++tb) { float fp[8]; ld8bf(fsrc + (size_t)(16 * tb + lo) * NIN, fp);
; #pragma unroll
;         for (int j = 0; j < 8; ++j) { float key; hg_lf_key(fp[j], lbv[j], bb[tb][j], key); } }
.LBB0_297:
	s_or_b64 exec, exec, s[34:35]
	v_add_co_u32_e32 v4, vcc, 0x48000, v52
	s_nop 1
	v_addc_co_u32_e32 v5, vcc, 0, v53, vcc
	v_mov_b64_e32 v[4:5], v[234:235]
	v_mov_b64_e32 v[6:7], v[236:237]
	s_waitcnt vmcnt(0) lgkmcnt(0)
	v_lshlrev_b32_e32 v48, 16, v4
	v_mul_f32_e64 v49, |v48|, s26
	v_exp_f32_e32 v55, v49
	v_cmp_le_f32_e32 vcc, 0, v48
	v_add_f32_e32 v49, 1.0, v55
	v_rcp_f32_e32 v49, v49
	s_and_saveexec_b64 s[20:21], s[40:41]
	s_xor_b64 s[34:35], exec, s[20:21]
	s_cbranch_execz .LBB0_299
	v_mul_f32_e32 v48, v55, v49
	v_cndmask_b32_e32 v48, v48, v49, vcc
	v_fma_f32 v20, v20, v48, v42
	v_cmp_gt_f32_e64 s[40:41], s29, v20
	s_nop 1
	v_cndmask_b32_e64 v48, 0, 32, s[40:41]
	v_ldexp_f32 v20, v20, v48
	v_log_f32_e32 v20, v20
	s_nop 0
	v_mul_f32_e32 v48, 0x3f317217, v20
	v_fma_f32 v48, v20, s17, -v48
	v_fmac_f32_e32 v48, 0x3377d1cf, v20
	v_fmac_f32_e32 v48, 0x3f317217, v20
	v_cmp_lt_f32_e64 s[56:57], |v20|, s22
	s_nop 1
	v_cndmask_b32_e64 v20, v20, v48, s[56:57]
	v_cndmask_b32_e64 v48, 0, v203, s[40:41]
	v_sub_f32_e32 v54, v20, v48

; __device__ __forceinline__ void ld8bf(const bf16_t* p, float (&o)[8]) { unpack8(*(const u32x4*)p, o); }
; __device__ __forceinline__ float sigmoidf_(float x) { return __builtin_amdgcn_rcpf(1.0f + __expf(-x)); }
; __device__ __forceinline__ const float* in_ptr(const Args& a, int i) { asm volatile("" : "+s"(i)); return a.in[i]; }
; __device__ __forceinline__ float hg_lb(const Args& a, int l, int ch) {
;     if (l == 0) return 0.f;
;     const float* hb = in_ptr(a, I_HLB); return sigmoidf_(hb[256 + ch] - hb[ch]);
; __device__ __forceinline__ void hg_lf_key(float fp, float lb, float& lf, float& key) {
;     const float e = __expf(-fabsf(fp));
;     const float rc = __builtin_amdgcn_rcpf(1.0f + e);
;     const float sp = fp >= 0.f ? rc : e * rc;
;     const float sn = fp >= 0.f ? e * rc : rc;
;     const float lsig = (fp >= 0.f ? 0.f : fp) + __logf(rc);
;     lf = (lb == 0.f) ? lsig : __logf(lb + (1.0f - lb) * sp); key = (1.0f - lb) * sn;
; }
; __device__ __forceinline__ void w_hg_scan(const float (&lbv)[8], const bf16_t* fsrc, int lane, float (&bb)[4][8], float (&r31)[8], float (&r63)[8]) {
;     const int lo = lane & 15;
; #pragma unroll
;     for (int tb = 0; tb < 4; ++tb) { float fp[8]; ld8bf(fsrc + (size_t)(16 * tb + lo) * NIN, fp);
; #pragma unroll
;         for (int j = 0; j < 8; ++j) { float key; hg_lf_key(fp[j], lbv[j], bb[tb][j], key); } }
.LBB0_337:
	s_mov_b32 s20, 11
	s_ashr_i32 s21, s20, 31
	s_lshl_b64 s[20:21], s[20:21], 3
	s_add_u32 s20, s0, s20
	s_addc_u32 s21, s1, s21
	s_load_dwordx2 s[20:21], s[20:21], 0x0
	s_waitcnt lgkmcnt(0)
	v_lshl_add_u64 v[36:37], v[36:37], 2, s[20:21]
	v_mov_b32_e32 v38, v127
	s_nop 0
	v_mov_b32_e32 v36, v193
	s_waitcnt vmcnt(0)
	v_sub_f32_e32 v36, v38, v36
	v_mul_f32_e32 v36, 0xbfb8aa3b, v36
	v_exp_f32_e32 v36, v36
	s_nop 0
	v_add_f32_e32 v36, 1.0, v36
	v_rcp_f32_e32 v71, v36
.LBB0_338:
	v_mov_b64_e32 v[36:37], v[238:239]
	v_mov_b64_e32 v[38:39], v[240:241]
	v_cmp_neq_f32_e64 s[38:39], 0, v56
	v_sub_f32_e32 v77, 1.0, v56
	s_waitcnt lgkmcnt(0)
	v_lshlrev_b32_e32 v60, 16, v36
	v_mul_f32_e64 v61, |v60|, s26
	v_exp_f32_e32 v68, v61
	v_cmp_le_f32_e32 vcc, 0, v60
	v_add_f32_e32 v61, 1.0, v68
	v_rcp_f32_e32 v61, v61
	s_and_saveexec_b64 s[20:21], s[38:39]
	s_xor_b64 s[34:35], exec, s[20:21]
	s_cbranch_execz .LBB0_340
	v_mul_f32_e32 v60, v68, v61
	v_cndmask_b32_e32 v60, v60, v61, vcc
	v_fma_f32 v60, v77, v60, v56
	v_cmp_gt_f32_e64 s[40:41], s29, v60
	s_nop 1
	v_cndmask_b32_e64 v61, 0, 32, s[40:41]
	v_ldexp_f32 v60, v60, v61
	v_log_f32_e32 v60, v60
	s_nop 0
	v_mul_f32_e32 v61, 0x3f317217, v60
	v_fma_f32 v61, v60, s17, -v61
	v_fmac_f32_e32 v61, 0x3377d1cf, v60
	v_fmac_f32_e32 v61, 0x3f317217, v60
	v_cmp_lt_f32_e64 s[42:43], |v60|, s22
	s_nop 1
	v_cndmask_b32_e64 v60, v60, v61, s[42:43]
	v_cndmask_b32_e64 v61, 0, v203, s[40:41]
	v_sub_f32_e32 v103, v60, v61

; __device__ __forceinline__ void ld8bf(const bf16_t* p, float (&o)[8]) { unpack8(*(const u32x4*)p, o); }
; __device__ __forceinline__ void hg_lf_key(float fp, float lb, float& lf, float& key) {
;     const float e = __expf(-fabsf(fp));
;     const float rc = __builtin_amdgcn_rcpf(1.0f + e);
;     const float sp = fp >= 0.f ? rc : e * rc;
;     const float sn = fp >= 0.f ? e * rc : rc;
;     const float lsig = (fp >= 0.f ? 0.f : fp) + __logf(rc);
;     lf = (lb == 0.f) ? lsig : __logf(lb + (1.0f - lb) * sp); key = (1.0f - lb) * sn;
; }
; __device__ __forceinline__ void w_hg_scan(const float (&lbv)[8], const bf16_t* fsrc, int lane, float (&bb)[4][8], float (&r31)[8], float (&r63)[8]) {
;     const int lo = lane & 15;
; #pragma unroll
;     for (int tb = 0; tb < 4; ++tb) { float fp[8]; ld8bf(fsrc + (size_t)(16 * tb + lo) * NIN, fp);
; #pragma unroll
;         for (int j = 0; j < 8; ++j) { float key; hg_lf_key(fp[j], lbv[j], bb[tb][j], key); } }
.LBB0_370:
	s_or_b64 exec, exec, s[34:35]
	v_lshl_add_u64 v[60:61], v[52:53], 0, 64
	v_add_co_u32_e32 v36, vcc, 0x18000, v60
	s_nop 1
	v_addc_co_u32_e32 v37, vcc, 0, v61, vcc
	v_mov_b64_e32 v[36:37], v[242:243]
	v_mov_b64_e32 v[38:39], v[244:245]
	s_waitcnt vmcnt(0) lgkmcnt(0)
	v_lshlrev_b32_e32 v52, 16, v36
	v_mul_f32_e64 v53, |v52|, s26
	v_exp_f32_e32 v83, v53
	v_cmp_le_f32_e32 vcc, 0, v52
	v_add_f32_e32 v53, 1.0, v83
	v_rcp_f32_e32 v53, v53
	s_and_saveexec_b64 s[20:21], s[38:39]
	s_xor_b64 s[34:35], exec, s[20:21]
	s_cbranch_execz .LBB0_372
	v_mul_f32_e32 v52, v83, v53
	v_cndmask_b32_e32 v52, v52, v53, vcc
	v_fma_f32 v52, v77, v52, v56
	v_cmp_gt_f32_e64 s[54:55], s29, v52
	s_nop 1
	v_cndmask_b32_e64 v53, 0, 32, s[54:55]
	v_ldexp_f32 v52, v52, v53
	v_log_f32_e32 v52, v52
	s_nop 0
	v_mul_f32_e32 v53, 0x3f317217, v52
	v_fma_f32 v53, v52, s17, -v53
	v_fmac_f32_e32 v53, 0x3377d1cf, v52
	v_fmac_f32_e32 v53, 0x3f317217, v52
	v_cmp_lt_f32_e64 s[56:57], |v52|, s22
	s_nop 1
	v_cndmask_b32_e64 v52, v52, v53, s[56:57]
	v_cndmask_b32_e64 v53, 0, v203, s[54:55]
	v_sub_f32_e32 v130, v52, v53

; __device__ __forceinline__ void ld8bf(const bf16_t* p, float (&o)[8]) { unpack8(*(const u32x4*)p, o); }
; __device__ __forceinline__ void hg_lf_key(float fp, float lb, float& lf, float& key) {
;     const float e = __expf(-fabsf(fp));
;     const float rc = __builtin_amdgcn_rcpf(1.0f + e);
;     const float sp = fp >= 0.f ? rc : e * rc;
;     const float sn = fp >= 0.f ? e * rc : rc;
;     const float lsig = (fp >= 0.f ? 0.f : fp) + __logf(rc);
;     lf = (lb == 0.f) ? lsig : __logf(lb + (1.0f - lb) * sp); key = (1.0f - lb) * sn;
; }
; __device__ __forceinline__ void w_hg_scan(const float (&lbv)[8], const bf16_t* fsrc, int lane, float (&bb)[4][8], float (&r31)[8], float (&r63)[8]) {
;     const int lo = lane & 15;
; #pragma unroll
;     for (int tb = 0; tb < 4; ++tb) { float fp[8]; ld8bf(fsrc + (size_t)(16 * tb + lo) * NIN, fp);
; #pragma unroll
;         for (int j = 0; j < 8; ++j) { float key; hg_lf_key(fp[j], lbv[j], bb[tb][j], key); } }
.LBB0_402:
	s_or_b64 exec, exec, s[34:35]
	v_add_co_u32_e32 v36, vcc, 0x30000, v60
	s_nop 1
	v_addc_co_u32_e32 v37, vcc, 0, v61, vcc
	v_mov_b64_e32 v[36:37], v[246:247]
	v_mov_b64_e32 v[38:39], v[248:249]
	s_waitcnt vmcnt(0) lgkmcnt(0)
	v_lshlrev_b32_e32 v52, 16, v36
	v_mul_f32_e64 v53, |v52|, s26
	v_exp_f32_e32 v83, v53
	v_cmp_le_f32_e32 vcc, 0, v52
	v_add_f32_e32 v53, 1.0, v83
	v_rcp_f32_e32 v53, v53
	s_and_saveexec_b64 s[20:21], s[38:39]
	s_xor_b64 s[34:35], exec, s[20:21]
	s_cbranch_execz .LBB0_404
	v_mul_f32_e32 v52, v83, v53
	v_cndmask_b32_e32 v52, v52, v53, vcc
	v_fma_f32 v52, v77, v52, v56
	v_cmp_gt_f32_e64 s[54:55], s29, v52
	s_nop 1
	v_cndmask_b32_e64 v53, 0, 32, s[54:55]
	v_ldexp_f32 v52, v52, v53
	v_log_f32_e32 v52, v52
	s_nop 0
	v_mul_f32_e32 v53, 0x3f317217, v52
	v_fma_f32 v53, v52, s17, -v53
	v_fmac_f32_e32 v53, 0x3377d1cf, v52
	v_fmac_f32_e32 v53, 0x3f317217, v52
	v_cmp_lt_f32_e64 s[56:57], |v52|, s22
	s_nop 1
	v_cndmask_b32_e64 v52, v52, v53, s[56:57]
	v_cndmask_b32_e64 v53, 0, v203, s[54:55]
	v_sub_f32_e32 v161, v52, v53

; __device__ __forceinline__ void ld8bf(const bf16_t* p, float (&o)[8]) { unpack8(*(const u32x4*)p, o); }
; __device__ __forceinline__ void hg_lf_key(float fp, float lb, float& lf, float& key) {
;     const float e = __expf(-fabsf(fp));
;     const float rc = __builtin_amdgcn_rcpf(1.0f + e);
;     const float sp = fp >= 0.f ? rc : e * rc;
;     const float sn = fp >= 0.f ? e * rc : rc;
;     const float lsig = (fp >= 0.f ? 0.f : fp) + __logf(rc);
;     lf = (lb == 0.f) ? lsig : __logf(lb + (1.0f - lb) * sp); key = (1.0f - lb) * sn;
; }
; __device__ __forceinline__ void w_hg_scan(const float (&lbv)[8], const bf16_t* fsrc, int lane, float (&bb)[4][8], float (&r31)[8], float (&r63)[8]) {
;     const int lo = lane & 15;
; #pragma unroll
;     for (int tb = 0; tb < 4; ++tb) { float fp[8]; ld8bf(fsrc + (size_t)(16 * tb + lo) * NIN, fp);
; #pragma unroll
;         for (int j = 0; j < 8; ++j) { float key; hg_lf_key(fp[j], lbv[j], bb[tb][j], key); } }
.LBB0_434:
	s_or_b64 exec, exec, s[34:35]
	v_add_co_u32_e32 v36, vcc, 0x48000, v60
	s_nop 1
	v_addc_co_u32_e32 v37, vcc, 0, v61, vcc
	v_mov_b64_e32 v[36:37], v[250:251]
	v_mov_b64_e32 v[38:39], v[252:253]
	s_waitcnt vmcnt(0) lgkmcnt(0)
	v_lshlrev_b32_e32 v52, 16, v36
	v_mul_f32_e64 v53, |v52|, s26
	v_exp_f32_e32 v83, v53
	v_cmp_le_f32_e32 vcc, 0, v52
	v_add_f32_e32 v53, 1.0, v83
	v_rcp_f32_e32 v53, v53
	s_and_saveexec_b64 s[20:21], s[38:39]
	s_xor_b64 s[34:35], exec, s[20:21]
	s_cbranch_execz .LBB0_436
	v_mul_f32_e32 v52, v83, v53
	v_cndmask_b32_e32 v52, v52, v53, vcc
	v_fma_f32 v52, v77, v52, v56
	v_cmp_gt_f32_e64 s[38:39], s29, v52
	s_nop 1
	v_cndmask_b32_e64 v53, 0, 32, s[38:39]
	v_ldexp_f32 v52, v52, v53
	v_log_f32_e32 v52, v52
	s_nop 0
	v_mul_f32_e32 v53, 0x3f317217, v52
	v_fma_f32 v53, v52, s17, -v53
	v_fmac_f32_e32 v53, 0x3377d1cf, v52
	v_fmac_f32_e32 v53, 0x3f317217, v52
	v_cmp_lt_f32_e64 s[54:55], |v52|, s22
	s_nop 1
	v_cndmask_b32_e64 v52, v52, v53, s[54:55]
	v_cndmask_b32_e64 v53, 0, v203, s[38:39]
	v_sub_f32_e32 v178, v52, v53

; __device__ __forceinline__ float sigmoidf_(float x) { return __builtin_amdgcn_rcpf(1.0f + __expf(-x)); }
; __device__ __forceinline__ const float* in_ptr(const Args& a, int i) { asm volatile("" : "+s"(i)); return a.in[i]; }
; __device__ __forceinline__ float hg_lb(const Args& a, int l, int ch) {
;     if (l == 0) return 0.f;
;     const float* hb = in_ptr(a, I_HLB); return sigmoidf_(hb[256 + ch] - hb[ch]);
; __device__ __forceinline__ void w_hg_m3(const Args& a, int l, unsigned char* ws, const bf16_t* proj, bf16_t* y, LAS unsigned char* wl, int b, int ck_, int h, int lane) {
;     ...
;     for (int kk = 0; kk < 2; ++kk) { float bb[4][8], r31[8], r63[8], lbv[8];
; #pragma unroll
;         for (int j = 0; j < 8; ++j) lbv[j] = hg_lb(a, l, 64 * h + 32 * kk + 8 * fq + j);
.LBB0_466:
	s_mov_b32 s20, 11
	s_ashr_i32 s21, s20, 31
	s_lshl_b64 s[20:21], s[20:21], 3
	s_add_u32 s20, s0, s20
	s_addc_u32 s21, s1, s21
	s_load_dwordx2 s[20:21], s[20:21], 0x0
	s_waitcnt lgkmcnt(0)
	v_lshl_add_u64 v[4:5], v[36:37], 2, s[20:21]
	global_load_dwordx4 v[186:189], v[4:5], off
	global_load_dwordx4 v[190:193], v[4:5], off offset:16
	global_load_dwordx4 v[194:197], v[4:5], off offset:1024
	global_load_dwordx2 v[198:199], v[4:5], off offset:1040
	global_load_dwordx2 v[126:127], v[4:5], off offset:1048
	s_waitcnt vmcnt(0)
	v_mov_b32_e32 v1, v194
	v_mov_b32_e32 v2, v186
	v_sub_f32_e32 v1, v1, v2
	v_mul_f32_e32 v1, 0xbfb8aa3b, v1
	v_exp_f32_e32 v1, v1
	s_nop 0
	v_add_f32_e32 v1, 1.0, v1
	v_rcp_f32_e32 v42, v1
	v_cndmask_b32_e64 v1, 0, 1, s[14:15]
	v_cmp_ne_u32_e64 s[38:39], 1, v1
	s_andn2_b64 vcc, exec, s[14:15]
	s_cbranch_vccnz .LBB0_194
.LBB0_467:
	s_mov_b32 s20, 11
	s_ashr_i32 s21, s20, 31
	s_lshl_b64 s[20:21], s[20:21], 3
	s_add_u32 s20, s0, s20
	s_addc_u32 s21, s1, s21
	s_load_dwordx2 s[20:21], s[20:21], 0x0
	s_waitcnt lgkmcnt(0)
	v_lshl_add_u64 v[4:5], v[36:37], 2, s[20:21]
	v_mov_b32_e32 v1, v195
	v_mov_b32_e32 v2, v187
	s_waitcnt vmcnt(0)
	v_sub_f32_e32 v1, v1, v2
	v_mul_f32_e32 v1, 0xbfb8aa3b, v1
	v_exp_f32_e32 v1, v1
	s_nop 0
	v_add_f32_e32 v1, 1.0, v1
	v_rcp_f32_e32 v43, v1
	v_mov_b32_e32 v45, 0
	s_and_b64 vcc, exec, s[38:39]
	v_mov_b32_e32 v44, 0
	s_cbranch_vccnz .LBB0_195
.LBB0_468:
	s_mov_b32 s20, 11
	s_ashr_i32 s21, s20, 31
	s_lshl_b64 s[20:21], s[20:21], 3
	s_add_u32 s20, s0, s20
	s_addc_u32 s21, s1, s21
	s_load_dwordx2 s[20:21], s[20:21], 0x0
	s_waitcnt lgkmcnt(0)
	v_lshl_add_u64 v[4:5], v[36:37], 2, s[20:21]
	v_mov_b32_e32 v1, v196
	v_mov_b32_e32 v2, v188
	s_waitcnt vmcnt(0)
	v_sub_f32_e32 v1, v1, v2
	v_mul_f32_e32 v1, 0xbfb8aa3b, v1
	v_exp_f32_e32 v1, v1
	s_nop 0
	v_add_f32_e32 v1, 1.0, v1
	v_rcp_f32_e32 v44, v1
	s_and_b64 vcc, exec, s[38:39]
	s_cbranch_vccnz .LBB0_196
.LBB0_469:
	s_mov_b32 s20, 11
	s_ashr_i32 s21, s20, 31
	s_lshl_b64 s[20:21], s[20:21], 3
	s_add_u32 s20, s0, s20
	s_addc_u32 s21, s1, s21
	s_load_dwordx2 s[20:21], s[20:21], 0x0
	s_waitcnt lgkmcnt(0)
	v_lshl_add_u64 v[4:5], v[36:37], 2, s[20:21]
	v_mov_b32_e32 v1, v197
	v_mov_b32_e32 v2, v189
	s_waitcnt vmcnt(0)
	v_sub_f32_e32 v1, v1, v2
	v_mul_f32_e32 v1, 0xbfb8aa3b, v1
	v_exp_f32_e32 v1, v1
	s_nop 0
	v_add_f32_e32 v1, 1.0, v1
	v_rcp_f32_e32 v45, v1
	v_mov_b32_e32 v47, 0
	s_and_b64 vcc, exec, s[38:39]
	v_mov_b32_e32 v46, 0
	s_cbranch_vccnz .LBB0_197
.LBB0_470:
	s_mov_b32 s20, 11
	s_ashr_i32 s21, s20, 31
	s_lshl_b64 s[20:21], s[20:21], 3
	s_add_u32 s20, s0, s20
	s_addc_u32 s21, s1, s21
	s_load_dwordx2 s[20:21], s[20:21], 0x0
	s_waitcnt lgkmcnt(0)
	v_lshl_add_u64 v[4:5], v[36:37], 2, s[20:21]
	v_mov_b32_e32 v1, v198
	v_mov_b32_e32 v2, v190
	s_waitcnt vmcnt(0)
	v_sub_f32_e32 v1, v1, v2
	v_mul_f32_e32 v1, 0xbfb8aa3b, v1
	v_exp_f32_e32 v1, v1
	s_nop 0
	v_add_f32_e32 v1, 1.0, v1
	v_rcp_f32_e32 v46, v1
	s_and_b64 vcc, exec, s[38:39]
	s_cbranch_vccnz .LBB0_198
.LBB0_471:
	s_mov_b32 s20, 11
	s_ashr_i32 s21, s20, 31
	s_lshl_b64 s[20:21], s[20:21], 3
	s_add_u32 s20, s0, s20
	s_addc_u32 s21, s1, s21
	s_load_dwordx2 s[20:21], s[20:21], 0x0
	s_waitcnt lgkmcnt(0)
	v_lshl_add_u64 v[4:5], v[36:37], 2, s[20:21]
	v_mov_b32_e32 v1, v199
	v_mov_b32_e32 v2, v191
	s_waitcnt vmcnt(0)
	v_sub_f32_e32 v1, v1, v2
	v_mul_f32_e32 v1, 0xbfb8aa3b, v1
	v_exp_f32_e32 v1, v1
	s_nop 0
	v_add_f32_e32 v1, 1.0, v1
	v_rcp_f32_e32 v47, v1
	v_mov_b32_e32 v11, 0
	s_and_b64 vcc, exec, s[38:39]
	v_mov_b32_e32 v12, 0
	s_cbranch_vccnz .LBB0_199
.LBB0_472:
	s_mov_b32 s20, 11
	s_ashr_i32 s21, s20, 31
	s_lshl_b64 s[20:21], s[20:21], 3
	s_add_u32 s20, s0, s20
	s_addc_u32 s21, s1, s21
	s_load_dwordx2 s[20:21], s[20:21], 0x0
	s_waitcnt lgkmcnt(0)
	v_lshl_add_u64 v[4:5], v[36:37], 2, s[20:21]
	v_mov_b32_e32 v1, v126
	v_mov_b32_e32 v2, v192
	s_waitcnt vmcnt(0)
	v_sub_f32_e32 v1, v1, v2
	v_mul_f32_e32 v1, 0xbfb8aa3b, v1
	v_exp_f32_e32 v1, v1
	s_nop 0
	v_add_f32_e32 v1, 1.0, v1
	v_rcp_f32_e32 v12, v1
	s_and_b64 vcc, exec, s[38:39]
	s_cbranch_vccz .LBB0_200
	s_branch .LBB0_201
; __device__ __forceinline__ float sigmoidf_(float x) { return __builtin_amdgcn_rcpf(1.0f + __expf(-x)); }
; __device__ __forceinline__ const float* in_ptr(const Args& a, int i) { asm volatile("" : "+s"(i)); return a.in[i]; }
; __device__ __forceinline__ float hg_lb(const Args& a, int l, int ch) {
;     if (l == 0) return 0.f;
;     const float* hb = in_ptr(a, I_HLB); return sigmoidf_(hb[256 + ch] - hb[ch]);
; __device__ __forceinline__ void w_hg_m3(const Args& a, int l, unsigned char* ws, const bf16_t* proj, bf16_t* y, LAS unsigned char* wl, int b, int ck_, int h, int lane) {
;     ...
;     for (int kk = 0; kk < 2; ++kk) { float bb[4][8], r31[8], r63[8], lbv[8];
; #pragma unroll
;         for (int j = 0; j < 8; ++j) lbv[j] = hg_lb(a, l, 64 * h + 32 * kk + 8 * fq + j);
.LBB0_473:
	s_mov_b32 s20, 11
	s_ashr_i32 s21, s20, 31
	s_lshl_b64 s[20:21], s[20:21], 3
	s_add_u32 s20, s0, s20
	s_addc_u32 s21, s1, s21
	s_load_dwordx2 s[20:21], s[20:21], 0x0
	s_waitcnt lgkmcnt(0)
	v_lshl_add_u64 v[38:39], v[36:37], 2, s[20:21]
	global_load_dwordx4 v[186:189], v[38:39], off offset:128
	global_load_dwordx4 v[190:193], v[38:39], off offset:144
	global_load_dwordx4 v[194:197], v[38:39], off offset:1152
	global_load_dwordx2 v[198:199], v[38:39], off offset:1168
	global_load_dwordx2 v[126:127], v[38:39], off offset:1176
	s_nop 0
	s_waitcnt vmcnt(0)
	v_mov_b32_e32 v50, v194
	v_mov_b32_e32 v38, v186
	v_sub_f32_e32 v38, v50, v38
	v_mul_f32_e32 v38, 0xbfb8aa3b, v38
	v_exp_f32_e32 v38, v38
	s_nop 0
	v_add_f32_e32 v38, 1.0, v38
	v_rcp_f32_e32 v56, v38
	s_and_b64 vcc, exec, s[38:39]
	s_cbranch_vccnz .LBB0_331
.LBB0_474:
	s_mov_b32 s20, 11
	s_ashr_i32 s21, s20, 31
	s_lshl_b64 s[20:21], s[20:21], 3
	s_add_u32 s20, s0, s20
	s_addc_u32 s21, s1, s21
	s_load_dwordx2 s[20:21], s[20:21], 0x0
	s_waitcnt lgkmcnt(0)
	v_lshl_add_u64 v[38:39], v[36:37], 2, s[20:21]
	v_mov_b32_e32 v50, v195
	s_nop 0
	v_mov_b32_e32 v38, v187
	s_waitcnt vmcnt(0)
	v_sub_f32_e32 v38, v50, v38
	v_mul_f32_e32 v38, 0xbfb8aa3b, v38
	v_exp_f32_e32 v38, v38
	s_nop 0
	v_add_f32_e32 v38, 1.0, v38
	v_rcp_f32_e32 v57, v38
	v_mov_b32_e32 v59, 0
	s_and_b64 vcc, exec, s[38:39]
	v_mov_b32_e32 v58, 0
	s_cbranch_vccnz .LBB0_332
.LBB0_475:
	s_mov_b32 s20, 11
	s_ashr_i32 s21, s20, 31
	s_lshl_b64 s[20:21], s[20:21], 3
	s_add_u32 s20, s0, s20
	s_addc_u32 s21, s1, s21
	s_load_dwordx2 s[20:21], s[20:21], 0x0
	s_waitcnt lgkmcnt(0)
	v_lshl_add_u64 v[38:39], v[36:37], 2, s[20:21]
	v_mov_b32_e32 v50, v196
	s_nop 0
	v_mov_b32_e32 v38, v188
	s_waitcnt vmcnt(0)
	v_sub_f32_e32 v38, v50, v38
	v_mul_f32_e32 v38, 0xbfb8aa3b, v38
	v_exp_f32_e32 v38, v38
	s_nop 0
	v_add_f32_e32 v38, 1.0, v38
	v_rcp_f32_e32 v58, v38
	s_and_b64 vcc, exec, s[38:39]
	s_cbranch_vccnz .LBB0_333
.LBB0_476:
	s_mov_b32 s20, 11
	s_ashr_i32 s21, s20, 31
	s_lshl_b64 s[20:21], s[20:21], 3
	s_add_u32 s20, s0, s20
	s_addc_u32 s21, s1, s21
	s_load_dwordx2 s[20:21], s[20:21], 0x0
	s_waitcnt lgkmcnt(0)
	v_lshl_add_u64 v[38:39], v[36:37], 2, s[20:21]
	v_mov_b32_e32 v50, v197
	s_nop 0
	v_mov_b32_e32 v38, v189
	s_waitcnt vmcnt(0)
	v_sub_f32_e32 v38, v50, v38
	v_mul_f32_e32 v38, 0xbfb8aa3b, v38
	v_exp_f32_e32 v38, v38
	s_nop 0
	v_add_f32_e32 v38, 1.0, v38
	v_rcp_f32_e32 v59, v38
	v_mov_b32_e32 v51, 0
	s_and_b64 vcc, exec, s[38:39]
	v_mov_b32_e32 v50, 0
	s_cbranch_vccnz .LBB0_334
.LBB0_477:
	s_mov_b32 s20, 11
	s_ashr_i32 s21, s20, 31
	s_lshl_b64 s[20:21], s[20:21], 3
	s_add_u32 s20, s0, s20
	s_addc_u32 s21, s1, s21
	s_load_dwordx2 s[20:21], s[20:21], 0x0
	s_waitcnt lgkmcnt(0)
	v_lshl_add_u64 v[38:39], v[36:37], 2, s[20:21]
	v_mov_b32_e32 v50, v198
	s_nop 0
	v_mov_b32_e32 v38, v190
	s_waitcnt vmcnt(0)
	v_sub_f32_e32 v38, v50, v38
	v_mul_f32_e32 v38, 0xbfb8aa3b, v38
	v_exp_f32_e32 v38, v38
	s_nop 0
	v_add_f32_e32 v38, 1.0, v38
	v_rcp_f32_e32 v50, v38
	s_and_b64 vcc, exec, s[38:39]
	s_cbranch_vccnz .LBB0_335
.LBB0_478:
	s_mov_b32 s20, 11
	s_ashr_i32 s21, s20, 31
	s_lshl_b64 s[20:21], s[20:21], 3
	s_add_u32 s20, s0, s20
	s_addc_u32 s21, s1, s21
	s_load_dwordx2 s[20:21], s[20:21], 0x0
	s_waitcnt lgkmcnt(0)
	v_lshl_add_u64 v[38:39], v[36:37], 2, s[20:21]
	v_mov_b32_e32 v51, v199
	s_nop 0
	v_mov_b32_e32 v38, v191
	s_waitcnt vmcnt(0)
	v_sub_f32_e32 v38, v51, v38
	v_mul_f32_e32 v38, 0xbfb8aa3b, v38
	v_exp_f32_e32 v38, v38
	s_nop 0
	v_add_f32_e32 v38, 1.0, v38
	v_rcp_f32_e32 v51, v38
	v_mov_b32_e32 v71, 0
	s_and_b64 vcc, exec, s[38:39]
	v_mov_b32_e32 v76, 0
	s_cbranch_vccnz .LBB0_336
.LBB0_479:
	s_mov_b32 s20, 11
	s_ashr_i32 s21, s20, 31
	s_lshl_b64 s[20:21], s[20:21], 3
	s_add_u32 s20, s0, s20
	s_addc_u32 s21, s1, s21
	s_load_dwordx2 s[20:21], s[20:21], 0x0
	s_waitcnt lgkmcnt(0)
	v_lshl_add_u64 v[38:39], v[36:37], 2, s[20:21]
	v_mov_b32_e32 v60, v126
	s_nop 0
	v_mov_b32_e32 v38, v192
	s_waitcnt vmcnt(0)
	v_sub_f32_e32 v38, v60, v38
	v_mul_f32_e32 v38, 0xbfb8aa3b, v38
	v_exp_f32_e32 v38, v38
	s_nop 0
	v_add_f32_e32 v38, 1.0, v38
	v_rcp_f32_e32 v76, v38
	s_and_b64 vcc, exec, s[38:39]
	s_cbranch_vccz .LBB0_337
	s_branch .LBB0_338

; __device__ __forceinline__ float sigmoidf_(float x) { return __builtin_amdgcn_rcpf(1.0f + __expf(-x)); }
; __device__ __forceinline__ const float* in_ptr(const Args& a, int i) { asm volatile("" : "+s"(i)); return a.in[i]; }
; __device__ __forceinline__ float hg_lb(const Args& a, int l, int ch) {
;     if (l == 0) return 0.f;
;     const float* hb = in_ptr(a, I_HLB); return sigmoidf_(hb[256 + ch] - hb[ch]);
.LBB0_540:
	s_mov_b32 s38, 11
	s_ashr_i32 s39, s38, 31
	s_lshl_b64 s[38:39], s[38:39], 3
	s_add_u32 s38, s0, s38
	s_addc_u32 s39, s1, s39
	s_load_dwordx2 s[38:39], s[38:39], 0x0
	s_waitcnt lgkmcnt(0)
	v_lshl_add_u64 v[4:5], v[12:13], 2, s[38:39]
	v_mov_b32_e32 v1, v127
	v_mov_b32_e32 v2, v193
	s_waitcnt vmcnt(0)
	v_sub_f32_e32 v1, v1, v2
	v_mul_f32_e32 v1, 0xbfb8aa3b, v1
	v_exp_f32_e32 v1, v1
	s_nop 0
	v_add_f32_e32 v1, 1.0, v1
	v_rcp_f32_e32 v10, v1

; __device__ __forceinline__ float sigmoidf_(float x) { return __builtin_amdgcn_rcpf(1.0f + __expf(-x)); }
; __device__ __forceinline__ const float* in_ptr(const Args& a, int i) { asm volatile("" : "+s"(i)); return a.in[i]; }
; __device__ __forceinline__ float hg_lb(const Args& a, int l, int ch) {
;     if (l == 0) return 0.f;
;     const float* hb = in_ptr(a, I_HLB); return sigmoidf_(hb[256 + ch] - hb[ch]);
.LBB0_679:
	s_mov_b32 s20, 11
	s_ashr_i32 s21, s20, 31
	s_lshl_b64 s[20:21], s[20:21], 3
	s_add_u32 s20, s0, s20
	s_addc_u32 s21, s1, s21
	s_load_dwordx2 s[20:21], s[20:21], 0x0
	s_waitcnt lgkmcnt(0)
	v_lshl_add_u64 v[4:5], v[12:13], 2, s[20:21]
	v_mov_b32_e32 v1, v127
	s_nop 0
	v_mov_b32_e32 v4, v193
	s_waitcnt vmcnt(0)
	v_sub_f32_e32 v1, v1, v4
	v_mul_f32_e32 v1, 0xbfb8aa3b, v1
	v_exp_f32_e32 v1, v1
	s_nop 0
	v_add_f32_e32 v1, 1.0, v1
	v_rcp_f32_e32 v1, v1

; __device__ __forceinline__ float sigmoidf_(float x) { return __builtin_amdgcn_rcpf(1.0f + __expf(-x)); }
; __device__ __forceinline__ const float* in_ptr(const Args& a, int i) { asm volatile("" : "+s"(i)); return a.in[i]; }
; __device__ __forceinline__ float hg_lb(const Args& a, int l, int ch) {
;     if (l == 0) return 0.f;
;     const float* hb = in_ptr(a, I_HLB); return sigmoidf_(hb[256 + ch] - hb[ch]);
.LBB0_810:
	s_mov_b32 s38, 11
	s_ashr_i32 s39, s38, 31
	s_lshl_b64 s[38:39], s[38:39], 3
	s_add_u32 s38, s0, s38
	s_addc_u32 s39, s1, s39
	s_load_dwordx2 s[38:39], s[38:39], 0x0
	s_waitcnt lgkmcnt(0)
	v_lshl_add_u64 v[4:5], v[12:13], 2, s[38:39]
	global_load_dwordx4 v[186:189], v[4:5], off
	global_load_dwordx4 v[190:193], v[4:5], off offset:16
	global_load_dwordx4 v[194:197], v[4:5], off offset:1024
	global_load_dwordx2 v[198:199], v[4:5], off offset:1040
	global_load_dwordx2 v[126:127], v[4:5], off offset:1048
	s_waitcnt vmcnt(0)
	v_mov_b32_e32 v1, v194
	v_mov_b32_e32 v2, v186
	v_sub_f32_e32 v1, v1, v2
	v_mul_f32_e32 v1, 0xbfb8aa3b, v1
	v_exp_f32_e32 v1, v1
	s_nop 0
	v_add_f32_e32 v1, 1.0, v1
	v_rcp_f32_e32 v22, v1
	v_cndmask_b32_e64 v1, 0, 1, s[36:37]
	v_cmp_ne_u32_e64 s[40:41], 1, v1
	s_andn2_b64 vcc, exec, s[36:37]
	s_cbranch_vccnz .LBB0_534
.LBB0_811:
	s_mov_b32 s38, 11
	s_ashr_i32 s39, s38, 31
	s_lshl_b64 s[38:39], s[38:39], 3
	s_add_u32 s38, s0, s38
	s_addc_u32 s39, s1, s39
	s_load_dwordx2 s[38:39], s[38:39], 0x0
	s_waitcnt lgkmcnt(0)
	v_lshl_add_u64 v[4:5], v[12:13], 2, s[38:39]
	v_mov_b32_e32 v1, v195
	v_mov_b32_e32 v2, v187
	s_waitcnt vmcnt(0)
	v_sub_f32_e32 v1, v1, v2
	v_mul_f32_e32 v1, 0xbfb8aa3b, v1
	v_exp_f32_e32 v1, v1
	s_nop 0
	v_add_f32_e32 v1, 1.0, v1
	v_rcp_f32_e32 v23, v1
	v_mov_b32_e32 v21, 0
	s_and_b64 vcc, exec, s[40:41]
	v_mov_b32_e32 v20, 0
	s_cbranch_vccnz .LBB0_535
.LBB0_812:
	s_mov_b32 s38, 11
	s_ashr_i32 s39, s38, 31
	s_lshl_b64 s[38:39], s[38:39], 3
	s_add_u32 s38, s0, s38
	s_addc_u32 s39, s1, s39
	s_load_dwordx2 s[38:39], s[38:39], 0x0
	s_waitcnt lgkmcnt(0)
	v_lshl_add_u64 v[4:5], v[12:13], 2, s[38:39]
	v_mov_b32_e32 v1, v196
	v_mov_b32_e32 v2, v188
	s_waitcnt vmcnt(0)
	v_sub_f32_e32 v1, v1, v2
	v_mul_f32_e32 v1, 0xbfb8aa3b, v1
	v_exp_f32_e32 v1, v1
	s_nop 0
	v_add_f32_e32 v1, 1.0, v1
	v_rcp_f32_e32 v20, v1
	s_and_b64 vcc, exec, s[40:41]
	s_cbranch_vccnz .LBB0_536
.LBB0_813:
	s_mov_b32 s38, 11
	s_ashr_i32 s39, s38, 31
	s_lshl_b64 s[38:39], s[38:39], 3
	s_add_u32 s38, s0, s38
	s_addc_u32 s39, s1, s39
	s_load_dwordx2 s[38:39], s[38:39], 0x0
	s_waitcnt lgkmcnt(0)
	v_lshl_add_u64 v[4:5], v[12:13], 2, s[38:39]
	v_mov_b32_e32 v1, v197
	v_mov_b32_e32 v2, v189
	s_waitcnt vmcnt(0)
	v_sub_f32_e32 v1, v1, v2
	v_mul_f32_e32 v1, 0xbfb8aa3b, v1
	v_exp_f32_e32 v1, v1
	s_nop 0
	v_add_f32_e32 v1, 1.0, v1
	v_rcp_f32_e32 v21, v1
	v_mov_b32_e32 v19, 0
	s_and_b64 vcc, exec, s[40:41]
	v_mov_b32_e32 v18, 0
	s_cbranch_vccnz .LBB0_537
.LBB0_814:
	s_mov_b32 s38, 11
	s_ashr_i32 s39, s38, 31
	s_lshl_b64 s[38:39], s[38:39], 3
	s_add_u32 s38, s0, s38
	s_addc_u32 s39, s1, s39
	s_load_dwordx2 s[38:39], s[38:39], 0x0
	s_waitcnt lgkmcnt(0)
	v_lshl_add_u64 v[4:5], v[12:13], 2, s[38:39]
	v_mov_b32_e32 v1, v198
	v_mov_b32_e32 v2, v190
	s_waitcnt vmcnt(0)
	v_sub_f32_e32 v1, v1, v2
	v_mul_f32_e32 v1, 0xbfb8aa3b, v1
	v_exp_f32_e32 v1, v1
	s_nop 0
	v_add_f32_e32 v1, 1.0, v1
	v_rcp_f32_e32 v18, v1
	s_and_b64 vcc, exec, s[40:41]
	s_cbranch_vccnz .LBB0_538
.LBB0_815:
	s_mov_b32 s38, 11
	s_ashr_i32 s39, s38, 31
	s_lshl_b64 s[38:39], s[38:39], 3
	s_add_u32 s38, s0, s38
	s_addc_u32 s39, s1, s39
	s_load_dwordx2 s[38:39], s[38:39], 0x0
	s_waitcnt lgkmcnt(0)
	v_lshl_add_u64 v[4:5], v[12:13], 2, s[38:39]
	v_mov_b32_e32 v1, v199
	v_mov_b32_e32 v2, v191
	s_waitcnt vmcnt(0)
	v_sub_f32_e32 v1, v1, v2
	v_mul_f32_e32 v1, 0xbfb8aa3b, v1
	v_exp_f32_e32 v1, v1
	s_nop 0
	v_add_f32_e32 v1, 1.0, v1
	v_rcp_f32_e32 v19, v1
	v_mov_b32_e32 v10, 0
	s_and_b64 vcc, exec, s[40:41]
	v_mov_b32_e32 v11, 0
	s_cbranch_vccnz .LBB0_539
.LBB0_816:
	s_mov_b32 s38, 11
	s_ashr_i32 s39, s38, 31
	s_lshl_b64 s[38:39], s[38:39], 3
	s_add_u32 s38, s0, s38
	s_addc_u32 s39, s1, s39
	s_load_dwordx2 s[38:39], s[38:39], 0x0
	s_waitcnt lgkmcnt(0)
	v_lshl_add_u64 v[4:5], v[12:13], 2, s[38:39]
	v_mov_b32_e32 v1, v126
	v_mov_b32_e32 v2, v192
	s_waitcnt vmcnt(0)
	v_sub_f32_e32 v1, v1, v2
	v_mul_f32_e32 v1, 0xbfb8aa3b, v1
	v_exp_f32_e32 v1, v1
	s_nop 0
	v_add_f32_e32 v1, 1.0, v1
	v_rcp_f32_e32 v11, v1
	s_and_b64 vcc, exec, s[40:41]
	s_cbranch_vccz .LBB0_540
	s_branch .LBB0_541
; __device__ __forceinline__ float sigmoidf_(float x) { return __builtin_amdgcn_rcpf(1.0f + __expf(-x)); }
; __device__ __forceinline__ const float* in_ptr(const Args& a, int i) { asm volatile("" : "+s"(i)); return a.in[i]; }
; __device__ __forceinline__ float hg_lb(const Args& a, int l, int ch) {
;     if (l == 0) return 0.f;
;     const float* hb = in_ptr(a, I_HLB); return sigmoidf_(hb[256 + ch] - hb[ch]);
.LBB0_817:
	s_mov_b32 s20, 11
	s_ashr_i32 s21, s20, 31
	s_lshl_b64 s[20:21], s[20:21], 3
	s_add_u32 s20, s0, s20
	s_addc_u32 s21, s1, s21
	s_load_dwordx2 s[20:21], s[20:21], 0x0
	s_waitcnt lgkmcnt(0)
	v_lshl_add_u64 v[4:5], v[12:13], 2, s[20:21]
	global_load_dwordx4 v[186:189], v[4:5], off offset:128
	global_load_dwordx4 v[190:193], v[4:5], off offset:144
	global_load_dwordx4 v[194:197], v[4:5], off offset:1152
	global_load_dwordx2 v[198:199], v[4:5], off offset:1168
	global_load_dwordx2 v[126:127], v[4:5], off offset:1176
	s_nop 0
	s_waitcnt vmcnt(0)
	v_mov_b32_e32 v1, v194
	v_mov_b32_e32 v4, v186
	v_sub_f32_e32 v1, v1, v4
	v_mul_f32_e32 v1, 0xbfb8aa3b, v1
	v_exp_f32_e32 v1, v1
	s_nop 0
	v_add_f32_e32 v1, 1.0, v1
	v_rcp_f32_e32 v20, v1
	s_and_b64 vcc, exec, s[40:41]
	s_cbranch_vccnz .LBB0_673
.LBB0_818:
	s_mov_b32 s20, 11
	s_ashr_i32 s21, s20, 31
	s_lshl_b64 s[20:21], s[20:21], 3
	s_add_u32 s20, s0, s20
	s_addc_u32 s21, s1, s21
	s_load_dwordx2 s[20:21], s[20:21], 0x0
	s_waitcnt lgkmcnt(0)
	v_lshl_add_u64 v[4:5], v[12:13], 2, s[20:21]
	v_mov_b32_e32 v1, v195
	s_nop 0
	v_mov_b32_e32 v4, v187
	s_waitcnt vmcnt(0)
	v_sub_f32_e32 v1, v1, v4
	v_mul_f32_e32 v1, 0xbfb8aa3b, v1
	v_exp_f32_e32 v1, v1
	s_nop 0
	v_add_f32_e32 v1, 1.0, v1
	v_rcp_f32_e32 v21, v1
	v_mov_b32_e32 v19, 0
	s_and_b64 vcc, exec, s[40:41]
	v_mov_b32_e32 v18, 0
	s_cbranch_vccnz .LBB0_674
.LBB0_819:
	s_mov_b32 s20, 11
	s_ashr_i32 s21, s20, 31
	s_lshl_b64 s[20:21], s[20:21], 3
	s_add_u32 s20, s0, s20
	s_addc_u32 s21, s1, s21
	s_load_dwordx2 s[20:21], s[20:21], 0x0
	s_waitcnt lgkmcnt(0)
	v_lshl_add_u64 v[4:5], v[12:13], 2, s[20:21]
	v_mov_b32_e32 v1, v196
	s_nop 0
	v_mov_b32_e32 v4, v188
	s_waitcnt vmcnt(0)
	v_sub_f32_e32 v1, v1, v4
	v_mul_f32_e32 v1, 0xbfb8aa3b, v1
	v_exp_f32_e32 v1, v1
	s_nop 0
	v_add_f32_e32 v1, 1.0, v1
	v_rcp_f32_e32 v18, v1
	s_and_b64 vcc, exec, s[40:41]
	s_cbranch_vccnz .LBB0_675
.LBB0_820:
	s_mov_b32 s20, 11
	s_ashr_i32 s21, s20, 31
	s_lshl_b64 s[20:21], s[20:21], 3
	s_add_u32 s20, s0, s20
	s_addc_u32 s21, s1, s21
	s_load_dwordx2 s[20:21], s[20:21], 0x0
	s_waitcnt lgkmcnt(0)
	v_lshl_add_u64 v[4:5], v[12:13], 2, s[20:21]
	v_mov_b32_e32 v1, v197
	s_nop 0
	v_mov_b32_e32 v4, v189
	s_waitcnt vmcnt(0)
	v_sub_f32_e32 v1, v1, v4
	v_mul_f32_e32 v1, 0xbfb8aa3b, v1
	v_exp_f32_e32 v1, v1
	s_nop 0
	v_add_f32_e32 v1, 1.0, v1
	v_rcp_f32_e32 v19, v1
	v_mov_b32_e32 v17, 0
	s_and_b64 vcc, exec, s[40:41]
	v_mov_b32_e32 v16, 0
	s_cbranch_vccnz .LBB0_676
.LBB0_821:
	s_mov_b32 s20, 11
	s_ashr_i32 s21, s20, 31
	s_lshl_b64 s[20:21], s[20:21], 3
	s_add_u32 s20, s0, s20
	s_addc_u32 s21, s1, s21
	s_load_dwordx2 s[20:21], s[20:21], 0x0
	s_waitcnt lgkmcnt(0)
	v_lshl_add_u64 v[4:5], v[12:13], 2, s[20:21]
	v_mov_b32_e32 v1, v198
	s_nop 0
	v_mov_b32_e32 v4, v190
	s_waitcnt vmcnt(0)
	v_sub_f32_e32 v1, v1, v4
	v_mul_f32_e32 v1, 0xbfb8aa3b, v1
	v_exp_f32_e32 v1, v1
	s_nop 0
	v_add_f32_e32 v1, 1.0, v1
	v_rcp_f32_e32 v16, v1
	s_and_b64 vcc, exec, s[40:41]
	s_cbranch_vccnz .LBB0_677
.LBB0_822:
	s_mov_b32 s20, 11
	s_ashr_i32 s21, s20, 31
	s_lshl_b64 s[20:21], s[20:21], 3
	s_add_u32 s20, s0, s20
	s_addc_u32 s21, s1, s21
	s_load_dwordx2 s[20:21], s[20:21], 0x0
	s_waitcnt lgkmcnt(0)
	v_lshl_add_u64 v[4:5], v[12:13], 2, s[20:21]
	v_mov_b32_e32 v1, v199
	s_nop 0
	v_mov_b32_e32 v4, v191
	s_waitcnt vmcnt(0)
	v_sub_f32_e32 v1, v1, v4
	v_mul_f32_e32 v1, 0xbfb8aa3b, v1
	v_exp_f32_e32 v1, v1
	s_nop 0
	v_add_f32_e32 v1, 1.0, v1
	v_rcp_f32_e32 v17, v1
	v_mov_b32_e32 v1, 0
	s_and_b64 vcc, exec, s[40:41]
	v_mov_b32_e32 v23, 0
	s_cbranch_vccnz .LBB0_678
.LBB0_823:
	s_mov_b32 s20, 11
	s_ashr_i32 s21, s20, 31
	s_lshl_b64 s[20:21], s[20:21], 3
	s_add_u32 s20, s0, s20
	s_addc_u32 s21, s1, s21
	s_load_dwordx2 s[20:21], s[20:21], 0x0
	s_waitcnt lgkmcnt(0)
	v_lshl_add_u64 v[4:5], v[12:13], 2, s[20:21]
	v_mov_b32_e32 v6, v126
	s_nop 0
	v_mov_b32_e32 v4, v192
	s_waitcnt vmcnt(0)
	v_sub_f32_e32 v4, v6, v4
	v_mul_f32_e32 v4, 0xbfb8aa3b, v4
	v_exp_f32_e32 v4, v4
	s_nop 0
	v_add_f32_e32 v4, 1.0, v4
	v_rcp_f32_e32 v23, v4
	s_and_b64 vcc, exec, s[40:41]
	s_cbranch_vccz .LBB0_679
	s_branch .LBB0_680
